# write-through (sc1) on all 16-byte global stores so the barrier L2 write-back finds less dirty data
# baseline (speedup 1.0000x reference)
; template <bool COMBINE, bool MOD>
; __device__ __forceinline__ void phase_combine_modulate(const Params& p, int lprev, int lnext, const float* xlat, const float* xctx,
;                                                        float* olat, float* octx, int nrows) {
;     ...
; #pragma unroll
;         for (int i = 0; i < 4; ++i) {
;           const int col = i * 256 + lane * 4;
;           const float4 g4 = *(const float4*)(g2 + col);
;           v[r][i].x += g4.x * s[i].x; v[r][i].y += g4.y * s[i].y; v[r][i].z += g4.z * s[i].z; v[r][i].w += g4.w * s[i].w;
;           *(float4*)(orow + (size_t)r * DM + col) = v[r][i];
;         }
;       }
;     }
;     if (MOD) {
;       const float* sh = p.mada + (size_t)(lnext * 3 + cond) * 6144;
;       const float* sc = sh + 1024;
;       float rstd[R];
; #pragma unroll
;       for (int r = 0; r < R; ++r) {
;         float ss = 0.f;
; #pragma unroll
;         for (int i = 0; i < 4; ++i) ss += v[r][i].x * v[r][i].x + v[r][i].y * v[r][i].y + v[r][i].z * v[r][i].z + v[r][i].w * v[r][i].w;
;         rstd[r] = rsqrtf(wave_sum(ss) * (1.f / 1024.f) + 1e-6f);
.Lcb1_acc1:
	v_pk_fma_f32 v[100:101], v[34:35], v[2:3], v[100:101]
	v_pk_fma_f32 v[102:103], v[36:37], v[4:5], v[102:103]
	global_store_dwordx4 v188, v[100:103], s[98:99] sc1
	v_pk_fma_f32 v[104:105], v[38:39], v[6:7], v[104:105]
	v_pk_fma_f32 v[106:107], v[40:41], v[8:9], v[106:107]
	global_store_dwordx4 v188, v[104:107], s[98:99] offset:1024 sc1
	v_pk_fma_f32 v[108:109], v[42:43], v[10:11], v[108:109]
	v_pk_fma_f32 v[110:111], v[44:45], v[12:13], v[110:111]
	global_store_dwordx4 v188, v[108:111], s[98:99] offset:2048 sc1
	v_pk_fma_f32 v[112:113], v[46:47], v[14:15], v[112:113]
	v_pk_fma_f32 v[114:115], v[48:49], v[16:17], v[114:115]
	global_store_dwordx4 v188, v[112:115], s[98:99] offset:3072 sc1
	v_pk_fma_f32 v[116:117], v[34:35], v[18:19], v[116:117]
	v_pk_fma_f32 v[118:119], v[36:37], v[20:21], v[118:119]
	global_store_dwordx4 v189, v[116:119], s[98:99] sc1
	v_pk_fma_f32 v[120:121], v[38:39], v[22:23], v[120:121]
	v_pk_fma_f32 v[122:123], v[40:41], v[24:25], v[122:123]
	global_store_dwordx4 v189, v[120:123], s[98:99] offset:1024 sc1
	v_pk_fma_f32 v[124:125], v[42:43], v[26:27], v[124:125]
	v_pk_fma_f32 v[126:127], v[44:45], v[28:29], v[126:127]
	global_store_dwordx4 v189, v[124:127], s[98:99] offset:2048 sc1
	v_pk_fma_f32 v[128:129], v[46:47], v[30:31], v[128:129]
	v_pk_fma_f32 v[130:131], v[48:49], v[32:33], v[130:131]
	global_store_dwordx4 v189, v[128:131], s[98:99] offset:3072 sc1
	v_pk_mul_f32 v[2:3], v[100:101], v[100:101]
	v_pk_fma_f32 v[2:3], v[102:103], v[102:103], v[2:3]
	v_pk_fma_f32 v[2:3], v[104:105], v[104:105], v[2:3]
	v_pk_fma_f32 v[2:3], v[106:107], v[106:107], v[2:3]
	v_pk_fma_f32 v[2:3], v[108:109], v[108:109], v[2:3]
	v_pk_fma_f32 v[2:3], v[110:111], v[110:111], v[2:3]
	v_pk_fma_f32 v[2:3], v[112:113], v[112:113], v[2:3]
	v_pk_fma_f32 v[2:3], v[114:115], v[114:115], v[2:3]
	v_pk_mul_f32 v[4:5], v[116:117], v[116:117]
	v_pk_fma_f32 v[4:5], v[118:119], v[118:119], v[4:5]
	v_pk_fma_f32 v[4:5], v[120:121], v[120:121], v[4:5]
	v_pk_fma_f32 v[4:5], v[122:123], v[122:123], v[4:5]
	v_pk_fma_f32 v[4:5], v[124:125], v[124:125], v[4:5]
	v_pk_fma_f32 v[4:5], v[126:127], v[126:127], v[4:5]
	v_pk_fma_f32 v[4:5], v[128:129], v[128:129], v[4:5]
	v_pk_fma_f32 v[4:5], v[130:131], v[130:131], v[4:5]
	v_add_f32_e32 v6, v2, v3
	v_add_f32_e32 v7, v4, v5
	s_nop 1
	v_add_f32_dpp v6, v6, v6 quad_perm:[1,0,3,2] row_mask:0xf bank_mask:0xf
	v_add_f32_dpp v7, v7, v7 quad_perm:[1,0,3,2] row_mask:0xf bank_mask:0xf
	s_nop 1
	v_add_f32_dpp v6, v6, v6 quad_perm:[2,3,0,1] row_mask:0xf bank_mask:0xf
	v_add_f32_dpp v7, v7, v7 quad_perm:[2,3,0,1] row_mask:0xf bank_mask:0xf
	s_nop 1
	v_add_f32_dpp v6, v6, v6 row_half_mirror row_mask:0xf bank_mask:0xf
	v_add_f32_dpp v7, v7, v7 row_half_mirror row_mask:0xf bank_mask:0xf
	s_nop 1
	v_add_f32_dpp v6, v6, v6 row_mirror row_mask:0xf bank_mask:0xf
	v_add_f32_dpp v7, v7, v7 row_mirror row_mask:0xf bank_mask:0xf
	ds_bpermute_b32 v8, v208, v6
	ds_bpermute_b32 v9, v208, v7
	s_waitcnt lgkmcnt(0)
	v_pk_add_f32 v[6:7], v[6:7], v[8:9]
	ds_bpermute_b32 v8, v209, v6
	ds_bpermute_b32 v9, v209, v7
	s_waitcnt lgkmcnt(0)
; template <bool COMBINE, bool MOD>
; __device__ __forceinline__ void phase_combine_modulate(const Params& p, int lprev, int lnext, const float* xlat, const float* xctx,
;                                                        float* olat, float* octx, int nrows) {
;     ...
;       float rstd[R];
; #pragma unroll
;       for (int r = 0; r < R; ++r) {
;         float ss = 0.f;
; #pragma unroll
;         for (int i = 0; i < 4; ++i) ss += v[r][i].x * v[r][i].x + v[r][i].y * v[r][i].y + v[r][i].z * v[r][i].z + v[r][i].w * v[r][i].w;
;         rstd[r] = rsqrtf(wave_sum(ss) * (1.f / 1024.f) + 1e-6f);
;       }
; #pragma unroll
;       for (int i = 0; i < 4; ++i) {
;         const int col = i * 256 + lane * 4;
;         const float4 s4 = *(const float4*)(sc + col);
;         const float4 h4 = *(const float4*)(sh + col);
; #pragma unroll
;         for (int r = 0; r < R; ++r) {
;           u32x2 pk;
;           pk.x = pack2(v[r][i].x * rstd[r] * (1.f + s4.x) + h4.x, v[r][i].y * rstd[r] * (1.f + s4.y) + h4.y);
;           pk.y = pack2(v[r][i].z * rstd[r] * (1.f + s4.z) + h4.z, v[r][i].w * rstd[r] * (1.f + s4.w) + h4.w);
;           *(u32x2*)(p.H + (size_t)(row0 + r) * DM + col) = pk;
;         }
;       }
	v_pk_add_f32 v[6:7], v[6:7], v[8:9]
	s_nop 0
	v_fma_f32 v6, v6, s18, v224
	v_fma_f32 v7, v7, s18, v224
	v_cmp_gt_f32_e32 vcc, s85, v6
	v_mul_f32_e32 v10, 0x4b800000, v6
	s_nop 1
	v_cndmask_b32_e32 v10, v6, v10, vcc
	v_rsq_f32_e32 v10, v10
	s_nop 0
	v_mul_f32_e32 v6, 0x45800000, v10
	v_cndmask_b32_e32 v10, v10, v6, vcc
	v_cmp_gt_f32_e32 vcc, s85, v7
	v_mul_f32_e32 v12, 0x4b800000, v7
	s_nop 1
	v_cndmask_b32_e32 v12, v7, v12, vcc
	v_rsq_f32_e32 v12, v12
	s_nop 0
	v_mul_f32_e32 v7, 0x45800000, v12
	v_cndmask_b32_e32 v12, v12, v7, vcc
	v_pk_add_f32 v[66:67], v[66:67], 1.0 op_sel_hi:[1,0]
	v_pk_add_f32 v[68:69], v[68:69], 1.0 op_sel_hi:[1,0]
	v_pk_mul_f32 v[14:15], v[100:101], v[10:11] op_sel_hi:[1,0]
	v_pk_mul_f32 v[16:17], v[102:103], v[10:11] op_sel_hi:[1,0]
	v_pk_fma_f32 v[14:15], v[66:67], v[14:15], v[50:51]
	v_pk_fma_f32 v[16:17], v[68:69], v[16:17], v[52:53]
	v_cvt_pk_bf16_f32 v164, v14, v15
	v_cvt_pk_bf16_f32 v165, v16, v17
	global_store_dwordx2 v190, v[164:165], s[46:47]
	v_pk_mul_f32 v[18:19], v[116:117], v[12:13] op_sel_hi:[1,0]
	v_pk_mul_f32 v[20:21], v[118:119], v[12:13] op_sel_hi:[1,0]
	v_pk_fma_f32 v[18:19], v[66:67], v[18:19], v[50:51]
	v_pk_fma_f32 v[20:21], v[68:69], v[20:21], v[52:53]
	v_cvt_pk_bf16_f32 v166, v18, v19
	v_cvt_pk_bf16_f32 v167, v20, v21
	global_store_dwordx2 v190, v[166:167], s[46:47] offset:2048
	v_pk_add_f32 v[70:71], v[70:71], 1.0 op_sel_hi:[1,0]
	v_pk_add_f32 v[72:73], v[72:73], 1.0 op_sel_hi:[1,0]
	v_pk_mul_f32 v[14:15], v[104:105], v[10:11] op_sel_hi:[1,0]
	v_pk_mul_f32 v[16:17], v[106:107], v[10:11] op_sel_hi:[1,0]
	v_pk_fma_f32 v[14:15], v[70:71], v[14:15], v[54:55]
	v_pk_fma_f32 v[16:17], v[72:73], v[16:17], v[56:57]
	v_cvt_pk_bf16_f32 v168, v14, v15
	v_cvt_pk_bf16_f32 v169, v16, v17
	global_store_dwordx2 v190, v[168:169], s[46:47] offset:512
	v_pk_mul_f32 v[18:19], v[120:121], v[12:13] op_sel_hi:[1,0]
	v_pk_mul_f32 v[20:21], v[122:123], v[12:13] op_sel_hi:[1,0]
	v_pk_fma_f32 v[18:19], v[70:71], v[18:19], v[54:55]
	v_pk_fma_f32 v[20:21], v[72:73], v[20:21], v[56:57]
	v_cvt_pk_bf16_f32 v170, v18, v19
	v_cvt_pk_bf16_f32 v171, v20, v21
	global_store_dwordx2 v190, v[170:171], s[46:47] offset:2560
	v_pk_add_f32 v[74:75], v[74:75], 1.0 op_sel_hi:[1,0]
	v_pk_add_f32 v[76:77], v[76:77], 1.0 op_sel_hi:[1,0]
	v_pk_mul_f32 v[14:15], v[108:109], v[10:11] op_sel_hi:[1,0]
	v_pk_mul_f32 v[16:17], v[110:111], v[10:11] op_sel_hi:[1,0]
	v_pk_fma_f32 v[14:15], v[74:75], v[14:15], v[58:59]
	v_pk_fma_f32 v[16:17], v[76:77], v[16:17], v[60:61]
	v_cvt_pk_bf16_f32 v172, v14, v15
	v_cvt_pk_bf16_f32 v173, v16, v17
	global_store_dwordx2 v190, v[172:173], s[46:47] offset:1024
	v_pk_mul_f32 v[18:19], v[124:125], v[12:13] op_sel_hi:[1,0]
	v_pk_mul_f32 v[20:21], v[126:127], v[12:13] op_sel_hi:[1,0]
	v_pk_fma_f32 v[18:19], v[74:75], v[18:19], v[58:59]
	v_pk_fma_f32 v[20:21], v[76:77], v[20:21], v[60:61]
	v_cvt_pk_bf16_f32 v174, v18, v19
	v_cvt_pk_bf16_f32 v175, v20, v21
	global_store_dwordx2 v190, v[174:175], s[46:47] offset:3072
	v_pk_add_f32 v[78:79], v[78:79], 1.0 op_sel_hi:[1,0]
	v_pk_add_f32 v[80:81], v[80:81], 1.0 op_sel_hi:[1,0]
	v_pk_mul_f32 v[14:15], v[112:113], v[10:11] op_sel_hi:[1,0]
	v_pk_mul_f32 v[16:17], v[114:115], v[10:11] op_sel_hi:[1,0]
	v_pk_fma_f32 v[14:15], v[78:79], v[14:15], v[62:63]
	v_pk_fma_f32 v[16:17], v[80:81], v[16:17], v[64:65]
	v_cvt_pk_bf16_f32 v176, v14, v15
	v_cvt_pk_bf16_f32 v177, v16, v17
	global_store_dwordx2 v190, v[176:177], s[46:47] offset:1536
	v_pk_mul_f32 v[18:19], v[128:129], v[12:13] op_sel_hi:[1,0]
	v_pk_mul_f32 v[20:21], v[130:131], v[12:13] op_sel_hi:[1,0]
	v_pk_fma_f32 v[18:19], v[78:79], v[18:19], v[62:63]
	v_pk_fma_f32 v[20:21], v[80:81], v[20:21], v[64:65]
	v_cvt_pk_bf16_f32 v178, v18, v19
	v_cvt_pk_bf16_f32 v179, v20, v21
	global_store_dwordx2 v190, v[178:179], s[46:47] offset:3584
	v_mov_b32_e32 v100, v132
	v_mov_b32_e32 v101, v133
	v_mov_b32_e32 v102, v134
	v_mov_b32_e32 v103, v135
	v_mov_b32_e32 v104, v136
	v_mov_b32_e32 v105, v137
	v_mov_b32_e32 v106, v138
	v_mov_b32_e32 v107, v139
	v_mov_b32_e32 v108, v140
	v_mov_b32_e32 v109, v141
	v_mov_b32_e32 v110, v142
	v_mov_b32_e32 v111, v143
	v_mov_b32_e32 v112, v144
	v_mov_b32_e32 v113, v145
	v_mov_b32_e32 v114, v146
	v_mov_b32_e32 v115, v147
	v_mov_b32_e32 v116, v148
	v_mov_b32_e32 v117, v149
	v_mov_b32_e32 v118, v150
	v_mov_b32_e32 v119, v151
	v_mov_b32_e32 v120, v152
	v_mov_b32_e32 v121, v153
	v_mov_b32_e32 v122, v154
	v_mov_b32_e32 v123, v155
	v_mov_b32_e32 v124, v156
	v_mov_b32_e32 v125, v157
	v_mov_b32_e32 v126, v158
	v_mov_b32_e32 v127, v159
	v_mov_b32_e32 v128, v160
	v_mov_b32_e32 v129, v161
	v_mov_b32_e32 v130, v162
	v_mov_b32_e32 v131, v163
	v_mov_b32_e32 v199, v211
	s_mov_b64 s[98:99], s[100:101]
	s_mov_b32 s52, s94
	s_cmp_lt_i32 s52, s68
	s_cbranch_scc1 .Lcb1_loop
	s_waitcnt vmcnt(0)

; template <int NT, class VF, class RP>
; __device__ __forceinline__ void epi_staged_bf16(f32x4 (&acc)[4][NT], int r0, int c0, unsigned char* smem, VF vf, RP rowptr) {
;     ...
; #pragma unroll
;   for (int i = 0; i < CPR / 2; ++i) {
;     const int c = t + 256 * i, row = c / CPR, ch = c % CPR;
;     u16* d = rowptr(row);
;     if (d) *(u32x4*)(d + ch * 8) = *(const u32x4*)(Ts + row * PITCH + ch * 8);
;   }
.LBB0_326:
	v_lshlrev_b32_e32 v0, 4, v6
	v_sub_u32_e32 v0, v66, v0
	v_mul_lo_u32 v2, v6, s23
	v_lshl_add_u32 v2, v0, 4, v2
	ds_read_b128 v[6:9], v2
	v_lshlrev_b32_e32 v2, 3, v0
	v_ashrrev_i32_e32 v3, 31, v2
	v_lshl_add_u64 v[2:3], v[2:3], 1, v[4:5]
	s_waitcnt lgkmcnt(0)
	global_store_dwordx4 v[2:3], v[6:9], off sc1

; template <int NT, class VF, class RP>
; __device__ __forceinline__ void epi_staged_bf16(f32x4 (&acc)[4][NT], int r0, int c0, unsigned char* smem, VF vf, RP rowptr) {
;     ...
; #pragma unroll
;   for (int i = 0; i < CPR / 2; ++i) {
;     const int c = t + 256 * i, row = c / CPR, ch = c % CPR;
;     u16* d = rowptr(row);
;     if (d) *(u32x4*)(d + ch * 8) = *(const u32x4*)(Ts + row * PITCH + ch * 8);
;   }
.LBB0_338:
	v_lshlrev_b32_e32 v0, 4, v7
	v_sub_u32_e32 v0, v6, v0
	v_mul_lo_u32 v2, v7, s23
	v_lshl_add_u32 v2, v0, 4, v2
	ds_read_b128 v[6:9], v2
	v_lshlrev_b32_e32 v2, 3, v0
	v_ashrrev_i32_e32 v3, 31, v2
	v_lshl_add_u64 v[2:3], v[2:3], 1, v[4:5]
	s_waitcnt lgkmcnt(0)
	global_store_dwordx4 v[2:3], v[6:9], off sc1

; template <int NT, class VF, class RP>
; __device__ __forceinline__ void epi_staged_bf16(f32x4 (&acc)[4][NT], int r0, int c0, unsigned char* smem, VF vf, RP rowptr) {
;     ...
; #pragma unroll
;   for (int i = 0; i < CPR / 2; ++i) {
;     const int c = t + 256 * i, row = c / CPR, ch = c % CPR;
;     u16* d = rowptr(row);
;     if (d) *(u32x4*)(d + ch * 8) = *(const u32x4*)(Ts + row * PITCH + ch * 8);
;   }
.LBB0_484:
	v_lshlrev_b32_e32 v0, 4, v7
	v_sub_u32_e32 v0, v6, v0
	v_mul_lo_u32 v2, v7, s23
	v_lshl_add_u32 v2, v0, 4, v2
	ds_read_b128 v[6:9], v2
	v_lshlrev_b32_e32 v2, 3, v0
	v_ashrrev_i32_e32 v3, 31, v2
	v_lshl_add_u64 v[2:3], v[2:3], 1, v[4:5]
	s_waitcnt lgkmcnt(0)
	global_store_dwordx4 v[2:3], v[6:9], off sc1
	s_branch .LBB0_242

; #define XCD_FOR(u, T)                                                                                         \
;   for (int _x = bid_() & 7, _gb = gridDim.x >> 3, _hi = (int)(((long)(_x + 1) * (T)) >> 3),                    \
;            u = (int)(((long)_x * (T)) >> 3) + (bid_() >> 3);                                                  \
;        u < _hi; u += _gb)
; template <int NT, bool BKN, bool MASK = false, bool ROWSS = false, class Epi> ...
;     ...
;   for (int kt = 0; kt < nk - 2; kt += 2) {
;     GEMM_COMPUTE(0);
;     GEMM_STORE(ra1, rb1, 1);
;     GEMM_LOAD(ra1, rb1, kt + 3);
;     __syncthreads();
;     GEMM_COMPUTE(1);
;     GEMM_STORE(ra0, rb0, 0);
;     GEMM_LOAD(ra0, rb0, (kt + 4 < nkm1 ? kt + 4 : nkm1));
;     __syncthreads();
;   }
; __device__ __forceinline__ void phase_in_gemm(const Params& p, int l, unsigned char* smem) {
;     ...
;   XCD_FOR(t, 132) {
;     const int row_base = t * 128;
;     auto epi = [&](f32x4(&acc)[4][2], int r0, int c0) {
;       auto vf = [&](int, int, float v) { return v; };
;       auto rp = [&](int r) -> u16* { return p.PX + (size_t)(row_base + r) * 1024 + 896; };
;       epi_staged_bf16<2>(acc, r0, c0, smem, vf, rp);
;     };
;     gemm_tile<2, false>(p.H + (size_t)row_base * 1024, 1024, nullptr, 128, W + (size_t)11 * 128 * 1024, 1024, 1024, smem, epi);
;   }
.LBB0_488:
	s_nop 0
	ds_read_b128 v[112:115], v109
	ds_read_b128 v[116:119], v109 offset:2048
	ds_read_b128 v[120:123], v109 offset:4096
	ds_read_b128 v[124:127], v109 offset:6144
	ds_read_b128 v[128:131], v108 offset:16384
	ds_read_b128 v[132:135], v108 offset:18432
	s_mov_b32 s9, 0x2c0000
	s_add_i32 s8, s8, 2
	s_waitcnt lgkmcnt(0)
	v_mfma_f32_16x16x32_bf16 v[78:81], v[112:115], v[128:131], v[78:81]
	s_waitcnt lgkmcnt(0)
	v_mfma_f32_16x16x32_bf16 v[74:77], v[112:115], v[132:135], v[74:77]
	v_mfma_f32_16x16x32_bf16 v[70:73], v[116:119], v[128:131], v[70:73]
	v_mfma_f32_16x16x32_bf16 v[66:69], v[116:119], v[132:135], v[66:69]
	v_mfma_f32_16x16x32_bf16 v[62:65], v[120:123], v[128:131], v[62:65]
	v_mfma_f32_16x16x32_bf16 v[58:61], v[120:123], v[132:135], v[58:61]
	v_mfma_f32_16x16x32_bf16 v[112:115], v[124:127], v[128:131], v[54:57]
	v_mfma_f32_16x16x32_bf16 v[116:119], v[124:127], v[132:135], v[50:53]
	s_nop 2
	ds_read_b128 v[50:53], v107
	ds_read_b128 v[54:57], v107 offset:2048
	ds_read_b128 v[120:123], v107 offset:4096
	ds_read_b128 v[124:127], v107 offset:6144
	ds_read_b128 v[128:131], v106 offset:16384
	ds_read_b128 v[132:135], v106 offset:18432
	s_waitcnt vmcnt(0)
	ds_write_b128 v110, v[2:5] offset:32768
	ds_write_b128 v110, v[10:13] offset:36864
	ds_write_b128 v110, v[14:17] offset:40960
	ds_write_b128 v110, v[18:21] offset:45056
	ds_write_b128 v110, v[6:9] offset:49152
	ds_write_b128 v110, v[22:25] offset:53248
	v_lshl_add_u64 v[6:7], v[100:101], 0, v[0:1]
	v_add_co_u32_e32 v8, vcc, s15, v6
	global_load_dwordx4 v[2:5], v[6:7], off offset:384
	s_nop 0
	v_addc_co_u32_e32 v9, vcc, 0, v7, vcc
	global_load_dwordx4 v[10:13], v[8:9], off offset:384
	v_add_co_u32_e32 v8, vcc, s16, v6
	v_lshl_add_u64 v[22:23], v[98:99], 0, v[0:1]
	s_nop 0
	v_addc_co_u32_e32 v9, vcc, 0, v7, vcc
	v_add_co_u32_e32 v6, vcc, s17, v6
	global_load_dwordx4 v[14:17], v[8:9], off offset:384
	s_nop 0
	v_addc_co_u32_e32 v7, vcc, 0, v7, vcc
	global_load_dwordx4 v[18:21], v[6:7], off offset:384
	v_add_co_u32_e32 v6, vcc, s9, v22
	s_mov_b32 s9, 0x2d0000
	s_nop 0
	v_addc_co_u32_e32 v7, vcc, 0, v23, vcc
	v_add_co_u32_e32 v22, vcc, s9, v22
	s_waitcnt lgkmcnt(0)
	v_mfma_f32_16x16x32_bf16 v[78:81], v[50:53], v[128:131], v[78:81]
	v_addc_co_u32_e32 v23, vcc, 0, v23, vcc
	global_load_dwordx4 v[6:9], v[6:7], off offset:384
	v_mfma_f32_16x16x32_bf16 v[74:77], v[50:53], v[132:135], v[74:77]
	global_load_dwordx4 v[22:25], v[22:23], off offset:384
	s_waitcnt lgkmcnt(0)
	s_barrier
	v_mfma_f32_16x16x32_bf16 v[70:73], v[54:57], v[128:131], v[70:73]
	s_min_u32 s9, s8, 11
	s_lshl_b32 s94, s9, 7
	v_mfma_f32_16x16x32_bf16 v[66:69], v[54:57], v[132:135], v[66:69]
	v_lshl_add_u64 v[98:99], v[98:99], 0, s[6:7]
	v_lshl_add_u64 v[100:101], v[100:101], 0, s[6:7]
	s_cmp_lt_u32 s8, 12
	v_mfma_f32_16x16x32_bf16 v[50:53], v[120:123], v[128:131], v[62:65]
	v_mfma_f32_16x16x32_bf16 v[54:57], v[120:123], v[132:135], v[58:61]
	v_mfma_f32_16x16x32_bf16 v[58:61], v[124:127], v[128:131], v[112:115]
	v_mfma_f32_16x16x32_bf16 v[62:65], v[124:127], v[132:135], v[116:119]
	s_nop 1
	ds_read_b128 v[112:115], v109 offset:32768
	ds_read_b128 v[116:119], v109 offset:34816
	ds_read_b128 v[120:123], v109 offset:36864
	ds_read_b128 v[124:127], v109 offset:38912
	ds_read_b128 v[128:131], v108 offset:49152
	ds_read_b128 v[132:135], v108 offset:51200
	s_waitcnt lgkmcnt(0)
	v_mfma_f32_16x16x32_bf16 v[78:81], v[112:115], v[128:131], v[78:81]
	v_mfma_f32_16x16x32_bf16 v[74:77], v[112:115], v[132:135], v[74:77]
	v_mfma_f32_16x16x32_bf16 v[70:73], v[116:119], v[128:131], v[70:73]
	v_mfma_f32_16x16x32_bf16 v[66:69], v[116:119], v[132:135], v[66:69]
	v_mfma_f32_16x16x32_bf16 v[50:53], v[120:123], v[128:131], v[50:53]
	v_mfma_f32_16x16x32_bf16 v[54:57], v[120:123], v[132:135], v[54:57]
	v_mfma_f32_16x16x32_bf16 v[112:115], v[124:127], v[128:131], v[58:61]
	v_mfma_f32_16x16x32_bf16 v[116:119], v[124:127], v[132:135], v[62:65]
	s_nop 1
	ds_read_b128 v[58:61], v107 offset:32768
	ds_read_b128 v[62:65], v107 offset:34816
	ds_read_b128 v[120:123], v107 offset:36864
	ds_read_b128 v[124:127], v107 offset:38912
	ds_read_b128 v[128:131], v106 offset:49152
	ds_read_b128 v[132:135], v106 offset:51200
	ds_write_b128 v110, v[26:29]
	ds_write_b128 v110, v[34:37] offset:4096
	ds_write_b128 v110, v[38:41] offset:8192
	ds_write_b128 v110, v[42:45] offset:12288
	ds_write_b128 v110, v[30:33] offset:16384
	ds_write_b128 v110, v[46:49] offset:20480
	v_lshl_add_u64 v[26:27], v[90:91], 0, s[94:95]
	v_lshl_add_u64 v[30:31], v[92:93], 0, s[94:95]
	global_load_dwordx4 v[26:29], v[26:27], off offset:512
	v_lshl_add_u64 v[46:47], v[88:89], 0, s[94:95]
	global_load_dwordx4 v[34:37], v[30:31], off offset:512
	v_lshl_add_u64 v[30:31], v[94:95], 0, s[94:95]
	global_load_dwordx4 v[38:41], v[30:31], off offset:512
	v_lshl_add_u64 v[30:31], v[96:97], 0, s[94:95]
	global_load_dwordx4 v[42:45], v[30:31], off offset:512
	v_lshl_add_u64 v[30:31], v[86:87], 0, s[94:95]
	global_load_dwordx4 v[30:33], v[30:31], off offset:512
	s_waitcnt lgkmcnt(0)
	v_mfma_f32_16x16x32_bf16 v[78:81], v[58:61], v[128:131], v[78:81]
	global_load_dwordx4 v[46:49], v[46:47], off offset:512
	s_waitcnt lgkmcnt(0)
	s_barrier
	v_mfma_f32_16x16x32_bf16 v[74:77], v[58:61], v[132:135], v[74:77]
	v_mfma_f32_16x16x32_bf16 v[70:73], v[62:65], v[128:131], v[70:73]
	v_mfma_f32_16x16x32_bf16 v[66:69], v[62:65], v[132:135], v[66:69]
	v_mfma_f32_16x16x32_bf16 v[62:65], v[120:123], v[128:131], v[50:53]
	v_mfma_f32_16x16x32_bf16 v[58:61], v[120:123], v[132:135], v[54:57]
	v_mfma_f32_16x16x32_bf16 v[54:57], v[124:127], v[128:131], v[112:115]
	v_mfma_f32_16x16x32_bf16 v[50:53], v[124:127], v[132:135], v[116:119]
	s_cbranch_scc1 .LBB0_488
; __device__ __forceinline__ u16 f2bf(float f) { return (u16)(pack2(f, 0.f) & 0xffffu); }
; template <int NT, bool BKN, bool MASK = false, bool ROWSS = false, class Epi> ...
;     ...
;   GEMM_COMPUTE(0);
;   GEMM_STORE(ra1, rb1, 1);
;   __syncthreads();
;   GEMM_COMPUTE(1);
; template <int NT, class VF, class RP>
; __device__ __forceinline__ void epi_staged_bf16(f32x4 (&acc)[4][NT], int r0, int c0, unsigned char* smem, VF vf, RP rowptr) {
;     ...
;         const int r = r0 + mi * 16 + j, c = c0 + ni * 16;
;         Ts[r * PITCH + c] = f2bf(vf(r, c, acc[mi][ni][j]));
	s_waitcnt vmcnt(0)
	ds_read_b128 v[26:29], v109
	ds_read_b128 v[30:33], v109 offset:2048
	ds_read_b128 v[34:37], v109 offset:4096
	ds_read_b128 v[38:41], v109 offset:6144
	ds_read_b128 v[42:45], v108 offset:16384
	ds_read_b128 v[46:49], v108 offset:18432
	v_lshlrev_b32_e32 v0, 6, v105
	s_add_i32 s1, s1, 10
	s_waitcnt lgkmcnt(1)
	v_mfma_f32_16x16x32_bf16 v[78:81], v[26:29], v[42:45], v[78:81]
	s_waitcnt lgkmcnt(0)
	v_mfma_f32_16x16x32_bf16 v[26:29], v[26:29], v[46:49], v[74:77]
	v_mfma_f32_16x16x32_bf16 v[70:73], v[30:33], v[42:45], v[70:73]
	v_mfma_f32_16x16x32_bf16 v[30:33], v[30:33], v[46:49], v[66:69]
	v_mfma_f32_16x16x32_bf16 v[62:65], v[34:37], v[42:45], v[62:65]
	v_mfma_f32_16x16x32_bf16 v[34:37], v[34:37], v[46:49], v[58:61]
	v_mfma_f32_16x16x32_bf16 v[42:45], v[38:41], v[42:45], v[54:57]
	v_mfma_f32_16x16x32_bf16 v[38:41], v[38:41], v[46:49], v[50:53]
	ds_read_b128 v[46:49], v107
	s_nop 1
	ds_read_b128 v[50:53], v107 offset:2048
	ds_read_b128 v[54:57], v107 offset:4096
	ds_read_b128 v[58:61], v107 offset:6144
	ds_read_b128 v[66:69], v106 offset:16384
	ds_read_b128 v[74:77], v106 offset:18432
	ds_write_b128 v110, v[2:5] offset:32768
	ds_write_b128 v110, v[10:13] offset:36864
	ds_write_b128 v110, v[14:17] offset:40960
	ds_write_b128 v110, v[18:21] offset:45056
	ds_write_b128 v110, v[6:9] offset:49152
	ds_write_b128 v110, v[22:25] offset:53248
	s_waitcnt lgkmcnt(0)
	s_barrier
	ds_read_b128 v[2:5], v109 offset:32768
	ds_read_b128 v[6:9], v109 offset:34816
	ds_read_b128 v[10:13], v109 offset:36864
	ds_read_b128 v[14:17], v109 offset:38912
	ds_read_b128 v[18:21], v108 offset:49152
	ds_read_b128 v[22:25], v108 offset:51200
	v_mfma_f32_16x16x32_bf16 v[78:81], v[46:49], v[66:69], v[78:81]
	v_mfma_f32_16x16x32_bf16 v[26:29], v[46:49], v[74:77], v[26:29]
	v_mfma_f32_16x16x32_bf16 v[46:49], v[50:53], v[66:69], v[70:73]
	v_mfma_f32_16x16x32_bf16 v[30:33], v[50:53], v[74:77], v[30:33]
	v_mfma_f32_16x16x32_bf16 v[50:53], v[54:57], v[66:69], v[62:65]
	v_mfma_f32_16x16x32_bf16 v[34:37], v[54:57], v[74:77], v[34:37]
	v_mfma_f32_16x16x32_bf16 v[42:45], v[58:61], v[66:69], v[42:45]
	v_mfma_f32_16x16x32_bf16 v[38:41], v[58:61], v[74:77], v[38:41]
	s_waitcnt lgkmcnt(1)
	v_mfma_f32_16x16x32_bf16 v[54:57], v[2:5], v[18:21], v[78:81]
	s_waitcnt lgkmcnt(0)
	v_mfma_f32_16x16x32_bf16 v[2:5], v[2:5], v[22:25], v[26:29]
	v_mfma_f32_16x16x32_bf16 v[26:29], v[6:9], v[18:21], v[46:49]
	v_mfma_f32_16x16x32_bf16 v[6:9], v[6:9], v[22:25], v[30:33]
	v_mfma_f32_16x16x32_bf16 v[30:33], v[10:13], v[18:21], v[50:53]
	v_mfma_f32_16x16x32_bf16 v[10:13], v[10:13], v[22:25], v[34:37]
	v_mfma_f32_16x16x32_bf16 v[18:21], v[14:17], v[18:21], v[42:45]
	v_mfma_f32_16x16x32_bf16 v[14:17], v[14:17], v[22:25], v[38:41]
	ds_read_b128 v[22:25], v107 offset:32768
	ds_read_b128 v[34:37], v107 offset:34816
	s_nop 0
	ds_read_b128 v[38:41], v107 offset:36864
	ds_read_b128 v[42:45], v107 offset:38912
	ds_read_b128 v[46:49], v106 offset:49152
	ds_read_b128 v[50:53], v106 offset:51200
	s_waitcnt lgkmcnt(1)
	v_mfma_f32_16x16x32_bf16 v[54:57], v[22:25], v[46:49], v[54:57]
	s_waitcnt lgkmcnt(0)
	v_mfma_f32_16x16x32_bf16 v[2:5], v[22:25], v[50:53], v[2:5]
	v_mfma_f32_16x16x32_bf16 v[22:25], v[34:37], v[46:49], v[26:29]
	v_mfma_f32_16x16x32_bf16 v[26:29], v[38:41], v[46:49], v[30:33]
	s_nop 2
	v_lshl_or_b32 v30, v104, 2, v0
	v_lshlrev_b32_e32 v0, 1, v103
	v_lshl_or_b32 v0, v102, 6, v0
	v_mov_b32_e32 v32, v187
	v_mad_u64_u32 v[30:31], s[8:9], v30, s96, v[0:1]
	v_cvt_pk_bf16_f32 v0, v55, s0
	s_barrier
; #define XCD_FOR(u, T)                                                                                         \
;   for (int _x = bid_() & 7, _gb = gridDim.x >> 3, _hi = (int)(((long)(_x + 1) * (T)) >> 3),                    \
;            u = (int)(((long)_x * (T)) >> 3) + (bid_() >> 3);                                                  \
;        u < _hi; u += _gb)
; template <int NT, class VF, class RP>
; __device__ __forceinline__ void epi_staged_bf16(f32x4 (&acc)[4][NT], int r0, int c0, unsigned char* smem, VF vf, RP rowptr) {
;     ...
; #pragma unroll
;   for (int i = 0; i < CPR / 2; ++i) {
;     const int c = t + 256 * i, row = c / CPR, ch = c % CPR;
;     u16* d = rowptr(row);
;     if (d) *(u32x4*)(d + ch * 8) = *(const u32x4*)(Ts + row * PITCH + ch * 8);
;   }
; __device__ __forceinline__ void phase_in_gemm(const Params& p, int l, unsigned char* smem) {
;     ...
;   XCD_FOR(t, 132) {
;     const int row_base = t * 128;
;     auto epi = [&](f32x4(&acc)[4][2], int r0, int c0) {
;       auto vf = [&](int, int, float v) { return v; };
;       auto rp = [&](int r) -> u16* { return p.PX + (size_t)(row_base + r) * 1024 + 896; };
;       epi_staged_bf16<2>(acc, r0, c0, smem, vf, rp);
;     };
;     gemm_tile<2, false>(p.H + (size_t)row_base * 1024, 1024, nullptr, 128, W + (size_t)11 * 128 * 1024, 1024, 1024, smem, epi);
;   }
	ds_write_b16 v30, v0 offset:144
	v_cvt_pk_bf16_f32 v0, v56, s0
	ds_write_b16 v30, v0 offset:288
	v_cvt_pk_bf16_f32 v0, v57, s0
	ds_write_b16 v30, v0 offset:432
	v_cvt_pk_bf16_f32 v0, v2, s0
	ds_write_b16 v30, v0 offset:32
	v_cvt_pk_bf16_f32 v0, v3, s0
	ds_write_b16 v30, v0 offset:176
	v_cvt_pk_bf16_f32 v0, v4, s0
	ds_write_b16 v30, v0 offset:320
	v_cvt_pk_bf16_f32 v0, v5, s0
	v_mfma_f32_16x16x32_bf16 v[6:9], v[34:37], v[50:53], v[6:9]
	ds_write_b16 v30, v0 offset:464
	v_cvt_pk_bf16_f32 v0, v22, s0
	ds_write_b16 v30, v0 offset:2304
	v_cvt_pk_bf16_f32 v0, v23, s0
	ds_write_b16 v30, v0 offset:2448
	v_cvt_pk_bf16_f32 v0, v24, s0
	ds_write_b16 v30, v0 offset:2592
	v_cvt_pk_bf16_f32 v0, v25, s0
	ds_write_b16 v30, v0 offset:2736
	v_cvt_pk_bf16_f32 v0, v6, s0
	ds_write_b16 v30, v0 offset:2336
	v_cvt_pk_bf16_f32 v0, v7, s0
	ds_write_b16 v30, v0 offset:2480
	v_cvt_pk_bf16_f32 v0, v8, s0
	ds_write_b16 v30, v0 offset:2624
	v_cvt_pk_bf16_f32 v0, v9, s0
	v_mfma_f32_16x16x32_bf16 v[10:13], v[38:41], v[50:53], v[10:13]
	ds_write_b16 v30, v0 offset:2768
	v_cvt_pk_bf16_f32 v0, v26, s0
	ds_write_b16 v30, v0 offset:4608
	v_cvt_pk_bf16_f32 v0, v27, s0
	ds_write_b16 v30, v0 offset:4752
	v_cvt_pk_bf16_f32 v0, v28, s0
	ds_write_b16 v30, v0 offset:4896
	v_cvt_pk_bf16_f32 v0, v29, s0
	v_mfma_f32_16x16x32_bf16 v[18:21], v[42:45], v[46:49], v[18:21]
	ds_write_b16 v30, v0 offset:5040
	v_cvt_pk_bf16_f32 v0, v10, s0
	ds_write_b16 v30, v0 offset:4640
	v_cvt_pk_bf16_f32 v0, v11, s0
	ds_write_b16 v30, v0 offset:4784
	v_cvt_pk_bf16_f32 v0, v12, s0
	ds_write_b16 v30, v0 offset:4928
	v_cvt_pk_bf16_f32 v0, v13, s0
	v_mfma_f32_16x16x32_bf16 v[14:17], v[42:45], v[50:53], v[14:17]
	ds_write_b16 v30, v0 offset:5072
	v_cvt_pk_bf16_f32 v0, v18, s0
	ds_write_b16 v30, v0 offset:6912
	v_cvt_pk_bf16_f32 v0, v19, s0
	ds_write_b16 v30, v0 offset:7056
	v_cvt_pk_bf16_f32 v0, v20, s0
	ds_write_b16 v30, v0 offset:7200
	v_cvt_pk_bf16_f32 v0, v21, s0
	ds_write_b16 v30, v0 offset:7344
	v_cvt_pk_bf16_f32 v0, v14, s0
	ds_write_b16 v30, v0 offset:6944
	v_cvt_pk_bf16_f32 v0, v15, s0
	ds_write_b16 v30, v0 offset:7088
	v_cvt_pk_bf16_f32 v0, v16, s0
	v_cvt_pk_bf16_f32 v33, v54, s0
	ds_write_b16 v30, v0 offset:7232
	v_cvt_pk_bf16_f32 v0, v17, s0
	v_mov_b64_e32 v[2:3], s[4:5]
	ds_write_b16 v30, v33
	ds_write_b16 v30, v0 offset:7376
	s_waitcnt lgkmcnt(0)
	s_barrier
	s_load_dwordx2 s[100:101], s[4:5], 0x120
	s_waitcnt lgkmcnt(0)
	v_mov_b32_e32 v4, s100
	v_mov_b32_e32 v5, s101
	v_ashrrev_i32_e32 v0, 31, v32
	v_lshrrev_b32_e32 v0, 29, v0
	v_add_u32_e32 v0, v32, v0
	v_ashrrev_i32_e32 v10, 3, v0
	v_add_u32_e32 v6, s40, v10
	v_ashrrev_i32_e32 v7, 31, v6
	v_lshlrev_b64 v[6:7], 11, v[6:7]
	v_and_b32_e32 v0, -8, v0
	v_sub_u32_e32 v0, v32, v0
	s_nop 0
	s_add_i32 s38, s38, 0x500
	s_cmp_lt_i32 s1, s0
	s_waitcnt lgkmcnt(0)
	v_lshl_add_u64 v[8:9], v[4:5], 0, v[6:7]
	v_mul_lo_u32 v4, v10, s96
	v_lshlrev_b32_e32 v10, 3, v0
	v_lshl_add_u32 v0, v0, 4, v4
	ds_read_b128 v[4:7], v0
	v_ashrrev_i32_e32 v11, 31, v10
	v_lshl_add_u64 v[8:9], v[10:11], 1, v[8:9]
	v_add_u32_e32 v0, 0x100, v32
	s_waitcnt lgkmcnt(0)
	global_store_dwordx4 v[8:9], v[4:7], off offset:1792 sc1
	s_nop 1
	v_ashrrev_i32_e32 v4, 31, v0
	v_lshrrev_b32_e32 v4, 29, v4
	v_add_u32_e32 v10, v0, v4
	s_load_dwordx2 s[100:101], s[4:5], 0x120
	s_waitcnt lgkmcnt(0)
	v_mov_b32_e32 v4, s100
	v_mov_b32_e32 v5, s101
	v_ashrrev_i32_e32 v11, 3, v10
	v_add_u32_e32 v6, s40, v11
	v_ashrrev_i32_e32 v7, 31, v6
	v_lshlrev_b64 v[6:7], 11, v[6:7]
	s_waitcnt lgkmcnt(0)
	v_lshl_add_u64 v[8:9], v[4:5], 0, v[6:7]
	v_and_b32_e32 v4, -8, v10
	v_sub_u32_e32 v0, v0, v4
	v_mul_lo_u32 v4, v11, s96
	v_lshlrev_b32_e32 v10, 3, v0
	v_lshl_add_u32 v0, v0, 4, v4
	ds_read_b128 v[4:7], v0
	v_ashrrev_i32_e32 v11, 31, v10
	v_lshl_add_u64 v[8:9], v[10:11], 1, v[8:9]
	v_add_u32_e32 v0, 0x200, v32
	s_waitcnt lgkmcnt(0)
	global_store_dwordx4 v[8:9], v[4:7], off offset:1792 sc1
	s_nop 1
	v_ashrrev_i32_e32 v4, 31, v0
	v_lshrrev_b32_e32 v4, 29, v4
	v_add_u32_e32 v10, v0, v4
	s_load_dwordx2 s[100:101], s[4:5], 0x120
	s_waitcnt lgkmcnt(0)
	v_mov_b32_e32 v4, s100
	v_mov_b32_e32 v5, s101
	v_ashrrev_i32_e32 v11, 3, v10
	v_add_u32_e32 v6, s40, v11
	v_ashrrev_i32_e32 v7, 31, v6
	v_lshlrev_b64 v[6:7], 11, v[6:7]
	s_waitcnt lgkmcnt(0)
	v_lshl_add_u64 v[8:9], v[4:5], 0, v[6:7]
	v_and_b32_e32 v4, -8, v10
	v_sub_u32_e32 v0, v0, v4
	v_mul_lo_u32 v4, v11, s96
	v_lshlrev_b32_e32 v10, 3, v0
	v_lshl_add_u32 v0, v0, 4, v4
	ds_read_b128 v[4:7], v0
	v_ashrrev_i32_e32 v11, 31, v10
	v_lshl_add_u64 v[8:9], v[10:11], 1, v[8:9]
	v_add_u32_e32 v0, 0x300, v32
	s_waitcnt lgkmcnt(0)
	global_store_dwordx4 v[8:9], v[4:7], off offset:1792 sc1
	global_load_dwordx2 v[2:3], v[2:3], off offset:288
	s_nop 0
	v_ashrrev_i32_e32 v4, 31, v0
	v_lshrrev_b32_e32 v4, 29, v4
	v_add_u32_e32 v8, v0, v4
	v_ashrrev_i32_e32 v9, 3, v8
	v_add_u32_e32 v4, s40, v9
	v_ashrrev_i32_e32 v5, 31, v4
	v_lshlrev_b64 v[4:5], 11, v[4:5]
	s_waitcnt vmcnt(0) lgkmcnt(0)
	v_lshl_add_u64 v[6:7], v[2:3], 0, v[4:5]
	v_and_b32_e32 v2, -8, v8
	v_sub_u32_e32 v0, v0, v2
	v_mul_lo_u32 v2, v9, s96
	v_lshlrev_b32_e32 v8, 3, v0
	v_lshl_add_u32 v0, v0, 4, v2
	ds_read_b128 v[2:5], v0
	v_ashrrev_i32_e32 v9, 31, v8
	v_lshl_add_u64 v[6:7], v[8:9], 1, v[6:7]
	s_waitcnt lgkmcnt(0)
	global_store_dwordx4 v[6:7], v[2:5], off offset:1792 sc1
	s_cbranch_scc1 .LBB0_487

; __device__ __forceinline__ u16 f2bf(float f) { return (u16)(pack2(f, 0.f) & 0xffffu); }
; __device__ __forceinline__ int tid_() { int t = threadIdx.x; asm volatile("" : "+v"(t)); return t; }
; template <int NT, class VF, class RP>
; __device__ __forceinline__ void epi_staged_bf16(f32x4 (&acc)[4][NT], int r0, int c0, unsigned char* smem, VF vf, RP rowptr) {
;   constexpr int BN = NT * 32, PITCH = BN + 8, CPR = BN / 8;
;   u16* Ts = (u16*)smem;
;   const int t = tid_();
;   __syncthreads();
; #pragma unroll
;   for (int mi = 0; mi < 4; ++mi)
; #pragma unroll
;     for (int ni = 0; ni < NT; ++ni)
; #pragma unroll
;       for (int j = 0; j < 4; ++j) {
;         const int r = r0 + mi * 16 + j, c = c0 + ni * 16;
;         Ts[r * PITCH + c] = f2bf(vf(r, c, acc[mi][ni][j]));
;       }
;   __syncthreads();
; __device__ __forceinline__ void phase_mix_a(const Params& p, int l, bool last, unsigned char* smem) {
;     ...
;       auto epi = [&](f32x4(&acc)[4][4], int r0, int c0) {
;         const float* rs = (const float*)(smem + 65536);
;         auto vf = [&](int r, int, float v) { return v * rs[r]; };
;         auto rp = [&](int r) -> u16* { return p.QR + (size_t)(row_base + r) * 768 + nt * 128; };
;         epi_staged_bf16<4>(acc, r0, c0, smem, vf, rp);
;       };
;       gemm_tile<4, false, false, true>(p.PX + (size_t)row_base * 1024 + 512, 1024, nullptr, 128, W + (size_t)nt * 128 * 256, 256, 256, smem, epi);
.LBB0_553:
	s_or_b64 exec, exec, s[0:1]
	v_lshlrev_b32_e32 v0, 6, v0
	s_waitcnt lgkmcnt(0)
	v_lshl_or_b32 v3, v137, 2, v0
	v_mov_b32_e32 v0, v187
	v_lshl_add_u32 v4, v3, 2, v213
	s_barrier
	s_barrier
	ds_read_b128 v[6:9], v4
	s_mulk_i32 s19, 0xfd00
	s_waitcnt lgkmcnt(0)
	v_mul_f32_e32 v2, v98, v6
	v_cvt_pk_bf16_f32 v5, v2, s0
	v_lshlrev_b32_e32 v2, 1, v145
	v_lshl_or_b32 v2, v144, 7, v2
	v_mad_u64_u32 v[10:11], s[0:1], v3, s23, v[2:3]
	ds_write_b16 v10, v5
	v_or_b32_e32 v3, 1, v3
	v_mul_f32_e32 v5, v99, v7
	v_cvt_pk_bf16_f32 v5, v5, s0
	v_mad_u64_u32 v[2:3], s[0:1], v3, s23, v[2:3]
	v_mul_f32_e32 v3, v100, v8
	s_nop 0
	v_cvt_pk_bf16_f32 v3, v3, s0
	ds_write_b16 v2, v3 offset:272
	v_mul_f32_e32 v3, v101, v9
	v_cvt_pk_bf16_f32 v3, v3, s0
	ds_write_b16 v2, v3 offset:544
	v_mul_f32_e32 v3, v102, v6
	v_cvt_pk_bf16_f32 v3, v3, s0
	ds_write_b16 v10, v3 offset:32
	v_mul_f32_e32 v3, v103, v7
	v_cvt_pk_bf16_f32 v3, v3, s0
	ds_write_b16 v2, v3 offset:32
	v_mul_f32_e32 v3, v104, v8
	v_cvt_pk_bf16_f32 v3, v3, s0
	ds_write_b16 v2, v3 offset:304
	v_mul_f32_e32 v3, v105, v9
	v_cvt_pk_bf16_f32 v3, v3, s0
	ds_write_b16 v2, v3 offset:576
	v_mul_f32_e32 v3, v106, v6
	v_cvt_pk_bf16_f32 v3, v3, s0
	ds_write_b16 v10, v3 offset:64
	v_mul_f32_e32 v3, v107, v7
	v_cvt_pk_bf16_f32 v3, v3, s0
	ds_write_b16 v2, v3 offset:64
	v_mul_f32_e32 v3, v108, v8
	v_cvt_pk_bf16_f32 v3, v3, s0
	ds_write_b16 v2, v3 offset:336
	v_mul_f32_e32 v3, v109, v9
	v_cvt_pk_bf16_f32 v3, v3, s0
	ds_write_b16 v2, v3 offset:608
	v_mul_f32_e32 v3, v110, v6
	v_cvt_pk_bf16_f32 v3, v3, s0
	ds_write_b16 v10, v3 offset:96
	v_mul_f32_e32 v3, v111, v7
	v_cvt_pk_bf16_f32 v3, v3, s0
	ds_write_b16 v2, v3 offset:96
	v_mul_f32_e32 v3, v112, v8
	v_cvt_pk_bf16_f32 v3, v3, s0
	ds_write_b16 v2, v3 offset:368
	v_mul_f32_e32 v3, v113, v9
	ds_read_b128 v[6:9], v4 offset:64
	v_cvt_pk_bf16_f32 v3, v3, s0
	ds_write_b16 v2, v3 offset:640
	ds_write_b16 v2, v5
	s_waitcnt lgkmcnt(2)
	v_mul_f32_e32 v3, v82, v6
	v_cvt_pk_bf16_f32 v3, v3, s0
	ds_write_b16 v2, v3 offset:4080
	v_mul_f32_e32 v3, v83, v7
	v_cvt_pk_bf16_f32 v3, v3, s0
	ds_write_b16 v2, v3 offset:4352
	v_mul_f32_e32 v3, v84, v8
	v_cvt_pk_bf16_f32 v3, v3, s0
	ds_write_b16 v2, v3 offset:4624
	v_mul_f32_e32 v3, v85, v9
	v_cvt_pk_bf16_f32 v3, v3, s0
	ds_write_b16 v2, v3 offset:4896
	v_mul_f32_e32 v3, v86, v6
	v_cvt_pk_bf16_f32 v3, v3, s0
	ds_write_b16 v2, v3 offset:4112
	v_mul_f32_e32 v3, v87, v7
	v_cvt_pk_bf16_f32 v3, v3, s0
	ds_write_b16 v2, v3 offset:4384
	v_mul_f32_e32 v3, v88, v8
	v_cvt_pk_bf16_f32 v3, v3, s0
	ds_write_b16 v2, v3 offset:4656
	v_mul_f32_e32 v3, v89, v9
	v_cvt_pk_bf16_f32 v3, v3, s0
	ds_write_b16 v2, v3 offset:4928
	v_mul_f32_e32 v3, v90, v6
	v_cvt_pk_bf16_f32 v3, v3, s0
	ds_write_b16 v2, v3 offset:4144
	v_mul_f32_e32 v3, v91, v7
	v_cvt_pk_bf16_f32 v3, v3, s0
	ds_write_b16 v2, v3 offset:4416
	v_mul_f32_e32 v3, v92, v8
	v_cvt_pk_bf16_f32 v3, v3, s0
	ds_write_b16 v2, v3 offset:4688
	v_mul_f32_e32 v3, v93, v9
	v_cvt_pk_bf16_f32 v3, v3, s0
	ds_write_b16 v2, v3 offset:4960
	v_mul_f32_e32 v3, v94, v6
	v_cvt_pk_bf16_f32 v3, v3, s0
	ds_write_b16 v2, v3 offset:4176
	v_mul_f32_e32 v3, v95, v7
	v_cvt_pk_bf16_f32 v3, v3, s0
	ds_write_b16 v2, v3 offset:4448
	v_mul_f32_e32 v3, v96, v8
	v_cvt_pk_bf16_f32 v3, v3, s0
	ds_write_b16 v2, v3 offset:4720
	v_mul_f32_e32 v3, v97, v9
	ds_read_b128 v[6:9], v4 offset:128
	v_cvt_pk_bf16_f32 v3, v3, s0
	ds_write_b16 v2, v3 offset:4992
	s_waitcnt lgkmcnt(1)
	v_mul_f32_e32 v3, v70, v6
	v_cvt_pk_bf16_f32 v3, v3, s0
	ds_write_b16 v2, v3 offset:8432
	v_mul_f32_e32 v3, v71, v7
	v_cvt_pk_bf16_f32 v3, v3, s0
	ds_write_b16 v2, v3 offset:8704
	v_mul_f32_e32 v3, v72, v8
	v_cvt_pk_bf16_f32 v3, v3, s0
	ds_write_b16 v2, v3 offset:8976
	v_mul_f32_e32 v3, v73, v9
	v_cvt_pk_bf16_f32 v3, v3, s0
	ds_write_b16 v2, v3 offset:9248
	v_mul_f32_e32 v3, v74, v6
	v_cvt_pk_bf16_f32 v3, v3, s0
	ds_write_b16 v2, v3 offset:8464
	v_mul_f32_e32 v3, v75, v7
	v_cvt_pk_bf16_f32 v3, v3, s0
	ds_write_b16 v2, v3 offset:8736
	v_mul_f32_e32 v3, v76, v8
	v_cvt_pk_bf16_f32 v3, v3, s0
	ds_write_b16 v2, v3 offset:9008
	v_mul_f32_e32 v3, v77, v9
	v_cvt_pk_bf16_f32 v3, v3, s0
	ds_write_b16 v2, v3 offset:9280
	v_mul_f32_e32 v3, v78, v6
	v_cvt_pk_bf16_f32 v3, v3, s0
	ds_write_b16 v2, v3 offset:8496
	v_mul_f32_e32 v3, v79, v7
	v_cvt_pk_bf16_f32 v3, v3, s0
	ds_write_b16 v2, v3 offset:8768
	v_mul_f32_e32 v3, v80, v8
	v_cvt_pk_bf16_f32 v3, v3, s0
	ds_write_b16 v2, v3 offset:9040
	v_mul_f32_e32 v3, v81, v9
	v_cvt_pk_bf16_f32 v3, v3, s0
	ds_write_b16 v2, v3 offset:9312
	v_mul_f32_e32 v3, v66, v6
	v_cvt_pk_bf16_f32 v3, v3, s0
	ds_write_b16 v2, v3 offset:8528
	v_mul_f32_e32 v3, v67, v7
	v_cvt_pk_bf16_f32 v3, v3, s0
	ds_read_b128 v[4:7], v4 offset:192
	ds_write_b16 v2, v3 offset:8800
	v_mul_f32_e32 v3, v68, v8
	v_cvt_pk_bf16_f32 v3, v3, s0
	ds_write_b16 v2, v3 offset:9072
	v_mul_f32_e32 v3, v69, v9
	v_cvt_pk_bf16_f32 v3, v3, s0
	ds_write_b16 v2, v3 offset:9344
	s_waitcnt lgkmcnt(3)
	v_mul_f32_e32 v3, v58, v4
	v_cvt_pk_bf16_f32 v3, v3, s0
	ds_write_b16 v2, v3 offset:12784
	v_mul_f32_e32 v3, v59, v5
	v_cvt_pk_bf16_f32 v3, v3, s0
	ds_write_b16 v2, v3 offset:13056
	v_mul_f32_e32 v3, v60, v6
	v_cvt_pk_bf16_f32 v3, v3, s0
	ds_write_b16 v2, v3 offset:13328
	v_mul_f32_e32 v3, v61, v7
	v_cvt_pk_bf16_f32 v3, v3, s0
	ds_write_b16 v2, v3 offset:13600
	v_mul_f32_e32 v3, v54, v4
	v_cvt_pk_bf16_f32 v3, v3, s0
	ds_write_b16 v2, v3 offset:12816
	v_mul_f32_e32 v3, v55, v5
	v_cvt_pk_bf16_f32 v3, v3, s0
	ds_write_b16 v2, v3 offset:13088
	v_mul_f32_e32 v3, v56, v6
	v_cvt_pk_bf16_f32 v3, v3, s0
	ds_write_b16 v2, v3 offset:13360
	v_mul_f32_e32 v3, v57, v7
	v_cvt_pk_bf16_f32 v3, v3, s0
	ds_write_b16 v2, v3 offset:13632
	v_mul_f32_e32 v3, v50, v4
	v_cvt_pk_bf16_f32 v3, v3, s0
	ds_write_b16 v2, v3 offset:12848
	v_mul_f32_e32 v3, v51, v5
	v_cvt_pk_bf16_f32 v3, v3, s0
	ds_write_b16 v2, v3 offset:13120
	v_mul_f32_e32 v3, v52, v6
	v_cvt_pk_bf16_f32 v3, v3, s0
	ds_write_b16 v2, v3 offset:13392
	v_mul_f32_e32 v3, v53, v7
	v_cvt_pk_bf16_f32 v3, v3, s0
	ds_write_b16 v2, v3 offset:13664
	v_mul_f32_e32 v3, v46, v4
	v_cvt_pk_bf16_f32 v3, v3, s0
	ds_write_b16 v2, v3 offset:12880
	v_mul_f32_e32 v3, v47, v5
	v_cvt_pk_bf16_f32 v3, v3, s0
	ds_write_b16 v2, v3 offset:13152
	v_mul_f32_e32 v3, v48, v6
	v_cvt_pk_bf16_f32 v3, v3, s0
	ds_write_b16 v2, v3 offset:13424
	v_mul_f32_e32 v3, v49, v7
	v_cvt_pk_bf16_f32 v3, v3, s0
	ds_write_b16 v2, v3 offset:13696
	v_mov_b64_e32 v[2:3], s[40:41]
	s_waitcnt lgkmcnt(0)
	s_barrier
; template <int NT, class VF, class RP>
; __device__ __forceinline__ void epi_staged_bf16(f32x4 (&acc)[4][NT], int r0, int c0, unsigned char* smem, VF vf, RP rowptr) {
;     ...
; #pragma unroll
;   for (int i = 0; i < CPR / 2; ++i) {
;     const int c = t + 256 * i, row = c / CPR, ch = c % CPR;
;     u16* d = rowptr(row);
;     if (d) *(u32x4*)(d + ch * 8) = *(const u32x4*)(Ts + row * PITCH + ch * 8);
;   }
; __device__ __forceinline__ void phase_mix_a(const Params& p, int l, bool last, unsigned char* smem) {
;     ...
;         auto rp = [&](int r) -> u16* { return p.QR + (size_t)(row_base + r) * 768 + nt * 128; };
	s_load_dwordx2 s[100:101], s[40:41], 0x148
	s_waitcnt lgkmcnt(0)
	v_mov_b32_e32 v6, s100
	v_mov_b32_e32 v7, s101
	v_mov_b64_e32 v[2:3], 0
	v_mov_b64_e32 v[4:5], 0
	s_waitcnt lgkmcnt(0)
	v_cmp_ne_u64_e32 vcc, 0, v[6:7]
	s_and_saveexec_b64 s[0:1], vcc
	s_xor_b64 s[0:1], exec, s[0:1]
	s_cbranch_execz .LBB0_555
	v_ashrrev_i32_e32 v4, 31, v0
	v_lshrrev_b32_e32 v4, 28, v4
	v_add_u32_e32 v4, v0, v4
	v_ashrrev_i32_e32 v5, 4, v4
	v_and_b32_e32 v4, -16, v4
	v_sub_u32_e32 v10, v0, v4
	v_mul_lo_u32 v4, v5, s23
	v_add_u32_e32 v8, s4, v5
	s_movk_i32 s5, 0x600
	v_lshl_add_u32 v4, v10, 4, v4
	v_mad_i64_i32 v[8:9], s[34:35], v8, s5, v[6:7]
	ds_read_b128 v[4:7], v4
	s_add_i32 s34, s18, s19
	s_ashr_i32 s35, s34, 31
	v_lshlrev_b32_e32 v10, 3, v10
	v_lshl_add_u64 v[8:9], s[34:35], 1, v[8:9]
	v_ashrrev_i32_e32 v11, 31, v10
	v_lshl_add_u64 v[8:9], v[10:11], 1, v[8:9]
	s_waitcnt lgkmcnt(0)
	global_store_dwordx4 v[8:9], v[4:7], off sc1
	s_nop 1
	v_mov_b64_e32 v[4:5], s[40:41]
	s_load_dwordx2 s[100:101], s[40:41], 0x148
	s_waitcnt lgkmcnt(0)
	v_mov_b32_e32 v4, s100
	v_mov_b32_e32 v5, s101
.LBB0_555:
	s_or_b64 exec, exec, s[0:1]
	s_waitcnt lgkmcnt(0)
	v_cmp_ne_u64_e32 vcc, 0, v[4:5]
	s_and_saveexec_b64 s[0:1], vcc
	s_cbranch_execz .LBB0_557
	v_add_u32_e32 v2, 0x100, v0
	v_ashrrev_i32_e32 v3, 31, v2
	v_lshrrev_b32_e32 v3, 28, v3
	v_add_u32_e32 v3, v2, v3
	v_ashrrev_i32_e32 v8, 4, v3
	v_and_b32_e32 v3, -16, v3
	v_sub_u32_e32 v9, v2, v3
	v_mul_lo_u32 v2, v8, s23
	v_add_u32_e32 v6, s4, v8
	s_movk_i32 s5, 0x600
	v_lshl_add_u32 v2, v9, 4, v2
	v_mad_i64_i32 v[6:7], s[34:35], v6, s5, v[4:5]
	ds_read_b128 v[2:5], v2
	s_add_i32 s34, s18, s19
	s_ashr_i32 s35, s34, 31
	v_lshlrev_b32_e32 v8, 3, v9
	v_lshl_add_u64 v[6:7], s[34:35], 1, v[6:7]
	v_ashrrev_i32_e32 v9, 31, v8
	v_lshl_add_u64 v[6:7], v[8:9], 1, v[6:7]
	s_waitcnt lgkmcnt(0)
	global_store_dwordx4 v[6:7], v[2:5], off sc1
	s_nop 1
	v_mov_b64_e32 v[2:3], s[40:41]
	s_load_dwordx2 s[100:101], s[40:41], 0x148
	s_waitcnt lgkmcnt(0)
	v_mov_b32_e32 v2, s100
	v_mov_b32_e32 v3, s101
.LBB0_557:
	s_or_b64 exec, exec, s[0:1]
	v_mov_b64_e32 v[4:5], 0
	s_waitcnt lgkmcnt(0)
	v_cmp_ne_u64_e32 vcc, 0, v[2:3]
	v_mov_b64_e32 v[6:7], 0
	s_and_saveexec_b64 s[0:1], vcc
	s_cbranch_execz .LBB0_559
	v_add_u32_e32 v6, 0x200, v0
	v_ashrrev_i32_e32 v7, 31, v6
	v_lshrrev_b32_e32 v7, 28, v7
	v_add_u32_e32 v7, v6, v7
	v_ashrrev_i32_e32 v8, 4, v7
	v_and_b32_e32 v7, -16, v7
	v_sub_u32_e32 v10, v6, v7
	v_mul_lo_u32 v6, v8, s23
	v_add_u32_e32 v9, s4, v8
	s_movk_i32 s5, 0x600
	v_lshl_add_u32 v6, v10, 4, v6
	v_mad_i64_i32 v[2:3], s[34:35], v9, s5, v[2:3]
	ds_read_b128 v[6:9], v6
	s_add_i32 s34, s18, s19
	s_ashr_i32 s35, s34, 31
	v_lshlrev_b32_e32 v10, 3, v10
	v_lshl_add_u64 v[2:3], s[34:35], 1, v[2:3]
	v_ashrrev_i32_e32 v11, 31, v10
	v_lshl_add_u64 v[2:3], v[10:11], 1, v[2:3]
	s_waitcnt lgkmcnt(0)
	global_store_dwordx4 v[2:3], v[6:9], off sc1
	v_mov_b64_e32 v[2:3], s[40:41]
	s_load_dwordx2 s[100:101], s[40:41], 0x148
	s_waitcnt lgkmcnt(0)
	v_mov_b32_e32 v6, s100
	v_mov_b32_e32 v7, s101
.LBB0_559:
	s_or_b64 exec, exec, s[0:1]
	s_waitcnt lgkmcnt(0)
	v_cmp_ne_u64_e32 vcc, 0, v[6:7]
	s_and_saveexec_b64 s[0:1], vcc
	s_cbranch_execz .LBB0_561
	v_add_u32_e32 v2, 0x300, v0
	v_ashrrev_i32_e32 v3, 31, v2
	v_lshrrev_b32_e32 v3, 28, v3
	v_add_u32_e32 v3, v2, v3
	v_ashrrev_i32_e32 v4, 4, v3
	v_and_b32_e32 v3, -16, v3
	v_sub_u32_e32 v8, v2, v3
	v_mul_lo_u32 v2, v4, s23
	v_add_u32_e32 v5, s4, v4
	s_movk_i32 s5, 0x600
	v_lshl_add_u32 v2, v8, 4, v2
	v_mad_i64_i32 v[6:7], s[34:35], v5, s5, v[6:7]
	ds_read_b128 v[2:5], v2
	s_add_i32 s34, s18, s19
	s_ashr_i32 s35, s34, 31
	v_lshlrev_b32_e32 v8, 3, v8
	v_lshl_add_u64 v[6:7], s[34:35], 1, v[6:7]
	v_ashrrev_i32_e32 v9, 31, v8
	v_lshl_add_u64 v[6:7], v[8:9], 1, v[6:7]
	s_waitcnt lgkmcnt(0)
	global_store_dwordx4 v[6:7], v[2:5], off sc1
	s_nop 1
	v_mov_b64_e32 v[2:3], s[40:41]
	s_load_dwordx2 s[100:101], s[40:41], 0x148
	s_waitcnt lgkmcnt(0)
	v_mov_b32_e32 v4, s100
	v_mov_b32_e32 v5, s101
; template <int NT, class VF, class RP>
; __device__ __forceinline__ void epi_staged_bf16(f32x4 (&acc)[4][NT], int r0, int c0, unsigned char* smem, VF vf, RP rowptr) {
;     ...
; #pragma unroll
;   for (int i = 0; i < CPR / 2; ++i) {
;     const int c = t + 256 * i, row = c / CPR, ch = c % CPR;
;     u16* d = rowptr(row);
;     if (d) *(u32x4*)(d + ch * 8) = *(const u32x4*)(Ts + row * PITCH + ch * 8);
;   }
; __device__ __forceinline__ void phase_mix_a(const Params& p, int l, bool last, unsigned char* smem) {
;     ...
;         auto rp = [&](int r) -> u16* { return p.QR + (size_t)(row_base + r) * 768 + nt * 128; };
.LBB0_561:
	s_or_b64 exec, exec, s[0:1]
	v_mov_b64_e32 v[2:3], 0
	s_waitcnt lgkmcnt(0)
	v_cmp_ne_u64_e32 vcc, 0, v[4:5]
	v_mov_b64_e32 v[6:7], 0
	s_and_saveexec_b64 s[0:1], vcc
	s_cbranch_execz .LBB0_563
	v_add_u32_e32 v6, 0x400, v0
	v_ashrrev_i32_e32 v7, 31, v6
	v_lshrrev_b32_e32 v7, 28, v7
	v_add_u32_e32 v7, v6, v7
	v_ashrrev_i32_e32 v10, 4, v7
	v_add_u32_e32 v8, s4, v10
	s_movk_i32 s5, 0x600
	v_mad_i64_i32 v[8:9], s[34:35], v8, s5, v[4:5]
	v_and_b32_e32 v4, -16, v7
	v_sub_u32_e32 v11, v6, v4
	v_mul_lo_u32 v4, v10, s23
	v_lshl_add_u32 v4, v11, 4, v4
	ds_read_b128 v[4:7], v4
	s_add_i32 s34, s18, s19
	s_ashr_i32 s35, s34, 31
	v_lshlrev_b32_e32 v10, 3, v11
	v_lshl_add_u64 v[8:9], s[34:35], 1, v[8:9]
	v_ashrrev_i32_e32 v11, 31, v10
	v_lshl_add_u64 v[8:9], v[10:11], 1, v[8:9]
	s_waitcnt lgkmcnt(0)
	global_store_dwordx4 v[8:9], v[4:7], off sc1
	s_nop 1
	v_mov_b64_e32 v[4:5], s[40:41]
	s_load_dwordx2 s[100:101], s[40:41], 0x148
	s_waitcnt lgkmcnt(0)
	v_mov_b32_e32 v6, s100
	v_mov_b32_e32 v7, s101
.LBB0_563:
	s_or_b64 exec, exec, s[0:1]
	s_waitcnt lgkmcnt(0)
	v_cmp_ne_u64_e32 vcc, 0, v[6:7]
	s_and_saveexec_b64 s[0:1], vcc
	s_cbranch_execz .LBB0_565
	v_add_u32_e32 v2, 0x500, v0
	v_ashrrev_i32_e32 v3, 31, v2
	v_lshrrev_b32_e32 v3, 28, v3
	v_add_u32_e32 v3, v2, v3
	v_ashrrev_i32_e32 v4, 4, v3
	v_and_b32_e32 v3, -16, v3
	v_sub_u32_e32 v8, v2, v3
	v_mul_lo_u32 v2, v4, s23
	v_add_u32_e32 v5, s4, v4
	s_movk_i32 s5, 0x600
	v_lshl_add_u32 v2, v8, 4, v2
	v_mad_i64_i32 v[6:7], s[34:35], v5, s5, v[6:7]
	ds_read_b128 v[2:5], v2
	s_add_i32 s34, s18, s19
	s_ashr_i32 s35, s34, 31
	v_lshlrev_b32_e32 v8, 3, v8
	v_lshl_add_u64 v[6:7], s[34:35], 1, v[6:7]
	v_ashrrev_i32_e32 v9, 31, v8
	v_lshl_add_u64 v[6:7], v[8:9], 1, v[6:7]
	s_waitcnt lgkmcnt(0)
	global_store_dwordx4 v[6:7], v[2:5], off sc1
	s_nop 1
	v_mov_b64_e32 v[2:3], s[40:41]
	s_load_dwordx2 s[100:101], s[40:41], 0x148
	s_waitcnt lgkmcnt(0)
	v_mov_b32_e32 v2, s100
	v_mov_b32_e32 v3, s101
.LBB0_565:
	s_or_b64 exec, exec, s[0:1]
	v_mov_b64_e32 v[4:5], 0
	s_waitcnt lgkmcnt(0)
	v_cmp_ne_u64_e32 vcc, 0, v[2:3]
	s_and_saveexec_b64 s[0:1], vcc
	s_cbranch_execz .LBB0_567
	v_add_u32_e32 v4, 0x600, v0
	v_ashrrev_i32_e32 v5, 31, v4
	v_lshrrev_b32_e32 v5, 28, v5
	v_add_u32_e32 v5, v4, v5
	v_ashrrev_i32_e32 v8, 4, v5
	v_add_u32_e32 v6, s4, v8
	s_movk_i32 s5, 0x600
	v_mad_i64_i32 v[6:7], s[34:35], v6, s5, v[2:3]
	v_and_b32_e32 v2, -16, v5
	v_sub_u32_e32 v9, v4, v2
	v_mul_lo_u32 v2, v8, s23
	v_lshl_add_u32 v2, v9, 4, v2
	ds_read_b128 v[2:5], v2
	s_add_i32 s34, s18, s19
	s_ashr_i32 s35, s34, 31
	v_lshlrev_b32_e32 v8, 3, v9
	v_lshl_add_u64 v[6:7], s[34:35], 1, v[6:7]
	v_ashrrev_i32_e32 v9, 31, v8
	v_lshl_add_u64 v[6:7], v[8:9], 1, v[6:7]
	s_waitcnt lgkmcnt(0)
	global_store_dwordx4 v[6:7], v[2:5], off sc1
	s_nop 1
	v_mov_b64_e32 v[2:3], s[40:41]
	s_load_dwordx2 s[100:101], s[40:41], 0x148
	s_waitcnt lgkmcnt(0)
	v_mov_b32_e32 v4, s100
	v_mov_b32_e32 v5, s101
.LBB0_567:
	s_or_b64 exec, exec, s[0:1]
	s_waitcnt lgkmcnt(0)
	v_cmp_ne_u64_e32 vcc, 0, v[4:5]
	s_and_saveexec_b64 s[0:1], vcc
	s_cbranch_execz .LBB0_544
	v_add_u32_e32 v0, 0x700, v0
	v_ashrrev_i32_e32 v2, 31, v0
	v_lshrrev_b32_e32 v2, 28, v2
	v_add_u32_e32 v2, v0, v2
	v_ashrrev_i32_e32 v3, 4, v2
	v_and_b32_e32 v2, -16, v2
	v_sub_u32_e32 v0, v0, v2
	v_mul_lo_u32 v2, v3, s23
	v_add_u32_e32 v6, s4, v3
	s_movk_i32 s4, 0x600
	v_lshl_add_u32 v2, v0, 4, v2
	v_mad_i64_i32 v[6:7], s[4:5], v6, s4, v[4:5]
	ds_read_b128 v[2:5], v2
	s_add_i32 s4, s18, s19
	s_ashr_i32 s5, s4, 31
	v_lshlrev_b32_e32 v8, 3, v0
	v_lshl_add_u64 v[6:7], s[4:5], 1, v[6:7]
	v_ashrrev_i32_e32 v9, 31, v8
	v_lshl_add_u64 v[6:7], v[8:9], 1, v[6:7]
	s_waitcnt lgkmcnt(0)
	global_store_dwordx4 v[6:7], v[2:5], off sc1
	s_branch .LBB0_544

; template <class RP>
; __device__ __forceinline__ void epi_staged_bf16_T(f32x4 (&acc)[4][4], int r0, int c0, unsigned char* smem, RP colptr) {
;     ...
;   __syncthreads();
; #pragma unroll
;   for (int mi = 0; mi < 4; ++mi)
; #pragma unroll
;     for (int ni = 0; ni < 4; ++ni) {
;       u32x2 pk;
;       pk.x = pack2(acc[mi][ni][0], acc[mi][ni][1]);
;       pk.y = pack2(acc[mi][ni][2], acc[mi][ni][3]);
;       *(u32x2*)(Ts + (c0 + ni * 16) * PITCH + r0 + mi * 16) = pk;
;     }
;   __syncthreads();
; __device__ __forceinline__ void phase_mix_a(const Params& p, int l, bool last, unsigned char* smem) {
;     ...
; #pragma unroll
;           for (int mi = 0; mi < 4; ++mi)
; #pragma unroll
;             for (int j = 0; j < 4; ++j) {
;               const float sc = rs[r0 + mi * 16 + j];
; #pragma unroll
;               for (int ni = 0; ni < 4; ++ni) acc[mi][ni][j] *= sc;
;             }
;           auto cp = [&](int c) -> u16* { return p.Vt + ((size_t)(b * 4 + h) * 128 + c) * NPOS + pos_base; };
;           epi_staged_bf16_T(acc, r0, c0, smem, cp);
;         }
.LBB0_581:
	s_or_b64 exec, exec, s[0:1]
	s_lshr_b32 s5, s19, 1
	v_lshlrev_b32_e32 v0, 6, v0
	s_bitcmp1_b32 s9, 0
	v_lshl_or_b32 v18, v93, 2, v0
	s_cselect_b64 s[34:35], -1, 0
	s_waitcnt lgkmcnt(0)
	v_lshl_or_b32 v19, v100, 6, v101
	s_mov_b64 s[0:1], -1
	s_and_b64 vcc, exec, s[34:35]
	v_lshl_add_u32 v20, v18, 2, v213
	s_barrier
	s_cbranch_vccz .LBB0_583
	ds_read_b128 v[22:25], v20
	ds_read_b128 v[26:29], v20 offset:64
	v_mul_u32_u24_e32 v0, 0x88, v19
	v_lshlrev_b32_e32 v0, 1, v0
	v_mov_b32_e32 v21, v187
	s_waitcnt lgkmcnt(1)
	v_pk_mul_f32 v[30:31], v[86:87], v[22:23]
	v_pk_mul_f32 v[32:33], v[74:75], v[22:23]
	v_pk_mul_f32 v[50:51], v[78:79], v[22:23]
	v_pk_mul_f32 v[52:53], v[82:83], v[22:23]
	v_pk_mul_f32 v[70:71], v[88:89], v[24:25]
	v_pk_mul_f32 v[72:73], v[76:77], v[24:25]
	v_pk_mul_f32 v[92:93], v[80:81], v[24:25]
	v_pk_mul_f32 v[94:95], v[84:85], v[24:25]
	s_waitcnt lgkmcnt(0)
	v_pk_mul_f32 v[96:97], v[66:67], v[26:27]
	v_pk_mul_f32 v[98:99], v[54:55], v[26:27]
	v_pk_mul_f32 v[100:101], v[58:59], v[26:27]
	v_pk_mul_f32 v[102:103], v[62:63], v[26:27]
	v_pk_mul_f32 v[104:105], v[68:69], v[28:29]
	ds_read_b128 v[22:25], v20 offset:128
	v_pk_mul_f32 v[106:107], v[56:57], v[28:29]
	v_pk_mul_f32 v[108:109], v[60:61], v[28:29]
	v_pk_mul_f32 v[110:111], v[64:65], v[28:29]
	ds_read_b128 v[26:29], v20 offset:192
	v_cvt_pk_bf16_f32 v32, v32, v33
	v_cvt_pk_bf16_f32 v33, v72, v73
	v_lshl_add_u32 v0, v18, 1, v0
	v_cvt_pk_bf16_f32 v30, v30, v31
	v_cvt_pk_bf16_f32 v31, v70, v71
	v_cvt_pk_bf16_f32 v70, v98, v99
	v_cvt_pk_bf16_f32 v71, v106, v107
	s_waitcnt lgkmcnt(0)
	s_barrier
	v_cvt_pk_bf16_f32 v50, v50, v51
	v_cvt_pk_bf16_f32 v51, v92, v93
	ds_write2_b64 v0, v[32:33], v[70:71] offset1:4
	v_cvt_pk_bf16_f32 v32, v100, v101
	v_cvt_pk_bf16_f32 v33, v108, v109
	v_add_u32_e32 v70, 0x1000, v0
	v_cvt_pk_bf16_f32 v52, v52, v53
	v_cvt_pk_bf16_f32 v53, v94, v95
	ds_write2_b64 v70, v[50:51], v[32:33] offset0:32 offset1:36
	v_cvt_pk_bf16_f32 v32, v102, v103
	v_cvt_pk_bf16_f32 v33, v110, v111
	v_add_u32_e32 v71, 0x2000, v0
	v_pk_mul_f32 v[112:113], v[34:35], v[22:23]
	v_pk_mul_f32 v[114:115], v[38:39], v[22:23]
	v_pk_mul_f32 v[116:117], v[42:43], v[22:23]
	v_pk_mul_f32 v[22:23], v[46:47], v[22:23]
	v_pk_mul_f32 v[118:119], v[36:37], v[24:25]
	v_pk_mul_f32 v[120:121], v[40:41], v[24:25]
	v_pk_mul_f32 v[122:123], v[44:45], v[24:25]
	v_pk_mul_f32 v[24:25], v[48:49], v[24:25]
	v_pk_mul_f32 v[124:125], v[2:3], v[26:27]
	v_pk_mul_f32 v[126:127], v[14:15], v[26:27]
	v_pk_mul_f32 v[128:129], v[10:11], v[26:27]
	v_pk_mul_f32 v[26:27], v[6:7], v[26:27]
	v_pk_mul_f32 v[130:131], v[4:5], v[28:29]
	v_pk_mul_f32 v[132:133], v[16:17], v[28:29]
	v_pk_mul_f32 v[134:135], v[12:13], v[28:29]
	v_pk_mul_f32 v[28:29], v[8:9], v[28:29]
	ds_write2_b64 v71, v[52:53], v[32:33] offset0:64 offset1:68
	v_cvt_pk_bf16_f32 v32, v96, v97
	v_cvt_pk_bf16_f32 v33, v104, v105
	v_add_u32_e32 v52, 0x3000, v0
	ds_write2_b64 v52, v[30:31], v[32:33] offset0:96 offset1:100
	v_cvt_pk_bf16_f32 v30, v114, v115
	v_cvt_pk_bf16_f32 v31, v120, v121
	v_cvt_pk_bf16_f32 v22, v22, v23
	v_cvt_pk_bf16_f32 v23, v24, v25
	v_cvt_pk_bf16_f32 v50, v126, v127
	v_cvt_pk_bf16_f32 v51, v132, v133
	v_cvt_pk_bf16_f32 v26, v26, v27
	v_cvt_pk_bf16_f32 v27, v28, v29
	v_cvt_pk_bf16_f32 v32, v116, v117
	v_cvt_pk_bf16_f32 v33, v122, v123
	v_cvt_pk_bf16_f32 v24, v112, v113
	v_cvt_pk_bf16_f32 v25, v118, v119
	ds_write2_b64 v0, v[30:31], v[50:51] offset0:8 offset1:12
	v_cvt_pk_bf16_f32 v30, v128, v129
	v_cvt_pk_bf16_f32 v31, v134, v135
	ds_write2_b64 v71, v[22:23], v[26:27] offset0:72 offset1:76
	v_cvt_pk_bf16_f32 v22, v124, v125
	v_cvt_pk_bf16_f32 v23, v130, v131
	v_mov_b64_e32 v[26:27], s[40:41]
	ds_write2_b64 v70, v[32:33], v[30:31] offset0:40 offset1:44
	ds_write2_b64 v52, v[24:25], v[22:23] offset0:104 offset1:108
	s_waitcnt lgkmcnt(0)
	s_barrier
; template <class RP>
; __device__ __forceinline__ void epi_staged_bf16_T(f32x4 (&acc)[4][4], int r0, int c0, unsigned char* smem, RP colptr) {
;     ...
; #pragma unroll
;   for (int i = 0; i < 8; ++i) {
;     const int c = t + 256 * i, col = c >> 4, ch = c & 15;
;     *(u32x4*)(colptr(col) + ch * 8) = *(const u32x4*)(Ts + col * PITCH + ch * 8);
;   }
; __device__ __forceinline__ void phase_mix_a(const Params& p, int l, bool last, unsigned char* smem) {
;     ...
;           auto cp = [&](int c) -> u16* { return p.Vt + ((size_t)(b * 4 + h) * 128 + c) * NPOS + pos_base; };
	s_load_dwordx2 s[100:101], s[40:41], 0x158
	s_add_i32 s1, s18, 0xffffc000
	s_and_b32 s19, s18, 0x1f80
	s_ashr_i32 s0, s9, 9
	s_lshr_b32 s1, s1, 8
	s_addk_i32 s19, 0x100
	s_and_b32 s34, s18, 0x80
	v_lshlrev_b32_e32 v0, 4, v21
	s_cmpk_lt_i32 s4, 0x4000
	v_and_b32_e32 v0, 0xf0, v0
	v_ashrrev_i32_e32 v30, 4, v21
	s_cselect_b32 s35, s0, s1
	v_mad_u64_u32 v[22:23], s[0:1], v30, s23, v[0:1]
	s_cselect_b32 s19, s19, s34
	s_lshl_b32 s0, s35, 2
	s_or_b32 s0, s0, s5
	s_ashr_i32 s1, s0, 31
	s_lshl_b64 s[0:1], s[0:1], 7
	v_ashrrev_i32_e32 v31, 31, v30
	ds_read_b128 v[22:25], v22
	v_lshl_add_u64 v[30:31], s[0:1], 0, v[30:31]
	s_lshl_b32 s94, s19, 1
	s_waitcnt lgkmcnt(0)
	v_mov_b32_e32 v28, s100
	v_mov_b32_e32 v29, s101
	v_mad_u64_u32 v[28:29], s[34:35], v30, s68, v[28:29]
	v_mad_i32_i24 v29, v31, s68, v29
	v_lshl_add_u64 v[28:29], v[28:29], 0, s[94:95]
	v_lshl_add_u64 v[28:29], v[28:29], 0, v[0:1]
	global_store_dwordx4 v[28:29], v[22:25], off sc1
	s_load_dwordx2 s[100:101], s[40:41], 0x158
	s_waitcnt lgkmcnt(0)
	v_mov_b32_e32 v28, s100
	v_mov_b32_e32 v29, s101
	s_nop 0
	v_add_u32_e32 v22, 0x100, v21
	v_ashrrev_i32_e32 v22, 4, v22
	v_mad_u64_u32 v[24:25], s[34:35], v22, s23, v[0:1]
	v_ashrrev_i32_e32 v23, 31, v22
	v_lshl_add_u64 v[30:31], s[0:1], 0, v[22:23]
	ds_read_b128 v[22:25], v24
	s_waitcnt lgkmcnt(0)
	v_mad_u64_u32 v[28:29], s[34:35], v30, s68, v[28:29]
	v_mad_i32_i24 v29, v31, s68, v29
	v_lshl_add_u64 v[28:29], v[28:29], 0, s[94:95]
	v_lshl_add_u64 v[28:29], v[28:29], 0, v[0:1]
	global_store_dwordx4 v[28:29], v[22:25], off sc1
	s_load_dwordx2 s[100:101], s[40:41], 0x158
	s_waitcnt lgkmcnt(0)
	v_mov_b32_e32 v28, s100
	v_mov_b32_e32 v29, s101
	s_nop 0
	v_add_u32_e32 v22, 0x200, v21
	v_ashrrev_i32_e32 v22, 4, v22
	v_mad_u64_u32 v[24:25], s[34:35], v22, s23, v[0:1]
	v_ashrrev_i32_e32 v23, 31, v22
	v_lshl_add_u64 v[30:31], s[0:1], 0, v[22:23]
	ds_read_b128 v[22:25], v24
	s_waitcnt lgkmcnt(0)
	v_mad_u64_u32 v[28:29], s[34:35], v30, s68, v[28:29]
	v_mad_i32_i24 v29, v31, s68, v29
	v_lshl_add_u64 v[28:29], v[28:29], 0, s[94:95]
	v_lshl_add_u64 v[28:29], v[28:29], 0, v[0:1]
	global_store_dwordx4 v[28:29], v[22:25], off sc1
	v_mov_b32_e32 v28, s100
	v_mov_b32_e32 v29, s101
	s_nop 0
	v_add_u32_e32 v22, 0x300, v21
	v_ashrrev_i32_e32 v22, 4, v22
	v_mad_u64_u32 v[24:25], s[34:35], v22, s23, v[0:1]
	v_ashrrev_i32_e32 v23, 31, v22
	v_lshl_add_u64 v[30:31], s[0:1], 0, v[22:23]
	ds_read_b128 v[22:25], v24
	s_waitcnt lgkmcnt(0)
	v_mad_u64_u32 v[28:29], s[34:35], v30, s68, v[28:29]
	v_mad_i32_i24 v29, v31, s68, v29
	v_lshl_add_u64 v[28:29], v[28:29], 0, s[94:95]
	v_lshl_add_u64 v[28:29], v[28:29], 0, v[0:1]
	global_store_dwordx4 v[28:29], v[22:25], off sc1
	v_mov_b32_e32 v28, s100
	v_mov_b32_e32 v29, s101
	s_nop 0
	v_add_u32_e32 v22, 0x400, v21
	v_ashrrev_i32_e32 v22, 4, v22
	v_mad_u64_u32 v[24:25], s[34:35], v22, s23, v[0:1]
	v_ashrrev_i32_e32 v23, 31, v22
	v_lshl_add_u64 v[30:31], s[0:1], 0, v[22:23]
	ds_read_b128 v[22:25], v24
	s_waitcnt lgkmcnt(0)
	v_mad_u64_u32 v[28:29], s[34:35], v30, s68, v[28:29]
	v_mad_i32_i24 v29, v31, s68, v29
	v_lshl_add_u64 v[28:29], v[28:29], 0, s[94:95]
	v_lshl_add_u64 v[28:29], v[28:29], 0, v[0:1]
	global_store_dwordx4 v[28:29], v[22:25], off sc1
	v_mov_b32_e32 v28, s100
	v_mov_b32_e32 v29, s101
	s_nop 0
	v_add_u32_e32 v22, 0x500, v21
	v_ashrrev_i32_e32 v22, 4, v22
	v_mad_u64_u32 v[24:25], s[34:35], v22, s23, v[0:1]
	v_ashrrev_i32_e32 v23, 31, v22
	v_lshl_add_u64 v[30:31], s[0:1], 0, v[22:23]
	ds_read_b128 v[22:25], v24
	s_waitcnt lgkmcnt(0)
	v_mad_u64_u32 v[28:29], s[34:35], v30, s68, v[28:29]
	v_mad_i32_i24 v29, v31, s68, v29
	v_lshl_add_u64 v[28:29], v[28:29], 0, s[94:95]
	v_lshl_add_u64 v[28:29], v[28:29], 0, v[0:1]
	global_store_dwordx4 v[28:29], v[22:25], off sc1
	v_mov_b32_e32 v28, s100
	v_mov_b32_e32 v29, s101
	s_nop 0
	v_add_u32_e32 v22, 0x600, v21
	v_ashrrev_i32_e32 v22, 4, v22
	v_mad_u64_u32 v[24:25], s[34:35], v22, s23, v[0:1]
	v_ashrrev_i32_e32 v23, 31, v22
	v_lshl_add_u64 v[30:31], s[0:1], 0, v[22:23]
	ds_read_b128 v[22:25], v24
	v_add_u32_e32 v21, 0x700, v21
	s_waitcnt lgkmcnt(0)
	v_mad_u64_u32 v[28:29], s[34:35], v30, s68, v[28:29]
	v_mad_i32_i24 v29, v31, s68, v29
	v_lshl_add_u64 v[28:29], v[28:29], 0, s[94:95]
	v_lshl_add_u64 v[28:29], v[28:29], 0, v[0:1]
	global_store_dwordx4 v[28:29], v[22:25], off sc1
	v_mov_b32_e32 v26, s100
	v_mov_b32_e32 v27, s101
	s_nop 0
	v_ashrrev_i32_e32 v22, 4, v21
	v_mad_u64_u32 v[24:25], s[34:35], v22, s23, v[0:1]
	v_ashrrev_i32_e32 v23, 31, v22
	v_lshl_add_u64 v[28:29], s[0:1], 0, v[22:23]
	ds_read_b128 v[22:25], v24
	s_waitcnt lgkmcnt(0)
	v_mad_u64_u32 v[26:27], s[0:1], v28, s68, v[26:27]
	v_mad_i32_i24 v27, v29, s68, v27
	v_lshl_add_u64 v[26:27], v[26:27], 0, s[94:95]
	v_lshl_add_u64 v[26:27], v[26:27], 0, v[0:1]
	global_store_dwordx4 v[26:27], v[22:25], off sc1
	s_cbranch_execnz .LBB0_572
	s_branch .LBB0_584

; __device__ __forceinline__ u16 f2bf(float f) { return (u16)(pack2(f, 0.f) & 0xffffu); }
; __device__ __forceinline__ int tid_() { int t = threadIdx.x; asm volatile("" : "+v"(t)); return t; }
; template <int NT, class VF, class RP>
; __device__ __forceinline__ void epi_staged_bf16(f32x4 (&acc)[4][NT], int r0, int c0, unsigned char* smem, VF vf, RP rowptr) {
;   constexpr int BN = NT * 32, PITCH = BN + 8, CPR = BN / 8;
;   u16* Ts = (u16*)smem;
;   const int t = tid_();
;   __syncthreads();
; #pragma unroll
;   for (int mi = 0; mi < 4; ++mi)
; #pragma unroll
;     for (int ni = 0; ni < NT; ++ni)
; #pragma unroll
;       for (int j = 0; j < 4; ++j) {
;         const int r = r0 + mi * 16 + j, c = c0 + ni * 16;
;         Ts[r * PITCH + c] = f2bf(vf(r, c, acc[mi][ni][j]));
;       }
;   __syncthreads();
; __device__ __forceinline__ void phase_mix_a(const Params& p, int l, bool last, unsigned char* smem) {
;     ...
;         if ((nt & 1) == 0) {
;           auto vf = [&](int r, int, float v) { return v * rs[r]; };
;           auto rp = [&](int r) -> u16* { return p.KN + (size_t)(row_base + r) * 512 + h * 128; };
;           epi_staged_bf16<4>(acc, r0, c0, smem, vf, rp);
.LBB0_584:
	v_mov_b32_e32 v0, v187
	s_waitcnt lgkmcnt(0)
	s_barrier
	ds_read_b128 v[22:25], v20
	v_lshlrev_b32_e32 v26, 1, v19
	s_waitcnt lgkmcnt(0)
	v_mul_f32_e32 v21, v74, v22
	v_cvt_pk_bf16_f32 v21, v21, s0
	v_mad_u64_u32 v[28:29], s[0:1], v18, s23, v[26:27]
	v_or_b32_e32 v18, 1, v18
	v_mul_f32_e32 v19, v75, v23
	ds_write_b16 v28, v21
	v_cvt_pk_bf16_f32 v21, v19, s0
	v_mad_u64_u32 v[18:19], s[0:1], v18, s23, v[26:27]
	v_mul_f32_e32 v19, v76, v24
	s_nop 0
	v_cvt_pk_bf16_f32 v19, v19, s0
	ds_write_b16 v18, v19 offset:272
	v_mul_f32_e32 v19, v77, v25
	v_cvt_pk_bf16_f32 v19, v19, s0
	ds_write_b16 v18, v19 offset:544
	v_mul_f32_e32 v19, v78, v22
	v_cvt_pk_bf16_f32 v19, v19, s0
	ds_write_b16 v28, v19 offset:32
	v_mul_f32_e32 v19, v79, v23
	v_cvt_pk_bf16_f32 v19, v19, s0
	ds_write_b16 v18, v19 offset:32
	v_mul_f32_e32 v19, v80, v24
	v_cvt_pk_bf16_f32 v19, v19, s0
	ds_write_b16 v18, v19 offset:304
	v_mul_f32_e32 v19, v81, v25
	v_cvt_pk_bf16_f32 v19, v19, s0
	ds_write_b16 v18, v19 offset:576
	v_mul_f32_e32 v19, v82, v22
	v_cvt_pk_bf16_f32 v19, v19, s0
	ds_write_b16 v28, v19 offset:64
	v_mul_f32_e32 v19, v83, v23
	v_cvt_pk_bf16_f32 v19, v19, s0
	ds_write_b16 v18, v19 offset:64
	v_mul_f32_e32 v19, v84, v24
	v_cvt_pk_bf16_f32 v19, v19, s0
	ds_write_b16 v18, v19 offset:336
	v_mul_f32_e32 v19, v85, v25
	v_cvt_pk_bf16_f32 v19, v19, s0
	ds_write_b16 v18, v19 offset:608
	v_mul_f32_e32 v19, v86, v22
	v_cvt_pk_bf16_f32 v19, v19, s0
	ds_write_b16 v28, v19 offset:96
	v_mul_f32_e32 v19, v87, v23
	v_cvt_pk_bf16_f32 v19, v19, s0
	ds_write_b16 v18, v19 offset:96
	v_mul_f32_e32 v19, v88, v24
	v_cvt_pk_bf16_f32 v19, v19, s0
	ds_write_b16 v18, v19 offset:368
	v_mul_f32_e32 v19, v89, v25
	ds_read_b128 v[22:25], v20 offset:64
	v_cvt_pk_bf16_f32 v19, v19, s0
	ds_write_b16 v18, v19 offset:640
	ds_write_b16 v18, v21
	s_waitcnt lgkmcnt(0)
	v_mul_f32_e32 v19, v54, v22
	v_cvt_pk_bf16_f32 v19, v19, s0
	ds_write_b16 v18, v19 offset:4080
	v_mul_f32_e32 v19, v55, v23
	v_cvt_pk_bf16_f32 v19, v19, s0
	ds_write_b16 v18, v19 offset:4352
	v_mul_f32_e32 v19, v56, v24
	v_cvt_pk_bf16_f32 v19, v19, s0
	ds_write_b16 v18, v19 offset:4624
	v_mul_f32_e32 v19, v57, v25
	v_cvt_pk_bf16_f32 v19, v19, s0
	ds_write_b16 v18, v19 offset:4896
	v_mul_f32_e32 v19, v58, v22
	v_cvt_pk_bf16_f32 v19, v19, s0
	ds_write_b16 v18, v19 offset:4112
	v_mul_f32_e32 v19, v59, v23
	v_cvt_pk_bf16_f32 v19, v19, s0
	ds_write_b16 v18, v19 offset:4384
	v_mul_f32_e32 v19, v60, v24
	v_cvt_pk_bf16_f32 v19, v19, s0
	ds_write_b16 v18, v19 offset:4656
	v_mul_f32_e32 v19, v61, v25
	v_cvt_pk_bf16_f32 v19, v19, s0
	ds_write_b16 v18, v19 offset:4928
	v_mul_f32_e32 v19, v62, v22
	v_cvt_pk_bf16_f32 v19, v19, s0
	ds_write_b16 v18, v19 offset:4144
	v_mul_f32_e32 v19, v63, v23
	v_cvt_pk_bf16_f32 v19, v19, s0
	ds_write_b16 v18, v19 offset:4416
	v_mul_f32_e32 v19, v64, v24
	v_cvt_pk_bf16_f32 v19, v19, s0
	ds_write_b16 v18, v19 offset:4688
	v_mul_f32_e32 v19, v65, v25
	v_cvt_pk_bf16_f32 v19, v19, s0
	ds_write_b16 v18, v19 offset:4960
	v_mul_f32_e32 v19, v66, v22
	v_cvt_pk_bf16_f32 v19, v19, s0
	ds_write_b16 v18, v19 offset:4176
	v_mul_f32_e32 v19, v67, v23
	v_cvt_pk_bf16_f32 v19, v19, s0
	ds_write_b16 v18, v19 offset:4448
	v_mul_f32_e32 v19, v68, v24
	v_cvt_pk_bf16_f32 v19, v19, s0
	ds_write_b16 v18, v19 offset:4720
	v_mul_f32_e32 v19, v69, v25
	ds_read_b128 v[22:25], v20 offset:128
	v_cvt_pk_bf16_f32 v19, v19, s0
	ds_write_b16 v18, v19 offset:4992
	s_waitcnt lgkmcnt(0)
	v_mul_f32_e32 v19, v38, v22
	v_cvt_pk_bf16_f32 v19, v19, s0
	ds_write_b16 v18, v19 offset:8432
	v_mul_f32_e32 v19, v39, v23
	v_cvt_pk_bf16_f32 v19, v19, s0
	ds_write_b16 v18, v19 offset:8704
	v_mul_f32_e32 v19, v40, v24
	v_cvt_pk_bf16_f32 v19, v19, s0
	ds_write_b16 v18, v19 offset:8976
	v_mul_f32_e32 v19, v41, v25
	v_cvt_pk_bf16_f32 v19, v19, s0
	ds_write_b16 v18, v19 offset:9248
	v_mul_f32_e32 v19, v42, v22
	v_cvt_pk_bf16_f32 v19, v19, s0
	ds_write_b16 v18, v19 offset:8464
	v_mul_f32_e32 v19, v43, v23
	v_cvt_pk_bf16_f32 v19, v19, s0
	ds_write_b16 v18, v19 offset:8736
	v_mul_f32_e32 v19, v44, v24
	v_cvt_pk_bf16_f32 v19, v19, s0
	ds_write_b16 v18, v19 offset:9008
	v_mul_f32_e32 v19, v45, v25
	v_cvt_pk_bf16_f32 v19, v19, s0
	ds_write_b16 v18, v19 offset:9280
	v_mul_f32_e32 v19, v46, v22
	v_cvt_pk_bf16_f32 v19, v19, s0
	ds_write_b16 v18, v19 offset:8496
	v_mul_f32_e32 v19, v47, v23
	v_cvt_pk_bf16_f32 v19, v19, s0
	ds_write_b16 v18, v19 offset:8768
	v_mul_f32_e32 v19, v48, v24
	v_cvt_pk_bf16_f32 v19, v19, s0
	ds_write_b16 v18, v19 offset:9040
	v_mul_f32_e32 v19, v49, v25
	v_cvt_pk_bf16_f32 v19, v19, s0
	ds_write_b16 v18, v19 offset:9312
	v_mul_f32_e32 v19, v34, v22
	v_cvt_pk_bf16_f32 v19, v19, s0
	ds_write_b16 v18, v19 offset:8528
	v_mul_f32_e32 v19, v35, v23
	ds_read_b128 v[20:23], v20 offset:192
	v_cvt_pk_bf16_f32 v19, v19, s0
	ds_write_b16 v18, v19 offset:8800
	v_mul_f32_e32 v19, v36, v24
	v_cvt_pk_bf16_f32 v19, v19, s0
	s_waitcnt lgkmcnt(0)
	v_mul_f32_e32 v2, v2, v20
	v_mul_f32_e32 v14, v14, v20
	v_mul_f32_e32 v10, v10, v20
	v_mul_f32_e32 v6, v6, v20
	v_cvt_pk_bf16_f32 v2, v2, s0
	v_cvt_pk_bf16_f32 v14, v14, s0
	v_cvt_pk_bf16_f32 v10, v10, s0
	v_cvt_pk_bf16_f32 v6, v6, s0
	ds_write_b16 v18, v2 offset:12880
	v_mul_f32_e32 v2, v3, v21
	ds_write_b16 v18, v14 offset:12784
	v_mul_f32_e32 v14, v15, v21
	ds_write_b16 v18, v10 offset:12816
	v_mul_f32_e32 v10, v11, v21
	ds_write_b16 v18, v6 offset:12848
	v_mul_f32_e32 v6, v7, v21
	v_cvt_pk_bf16_f32 v2, v2, s0
	v_cvt_pk_bf16_f32 v14, v14, s0
	v_cvt_pk_bf16_f32 v10, v10, s0
	v_cvt_pk_bf16_f32 v6, v6, s0
	ds_write_b16 v18, v2 offset:13152
	v_mul_f32_e32 v2, v4, v22
	ds_write_b16 v18, v14 offset:13056
	v_mul_f32_e32 v14, v16, v22
	ds_write_b16 v18, v10 offset:13088
	v_mul_f32_e32 v10, v12, v22
	ds_write_b16 v18, v6 offset:13120
	v_mul_f32_e32 v6, v8, v22
	v_cvt_pk_bf16_f32 v2, v2, s0
	v_cvt_pk_bf16_f32 v14, v14, s0
	v_cvt_pk_bf16_f32 v10, v10, s0
	v_cvt_pk_bf16_f32 v6, v6, s0
	ds_write_b16 v18, v2 offset:13424
	v_mul_f32_e32 v2, v5, v23
	ds_write_b16 v18, v19 offset:9072
	v_mul_f32_e32 v19, v37, v25
	ds_write_b16 v18, v14 offset:13328
	v_mul_f32_e32 v14, v17, v23
	ds_write_b16 v18, v10 offset:13360
	v_mul_f32_e32 v10, v13, v23
	ds_write_b16 v18, v6 offset:13392
	v_mul_f32_e32 v6, v9, v23
	v_cvt_pk_bf16_f32 v2, v2, s0
	v_cvt_pk_bf16_f32 v19, v19, s0
	v_cvt_pk_bf16_f32 v14, v14, s0
	v_cvt_pk_bf16_f32 v10, v10, s0
	v_cvt_pk_bf16_f32 v6, v6, s0
	ds_write_b16 v18, v2 offset:13696
	v_mov_b64_e32 v[2:3], s[40:41]
	ds_write_b16 v18, v19 offset:9344
	ds_write_b16 v18, v14 offset:13600
	ds_write_b16 v18, v10 offset:13632
	ds_write_b16 v18, v6 offset:13664
	s_waitcnt lgkmcnt(0)
	s_barrier
; template <int NT, class VF, class RP>
; __device__ __forceinline__ void epi_staged_bf16(f32x4 (&acc)[4][NT], int r0, int c0, unsigned char* smem, VF vf, RP rowptr) {
;     ...
; #pragma unroll
;   for (int i = 0; i < CPR / 2; ++i) {
;     const int c = t + 256 * i, row = c / CPR, ch = c % CPR;
;     u16* d = rowptr(row);
;     if (d) *(u32x4*)(d + ch * 8) = *(const u32x4*)(Ts + row * PITCH + ch * 8);
;   }
; __device__ __forceinline__ void phase_mix_a(const Params& p, int l, bool last, unsigned char* smem) {
;     ...
;           auto rp = [&](int r) -> u16* { return p.KN + (size_t)(row_base + r) * 512 + h * 128; };
	s_load_dwordx2 s[100:101], s[40:41], 0x150
	s_waitcnt lgkmcnt(0)
	v_mov_b32_e32 v6, s100
	v_mov_b32_e32 v7, s101
	v_mov_b64_e32 v[2:3], 0
	v_mov_b64_e32 v[4:5], 0
	s_waitcnt lgkmcnt(0)
	v_cmp_ne_u64_e32 vcc, 0, v[6:7]
	s_and_saveexec_b64 s[0:1], vcc
	s_cbranch_execz .LBB0_586
	v_ashrrev_i32_e32 v4, 31, v0
	v_lshrrev_b32_e32 v4, 28, v4
	v_add_u32_e32 v10, v0, v4
	v_ashrrev_i32_e32 v11, 4, v10
	v_add_u32_e32 v4, s4, v11
	v_ashrrev_i32_e32 v5, 31, v4
	v_lshlrev_b64 v[4:5], 10, v[4:5]
	v_lshl_add_u64 v[8:9], v[6:7], 0, v[4:5]
	v_and_b32_e32 v4, -16, v10
	v_sub_u32_e32 v10, v0, v4
	v_mul_lo_u32 v4, v11, s23
	v_lshl_add_u32 v4, v10, 4, v4
	ds_read_b128 v[4:7], v4
	s_lshl_b32 s94, s5, 8
	v_lshlrev_b32_e32 v10, 3, v10
	v_lshl_add_u64 v[8:9], v[8:9], 0, s[94:95]
	v_ashrrev_i32_e32 v11, 31, v10
	v_lshl_add_u64 v[8:9], v[10:11], 1, v[8:9]
	s_waitcnt lgkmcnt(0)
	global_store_dwordx4 v[8:9], v[4:7], off sc1
	s_nop 1
	v_mov_b64_e32 v[4:5], s[40:41]
	s_load_dwordx2 s[100:101], s[40:41], 0x150
	s_waitcnt lgkmcnt(0)
	v_mov_b32_e32 v4, s100
	v_mov_b32_e32 v5, s101
.LBB0_586:
	s_or_b64 exec, exec, s[0:1]
	s_waitcnt lgkmcnt(0)
	v_cmp_ne_u64_e32 vcc, 0, v[4:5]
	s_and_saveexec_b64 s[0:1], vcc
	s_cbranch_execz .LBB0_588
	v_add_u32_e32 v8, 0x100, v0
	v_ashrrev_i32_e32 v2, 31, v8
	v_lshrrev_b32_e32 v2, 28, v2
	v_add_u32_e32 v9, v8, v2
	v_ashrrev_i32_e32 v10, 4, v9
	v_add_u32_e32 v2, s4, v10
	v_ashrrev_i32_e32 v3, 31, v2
	v_lshlrev_b64 v[2:3], 10, v[2:3]
	v_lshl_add_u64 v[6:7], v[4:5], 0, v[2:3]
	v_and_b32_e32 v2, -16, v9
	v_sub_u32_e32 v8, v8, v2
	v_mul_lo_u32 v2, v10, s23
	v_lshl_add_u32 v2, v8, 4, v2
	ds_read_b128 v[2:5], v2
	s_lshl_b32 s94, s5, 8
	v_lshlrev_b32_e32 v8, 3, v8
	v_lshl_add_u64 v[6:7], v[6:7], 0, s[94:95]
	v_ashrrev_i32_e32 v9, 31, v8
	v_lshl_add_u64 v[6:7], v[8:9], 1, v[6:7]
	s_waitcnt lgkmcnt(0)
	global_store_dwordx4 v[6:7], v[2:5], off sc1
	s_nop 1
	v_mov_b64_e32 v[2:3], s[40:41]
	s_load_dwordx2 s[100:101], s[40:41], 0x150
	s_waitcnt lgkmcnt(0)
	v_mov_b32_e32 v2, s100
	v_mov_b32_e32 v3, s101
.LBB0_588:
	s_or_b64 exec, exec, s[0:1]
	v_mov_b64_e32 v[4:5], 0
	s_waitcnt lgkmcnt(0)
	v_cmp_ne_u64_e32 vcc, 0, v[2:3]
	v_mov_b64_e32 v[6:7], 0
	s_and_saveexec_b64 s[0:1], vcc
	s_cbranch_execz .LBB0_590
	v_add_u32_e32 v8, 0x200, v0
	v_ashrrev_i32_e32 v6, 31, v8
	v_lshrrev_b32_e32 v6, 28, v6
	v_add_u32_e32 v9, v8, v6
	v_ashrrev_i32_e32 v10, 4, v9
	v_add_u32_e32 v6, s4, v10
	v_ashrrev_i32_e32 v7, 31, v6
	v_lshlrev_b64 v[6:7], 10, v[6:7]
	v_lshl_add_u64 v[2:3], v[2:3], 0, v[6:7]
	v_and_b32_e32 v6, -16, v9
	v_sub_u32_e32 v11, v8, v6
	v_mul_lo_u32 v6, v10, s23
	v_lshl_add_u32 v6, v11, 4, v6
	ds_read_b128 v[6:9], v6
	s_lshl_b32 s94, s5, 8
	v_lshlrev_b32_e32 v10, 3, v11
	v_lshl_add_u64 v[2:3], v[2:3], 0, s[94:95]
	v_ashrrev_i32_e32 v11, 31, v10
	v_lshl_add_u64 v[2:3], v[10:11], 1, v[2:3]
	s_waitcnt lgkmcnt(0)
	global_store_dwordx4 v[2:3], v[6:9], off sc1
	v_mov_b64_e32 v[2:3], s[40:41]
	s_load_dwordx2 s[100:101], s[40:41], 0x150
	s_waitcnt lgkmcnt(0)
	v_mov_b32_e32 v6, s100
	v_mov_b32_e32 v7, s101
.LBB0_590:
	s_or_b64 exec, exec, s[0:1]
	s_waitcnt lgkmcnt(0)
	v_cmp_ne_u64_e32 vcc, 0, v[6:7]
	s_and_saveexec_b64 s[0:1], vcc
	s_cbranch_execz .LBB0_592
	v_add_u32_e32 v4, 0x300, v0
	v_ashrrev_i32_e32 v2, 31, v4
	v_lshrrev_b32_e32 v2, 28, v2
	v_add_u32_e32 v5, v4, v2
	v_ashrrev_i32_e32 v8, 4, v5
	v_add_u32_e32 v2, s4, v8
	v_ashrrev_i32_e32 v3, 31, v2
	v_lshlrev_b64 v[2:3], 10, v[2:3]
	v_lshl_add_u64 v[6:7], v[6:7], 0, v[2:3]
	v_and_b32_e32 v2, -16, v5
	v_sub_u32_e32 v9, v4, v2
	v_mul_lo_u32 v2, v8, s23
	v_lshl_add_u32 v2, v9, 4, v2
	ds_read_b128 v[2:5], v2
	s_lshl_b32 s94, s5, 8
	v_lshlrev_b32_e32 v8, 3, v9
	v_lshl_add_u64 v[6:7], v[6:7], 0, s[94:95]
	v_ashrrev_i32_e32 v9, 31, v8
	v_lshl_add_u64 v[6:7], v[8:9], 1, v[6:7]
	s_waitcnt lgkmcnt(0)
	global_store_dwordx4 v[6:7], v[2:5], off sc1
	s_nop 1
	v_mov_b64_e32 v[2:3], s[40:41]
	s_load_dwordx2 s[100:101], s[40:41], 0x150
	s_waitcnt lgkmcnt(0)
	v_mov_b32_e32 v4, s100
	v_mov_b32_e32 v5, s101
; template <int NT, class VF, class RP>
; __device__ __forceinline__ void epi_staged_bf16(f32x4 (&acc)[4][NT], int r0, int c0, unsigned char* smem, VF vf, RP rowptr) {
;     ...
; #pragma unroll
;   for (int i = 0; i < CPR / 2; ++i) {
;     const int c = t + 256 * i, row = c / CPR, ch = c % CPR;
;     u16* d = rowptr(row);
;     if (d) *(u32x4*)(d + ch * 8) = *(const u32x4*)(Ts + row * PITCH + ch * 8);
;   }
; __device__ __forceinline__ void phase_mix_a(const Params& p, int l, bool last, unsigned char* smem) {
;     ...
;           auto rp = [&](int r) -> u16* { return p.KN + (size_t)(row_base + r) * 512 + h * 128; };
.LBB0_592:
	s_or_b64 exec, exec, s[0:1]
	v_mov_b64_e32 v[2:3], 0
	s_waitcnt lgkmcnt(0)
	v_cmp_ne_u64_e32 vcc, 0, v[4:5]
	v_mov_b64_e32 v[6:7], 0
	s_and_saveexec_b64 s[0:1], vcc
	s_cbranch_execz .LBB0_594
	v_add_u32_e32 v10, 0x400, v0
	v_ashrrev_i32_e32 v6, 31, v10
	v_lshrrev_b32_e32 v6, 28, v6
	v_add_u32_e32 v11, v10, v6
	v_ashrrev_i32_e32 v12, 4, v11
	v_add_u32_e32 v6, s4, v12
	v_ashrrev_i32_e32 v7, 31, v6
	v_lshlrev_b64 v[6:7], 10, v[6:7]
	v_lshl_add_u64 v[8:9], v[4:5], 0, v[6:7]
	v_and_b32_e32 v4, -16, v11
	v_sub_u32_e32 v10, v10, v4
	v_mul_lo_u32 v4, v12, s23
	v_lshl_add_u32 v4, v10, 4, v4
	ds_read_b128 v[4:7], v4
	s_lshl_b32 s94, s5, 8
	v_lshlrev_b32_e32 v10, 3, v10
	v_lshl_add_u64 v[8:9], v[8:9], 0, s[94:95]
	v_ashrrev_i32_e32 v11, 31, v10
	v_lshl_add_u64 v[8:9], v[10:11], 1, v[8:9]
	s_waitcnt lgkmcnt(0)
	global_store_dwordx4 v[8:9], v[4:7], off sc1
	s_nop 1
	v_mov_b64_e32 v[4:5], s[40:41]
	s_load_dwordx2 s[100:101], s[40:41], 0x150
	s_waitcnt lgkmcnt(0)
	v_mov_b32_e32 v6, s100
	v_mov_b32_e32 v7, s101
.LBB0_594:
	s_or_b64 exec, exec, s[0:1]
	s_waitcnt lgkmcnt(0)
	v_cmp_ne_u64_e32 vcc, 0, v[6:7]
	s_and_saveexec_b64 s[0:1], vcc
	s_cbranch_execz .LBB0_596
	v_add_u32_e32 v4, 0x500, v0
	v_ashrrev_i32_e32 v2, 31, v4
	v_lshrrev_b32_e32 v2, 28, v2
	v_add_u32_e32 v5, v4, v2
	v_ashrrev_i32_e32 v8, 4, v5
	v_add_u32_e32 v2, s4, v8
	v_ashrrev_i32_e32 v3, 31, v2
	v_lshlrev_b64 v[2:3], 10, v[2:3]
	v_lshl_add_u64 v[6:7], v[6:7], 0, v[2:3]
	v_and_b32_e32 v2, -16, v5
	v_sub_u32_e32 v9, v4, v2
	v_mul_lo_u32 v2, v8, s23
	v_lshl_add_u32 v2, v9, 4, v2
	ds_read_b128 v[2:5], v2
	s_lshl_b32 s94, s5, 8
	v_lshlrev_b32_e32 v8, 3, v9
	v_lshl_add_u64 v[6:7], v[6:7], 0, s[94:95]
	v_ashrrev_i32_e32 v9, 31, v8
	v_lshl_add_u64 v[6:7], v[8:9], 1, v[6:7]
	s_waitcnt lgkmcnt(0)
	global_store_dwordx4 v[6:7], v[2:5], off sc1
	s_nop 1
	v_mov_b64_e32 v[2:3], s[40:41]
	s_load_dwordx2 s[100:101], s[40:41], 0x150
	s_waitcnt lgkmcnt(0)
	v_mov_b32_e32 v2, s100
	v_mov_b32_e32 v3, s101
.LBB0_596:
	s_or_b64 exec, exec, s[0:1]
	v_mov_b64_e32 v[4:5], 0
	s_waitcnt lgkmcnt(0)
	v_cmp_ne_u64_e32 vcc, 0, v[2:3]
	s_and_saveexec_b64 s[0:1], vcc
	s_cbranch_execz .LBB0_598
	v_add_u32_e32 v8, 0x600, v0
	v_ashrrev_i32_e32 v4, 31, v8
	v_lshrrev_b32_e32 v4, 28, v4
	v_add_u32_e32 v9, v8, v4
	v_ashrrev_i32_e32 v10, 4, v9
	v_add_u32_e32 v4, s4, v10
	v_ashrrev_i32_e32 v5, 31, v4
	v_lshlrev_b64 v[4:5], 10, v[4:5]
	v_lshl_add_u64 v[6:7], v[2:3], 0, v[4:5]
	v_and_b32_e32 v2, -16, v9
	v_sub_u32_e32 v8, v8, v2
	v_mul_lo_u32 v2, v10, s23
	v_lshl_add_u32 v2, v8, 4, v2
	ds_read_b128 v[2:5], v2
	s_lshl_b32 s94, s5, 8
	v_lshlrev_b32_e32 v8, 3, v8
	v_lshl_add_u64 v[6:7], v[6:7], 0, s[94:95]
	v_ashrrev_i32_e32 v9, 31, v8
	v_lshl_add_u64 v[6:7], v[8:9], 1, v[6:7]
	s_waitcnt lgkmcnt(0)
	global_store_dwordx4 v[6:7], v[2:5], off sc1
	s_nop 1
	v_mov_b64_e32 v[2:3], s[40:41]
	s_load_dwordx2 s[100:101], s[40:41], 0x150
	s_waitcnt lgkmcnt(0)
	v_mov_b32_e32 v4, s100
	v_mov_b32_e32 v5, s101
.LBB0_598:
	s_or_b64 exec, exec, s[0:1]
	s_waitcnt lgkmcnt(0)
	v_cmp_ne_u64_e32 vcc, 0, v[4:5]
	s_and_saveexec_b64 s[0:1], vcc
	s_cbranch_execz .LBB0_571
	v_add_u32_e32 v0, 0x700, v0
	v_ashrrev_i32_e32 v2, 31, v0
	v_lshrrev_b32_e32 v2, 28, v2
	v_add_u32_e32 v8, v0, v2
	v_ashrrev_i32_e32 v9, 4, v8
	v_add_u32_e32 v2, s4, v9
	v_ashrrev_i32_e32 v3, 31, v2
	v_lshlrev_b64 v[2:3], 10, v[2:3]
	v_lshl_add_u64 v[6:7], v[4:5], 0, v[2:3]
	v_and_b32_e32 v2, -16, v8
	v_sub_u32_e32 v0, v0, v2
	v_mul_lo_u32 v2, v9, s23
	v_lshl_add_u32 v2, v0, 4, v2
	ds_read_b128 v[2:5], v2
	s_lshl_b32 s94, s5, 8
	v_lshlrev_b32_e32 v8, 3, v0
	v_lshl_add_u64 v[6:7], v[6:7], 0, s[94:95]
	v_ashrrev_i32_e32 v9, 31, v8
	v_lshl_add_u64 v[6:7], v[8:9], 1, v[6:7]
	s_waitcnt lgkmcnt(0)
	global_store_dwordx4 v[6:7], v[2:5], off sc1
	s_branch .LBB0_571

; __device__ __forceinline__ void phase_mix_a(const Params& p, int l, bool last, unsigned char* smem) {
;     ...
;       gemm_tile<2, true>(p.Wsgu + (size_t)(l * 4 + h) * 16384, 128, nullptr, 128, p.PX + (size_t)row_base * 1024 + 256 + h * 64, 1024, 128, smem, epi, rsv);
.LBB0_602:
	s_or_b64 exec, exec, s[0:1]
	s_and_b32 s1, s9, 3
	s_or_b32 s34, s1, s18
	s_lshl_b32 s94, s34, 7
	v_lshl_add_u64 v[60:61], s[94:95], 2, v[6:7]
	s_waitcnt lgkmcnt(0)
	v_lshl_add_u64 v[2:3], s[4:5], 2, v[8:9]
	s_lshl_b32 s94, s1, 8
	v_mov_b64_e32 v[58:59], s[40:41]
	v_lshl_add_u64 v[62:63], v[2:3], 0, s[94:95]
	global_load_dwordx2 v[2:3], v[58:59], off offset:240
	global_load_dwordx2 v[4:5], v[58:59], off offset:288
	v_mov_b32_e32 v46, v187
	s_ashr_i32 s39, s38, 31
	v_ashrrev_i32_e32 v10, 31, v46
	v_lshrrev_b32_e32 v10, 29, v10
	v_add_u32_e32 v12, v46, v10
	v_ashrrev_i32_e32 v44, 3, v12
	s_lshl_b32 s94, s34, 15
	s_lshl_b64 s[34:35], s[38:39], 11
	v_ashrrev_i32_e32 v45, 31, v44
	v_and_b32_e32 v12, -8, v12
	v_lshlrev_b64 v[10:11], 11, v[44:45]
	v_sub_u32_e32 v45, v46, v12
	v_lshlrev_b32_e32 v42, 3, v45
	v_ashrrev_i32_e32 v43, 31, v42
	v_add_u32_e32 v12, 0x100, v46
	v_lshlrev_b32_e32 v0, 3, v46
	v_and_b32_e32 v20, 56, v0
	v_lshlrev_b32_e32 v0, 1, v20
	s_waitcnt lgkmcnt(0)
	s_barrier
	s_lshl_b32 s0, s1, 6
	v_lshlrev_b32_e32 v67, 2, v20
	v_lshrrev_b32_e32 v47, 4, v46
	v_bfe_u32 v106, v46, 1, 3
	v_bfe_u32 v64, v46, 6, 1
	v_ashrrev_i32_e32 v65, 7, v46
	v_bfe_u32 v66, v46, 4, 2
	s_add_i32 s9, s9, s3
	s_waitcnt vmcnt(0)
	v_lshl_add_u64 v[2:3], v[2:3], 0, s[94:95]
	v_lshl_add_u64 v[4:5], v[4:5], 0, s[34:35]
	s_lshl_b32 s94, s1, 7
	v_lshl_add_u64 v[8:9], v[4:5], 0, s[94:95]
	v_lshl_add_u64 v[10:11], v[8:9], 0, v[10:11]
	v_lshl_add_u64 v[34:35], v[42:43], 1, v[10:11]
	v_ashrrev_i32_e32 v10, 31, v12
	v_lshrrev_b32_e32 v10, 29, v10
	v_add_u32_e32 v13, v12, v10
	v_ashrrev_i32_e32 v40, 3, v13
	v_ashrrev_i32_e32 v41, 31, v40
	v_lshlrev_b64 v[10:11], 11, v[40:41]
	v_ashrrev_i32_e32 v4, 3, v46
	v_lshl_add_u64 v[8:9], v[8:9], 0, v[10:11]
	v_and_b32_e32 v10, -8, v13
	v_ashrrev_i32_e32 v5, 31, v4
	v_sub_u32_e32 v41, v12, v10
	v_lshl_add_u64 v[2:3], v[2:3], 0, v[0:1]
	v_lshlrev_b64 v[4:5], 8, v[4:5]
	v_lshlrev_b32_e32 v38, 3, v41
	v_lshl_add_u64 v[2:3], v[2:3], 0, v[4:5]
	v_ashrrev_i32_e32 v39, 31, v38
	v_lshl_add_u64 v[36:37], v[38:39], 1, v[8:9]
	v_add_co_u32_e32 v8, vcc, s70, v2
	global_load_dwordx4 v[22:25], v[2:3], off
	s_nop 0
	v_addc_co_u32_e32 v9, vcc, 0, v3, vcc
	global_load_dwordx4 v[26:29], v[8:9], off
	v_add_co_u32_e32 v8, vcc, s69, v2
	s_movk_i32 s1, 0x6000
	s_nop 0
	v_addc_co_u32_e32 v9, vcc, 0, v3, vcc
	global_load_dwordx4 v[30:33], v[8:9], off
	s_mov_b64 s[34:35], 0x2000
	v_add_co_u32_e32 v8, vcc, s1, v2
	v_lshl_add_u64 v[4:5], v[2:3], 0, s[34:35]
	v_lshl_add_u64 v[6:7], v[2:3], 0, s[62:63]
	v_addc_co_u32_e32 v9, vcc, 0, v3, vcc
	v_lshl_add_u64 v[18:19], v[2:3], 0, s[24:25]
	global_load_dwordx4 v[48:51], v[8:9], off
	global_load_dwordx4 v[14:17], v[2:3], off offset:128
	global_load_dwordx4 v[10:13], v[4:5], off offset:128
	s_nop 0
	global_load_dwordx4 v[6:9], v[6:7], off offset:128
	s_nop 0
	global_load_dwordx4 v[2:5], v[18:19], off offset:128
	v_or_b32_e32 v18, 0x10200, v67
	ds_read_b128 v[52:55], v18
	v_or_b32_e32 v39, 0x10210, v67
	v_lshlrev_b32_e32 v43, 4, v46
	v_and_b32_e32 v43, 0xffffff80, v43
	v_and_b32_e32 v0, 15, v46
	s_waitcnt vmcnt(0) lgkmcnt(0)
	v_lshlrev_b32_e32 v18, 16, v22
	v_and_b32_e32 v19, 0xffff0000, v22
	v_pk_mul_f32 v[18:19], v[52:53], v[18:19]
	v_lshlrev_b32_e32 v20, 16, v26
	v_and_b32_e32 v21, 0xffff0000, v26
	v_pk_mul_f32 v[20:21], v[52:53], v[20:21]
	v_cvt_pk_bf16_f32 v18, v18, v19
	v_cvt_pk_bf16_f32 v22, v20, v21
	v_lshlrev_b32_e32 v20, 16, v30
	v_and_b32_e32 v21, 0xffff0000, v30
	v_pk_mul_f32 v[20:21], v[52:53], v[20:21]
	s_nop 0
	v_cvt_pk_bf16_f32 v26, v20, v21
	v_lshlrev_b32_e32 v20, 16, v48
	v_and_b32_e32 v21, 0xffff0000, v48
	v_pk_mul_f32 v[20:21], v[52:53], v[20:21]
	v_lshlrev_b32_e32 v48, 16, v28
	v_cvt_pk_bf16_f32 v30, v20, v21
	v_lshlrev_b32_e32 v20, 16, v23
	v_and_b32_e32 v21, 0xffff0000, v23
	v_pk_mul_f32 v[20:21], v[54:55], v[20:21]
	s_nop 0
	v_cvt_pk_bf16_f32 v19, v20, v21
	v_lshlrev_b32_e32 v20, 16, v27
	v_and_b32_e32 v21, 0xffff0000, v27
	v_pk_mul_f32 v[20:21], v[54:55], v[20:21]
	s_nop 0
	v_cvt_pk_bf16_f32 v23, v20, v21
	v_lshlrev_b32_e32 v20, 16, v31
	v_and_b32_e32 v21, 0xffff0000, v31
	v_pk_mul_f32 v[20:21], v[54:55], v[20:21]
	s_nop 0
	v_cvt_pk_bf16_f32 v27, v20, v21
	v_lshlrev_b32_e32 v20, 16, v49
	v_and_b32_e32 v21, 0xffff0000, v49
	v_pk_mul_f32 v[20:21], v[54:55], v[20:21]
	ds_read_b128 v[52:55], v39
	v_and_b32_e32 v49, 0xffff0000, v28
	v_cvt_pk_bf16_f32 v31, v20, v21
	v_lshlrev_b32_e32 v20, 16, v24
	v_and_b32_e32 v21, 0xffff0000, v24
	s_waitcnt lgkmcnt(0)
	v_pk_mul_f32 v[48:49], v[52:53], v[48:49]
	v_pk_mul_f32 v[20:21], v[52:53], v[20:21]
	v_cvt_pk_bf16_f32 v24, v48, v49
	v_lshlrev_b32_e32 v48, 16, v32
	v_and_b32_e32 v49, 0xffff0000, v32
	v_pk_mul_f32 v[48:49], v[52:53], v[48:49]
	v_cvt_pk_bf16_f32 v20, v20, v21
	v_cvt_pk_bf16_f32 v28, v48, v49
	v_lshlrev_b32_e32 v48, 16, v50
	v_and_b32_e32 v49, 0xffff0000, v50
	v_pk_mul_f32 v[48:49], v[52:53], v[48:49]
	v_xor_b32_e32 v39, v47, v46
	v_cvt_pk_bf16_f32 v32, v48, v49
	v_lshlrev_b32_e32 v48, 16, v25
	v_and_b32_e32 v49, 0xffff0000, v25
	v_pk_mul_f32 v[48:49], v[54:55], v[48:49]
	v_lshlrev_b32_e32 v39, 4, v39
	v_cvt_pk_bf16_f32 v21, v48, v49
	v_lshlrev_b32_e32 v48, 16, v29
	v_and_b32_e32 v49, 0xffff0000, v29
	v_pk_mul_f32 v[48:49], v[54:55], v[48:49]
	v_and_or_b32 v68, v39, s14, v43
	v_cvt_pk_bf16_f32 v25, v48, v49
	v_lshlrev_b32_e32 v48, 16, v33
	v_and_b32_e32 v49, 0xffff0000, v33
	v_pk_mul_f32 v[48:49], v[54:55], v[48:49]
	v_lshlrev_b32_e32 v43, 7, v0
	v_cvt_pk_bf16_f32 v29, v48, v49
	v_lshlrev_b32_e32 v48, 16, v51
	v_and_b32_e32 v49, 0xffff0000, v51
	v_pk_mul_f32 v[48:49], v[54:55], v[48:49]
	v_lshl_or_b32 v107, v65, 13, v43
	v_cvt_pk_bf16_f32 v33, v48, v49
	ds_write_b128 v68, v[18:21]
	ds_write_b128 v68, v[22:25] offset:4096
	ds_write_b128 v68, v[26:29] offset:8192
	ds_write_b128 v68, v[30:33] offset:12288
	v_and_b32_e32 v22, -8, v44
	v_lshlrev_b32_e32 v18, 5, v45
	v_lshlrev_b32_e32 v24, 9, v45
	v_bitop3_b32 v25, v18, v22, 32 bitop3:0x6c
	v_and_b32_e32 v23, 7, v44
	v_add_u32_e32 v18, v25, v24
	v_or_b32_e32 v18, v18, v23
	v_lshlrev_b32_e32 v69, 1, v18
	global_load_dwordx4 v[18:21], v[34:35], off offset:512
	v_or_b32_e32 v24, v23, v24
	v_add_lshl_u32 v70, v24, v25, 1
	v_bitop3_b32 v26, v47, v106, 3 bitop3:0x6c
	v_lshl_or_b32 v110, v64, 12, v43
	v_lshlrev_b32_e32 v0, 2, v0
	v_lshl_or_b32 v0, v64, 7, v0
	s_waitcnt vmcnt(0) lgkmcnt(0)
	ds_write_b16 v69, v18 offset:16384
	ds_write_b16_d16_hi v70, v18 offset:16512
	v_or_b32_e32 v18, 2, v42
	v_lshlrev_b32_e32 v24, 6, v18
	v_lshlrev_b32_e32 v18, 2, v18
	v_and_b32_e32 v18, 40, v18
	v_xad_u32 v18, v18, v22, v24
	v_or_b32_e32 v18, v18, v23
	v_lshlrev_b32_e32 v71, 1, v18
	v_or_b32_e32 v18, 3, v42
	v_lshlrev_b32_e32 v24, 6, v18
	v_lshlrev_b32_e32 v18, 2, v18
	v_and_b32_e32 v18, 40, v18
	v_xad_u32 v18, v18, v22, v24
	v_or_b32_e32 v18, v18, v23
	v_lshlrev_b32_e32 v72, 1, v18
	v_or_b32_e32 v18, 4, v42
	ds_write_b16 v71, v19 offset:16384
	ds_write_b16_d16_hi v72, v19 offset:16384
	v_lshlrev_b32_e32 v19, 6, v18
	v_lshlrev_b32_e32 v18, 2, v18
	v_and_b32_e32 v18, 48, v18
	v_xad_u32 v18, v18, v22, v19
	v_or_b32_e32 v18, v18, v23
	v_lshlrev_b32_e32 v73, 1, v18
	v_or_b32_e32 v18, 5, v42
	v_lshlrev_b32_e32 v19, 6, v18
	v_lshlrev_b32_e32 v18, 2, v18
	v_and_b32_e32 v18, 48, v18
	v_xad_u32 v18, v18, v22, v19
	v_or_b32_e32 v18, v18, v23
	v_lshlrev_b32_e32 v74, 1, v18
	v_or_b32_e32 v18, 6, v42
	v_lshlrev_b32_e32 v19, 6, v18
	v_lshlrev_b32_e32 v18, 2, v18
	v_and_b32_e32 v18, 56, v18
	v_xad_u32 v18, v18, v22, v19
	v_or_b32_e32 v18, v18, v23
	v_lshlrev_b32_e32 v75, 1, v18
	v_or_b32_e32 v18, 7, v42
	v_lshlrev_b32_e32 v19, 6, v18
	v_lshlrev_b32_e32 v18, 2, v18
	v_and_b32_e32 v18, 56, v18
	v_xad_u32 v18, v18, v22, v19
	v_or_b32_e32 v18, v18, v23
	v_lshlrev_b32_e32 v76, 1, v18
	v_and_b32_e32 v22, -8, v40
	v_lshlrev_b32_e32 v18, 5, v41
	v_lshlrev_b32_e32 v24, 9, v41
	v_bitop3_b32 v25, v18, v22, 32 bitop3:0x6c
	v_and_b32_e32 v23, 7, v40
	v_add_u32_e32 v18, v25, v24
	v_or_b32_e32 v18, v18, v23
	ds_write_b16 v73, v20 offset:16384
	ds_write_b16_d16_hi v74, v20 offset:16384
	ds_write_b16 v75, v21 offset:16384
	ds_write_b16_d16_hi v76, v21 offset:16384
	v_lshlrev_b32_e32 v77, 1, v18
	global_load_dwordx4 v[18:21], v[36:37], off offset:512
	v_or_b32_e32 v24, v23, v24
	v_add_lshl_u32 v78, v24, v25, 1
	v_lshlrev_b32_e32 v42, 4, v26
	v_or_b32_e32 v121, v42, v107
	v_or_b32_e32 v122, v42, v110
	s_waitcnt vmcnt(0) lgkmcnt(0)
	ds_write_b16 v77, v18 offset:16384
	ds_write_b16_d16_hi v78, v18 offset:16512
	v_or_b32_e32 v18, 2, v38
	v_lshlrev_b32_e32 v24, 6, v18
	v_lshlrev_b32_e32 v18, 2, v18
	v_and_b32_e32 v18, 40, v18
	v_xad_u32 v18, v18, v22, v24
	v_or_b32_e32 v18, v18, v23
	v_lshlrev_b32_e32 v79, 1, v18
	v_or_b32_e32 v18, 3, v38
	v_lshlrev_b32_e32 v24, 6, v18
	v_lshlrev_b32_e32 v18, 2, v18
	v_and_b32_e32 v18, 40, v18
	v_xad_u32 v18, v18, v22, v24
	v_or_b32_e32 v18, v18, v23
	v_lshlrev_b32_e32 v80, 1, v18
	v_or_b32_e32 v18, 4, v38
	ds_write_b16 v79, v19 offset:16384
	ds_write_b16_d16_hi v80, v19 offset:16384
	v_lshlrev_b32_e32 v19, 6, v18
	v_lshlrev_b32_e32 v18, 2, v18
	v_and_b32_e32 v18, 48, v18
	v_xad_u32 v18, v18, v22, v19
	v_or_b32_e32 v18, v18, v23
	v_lshlrev_b32_e32 v81, 1, v18
	v_or_b32_e32 v18, 5, v38
	v_lshlrev_b32_e32 v19, 6, v18
	v_lshlrev_b32_e32 v18, 2, v18
	v_and_b32_e32 v18, 48, v18
	v_xad_u32 v18, v18, v22, v19
	v_or_b32_e32 v18, v18, v23
	v_lshlrev_b32_e32 v118, 1, v18
	v_or_b32_e32 v18, 6, v38
	v_lshlrev_b32_e32 v19, 6, v18
	v_lshlrev_b32_e32 v18, 2, v18
	v_and_b32_e32 v18, 56, v18
	v_xad_u32 v18, v18, v22, v19
	v_or_b32_e32 v18, v18, v23
	v_lshlrev_b32_e32 v119, 1, v18
	v_or_b32_e32 v18, 7, v38
	v_lshlrev_b32_e32 v19, 6, v18
	v_lshlrev_b32_e32 v18, 2, v18
	v_and_b32_e32 v18, 56, v18
	v_xad_u32 v18, v18, v22, v19
	v_or_b32_e32 v18, v18, v23
	v_lshlrev_b32_e32 v120, 1, v18
	v_add_co_u32_e32 v18, vcc, s16, v34
	ds_write_b16 v81, v20 offset:16384
	s_nop 0
	v_addc_co_u32_e32 v19, vcc, 0, v35, vcc
	ds_write_b16_d16_hi v118, v20 offset:16384
	ds_write_b16 v119, v21 offset:16384
	ds_write_b16_d16_hi v120, v21 offset:16384
	global_load_dwordx4 v[18:21], v[18:19], off offset:512
	v_add_co_u32_e32 v22, vcc, s16, v36
	s_nop 1
	v_addc_co_u32_e32 v23, vcc, 0, v37, vcc
	global_load_dwordx4 v[22:25], v[22:23], off offset:512
	s_waitcnt lgkmcnt(0)
	s_barrier
	ds_read_b128 v[26:29], v121
	ds_read_b128 v[30:33], v121 offset:2048
	ds_read_b128 v[34:37], v121 offset:4096
	ds_read_b128 v[38:41], v121 offset:6144
	ds_read_b128 v[42:45], v122 offset:16384
	ds_read_b128 v[46:49], v122 offset:18432
	s_waitcnt lgkmcnt(0)
	v_mfma_f32_16x16x32_bf16 v[50:53], v[26:29], v[42:45], 0
	v_mfma_f32_16x16x32_bf16 v[54:57], v[26:29], v[46:49], 0
	v_bitop3_b32 v26, v66, v106, 4 bitop3:0x36
	v_lshlrev_b32_e32 v26, 4, v26
	v_or_b32_e32 v123, v26, v107
	v_or_b32_e32 v124, v26, v110
	v_mfma_f32_16x16x32_bf16 v[82:85], v[30:33], v[42:45], 0
	v_mfma_f32_16x16x32_bf16 v[86:89], v[30:33], v[46:49], 0
	v_mfma_f32_16x16x32_bf16 v[94:97], v[34:37], v[46:49], 0
	v_mfma_f32_16x16x32_bf16 v[98:101], v[38:41], v[42:45], 0
	v_mfma_f32_16x16x32_bf16 v[102:105], v[38:41], v[46:49], 0
	ds_read_b128 v[30:33], v123
	ds_read_b128 v[38:41], v123 offset:2048
	ds_read_b128 v[46:49], v123 offset:4096
	ds_read_b128 v[106:109], v123 offset:6144
	ds_read_b128 v[110:113], v124 offset:16384
	ds_read_b128 v[114:117], v124 offset:18432
	v_mfma_f32_16x16x32_bf16 v[90:93], v[34:37], v[42:45], 0
	s_waitcnt lgkmcnt(0)
	v_mfma_f32_16x16x32_bf16 v[34:37], v[38:41], v[110:113], v[82:85]
	s_nop 2
	v_or_b32_e32 v82, 0x10300, v67
	ds_read_b128 v[82:85], v82
	v_mfma_f32_16x16x32_bf16 v[38:41], v[38:41], v[114:117], v[86:89]
	v_or_b32_e32 v67, 0x10310, v67
	s_nop 1
	v_lshlrev_b32_e32 v86, 16, v14
	v_and_b32_e32 v87, 0xffff0000, v14
	s_waitcnt lgkmcnt(0)
; template <int NT, bool BKN, bool MASK = false, bool ROWSS = false, class Epi> ...
;     ...
;   GEMM_COMPUTE(0);
;   GEMM_STORE(ra1, rb1, 1);
;   __syncthreads();
;   GEMM_COMPUTE(1);
	v_pk_mul_f32 v[86:87], v[82:83], v[86:87]
	v_mfma_f32_16x16x32_bf16 v[26:29], v[30:33], v[110:113], v[50:53]
	v_cvt_pk_bf16_f32 v14, v86, v87
	v_lshlrev_b32_e32 v86, 16, v10
	v_and_b32_e32 v87, 0xffff0000, v10
	v_pk_mul_f32 v[86:87], v[82:83], v[86:87]
	v_mfma_f32_16x16x32_bf16 v[30:33], v[30:33], v[114:117], v[54:57]
	v_cvt_pk_bf16_f32 v10, v86, v87
	v_lshlrev_b32_e32 v86, 16, v6
	v_and_b32_e32 v87, 0xffff0000, v6
	v_pk_mul_f32 v[86:87], v[82:83], v[86:87]
	v_mfma_f32_16x16x32_bf16 v[42:45], v[46:49], v[110:113], v[90:93]
	v_cvt_pk_bf16_f32 v6, v86, v87
	v_lshlrev_b32_e32 v86, 16, v2
	v_and_b32_e32 v87, 0xffff0000, v2
	v_pk_mul_f32 v[82:83], v[82:83], v[86:87]
	v_lshlrev_b32_e32 v86, 16, v16
	v_cvt_pk_bf16_f32 v2, v82, v83
	v_lshlrev_b32_e32 v82, 16, v15
	v_and_b32_e32 v83, 0xffff0000, v15
	v_pk_mul_f32 v[82:83], v[84:85], v[82:83]
	v_and_b32_e32 v87, 0xffff0000, v16
	v_cvt_pk_bf16_f32 v15, v82, v83
	v_lshlrev_b32_e32 v82, 16, v11
	v_and_b32_e32 v83, 0xffff0000, v11
	v_pk_mul_f32 v[82:83], v[84:85], v[82:83]
	v_mfma_f32_16x16x32_bf16 v[46:49], v[46:49], v[114:117], v[94:97]
	v_cvt_pk_bf16_f32 v11, v82, v83
	v_lshlrev_b32_e32 v82, 16, v7
	v_and_b32_e32 v83, 0xffff0000, v7
	v_pk_mul_f32 v[82:83], v[84:85], v[82:83]
	v_mfma_f32_16x16x32_bf16 v[50:53], v[106:109], v[110:113], v[98:101]
	v_cvt_pk_bf16_f32 v7, v82, v83
	v_lshlrev_b32_e32 v82, 16, v3
	v_and_b32_e32 v83, 0xffff0000, v3
	v_pk_mul_f32 v[82:83], v[84:85], v[82:83]
	v_mfma_f32_16x16x32_bf16 v[54:57], v[106:109], v[114:117], v[102:105]
	v_cvt_pk_bf16_f32 v3, v82, v83
	ds_read_b128 v[82:85], v67
	s_waitcnt lgkmcnt(0)
	v_pk_mul_f32 v[86:87], v[82:83], v[86:87]
	s_nop 0
	v_cvt_pk_bf16_f32 v16, v86, v87
	v_lshlrev_b32_e32 v86, 16, v12
	v_and_b32_e32 v87, 0xffff0000, v12
	v_pk_mul_f32 v[86:87], v[82:83], v[86:87]
	s_nop 0
	v_cvt_pk_bf16_f32 v12, v86, v87
	v_lshlrev_b32_e32 v86, 16, v8
	v_and_b32_e32 v87, 0xffff0000, v8
	v_pk_mul_f32 v[86:87], v[82:83], v[86:87]
	s_nop 0
	v_cvt_pk_bf16_f32 v8, v86, v87
	v_lshlrev_b32_e32 v86, 16, v4
	v_and_b32_e32 v87, 0xffff0000, v4
	v_pk_mul_f32 v[82:83], v[82:83], v[86:87]
	s_nop 0
	v_cvt_pk_bf16_f32 v4, v82, v83
	v_lshlrev_b32_e32 v82, 16, v17
	v_and_b32_e32 v83, 0xffff0000, v17
	v_pk_mul_f32 v[82:83], v[84:85], v[82:83]
	s_nop 0
	v_cvt_pk_bf16_f32 v17, v82, v83
	v_lshlrev_b32_e32 v82, 16, v13
	v_and_b32_e32 v83, 0xffff0000, v13
	v_pk_mul_f32 v[82:83], v[84:85], v[82:83]
	s_nop 0
	v_cvt_pk_bf16_f32 v13, v82, v83
	v_lshlrev_b32_e32 v82, 16, v9
	v_and_b32_e32 v83, 0xffff0000, v9
	v_pk_mul_f32 v[82:83], v[84:85], v[82:83]
	s_nop 0
	v_cvt_pk_bf16_f32 v9, v82, v83
	v_lshlrev_b32_e32 v82, 16, v5
	v_and_b32_e32 v83, 0xffff0000, v5
	v_pk_mul_f32 v[82:83], v[84:85], v[82:83]
	s_nop 0
	v_cvt_pk_bf16_f32 v5, v82, v83
	ds_write_b128 v68, v[14:17] offset:32768
	ds_write_b128 v68, v[10:13] offset:36864
	ds_write_b128 v68, v[6:9] offset:40960
	ds_write_b128 v68, v[2:5] offset:45056
	s_waitcnt vmcnt(0)
	ds_write_b16 v69, v18 offset:49152
	ds_write_b16_d16_hi v70, v18 offset:49280
	ds_write_b16 v71, v19 offset:49152
	ds_write_b16_d16_hi v72, v19 offset:49152
	ds_write_b16 v73, v20 offset:49152
	ds_write_b16_d16_hi v74, v20 offset:49152
	ds_write_b16 v75, v21 offset:49152
	ds_write_b16_d16_hi v76, v21 offset:49152
	ds_write_b16 v77, v22 offset:49152
	ds_write_b16_d16_hi v78, v22 offset:49280
	ds_write_b16 v79, v23 offset:49152
	ds_write_b16_d16_hi v80, v23 offset:49152
	ds_write_b16 v81, v24 offset:49152
	ds_write_b16_d16_hi v118, v24 offset:49152
	ds_write_b16 v119, v25 offset:49152
	ds_write_b16_d16_hi v120, v25 offset:49152
	s_waitcnt lgkmcnt(0)
	s_barrier
	ds_read_b128 v[2:5], v121 offset:32768
	ds_read_b128 v[6:9], v121 offset:34816
	ds_read_b128 v[10:13], v121 offset:36864
	ds_read_b128 v[14:17], v121 offset:38912
	ds_read_b128 v[18:21], v122 offset:49152
	ds_read_b128 v[22:25], v122 offset:51200
	s_waitcnt lgkmcnt(1)
	v_mfma_f32_16x16x32_bf16 v[26:29], v[2:5], v[18:21], v[26:29]
	s_waitcnt lgkmcnt(0)
	v_mfma_f32_16x16x32_bf16 v[2:5], v[2:5], v[22:25], v[30:33]
	v_mfma_f32_16x16x32_bf16 v[30:33], v[6:9], v[18:21], v[34:37]
	v_mfma_f32_16x16x32_bf16 v[6:9], v[6:9], v[22:25], v[38:41]
	v_mfma_f32_16x16x32_bf16 v[34:37], v[10:13], v[18:21], v[42:45]
	v_mfma_f32_16x16x32_bf16 v[10:13], v[10:13], v[22:25], v[46:49]
	v_mfma_f32_16x16x32_bf16 v[18:21], v[14:17], v[18:21], v[50:53]
	v_mfma_f32_16x16x32_bf16 v[14:17], v[14:17], v[22:25], v[54:57]
	ds_read_b128 v[22:25], v123 offset:32768
	ds_read_b128 v[38:41], v123 offset:34816
	ds_read_b128 v[42:45], v123 offset:36864
	ds_read_b128 v[46:49], v123 offset:38912
	ds_read_b128 v[50:53], v124 offset:49152
	ds_read_b128 v[54:57], v124 offset:51200
	s_waitcnt lgkmcnt(1)
	v_mfma_f32_16x16x32_bf16 v[26:29], v[22:25], v[50:53], v[26:29]
	s_waitcnt lgkmcnt(0)
	v_mfma_f32_16x16x32_bf16 v[22:25], v[22:25], v[54:57], v[2:5]
	v_mfma_f32_16x16x32_bf16 v[2:5], v[46:49], v[54:57], v[14:17]
	s_nop 2
	v_lshlrev_b32_e32 v14, 6, v65
	v_mfma_f32_16x16x32_bf16 v[30:33], v[38:41], v[50:53], v[30:33]
	v_mfma_f32_16x16x32_bf16 v[38:41], v[38:41], v[54:57], v[6:9]
	v_mfma_f32_16x16x32_bf16 v[6:9], v[46:49], v[50:53], v[18:21]
	s_nop 2
	v_lshl_or_b32 v18, v66, 2, v14
	v_ashrrev_i32_e32 v19, 31, v18
	v_mov_b32_e32 v20, v187
	v_lshl_add_u64 v[14:15], v[62:63], 0, v[0:1]
	v_lshl_add_u64 v[16:17], v[18:19], 2, v[60:61]
	s_barrier
; __device__ __forceinline__ int tid_() { int t = threadIdx.x; asm volatile("" : "+v"(t)); return t; }
; __device__ __forceinline__ void phase_mix_a(const Params& p, int l, bool last, unsigned char* smem) {
;     ...
;       auto epi = [&](f32x4(&acc)[4][2], int r0, int c0) {
;         float* Ts = (float*)smem;
;         const int t2 = tid_();
;         __syncthreads();
; #pragma unroll
;         for (int mi = 0; mi < 4; ++mi)
; #pragma unroll
;           for (int ni = 0; ni < 2; ++ni)
; #pragma unroll
;             for (int j = 0; j < 4; ++j) {
;               const int pr = r0 + mi * 16 + j;
;               Ts[pr * 68 + c0 + ni * 16] = acc[mi][ni][j] * sgn[c0 + ni * 16] + bs[pr];
;             }
;         __syncthreads();
	global_load_dword v100, v[14:15], off
	global_load_dword v101, v[14:15], off offset:64
	global_load_dwordx4 v[104:107], v[16:17], off offset:0
	global_load_dwordx4 v[108:111], v[16:17], off offset:64
	global_load_dwordx4 v[112:115], v[16:17], off offset:128
	global_load_dwordx4 v[116:119], v[16:17], off offset:192
	s_waitcnt vmcnt(0)
	v_mov_b32_e32 v21, v100
	v_mov_b32_e32 v19, v104
	v_mfma_f32_16x16x32_bf16 v[34:37], v[42:45], v[50:53], v[34:37]
	s_waitcnt lgkmcnt(0)
	v_fmac_f32_e32 v19, v26, v21
	v_mfma_f32_16x16x32_bf16 v[10:13], v[42:45], v[54:57], v[10:13]
	v_mad_u64_u32 v[42:43], s[34:35], v18, s23, v[0:1]
	ds_write_b32 v42, v19
	v_mov_b32_e32 v19, v100
	v_mov_b32_e32 v21, v105
	v_or_b32_e32 v18, 1, v18
	s_waitcnt lgkmcnt(0)
	v_fmac_f32_e32 v21, v27, v19
	v_mad_u64_u32 v[18:19], s[34:35], v18, s23, v[0:1]
	ds_write_b32 v18, v21
	v_mov_b32_e32 v0, v100
	v_mov_b32_e32 v19, v106
	s_waitcnt lgkmcnt(0)
	v_fmac_f32_e32 v19, v28, v0
	ds_write_b32 v18, v19 offset:272
	v_mov_b32_e32 v0, v100
	v_mov_b32_e32 v19, v107
	s_waitcnt lgkmcnt(0)
	v_fmac_f32_e32 v19, v29, v0
	ds_write_b32 v18, v19 offset:544
	v_mov_b32_e32 v0, v101
	v_mov_b32_e32 v19, v104
	s_waitcnt lgkmcnt(0)
	v_fmac_f32_e32 v19, v22, v0
	ds_write_b32 v42, v19 offset:64
	v_mov_b32_e32 v0, v101
	v_mov_b32_e32 v19, v105
	s_waitcnt lgkmcnt(0)
	v_fmac_f32_e32 v19, v23, v0
	ds_write_b32 v18, v19 offset:64
	v_mov_b32_e32 v0, v101
	v_mov_b32_e32 v19, v106
	s_waitcnt lgkmcnt(0)
	v_fmac_f32_e32 v19, v24, v0
	ds_write_b32 v18, v19 offset:336
	v_mov_b32_e32 v0, v101
	v_mov_b32_e32 v19, v107
	s_waitcnt lgkmcnt(0)
	v_fmac_f32_e32 v19, v25, v0
	ds_write_b32 v18, v19 offset:608
	v_mov_b32_e32 v0, v100
	v_mov_b32_e32 v19, v108
	s_waitcnt lgkmcnt(0)
	v_fmac_f32_e32 v19, v30, v0
	ds_write_b32 v18, v19 offset:4080
	v_mov_b32_e32 v0, v100
	v_mov_b32_e32 v19, v109
	s_waitcnt lgkmcnt(0)
	v_fmac_f32_e32 v19, v31, v0
	ds_write_b32 v18, v19 offset:4352
	v_mov_b32_e32 v0, v100
	v_mov_b32_e32 v19, v110
	s_waitcnt lgkmcnt(0)
	v_fmac_f32_e32 v19, v32, v0
	ds_write_b32 v18, v19 offset:4624
	v_mov_b32_e32 v0, v100
	v_mov_b32_e32 v19, v111
	s_waitcnt lgkmcnt(0)
	v_fmac_f32_e32 v19, v33, v0
	ds_write_b32 v18, v19 offset:4896
	v_mov_b32_e32 v0, v101
	v_mov_b32_e32 v19, v108
	s_waitcnt lgkmcnt(0)
	v_fmac_f32_e32 v19, v38, v0
	ds_write_b32 v18, v19 offset:4144
	v_mov_b32_e32 v0, v101
	v_mov_b32_e32 v19, v109
	s_waitcnt lgkmcnt(0)
	v_fmac_f32_e32 v19, v39, v0
	ds_write_b32 v18, v19 offset:4416
	v_mov_b32_e32 v0, v101
	v_mov_b32_e32 v19, v110
	s_waitcnt lgkmcnt(0)
	v_fmac_f32_e32 v19, v40, v0
	ds_write_b32 v18, v19 offset:4688
	v_mov_b32_e32 v0, v101
	v_mov_b32_e32 v19, v111
	s_waitcnt lgkmcnt(0)
	v_fmac_f32_e32 v19, v41, v0
	ds_write_b32 v18, v19 offset:4960
	v_mov_b32_e32 v0, v100
	v_mov_b32_e32 v19, v112
	s_waitcnt lgkmcnt(0)
	v_fmac_f32_e32 v19, v34, v0
	ds_write_b32 v18, v19 offset:8432
	v_mov_b32_e32 v0, v100
	v_mov_b32_e32 v19, v113
	s_waitcnt lgkmcnt(0)
	v_fmac_f32_e32 v19, v35, v0
	ds_write_b32 v18, v19 offset:8704
	v_mov_b32_e32 v0, v100
	v_mov_b32_e32 v19, v114
	s_waitcnt lgkmcnt(0)
	v_fmac_f32_e32 v19, v36, v0
	ds_write_b32 v18, v19 offset:8976
	v_mov_b32_e32 v0, v100
	v_mov_b32_e32 v19, v115
	s_waitcnt lgkmcnt(0)
	v_fmac_f32_e32 v19, v37, v0
	ds_write_b32 v18, v19 offset:9248
	v_mov_b32_e32 v0, v101
	v_mov_b32_e32 v19, v112
	s_waitcnt lgkmcnt(0)
	v_fmac_f32_e32 v19, v10, v0
	ds_write_b32 v18, v19 offset:8496
	v_mov_b32_e32 v0, v101
	v_mov_b32_e32 v10, v113
	s_waitcnt lgkmcnt(0)
	v_fmac_f32_e32 v10, v11, v0
	ds_write_b32 v18, v10 offset:8768
	v_mov_b32_e32 v0, v101
	v_mov_b32_e32 v10, v114
	s_waitcnt lgkmcnt(0)
	v_fmac_f32_e32 v10, v12, v0
	ds_write_b32 v18, v10 offset:9040
	v_mov_b32_e32 v0, v101
	v_mov_b32_e32 v10, v115
	s_waitcnt lgkmcnt(0)
	v_fmac_f32_e32 v10, v13, v0
	ds_write_b32 v18, v10 offset:9312
	v_mov_b32_e32 v0, v100
	v_mov_b32_e32 v10, v116
	s_waitcnt lgkmcnt(0)
	v_fmac_f32_e32 v10, v6, v0
	ds_write_b32 v18, v10 offset:12784
	v_mov_b32_e32 v0, v100
	v_mov_b32_e32 v6, v117
	s_waitcnt lgkmcnt(0)
	v_fmac_f32_e32 v6, v7, v0
	ds_write_b32 v18, v6 offset:13056
	v_mov_b32_e32 v0, v100
	v_mov_b32_e32 v6, v118
	s_waitcnt lgkmcnt(0)
	v_fmac_f32_e32 v6, v8, v0
	ds_write_b32 v18, v6 offset:13328
	v_mov_b32_e32 v0, v100
	v_mov_b32_e32 v6, v119
	s_waitcnt lgkmcnt(0)
	v_fmac_f32_e32 v6, v9, v0
	ds_write_b32 v18, v6 offset:13600
	v_mov_b32_e32 v0, v101
	v_mov_b32_e32 v6, v116
	s_waitcnt lgkmcnt(0)
	v_fmac_f32_e32 v6, v2, v0
	ds_write_b32 v18, v6 offset:12848
	v_mov_b32_e32 v0, v101
	v_mov_b32_e32 v2, v117
	s_waitcnt lgkmcnt(0)
	v_fmac_f32_e32 v2, v3, v0
	ds_write_b32 v18, v2 offset:13120
	v_mov_b32_e32 v0, v101
	v_mov_b32_e32 v2, v118
	v_ashrrev_i32_e32 v3, 3, v20
	s_waitcnt lgkmcnt(0)
	v_fmac_f32_e32 v2, v4, v0
	ds_write_b32 v18, v2 offset:13392
	v_mov_b32_e32 v0, v101
	v_mov_b32_e32 v2, v119
	v_add_u32_e32 v4, s38, v3
	s_waitcnt lgkmcnt(0)
	v_fmac_f32_e32 v2, v5, v0
	v_ashrrev_i32_e32 v5, 31, v4
	ds_write_b32 v18, v2 offset:13664
	s_waitcnt lgkmcnt(0)
	s_barrier
; __device__ __forceinline__ float bf2f(u16 b) { return __uint_as_float(((unsigned)b) << 16); }
; __device__ __forceinline__ void phase_mix_a(const Params& p, int l, bool last, unsigned char* smem) {
;     ...
; #pragma unroll
;         for (int i = 0; i < 4; ++i) {
;           const int c = t2 + 256 * i, pr = c >> 3, ch = c & 7;
;           const size_t o = (size_t)(row_base + pr) * 1024 + h * 64 + ch * 8;
;           const u32x4 u = *(const u32x4*)(p.PX + o);
;           const float4 z0 = *(const float4*)(Ts + pr * 68 + ch * 8), z1 = *(const float4*)(Ts + pr * 68 + ch * 8 + 4);
;           u32x4 r;
;           r.x = pack2(bf2f((u16)(u.x & 0xffffu)) * z0.x, bf2f((u16)(u.x >> 16)) * z0.y);
;           r.y = pack2(bf2f((u16)(u.y & 0xffffu)) * z0.z, bf2f((u16)(u.y >> 16)) * z0.w);
;           r.z = pack2(bf2f((u16)(u.z & 0xffffu)) * z1.x, bf2f((u16)(u.z >> 16)) * z1.y);
;           r.w = pack2(bf2f((u16)(u.w & 0xffffu)) * z1.z, bf2f((u16)(u.w >> 16)) * z1.w);
;           *(u32x4*)(p.YM + o) = r;
;         }
	global_load_dwordx4 v[4:7], v[58:59], off offset:288
	v_lshlrev_b32_e32 v0, 3, v20
	v_and_b32_e32 v2, 56, v0
	v_lshlrev_b32_e32 v0, 2, v2
	v_lshrrev_b32_e32 v3, 3, v20
	v_add_u32_e32 v8, s38, v3
	v_lshlrev_b32_e32 v8, 10, v8
	v_or3_b32 v8, v8, s0, v2
	v_lshlrev_b32_e32 v22, 1, v8
	v_mov_b32_e32 v23, 0
	v_mad_u32_u24 v30, v3, s23, v0
	v_add_u32_e32 v3, 32, v3
	v_add_u32_e32 v8, s38, v3
	v_lshlrev_b32_e32 v8, 10, v8
	v_or3_b32 v8, v8, s0, v2
	v_lshlrev_b32_e32 v24, 1, v8
	v_mov_b32_e32 v25, 0
	v_mad_u32_u24 v31, v3, s23, v0
	v_add_u32_e32 v3, 32, v3
	v_add_u32_e32 v8, s38, v3
	v_lshlrev_b32_e32 v8, 10, v8
	v_or3_b32 v8, v8, s0, v2
	v_lshlrev_b32_e32 v26, 1, v8
	v_mov_b32_e32 v27, 0
	v_mad_u32_u24 v32, v3, s23, v0
	v_add_u32_e32 v3, 32, v3
	v_add_u32_e32 v8, s38, v3
	v_lshlrev_b32_e32 v8, 10, v8
	v_or3_b32 v8, v8, s0, v2
	v_lshlrev_b32_e32 v28, 1, v8
	v_mov_b32_e32 v29, 0
	v_mad_u32_u24 v33, v3, s23, v0
	ds_read_b128 v[60:63], v30
	ds_read_b128 v[64:67], v30 offset:16
	ds_read_b128 v[68:71], v31
	ds_read_b128 v[72:75], v31 offset:16
	ds_read_b128 v[76:79], v32
	ds_read_b128 v[80:83], v32 offset:16
	ds_read_b128 v[84:87], v33
	ds_read_b128 v[88:91], v33 offset:16
	s_waitcnt vmcnt(0)
	v_lshl_add_u64 v[10:11], v[4:5], 0, v[22:23]
	global_load_dwordx4 v[34:37], v[10:11], off
	v_lshl_add_u64 v[10:11], v[4:5], 0, v[24:25]
	global_load_dwordx4 v[38:41], v[10:11], off
	v_lshl_add_u64 v[10:11], v[4:5], 0, v[26:27]
	global_load_dwordx4 v[42:45], v[10:11], off
	v_lshl_add_u64 v[10:11], v[4:5], 0, v[28:29]
	global_load_dwordx4 v[46:49], v[10:11], off
	s_waitcnt vmcnt(3) lgkmcnt(6)
	v_and_b32_e32 v9, 0xffff0000, v34
	v_lshlrev_b32_e32 v8, 16, v34
	v_pk_mul_f32 v[8:9], v[60:61], v[8:9]
	s_nop 0
	v_cvt_pk_bf16_f32 v34, v8, v9
	v_and_b32_e32 v9, 0xffff0000, v35
	v_lshlrev_b32_e32 v8, 16, v35
	v_pk_mul_f32 v[8:9], v[62:63], v[8:9]
	s_nop 0
	v_cvt_pk_bf16_f32 v35, v8, v9
	v_and_b32_e32 v9, 0xffff0000, v36
	v_lshlrev_b32_e32 v8, 16, v36
	v_pk_mul_f32 v[8:9], v[64:65], v[8:9]
	s_nop 0
	v_cvt_pk_bf16_f32 v36, v8, v9
	v_and_b32_e32 v9, 0xffff0000, v37
	v_lshlrev_b32_e32 v8, 16, v37
	v_pk_mul_f32 v[8:9], v[66:67], v[8:9]
	s_nop 0
	v_cvt_pk_bf16_f32 v37, v8, v9
	v_lshl_add_u64 v[12:13], v[6:7], 0, v[22:23]
	global_store_dwordx4 v[12:13], v[34:37], off sc1
	s_waitcnt vmcnt(3) lgkmcnt(4)
	v_and_b32_e32 v9, 0xffff0000, v38
	v_lshlrev_b32_e32 v8, 16, v38
	v_pk_mul_f32 v[8:9], v[68:69], v[8:9]
	s_nop 0
	v_cvt_pk_bf16_f32 v38, v8, v9
	v_and_b32_e32 v9, 0xffff0000, v39
	v_lshlrev_b32_e32 v8, 16, v39
	v_pk_mul_f32 v[8:9], v[70:71], v[8:9]
	s_nop 0
	v_cvt_pk_bf16_f32 v39, v8, v9
	v_and_b32_e32 v9, 0xffff0000, v40
	v_lshlrev_b32_e32 v8, 16, v40
	v_pk_mul_f32 v[8:9], v[72:73], v[8:9]
	s_nop 0
	v_cvt_pk_bf16_f32 v40, v8, v9
	v_and_b32_e32 v9, 0xffff0000, v41
	v_lshlrev_b32_e32 v8, 16, v41
	v_pk_mul_f32 v[8:9], v[74:75], v[8:9]
	s_nop 0
	v_cvt_pk_bf16_f32 v41, v8, v9
	v_lshl_add_u64 v[12:13], v[6:7], 0, v[24:25]
	global_store_dwordx4 v[12:13], v[38:41], off sc1
	s_waitcnt vmcnt(3) lgkmcnt(2)
	v_and_b32_e32 v9, 0xffff0000, v42
	v_lshlrev_b32_e32 v8, 16, v42
	v_pk_mul_f32 v[8:9], v[76:77], v[8:9]
	s_nop 0
	v_cvt_pk_bf16_f32 v42, v8, v9
	v_and_b32_e32 v9, 0xffff0000, v43
	v_lshlrev_b32_e32 v8, 16, v43
	v_pk_mul_f32 v[8:9], v[78:79], v[8:9]
	s_nop 0
	v_cvt_pk_bf16_f32 v43, v8, v9
	v_and_b32_e32 v9, 0xffff0000, v44
	v_lshlrev_b32_e32 v8, 16, v44
	v_pk_mul_f32 v[8:9], v[80:81], v[8:9]
	s_nop 0
	v_cvt_pk_bf16_f32 v44, v8, v9
	v_and_b32_e32 v9, 0xffff0000, v45
	v_lshlrev_b32_e32 v8, 16, v45
	v_pk_mul_f32 v[8:9], v[82:83], v[8:9]
	s_nop 0
	v_cvt_pk_bf16_f32 v45, v8, v9
	v_lshl_add_u64 v[12:13], v[6:7], 0, v[26:27]
	global_store_dwordx4 v[12:13], v[42:45], off sc1
	s_waitcnt vmcnt(3) lgkmcnt(0)
	v_and_b32_e32 v9, 0xffff0000, v46
	v_lshlrev_b32_e32 v8, 16, v46
	v_pk_mul_f32 v[8:9], v[84:85], v[8:9]
	s_nop 0
	v_cvt_pk_bf16_f32 v46, v8, v9
	v_and_b32_e32 v9, 0xffff0000, v47
	v_lshlrev_b32_e32 v8, 16, v47
	v_pk_mul_f32 v[8:9], v[86:87], v[8:9]
	s_nop 0
	v_cvt_pk_bf16_f32 v47, v8, v9
	v_and_b32_e32 v9, 0xffff0000, v48
	v_lshlrev_b32_e32 v8, 16, v48
	v_pk_mul_f32 v[8:9], v[88:89], v[8:9]
	s_nop 0
	v_cvt_pk_bf16_f32 v48, v8, v9
	v_and_b32_e32 v9, 0xffff0000, v49
	v_lshlrev_b32_e32 v8, 16, v49
	v_pk_mul_f32 v[8:9], v[90:91], v[8:9]
	s_nop 0
	v_cvt_pk_bf16_f32 v49, v8, v9
	v_lshl_add_u64 v[12:13], v[6:7], 0, v[28:29]
	global_store_dwordx4 v[12:13], v[46:49], off sc1
	v_readlane_b32 s0, v254, 45
	s_add_i32 s19, s19, s0
	s_cmp_ge_i32 s9, s8
	s_cbranch_scc1 .LBB0_605

; __device__ __forceinline__ int tid_() { int t = threadIdx.x; asm volatile("" : "+v"(t)); return t; }
; template <int NT, bool BKN, bool MASK = false, bool ROWSS = false, class Epi> ...
;     ...
;   const int t = tid_(), lane = t & 63, wid = t >> 6, wr = wid >> 1, wc = wid & 1, l16 = lane & 15, quad = lane >> 4;
;   const u16* ap[4];
;   const u16* bp[NT];
;   unsigned amask = 0u;
; #pragma unroll
;   for (int i = 0; i < 4; ++i) {
;     const int row = (t >> 3) + 32 * i;
;     const bool v = MASK ? (row < mvalid) : true;
;     amask |= v ? (1u << i) : 0u;
;     int r = v ? row : 0;
;     if (arows) r = arows[r];
;     ap[i] = A + (size_t)r * lda + (t & 7) * 8;
;   }
; #pragma unroll
;   for (int i = 0; i < NT; ++i) {
;     if (!BKN) bp[i] = B + (size_t)((t >> 3) + 32 * i) * ldb + (t & 7) * 8;
;     else { const int c = t + 256 * i; bp[i] = B + (size_t)(c / CPR) * ldb + (c % CPR) * 8; }
;   }
;   const size_t bstep = BKN ? (size_t)64 * ldb : (size_t)64;
;   int nmi = 4;
;   if (MASK) { nmi = (mvalid - wr * 64 + 15) >> 4; nmi = nmi < 0 ? 0 : (nmi > 4 ? 4 : nmi); nmi = __builtin_amdgcn_readfirstlane(nmi); }
;   u32x4 ra0[4], rb0[NT], ra1[4], rb1[NT];
; __device__ __forceinline__ void phase_mix_a(const Params& p, int l, bool last, unsigned char* smem) {
;     ...
;       gemm_tile<4, true>(p.M1 + (size_t)n1 * 16384, 128, nullptr, 128, p.GD + (size_t)b * 2 * SEQ * 256 + (size_t)n1 * 256 + nh * 128, 128 * 256, 128, smem, epi);
.LBB0_608:
	v_mov_b64_e32 v[34:35], s[40:41]
	s_waitcnt vmcnt(0) lgkmcnt(0)
	global_load_dwordx2 v[2:3], v[34:35], off offset:248
	global_load_dwordx2 v[4:5], v[34:35], off offset:304
	v_mov_b32_e32 v46, v187
	s_ashr_i32 s4, s9, 8
	s_bfe_u32 s19, s9, 0x70001
	v_ashrrev_i32_e32 v9, 31, v46
	s_ashr_i32 s5, s4, 31
	v_lshrrev_b32_e32 v9, 28, v9
	s_lshl_b32 s94, s19, 15
	s_lshl_b64 s[34:35], s[4:5], 23
	v_ashrrev_i32_e32 v6, 3, v46
	v_lshlrev_b32_e32 v8, 4, v46
	v_add_u32_e32 v9, v46, v9
	s_and_b32 s0, s18, 0x80
	v_and_b32_e32 v0, 0x70, v8
	v_ashrrev_i32_e32 v7, 31, v6
	v_and_b32_e32 v17, 0xffffff80, v8
	v_ashrrev_i32_e32 v8, 4, v9
	s_mov_b32 s1, s95
	s_lshl_b32 s0, s0, 1
	v_add_u32_e32 v14, 0x100, v46
	v_lshlrev_b64 v[6:7], 8, v[6:7]
	v_and_b32_e32 v18, -16, v9
	v_ashrrev_i32_e32 v9, 31, v8
	v_lshrrev_b32_e32 v47, 4, v46
	v_add_u32_e32 v15, 0x200, v46
	v_ashrrev_i32_e32 v10, 31, v14
	v_and_b32_e32 v86, -8, v8
	v_and_b32_e32 v87, 7, v8
	v_lshlrev_b64 v[8:9], 16, v[8:9]
	v_add_u32_e32 v16, 0x300, v46
	v_ashrrev_i32_e32 v11, 31, v15
	v_xor_b32_e32 v13, v47, v46
	v_lshrrev_b32_e32 v10, 28, v10
	v_ashrrev_i32_e32 v12, 31, v16
	v_lshrrev_b32_e32 v11, 28, v11
	v_lshlrev_b32_e32 v13, 4, v13
	v_add_u32_e32 v10, v14, v10
	v_lshrrev_b32_e32 v12, 28, v12
	v_add_u32_e32 v11, v15, v11
	v_and_or_b32 v128, v13, s14, v17
	v_sub_u32_e32 v17, v46, v18
	v_ashrrev_i32_e32 v80, 4, v10
	v_and_b32_e32 v18, -16, v10
	v_add_u32_e32 v12, v16, v12
	v_ashrrev_i32_e32 v40, 4, v11
	v_and_b32_e32 v19, -16, v11
	s_movk_i32 s5, 0x6000
	v_ashrrev_i32_e32 v36, 4, v12
	v_and_b32_e32 v20, -16, v12
	v_lshlrev_b32_e32 v82, 3, v17
	v_ashrrev_i32_e32 v83, 31, v82
	v_ashrrev_i32_e32 v37, 31, v36
	s_waitcnt lgkmcnt(0)
	s_barrier
	v_ashrrev_i32_e32 v41, 31, v40
	v_sub_u32_e32 v88, v16, v20
	v_ashrrev_i32_e32 v81, 31, v80
	v_lshlrev_b32_e32 v38, 3, v88
	v_ashrrev_i32_e32 v39, 31, v38
	v_and_b32_e32 v44, 15, v46
	v_bfe_u32 v108, v46, 1, 3
	v_ashrrev_i32_e32 v45, 7, v46
	v_bfe_u32 v161, v46, 6, 1
	v_bfe_u32 v163, v46, 4, 2
	v_bitop3_b32 v46, v163, v108, 4 bitop3:0x36
	v_lshlrev_b32_e32 v46, 4, v46
	s_waitcnt vmcnt(0)
	v_lshl_add_u64 v[2:3], v[2:3], 0, s[94:95]
	v_lshl_add_u64 v[4:5], v[4:5], 0, s[34:35]
	s_lshl_b32 s94, s19, 9
	v_lshl_add_u64 v[4:5], v[4:5], 0, s[94:95]
	v_lshl_add_u64 v[2:3], v[2:3], 0, v[0:1]
	v_lshl_add_u64 v[4:5], v[4:5], 0, s[0:1]
	v_lshl_add_u64 v[2:3], v[2:3], 0, v[6:7]
	v_lshl_add_u64 v[6:7], v[4:5], 0, v[8:9]
	v_add_co_u32_e32 v8, vcc, s70, v2
	global_load_dwordx4 v[48:51], v[2:3], off
	s_nop 0
	v_addc_co_u32_e32 v9, vcc, 0, v3, vcc
	v_add_co_u32_e32 v10, vcc, s69, v2
	v_lshl_add_u64 v[6:7], v[82:83], 1, v[6:7]
	s_nop 0
	v_addc_co_u32_e32 v11, vcc, 0, v3, vcc
	v_add_co_u32_e32 v12, vcc, s5, v2
	v_sub_u32_e32 v0, v14, v18
	s_nop 0
	v_addc_co_u32_e32 v13, vcc, 0, v3, vcc
	global_load_dwordx4 v[52:55], v[8:9], off
	global_load_dwordx4 v[56:59], v[10:11], off
	global_load_dwordx4 v[60:63], v[12:13], off
	global_load_dwordx4 v[64:67], v[6:7], off
	v_lshlrev_b64 v[12:13], 16, v[36:37]
	v_or_b32_e32 v37, 4, v82
	v_sub_u32_e32 v83, v15, v19
	v_lshlrev_b32_e32 v14, 9, v17
	v_lshlrev_b32_e32 v15, 5, v17
	v_lshlrev_b64 v[10:11], 16, v[40:41]
	v_lshlrev_b32_e32 v41, 6, v37
	v_lshlrev_b32_e32 v37, 2, v37
	v_bitop3_b32 v15, v15, v86, 32 bitop3:0x6c
	v_or_b32_e32 v16, v87, v14
	v_or_b32_e32 v17, 2, v82
	v_or_b32_e32 v18, 3, v82
	v_and_b32_e32 v37, 48, v37
	v_add_u32_e32 v14, v15, v14
	v_add_lshl_u32 v129, v16, v15, 1
	v_lshlrev_b32_e32 v15, 6, v17
	v_lshlrev_b32_e32 v16, 2, v17
	v_lshlrev_b32_e32 v17, 6, v18
	v_lshlrev_b32_e32 v18, 2, v18
	v_xad_u32 v37, v37, v86, v41
	v_lshlrev_b64 v[8:9], 16, v[80:81]
	v_or_b32_e32 v14, v14, v87
	v_and_b32_e32 v16, 40, v16
	v_and_b32_e32 v18, 40, v18
	v_or_b32_e32 v37, v37, v87
	v_lshlrev_b32_e32 v130, 1, v14
	v_xad_u32 v14, v16, v86, v15
	v_xad_u32 v15, v18, v86, v17
	v_lshl_add_u64 v[8:9], v[4:5], 0, v[8:9]
	v_lshl_add_u64 v[16:17], v[4:5], 0, v[10:11]
	v_lshl_add_u64 v[4:5], v[4:5], 0, v[12:13]
	v_lshlrev_b32_e32 v133, 1, v37
	v_or_b32_e32 v37, 5, v82
	v_lshl_add_u64 v[4:5], v[38:39], 1, v[4:5]
	v_lshlrev_b32_e32 v39, 6, v37
	v_lshlrev_b32_e32 v37, 2, v37
	v_and_b32_e32 v37, 48, v37
	v_xad_u32 v37, v37, v86, v39
	v_or_b32_e32 v37, v37, v87
	v_lshlrev_b32_e32 v134, 1, v37
	v_or_b32_e32 v37, 6, v82
	v_lshlrev_b32_e32 v39, 6, v37
	v_lshlrev_b32_e32 v37, 2, v37
	v_and_b32_e32 v37, 56, v37
	v_xad_u32 v37, v37, v86, v39
	v_or_b32_e32 v37, v37, v87
	v_lshlrev_b32_e32 v135, 1, v37
	v_or_b32_e32 v37, 7, v82
	v_lshlrev_b32_e32 v39, 6, v37
	v_lshlrev_b32_e32 v37, 2, v37
	v_and_b32_e32 v37, 56, v37
	v_xad_u32 v37, v37, v86, v39
	v_or_b32_e32 v37, v37, v87
	v_lshlrev_b32_e32 v84, 3, v0
	v_lshlrev_b32_e32 v42, 3, v83
	v_lshlrev_b32_e32 v136, 1, v37
	v_and_b32_e32 v37, -8, v80
	v_lshlrev_b32_e32 v41, 9, v0
	v_lshlrev_b32_e32 v0, 5, v0
	v_ashrrev_i32_e32 v43, 31, v42
	v_or_b32_e32 v14, v14, v87
	v_or_b32_e32 v15, v15, v87
	s_mov_b64 s[34:35], 0x2000
	v_and_b32_e32 v39, 7, v80
	v_bitop3_b32 v0, v0, v37, 32 bitop3:0x6c
	v_lshlrev_b32_e32 v131, 1, v14
	v_lshlrev_b32_e32 v132, 1, v15
	v_lshl_add_u64 v[14:15], v[2:3], 0, s[34:35]
	v_lshl_add_u64 v[18:19], v[2:3], 0, s[62:63]
	v_lshl_add_u64 v[22:23], v[2:3], 0, s[24:25]
	global_load_dwordx4 v[10:13], v[2:3], off offset:128
	v_lshl_add_u64 v[2:3], v[42:43], 1, v[16:17]
	v_add_u32_e32 v43, v0, v41
	v_or_b32_e32 v41, v39, v41
	v_or_b32_e32 v43, v43, v39
	v_add_lshl_u32 v0, v41, v0, 1
	v_or_b32_e32 v41, 2, v84
	v_lshlrev_b32_e32 v137, 1, v43
	v_lshlrev_b32_e32 v43, 6, v41
	v_lshlrev_b32_e32 v41, 2, v41
	v_and_b32_e32 v41, 40, v41
	v_xad_u32 v41, v41, v37, v43
	v_or_b32_e32 v41, v41, v39
	v_lshlrev_b32_e32 v138, 1, v41
; template <int NT, bool BKN, bool MASK = false, bool ROWSS = false, class Epi> ...
;     ...
;   GEMM_LOAD(ra0, rb0, 0);
;   GEMM_LOAD(ra1, rb1, 1);
;   GEMM_STORE(ra0, rb0, 0);
;   GEMM_LOAD(ra0, rb0, (2 < nkm1 ? 2 : nkm1));
;   __syncthreads();
	v_or_b32_e32 v41, 3, v84
	v_lshlrev_b32_e32 v43, 6, v41
	v_lshlrev_b32_e32 v41, 2, v41
	v_and_b32_e32 v41, 40, v41
	v_xad_u32 v41, v41, v37, v43
	v_or_b32_e32 v41, v41, v39
	v_lshlrev_b32_e32 v139, 1, v41
	v_or_b32_e32 v41, 4, v84
	v_lshlrev_b32_e32 v43, 6, v41
	v_lshlrev_b32_e32 v41, 2, v41
	v_and_b32_e32 v41, 48, v41
	v_xad_u32 v41, v41, v37, v43
	v_or_b32_e32 v41, v41, v39
	v_lshlrev_b32_e32 v140, 1, v41
	v_or_b32_e32 v41, 5, v84
	v_ashrrev_i32_e32 v85, 31, v84
	v_lshlrev_b32_e32 v43, 6, v41
	v_lshlrev_b32_e32 v41, 2, v41
	v_lshl_add_u64 v[8:9], v[84:85], 1, v[8:9]
	v_and_b32_e32 v41, 48, v41
	global_load_dwordx4 v[68:71], v[8:9], off
	s_nop 0
	global_load_dwordx4 v[14:17], v[14:15], off offset:128
	s_nop 0
	global_load_dwordx4 v[18:21], v[18:19], off offset:128
	s_nop 0
	global_load_dwordx4 v[22:25], v[22:23], off offset:128
	s_nop 0
	global_load_dwordx4 v[72:75], v[2:3], off
	global_load_dwordx4 v[76:79], v[4:5], off
	v_xad_u32 v41, v41, v37, v43
	v_or_b32_e32 v41, v41, v39
	v_lshlrev_b32_e32 v141, 1, v41
	v_or_b32_e32 v41, 6, v84
	v_lshlrev_b32_e32 v43, 6, v41
	v_lshlrev_b32_e32 v41, 2, v41
	v_and_b32_e32 v41, 56, v41
	s_mov_b32 s5, 0x400000
	v_xad_u32 v41, v41, v37, v43
	v_add_co_u32_e32 v6, vcc, s5, v6
	v_or_b32_e32 v41, v41, v39
	s_nop 0
	v_addc_co_u32_e32 v7, vcc, 0, v7, vcc
	v_lshlrev_b32_e32 v142, 1, v41
	v_or_b32_e32 v41, 7, v84
	v_add_co_u32_e32 v8, vcc, s5, v8
	v_lshlrev_b32_e32 v43, 6, v41
	v_lshlrev_b32_e32 v41, 2, v41
	v_addc_co_u32_e32 v9, vcc, 0, v9, vcc
	v_and_b32_e32 v41, 56, v41
	v_add_co_u32_e32 v2, vcc, s5, v2
	v_xad_u32 v37, v41, v37, v43
	s_nop 0
	v_addc_co_u32_e32 v3, vcc, 0, v3, vcc
	v_or_b32_e32 v37, v37, v39
	v_add_co_u32_e32 v4, vcc, s5, v4
	v_lshlrev_b32_e32 v143, 1, v37
	v_and_b32_e32 v37, -8, v40
	v_lshlrev_b32_e32 v41, 5, v83
	v_addc_co_u32_e32 v5, vcc, 0, v5, vcc
	v_and_b32_e32 v39, 7, v40
	v_lshlrev_b32_e32 v40, 9, v83
	v_bitop3_b32 v41, v41, v37, 32 bitop3:0x6c
	global_load_dwordx4 v[30:33], v[6:7], off
	global_load_dwordx4 v[26:29], v[8:9], off
	s_nop 0
	global_load_dwordx4 v[6:9], v[2:3], off
	s_nop 0
	global_load_dwordx4 v[2:5], v[4:5], off
	v_add_u32_e32 v43, v41, v40
	v_or_b32_e32 v40, v39, v40
	v_add_lshl_u32 v145, v40, v41, 1
	v_or_b32_e32 v40, 2, v42
	v_lshlrev_b32_e32 v41, 6, v40
	v_lshlrev_b32_e32 v40, 2, v40
	v_and_b32_e32 v40, 40, v40
	v_xad_u32 v40, v40, v37, v41
	v_or_b32_e32 v40, v40, v39
	v_lshlrev_b32_e32 v146, 1, v40
	v_or_b32_e32 v40, 3, v42
	v_lshlrev_b32_e32 v41, 6, v40
	v_lshlrev_b32_e32 v40, 2, v40
	v_and_b32_e32 v40, 40, v40
	v_xad_u32 v40, v40, v37, v41
	v_or_b32_e32 v40, v40, v39
	v_lshlrev_b32_e32 v147, 1, v40
	v_or_b32_e32 v40, 4, v42
	v_lshlrev_b32_e32 v41, 6, v40
	v_lshlrev_b32_e32 v40, 2, v40
	v_and_b32_e32 v40, 48, v40
	v_xad_u32 v40, v40, v37, v41
	v_or_b32_e32 v40, v40, v39
	v_lshlrev_b32_e32 v148, 1, v40
	v_or_b32_e32 v40, 5, v42
	v_lshlrev_b32_e32 v41, 6, v40
	v_lshlrev_b32_e32 v40, 2, v40
	v_and_b32_e32 v40, 48, v40
	v_xad_u32 v40, v40, v37, v41
	v_or_b32_e32 v40, v40, v39
	v_lshlrev_b32_e32 v149, 1, v40
	v_or_b32_e32 v40, 6, v42
	v_lshlrev_b32_e32 v41, 6, v40
	v_lshlrev_b32_e32 v40, 2, v40
	v_and_b32_e32 v40, 56, v40
	v_xad_u32 v40, v40, v37, v41
	v_or_b32_e32 v40, v40, v39
	v_lshlrev_b32_e32 v150, 1, v40
	v_or_b32_e32 v40, 7, v42
	v_lshlrev_b32_e32 v41, 6, v40
	v_lshlrev_b32_e32 v40, 2, v40
	v_and_b32_e32 v40, 56, v40
	v_xad_u32 v37, v40, v37, v41
	v_or_b32_e32 v37, v37, v39
	v_lshlrev_b32_e32 v151, 1, v37
	v_and_b32_e32 v37, -8, v36
	v_lshlrev_b32_e32 v40, 5, v88
	v_or_b32_e32 v43, v43, v39
	v_and_b32_e32 v36, 7, v36
	v_lshlrev_b32_e32 v39, 9, v88
	v_bitop3_b32 v40, v40, v37, 32 bitop3:0x6c
	v_add_u32_e32 v41, v40, v39
	v_or_b32_e32 v39, v36, v39
	v_add_lshl_u32 v153, v39, v40, 1
	v_or_b32_e32 v39, 2, v38
	v_lshlrev_b32_e32 v40, 6, v39
	v_lshlrev_b32_e32 v39, 2, v39
	v_and_b32_e32 v39, 40, v39
	v_xad_u32 v39, v39, v37, v40
	v_or_b32_e32 v39, v39, v36
	v_lshlrev_b32_e32 v154, 1, v39
	v_or_b32_e32 v39, 3, v38
	v_lshlrev_b32_e32 v40, 6, v39
	v_lshlrev_b32_e32 v39, 2, v39
	v_and_b32_e32 v39, 40, v39
	v_xad_u32 v39, v39, v37, v40
	v_or_b32_e32 v39, v39, v36
	v_lshlrev_b32_e32 v155, 1, v39
	v_or_b32_e32 v39, 4, v38
	v_lshlrev_b32_e32 v40, 6, v39
	v_lshlrev_b32_e32 v39, 2, v39
	v_and_b32_e32 v39, 48, v39
	v_xad_u32 v39, v39, v37, v40
	v_or_b32_e32 v39, v39, v36
	v_lshlrev_b32_e32 v156, 1, v39
	v_or_b32_e32 v39, 5, v38
	v_lshlrev_b32_e32 v40, 6, v39
	v_lshlrev_b32_e32 v39, 2, v39
	v_and_b32_e32 v39, 48, v39
	v_xad_u32 v39, v39, v37, v40
	v_or_b32_e32 v39, v39, v36
	v_lshlrev_b32_e32 v157, 1, v39
	v_or_b32_e32 v39, 6, v38
	v_lshlrev_b32_e32 v40, 6, v39
	v_lshlrev_b32_e32 v39, 2, v39
	v_and_b32_e32 v39, 56, v39
	v_xad_u32 v39, v39, v37, v40
	v_or_b32_e32 v39, v39, v36
	v_or_b32_e32 v38, 7, v38
	v_lshlrev_b32_e32 v158, 1, v39
	v_lshlrev_b32_e32 v39, 6, v38
	v_lshlrev_b32_e32 v38, 2, v38
	v_and_b32_e32 v38, 56, v38
	v_xad_u32 v37, v38, v37, v39
	v_or_b32_e32 v41, v41, v36
	v_or_b32_e32 v36, v37, v36
	v_lshlrev_b32_e32 v152, 1, v41
	v_lshlrev_b32_e32 v159, 1, v36
	v_bitop3_b32 v36, v47, v108, 3 bitop3:0x6c
	v_lshlrev_b32_e32 v41, 7, v44
	v_lshlrev_b32_e32 v40, 4, v36
	v_lshl_or_b32 v47, v45, 13, v41
	v_lshlrev_b32_e32 v144, 1, v43
	v_or_b32_e32 v160, v40, v47
	s_waitcnt vmcnt(0) lgkmcnt(0)
	ds_write_b128 v128, v[48:51]
	ds_write_b128 v128, v[52:55] offset:4096
	ds_write_b128 v128, v[56:59] offset:8192
	ds_write_b128 v128, v[60:63] offset:12288
	ds_write_b16 v130, v64 offset:16384
	ds_write_b16_d16_hi v129, v64 offset:16512
	ds_write_b16 v131, v65 offset:16384
	ds_write_b16_d16_hi v132, v65 offset:16384
	ds_write_b16 v133, v66 offset:16384
	ds_write_b16_d16_hi v134, v66 offset:16384
	ds_write_b16 v135, v67 offset:16384
	ds_write_b16_d16_hi v136, v67 offset:16384
	ds_write_b16 v137, v68 offset:16384
	ds_write_b16_d16_hi v0, v68 offset:16512
	ds_write_b16 v138, v69 offset:16384
	ds_write_b16_d16_hi v139, v69 offset:16384
	ds_write_b16 v140, v70 offset:16384
	ds_write_b16_d16_hi v141, v70 offset:16384
	ds_write_b16 v142, v71 offset:16384
	ds_write_b16_d16_hi v143, v71 offset:16384
	ds_write_b16 v144, v72 offset:16384
	ds_write_b16_d16_hi v145, v72 offset:16512
	ds_write_b16 v146, v73 offset:16384
	ds_write_b16_d16_hi v147, v73 offset:16384
	ds_write_b16 v148, v74 offset:16384
	ds_write_b16_d16_hi v149, v74 offset:16384
	ds_write_b16 v150, v75 offset:16384
	ds_write_b16_d16_hi v151, v75 offset:16384
	ds_write_b16 v152, v76 offset:16384
	ds_write_b16_d16_hi v153, v76 offset:16512
	ds_write_b16 v154, v77 offset:16384
	ds_write_b16_d16_hi v155, v77 offset:16384
	ds_write_b16 v156, v78 offset:16384
	ds_write_b16_d16_hi v157, v78 offset:16384
	ds_write_b16 v158, v79 offset:16384
	ds_write_b16_d16_hi v159, v79 offset:16384
	s_waitcnt lgkmcnt(0)
	s_barrier
; template <int NT, bool BKN, bool MASK = false, bool ROWSS = false, class Epi> ...
;     ...
;   GEMM_COMPUTE(0);
;   GEMM_STORE(ra1, rb1, 1);
;   __syncthreads();
;   GEMM_COMPUTE(1);
	ds_read_b128 v[36:39], v160
	v_lshl_or_b32 v112, v161, 13, v41
	v_or_b32_e32 v162, v40, v112
	ds_read_b128 v[40:43], v162 offset:16384
	ds_read_b128 v[48:51], v160 offset:2048
	ds_read_b128 v[52:55], v162 offset:18432
	ds_read_b128 v[64:67], v162 offset:20480
	ds_read_b128 v[68:71], v162 offset:22528
	ds_read_b128 v[88:91], v160 offset:4096
	ds_read_b128 v[92:95], v160 offset:6144
	v_or_b32_e32 v164, v46, v47
	ds_read_b128 v[108:111], v164
	v_or_b32_e32 v165, v46, v112
	s_waitcnt lgkmcnt(7)
	v_mfma_f32_16x16x32_bf16 v[56:59], v[36:39], v[40:43], 0
	s_lshl_b32 s19, s4, 7
	s_waitcnt lgkmcnt(5)
	v_mfma_f32_16x16x32_bf16 v[60:63], v[36:39], v[52:55], 0
	s_waitcnt lgkmcnt(4)
	v_mfma_f32_16x16x32_bf16 v[72:75], v[36:39], v[64:67], 0
	s_waitcnt lgkmcnt(3)
	v_mfma_f32_16x16x32_bf16 v[36:39], v[36:39], v[68:71], 0
	v_mfma_f32_16x16x32_bf16 v[76:79], v[48:51], v[40:43], 0
	v_mfma_f32_16x16x32_bf16 v[80:83], v[48:51], v[52:55], 0
	v_mfma_f32_16x16x32_bf16 v[84:87], v[48:51], v[64:67], 0
	v_mfma_f32_16x16x32_bf16 v[48:51], v[48:51], v[68:71], 0
	s_waitcnt lgkmcnt(2)
	v_mfma_f32_16x16x32_bf16 v[96:99], v[88:91], v[40:43], 0
	v_mfma_f32_16x16x32_bf16 v[100:103], v[88:91], v[52:55], 0
	v_mfma_f32_16x16x32_bf16 v[104:107], v[88:91], v[64:67], 0
	v_mfma_f32_16x16x32_bf16 v[88:91], v[88:91], v[68:71], 0
	s_waitcnt lgkmcnt(1)
	v_mfma_f32_16x16x32_bf16 v[40:43], v[92:95], v[40:43], 0
	v_mfma_f32_16x16x32_bf16 v[52:55], v[92:95], v[52:55], 0
	v_mfma_f32_16x16x32_bf16 v[64:67], v[92:95], v[64:67], 0
	v_mfma_f32_16x16x32_bf16 v[68:71], v[92:95], v[68:71], 0
	ds_read_b128 v[92:95], v165 offset:16384
	ds_read_b128 v[112:115], v164 offset:2048
	ds_read_b128 v[116:119], v165 offset:18432
	ds_read_b128 v[120:123], v165 offset:20480
	ds_read_b128 v[124:127], v165 offset:22528
	s_waitcnt lgkmcnt(4)
	v_mfma_f32_16x16x32_bf16 v[56:59], v[108:111], v[92:95], v[56:59]
	s_waitcnt lgkmcnt(2)
	v_mfma_f32_16x16x32_bf16 v[60:63], v[108:111], v[116:119], v[60:63]
	s_waitcnt lgkmcnt(1)
	v_mfma_f32_16x16x32_bf16 v[72:75], v[108:111], v[120:123], v[72:75]
	s_waitcnt lgkmcnt(0)
	v_mfma_f32_16x16x32_bf16 v[36:39], v[108:111], v[124:127], v[36:39]
	v_mfma_f32_16x16x32_bf16 v[76:79], v[112:115], v[92:95], v[76:79]
	v_mfma_f32_16x16x32_bf16 v[80:83], v[112:115], v[116:119], v[80:83]
	v_mfma_f32_16x16x32_bf16 v[84:87], v[112:115], v[120:123], v[84:87]
	v_mfma_f32_16x16x32_bf16 v[46:49], v[112:115], v[124:127], v[48:51]
	ds_read_b128 v[108:111], v164 offset:4096
	ds_read_b128 v[112:115], v164 offset:6144
	ds_write_b128 v128, v[10:13] offset:32768
	ds_write_b128 v128, v[14:17] offset:36864
	ds_write_b128 v128, v[18:21] offset:40960
	ds_write_b128 v128, v[22:25] offset:45056
	ds_write_b16 v130, v30 offset:49152
	ds_write_b16_d16_hi v129, v30 offset:49280
	ds_write_b16 v131, v31 offset:49152
	ds_write_b16_d16_hi v132, v31 offset:49152
	ds_write_b16 v133, v32 offset:49152
	ds_write_b16_d16_hi v134, v32 offset:49152
	ds_write_b16 v135, v33 offset:49152
	ds_write_b16_d16_hi v136, v33 offset:49152
	ds_write_b16 v137, v26 offset:49152
	ds_write_b16_d16_hi v0, v26 offset:49280
	ds_write_b16 v138, v27 offset:49152
	ds_write_b16_d16_hi v139, v27 offset:49152
	ds_write_b16 v140, v28 offset:49152
	ds_write_b16_d16_hi v141, v28 offset:49152
	ds_write_b16 v142, v29 offset:49152
	ds_write_b16_d16_hi v143, v29 offset:49152
	ds_write_b16 v144, v6 offset:49152
	ds_write_b16_d16_hi v145, v6 offset:49280
	ds_write_b16 v146, v7 offset:49152
	ds_write_b16_d16_hi v147, v7 offset:49152
	ds_write_b16 v148, v8 offset:49152
	ds_write_b16_d16_hi v149, v8 offset:49152
	ds_write_b16 v150, v9 offset:49152
	ds_write_b16_d16_hi v151, v9 offset:49152
	ds_write_b16 v152, v2 offset:49152
	ds_write_b16_d16_hi v153, v2 offset:49280
	ds_write_b16 v154, v3 offset:49152
	ds_write_b16_d16_hi v155, v3 offset:49152
	ds_write_b16 v156, v4 offset:49152
	ds_write_b16_d16_hi v157, v4 offset:49152
	ds_write_b16 v158, v5 offset:49152
	ds_write_b16_d16_hi v159, v5 offset:49152
	s_waitcnt lgkmcnt(0)
	s_barrier
	ds_read_b128 v[2:5], v160 offset:32768
	ds_read_b128 v[10:13], v162 offset:49152
	ds_read_b128 v[14:17], v160 offset:34816
	ds_read_b128 v[18:21], v162 offset:51200
	v_mfma_f32_16x16x32_bf16 v[50:53], v[112:115], v[116:119], v[52:55]
	v_lshlrev_b32_e32 v0, 6, v45
	v_lshl_or_b32 v45, v163, 2, v0
	v_mov_b32_e32 v0, v187
	s_waitcnt lgkmcnt(2)
	v_mfma_f32_16x16x32_bf16 v[22:25], v[2:5], v[10:13], v[56:59]
	ds_read_b128 v[30:33], v162 offset:53248
	s_nop 1
	ds_read_b128 v[54:57], v162 offset:55296
	v_mfma_f32_16x16x32_bf16 v[6:9], v[112:115], v[124:127], v[68:71]
	s_waitcnt lgkmcnt(2)
	v_mfma_f32_16x16x32_bf16 v[26:29], v[2:5], v[18:21], v[60:63]
	s_waitcnt lgkmcnt(1)
	v_mfma_f32_16x16x32_bf16 v[58:61], v[2:5], v[30:33], v[72:75]
	s_waitcnt lgkmcnt(0)
	v_mfma_f32_16x16x32_bf16 v[2:5], v[2:5], v[54:57], v[36:39]
	v_mfma_f32_16x16x32_bf16 v[36:39], v[14:17], v[10:13], v[76:79]
	v_mfma_f32_16x16x32_bf16 v[68:71], v[14:17], v[18:21], v[80:83]
	v_mfma_f32_16x16x32_bf16 v[72:75], v[14:17], v[30:33], v[84:87]
	v_mfma_f32_16x16x32_bf16 v[14:17], v[14:17], v[54:57], v[46:49]
	s_nop 2
	ds_read_b128 v[46:49], v160 offset:36864
	ds_read_b128 v[76:79], v160 offset:38912
	v_mfma_f32_16x16x32_bf16 v[96:99], v[108:111], v[92:95], v[96:99]
	v_mfma_f32_16x16x32_bf16 v[40:43], v[112:115], v[92:95], v[40:43]
	v_mfma_f32_16x16x32_bf16 v[100:103], v[108:111], v[116:119], v[100:103]
	v_mfma_f32_16x16x32_bf16 v[104:107], v[108:111], v[120:123], v[104:107]
	v_mfma_f32_16x16x32_bf16 v[88:91], v[108:111], v[124:127], v[88:91]
	v_mfma_f32_16x16x32_bf16 v[64:67], v[112:115], v[120:123], v[64:67]
	s_waitcnt lgkmcnt(1)
	v_mfma_f32_16x16x32_bf16 v[80:83], v[46:49], v[10:13], v[96:99]
	s_waitcnt lgkmcnt(0)
; __device__ __forceinline__ u16 f2bf(float f) { return (u16)(pack2(f, 0.f) & 0xffffu); }
; __device__ __forceinline__ int tid_() { int t = threadIdx.x; asm volatile("" : "+v"(t)); return t; }
; template <int NT, class VF, class RP>
; __device__ __forceinline__ void epi_staged_bf16(f32x4 (&acc)[4][NT], int r0, int c0, unsigned char* smem, VF vf, RP rowptr) {
;   constexpr int BN = NT * 32, PITCH = BN + 8, CPR = BN / 8;
;   u16* Ts = (u16*)smem;
;   const int t = tid_();
;   __syncthreads();
; #pragma unroll
;   for (int mi = 0; mi < 4; ++mi)
; #pragma unroll
;     for (int ni = 0; ni < NT; ++ni)
; #pragma unroll
;       for (int j = 0; j < 4; ++j) {
;         const int r = r0 + mi * 16 + j, c = c0 + ni * 16;
;         Ts[r * PITCH + c] = f2bf(vf(r, c, acc[mi][ni][j]));
;       }
;   __syncthreads();
	v_mfma_f32_16x16x32_bf16 v[10:13], v[76:79], v[10:13], v[40:43]
	s_nop 2
	ds_read_b128 v[40:43], v164 offset:32768
	v_mfma_f32_16x16x32_bf16 v[84:87], v[46:49], v[18:21], v[100:103]
	v_mfma_f32_16x16x32_bf16 v[92:95], v[46:49], v[30:33], v[104:107]
	v_mfma_f32_16x16x32_bf16 v[46:49], v[46:49], v[54:57], v[88:91]
	v_mfma_f32_16x16x32_bf16 v[18:21], v[76:79], v[18:21], v[50:53]
	v_mfma_f32_16x16x32_bf16 v[30:33], v[76:79], v[30:33], v[64:67]
	v_mfma_f32_16x16x32_bf16 v[6:9], v[76:79], v[54:57], v[6:9]
	s_nop 0
	ds_read_b128 v[50:53], v165 offset:49152
	ds_read_b128 v[54:57], v164 offset:34816
	ds_read_b128 v[62:65], v165 offset:51200
	ds_read_b128 v[76:79], v165 offset:53248
	ds_read_b128 v[88:91], v165 offset:55296
	s_waitcnt lgkmcnt(4)
	v_mfma_f32_16x16x32_bf16 v[22:25], v[40:43], v[50:53], v[22:25]
	s_waitcnt lgkmcnt(2)
	v_mfma_f32_16x16x32_bf16 v[26:29], v[40:43], v[62:65], v[26:29]
	s_waitcnt lgkmcnt(1)
	v_mfma_f32_16x16x32_bf16 v[58:61], v[40:43], v[76:79], v[58:61]
	s_waitcnt lgkmcnt(0)
	v_mfma_f32_16x16x32_bf16 v[2:5], v[40:43], v[88:91], v[2:5]
	v_mfma_f32_16x16x32_bf16 v[36:39], v[54:57], v[50:53], v[36:39]
	v_mfma_f32_16x16x32_bf16 v[40:43], v[54:57], v[62:65], v[68:71]
	s_nop 5
	v_cvt_pk_bf16_f32 v2, v2, s0
	v_mfma_f32_16x16x32_bf16 v[66:69], v[54:57], v[76:79], v[72:75]
	v_mfma_f32_16x16x32_bf16 v[14:17], v[54:57], v[88:91], v[14:17]
	ds_read_b128 v[54:57], v164 offset:36864
	s_nop 0
	ds_read_b128 v[70:73], v164 offset:38912
	s_waitcnt lgkmcnt(0)
	v_mfma_f32_16x16x32_bf16 v[80:83], v[54:57], v[50:53], v[80:83]
	s_barrier
	v_mfma_f32_16x16x32_bf16 v[10:13], v[70:73], v[50:53], v[10:13]
	v_cvt_pk_bf16_f32 v50, v22, s0
	v_lshlrev_b32_e32 v22, 1, v44
	v_lshl_or_b32 v22, v161, 7, v22
	v_mad_u64_u32 v[44:45], s[34:35], v45, s23, v[22:23]
	ds_write_b16 v44, v2 offset:96
	v_cvt_pk_bf16_f32 v2, v3, s0
	ds_write_b16 v44, v2 offset:368
	v_cvt_pk_bf16_f32 v2, v4, s0
	ds_write_b16 v44, v2 offset:640
	v_cvt_pk_bf16_f32 v2, v5, s0
	ds_write_b16 v44, v2 offset:912
	v_cvt_pk_bf16_f32 v2, v36, s0
	ds_write_b16 v44, v2 offset:4352
	v_cvt_pk_bf16_f32 v2, v37, s0
	ds_write_b16 v44, v2 offset:4624
	v_cvt_pk_bf16_f32 v2, v38, s0
	ds_write_b16 v44, v2 offset:4896
	v_cvt_pk_bf16_f32 v2, v39, s0
	ds_write_b16 v44, v2 offset:5168
	v_cvt_pk_bf16_f32 v2, v40, s0
	ds_write_b16 v44, v2 offset:4384
	v_cvt_pk_bf16_f32 v2, v41, s0
	ds_write_b16 v44, v2 offset:4656
	v_cvt_pk_bf16_f32 v2, v42, s0
	ds_write_b16 v44, v2 offset:4928
	v_cvt_pk_bf16_f32 v2, v43, s0
	ds_write_b16 v44, v2 offset:5200
	v_cvt_pk_bf16_f32 v2, v66, s0
	ds_write_b16 v44, v2 offset:4416
	v_cvt_pk_bf16_f32 v2, v67, s0
	ds_write_b16 v44, v2 offset:4688
	v_cvt_pk_bf16_f32 v2, v68, s0
	ds_write_b16 v44, v2 offset:4960
	v_cvt_pk_bf16_f32 v2, v69, s0
	ds_write_b16 v44, v2 offset:5232
	v_cvt_pk_bf16_f32 v2, v14, s0
	ds_write_b16 v44, v2 offset:4448
	v_cvt_pk_bf16_f32 v2, v15, s0
	ds_write_b16 v44, v2 offset:4720
	v_cvt_pk_bf16_f32 v2, v16, s0
	ds_write_b16 v44, v2 offset:4992
	v_cvt_pk_bf16_f32 v2, v17, s0
	v_mfma_f32_16x16x32_bf16 v[84:87], v[54:57], v[62:65], v[84:87]
	ds_write_b16 v44, v2 offset:5264
	v_cvt_pk_bf16_f32 v2, v80, s0
	ds_write_b16 v44, v2 offset:8704
	v_cvt_pk_bf16_f32 v2, v81, s0
	ds_write_b16 v44, v2 offset:8976
	v_cvt_pk_bf16_f32 v2, v82, s0
	ds_write_b16 v44, v2 offset:9248
	v_cvt_pk_bf16_f32 v2, v83, s0
	v_mfma_f32_16x16x32_bf16 v[92:95], v[54:57], v[76:79], v[92:95]
	ds_write_b16 v44, v2 offset:9520
	v_cvt_pk_bf16_f32 v2, v84, s0
	ds_write_b16 v44, v2 offset:8736
	v_cvt_pk_bf16_f32 v2, v85, s0
	ds_write_b16 v44, v2 offset:9008
	v_cvt_pk_bf16_f32 v2, v86, s0
	ds_write_b16 v44, v2 offset:9280
	v_cvt_pk_bf16_f32 v2, v87, s0
	v_mfma_f32_16x16x32_bf16 v[46:49], v[54:57], v[88:91], v[46:49]
	ds_write_b16 v44, v2 offset:9552
	v_cvt_pk_bf16_f32 v2, v92, s0
	ds_write_b16 v44, v2 offset:8768
	v_cvt_pk_bf16_f32 v2, v93, s0
	ds_write_b16 v44, v2 offset:9040
	v_cvt_pk_bf16_f32 v2, v94, s0
	ds_write_b16 v44, v2 offset:9312
	v_cvt_pk_bf16_f32 v2, v95, s0
	ds_write_b16 v44, v2 offset:9584
	v_cvt_pk_bf16_f32 v2, v46, s0
	ds_write_b16 v44, v2 offset:8800
	v_cvt_pk_bf16_f32 v2, v47, s0
	ds_write_b16 v44, v2 offset:9072
	v_cvt_pk_bf16_f32 v2, v48, s0
	ds_write_b16 v44, v2 offset:9344
	v_cvt_pk_bf16_f32 v2, v49, s0
	v_mfma_f32_16x16x32_bf16 v[18:21], v[70:73], v[62:65], v[18:21]
	ds_write_b16 v44, v2 offset:9616
	v_cvt_pk_bf16_f32 v2, v10, s0
	ds_write_b16 v44, v2 offset:13056
	v_cvt_pk_bf16_f32 v2, v11, s0
	ds_write_b16 v44, v2 offset:13328
	v_cvt_pk_bf16_f32 v2, v12, s0
	ds_write_b16 v44, v2 offset:13600
	v_cvt_pk_bf16_f32 v2, v13, s0
	v_mfma_f32_16x16x32_bf16 v[30:33], v[70:73], v[76:79], v[30:33]
	ds_write_b16 v44, v2 offset:13872
	v_cvt_pk_bf16_f32 v2, v18, s0
	v_cvt_pk_bf16_f32 v22, v23, s0
	ds_write_b16 v44, v2 offset:13088
	v_cvt_pk_bf16_f32 v2, v19, s0
	ds_write_b16 v44, v22 offset:272
	v_cvt_pk_bf16_f32 v22, v24, s0
	ds_write_b16 v44, v2 offset:13360
	v_cvt_pk_bf16_f32 v2, v20, s0
	ds_write_b16 v44, v22 offset:544
	v_cvt_pk_bf16_f32 v22, v25, s0
	ds_write_b16 v44, v2 offset:13632
	v_cvt_pk_bf16_f32 v2, v21, s0
	v_mfma_f32_16x16x32_bf16 v[6:9], v[70:73], v[88:91], v[6:9]
	ds_write_b16 v44, v22 offset:816
	v_cvt_pk_bf16_f32 v22, v26, s0
	ds_write_b16 v44, v2 offset:13904
	v_cvt_pk_bf16_f32 v2, v30, s0
	ds_write_b16 v44, v22 offset:32
	v_cvt_pk_bf16_f32 v22, v27, s0
	ds_write_b16 v44, v2 offset:13120
	v_cvt_pk_bf16_f32 v2, v31, s0
	ds_write_b16 v44, v22 offset:304
	v_cvt_pk_bf16_f32 v22, v28, s0
	ds_write_b16 v44, v2 offset:13392
	v_cvt_pk_bf16_f32 v2, v32, s0
	ds_write_b16 v44, v22 offset:576
	v_cvt_pk_bf16_f32 v22, v29, s0
	ds_write_b16 v44, v2 offset:13664
	v_cvt_pk_bf16_f32 v2, v33, s0
	ds_write_b16 v44, v22 offset:848
	v_cvt_pk_bf16_f32 v22, v58, s0
	ds_write_b16 v44, v2 offset:13936
	v_cvt_pk_bf16_f32 v2, v6, s0
	ds_write_b16 v44, v22 offset:64
	v_cvt_pk_bf16_f32 v22, v59, s0
	ds_write_b16 v44, v2 offset:13152
	v_cvt_pk_bf16_f32 v2, v7, s0
	ds_write_b16 v44, v22 offset:336
	v_cvt_pk_bf16_f32 v22, v60, s0
	ds_write_b16 v44, v2 offset:13424
	v_cvt_pk_bf16_f32 v2, v8, s0
	ds_write_b16 v44, v22 offset:608
	v_cvt_pk_bf16_f32 v22, v61, s0
	ds_write_b16 v44, v2 offset:13696
	v_cvt_pk_bf16_f32 v2, v9, s0
	ds_write_b16 v44, v50
	ds_write_b16 v44, v22 offset:880
	ds_write_b16 v44, v2 offset:13968
	s_waitcnt lgkmcnt(0)
	s_barrier
; template <int NT, class VF, class RP>
; __device__ __forceinline__ void epi_staged_bf16(f32x4 (&acc)[4][NT], int r0, int c0, unsigned char* smem, VF vf, RP rowptr) {
;     ...
; #pragma unroll
;   for (int i = 0; i < CPR / 2; ++i) {
;     const int c = t + 256 * i, row = c / CPR, ch = c % CPR;
;     u16* d = rowptr(row);
;     if (d) *(u32x4*)(d + ch * 8) = *(const u32x4*)(Ts + row * PITCH + ch * 8);
;   }
; __device__ __forceinline__ void phase_mix_a(const Params& p, int l, bool last, unsigned char* smem) {
;     ...
;         auto rp = [&](int m) -> u16* { const int rip = m >> 6, k2 = m & 63; return p.PF + ((size_t)((b * 64 + k2) * 2 + rip) * 128 + n1) * 256 + nh * 128; };
	global_load_dwordx2 v[2:3], v[34:35], off offset:320
	v_ashrrev_i32_e32 v4, 31, v0
	v_lshrrev_b32_e32 v4, 28, v4
	v_add_u32_e32 v4, v0, v4
	v_ashrrev_i32_e32 v6, 4, v4
	v_lshlrev_b32_e32 v5, 1, v6
	v_ashrrev_i32_e32 v4, 10, v4
	v_and_b32_e32 v5, 0x7e, v5
	v_add3_u32 v4, v4, s19, v5
	v_ashrrev_i32_e32 v5, 31, v4
	v_lshlrev_b64 v[4:5], 16, v[4:5]
	s_waitcnt vmcnt(0) lgkmcnt(0)
	v_lshl_add_u64 v[4:5], v[2:3], 0, v[4:5]
	v_lshl_add_u64 v[4:5], v[4:5], 0, s[94:95]
	v_cmp_ne_u64_e32 vcc, 0, v[4:5]
	s_and_saveexec_b64 s[4:5], vcc
	s_cbranch_execz .LBB0_610
	v_lshlrev_b32_e32 v2, 4, v6
	v_sub_u32_e32 v10, v0, v2
	v_mul_lo_u32 v2, v6, s23
	v_lshl_add_u32 v2, v10, 4, v2
	ds_read_b128 v[6:9], v2
	v_lshl_add_u64 v[2:3], v[4:5], 0, s[0:1]
	v_lshlrev_b32_e32 v4, 3, v10
	v_ashrrev_i32_e32 v5, 31, v4
	v_lshl_add_u64 v[2:3], v[4:5], 1, v[2:3]
	s_waitcnt lgkmcnt(0)
	global_store_dwordx4 v[2:3], v[6:9], off sc1
	v_mov_b64_e32 v[2:3], s[40:41]
	s_load_dwordx2 s[100:101], s[40:41], 0x140
	s_waitcnt lgkmcnt(0)
	v_mov_b32_e32 v2, s100
	v_mov_b32_e32 v3, s101
.LBB0_610:
	s_or_b64 exec, exec, s[4:5]
	v_add_u32_e32 v6, 0x100, v0
	v_ashrrev_i32_e32 v4, 31, v6
	v_lshrrev_b32_e32 v4, 28, v4
	v_add_u32_e32 v4, v6, v4
	v_ashrrev_i32_e32 v7, 4, v4
	v_lshlrev_b32_e32 v5, 1, v7
	v_ashrrev_i32_e32 v4, 10, v4
	v_and_b32_e32 v5, 0x7e, v5
	v_add3_u32 v4, v4, s19, v5
	v_ashrrev_i32_e32 v5, 31, v4
	v_lshlrev_b64 v[4:5], 16, v[4:5]
	s_waitcnt lgkmcnt(0)
	v_lshl_add_u64 v[4:5], v[2:3], 0, v[4:5]
	v_lshl_add_u64 v[4:5], v[4:5], 0, s[94:95]
	v_cmp_ne_u64_e32 vcc, 0, v[4:5]
	s_and_saveexec_b64 s[4:5], vcc
	s_cbranch_execz .LBB0_612
	v_lshlrev_b32_e32 v2, 4, v7
	v_sub_u32_e32 v10, v6, v2
	v_mul_lo_u32 v2, v7, s23
	v_lshl_add_u32 v2, v10, 4, v2
	ds_read_b128 v[6:9], v2
	s_mov_b32 s1, s95
	v_lshl_add_u64 v[2:3], v[4:5], 0, s[0:1]
	v_lshlrev_b32_e32 v4, 3, v10
	v_ashrrev_i32_e32 v5, 31, v4
	v_lshl_add_u64 v[2:3], v[4:5], 1, v[2:3]
	s_waitcnt lgkmcnt(0)
	global_store_dwordx4 v[2:3], v[6:9], off sc1
	v_mov_b64_e32 v[2:3], s[40:41]
	s_load_dwordx2 s[100:101], s[40:41], 0x140
	s_waitcnt lgkmcnt(0)
	v_mov_b32_e32 v2, s100
	v_mov_b32_e32 v3, s101
.LBB0_612:
	s_or_b64 exec, exec, s[4:5]
	v_add_u32_e32 v6, 0x200, v0
	v_ashrrev_i32_e32 v4, 31, v6
	v_lshrrev_b32_e32 v4, 28, v4
	v_add_u32_e32 v4, v6, v4
	v_ashrrev_i32_e32 v7, 4, v4
	v_lshlrev_b32_e32 v5, 1, v7
	v_ashrrev_i32_e32 v4, 10, v4
	v_and_b32_e32 v5, 0x7e, v5
	v_add3_u32 v4, v4, s19, v5
	v_ashrrev_i32_e32 v5, 31, v4
	v_lshlrev_b64 v[4:5], 16, v[4:5]
	s_waitcnt lgkmcnt(0)
	v_lshl_add_u64 v[4:5], v[2:3], 0, v[4:5]
	v_lshl_add_u64 v[4:5], v[4:5], 0, s[94:95]
	v_cmp_ne_u64_e32 vcc, 0, v[4:5]
	s_and_saveexec_b64 s[4:5], vcc
	s_cbranch_execz .LBB0_614
	v_lshlrev_b32_e32 v2, 4, v7
	v_sub_u32_e32 v10, v6, v2
	v_mul_lo_u32 v2, v7, s23
	v_lshl_add_u32 v2, v10, 4, v2
	ds_read_b128 v[6:9], v2
	s_mov_b32 s1, s95
	v_lshl_add_u64 v[2:3], v[4:5], 0, s[0:1]
	v_lshlrev_b32_e32 v4, 3, v10
	v_ashrrev_i32_e32 v5, 31, v4
	v_lshl_add_u64 v[2:3], v[4:5], 1, v[2:3]
	s_waitcnt lgkmcnt(0)
	global_store_dwordx4 v[2:3], v[6:9], off sc1
	v_mov_b64_e32 v[2:3], s[40:41]
	s_load_dwordx2 s[100:101], s[40:41], 0x140
	s_waitcnt lgkmcnt(0)
	v_mov_b32_e32 v2, s100
	v_mov_b32_e32 v3, s101
.LBB0_614:
	s_or_b64 exec, exec, s[4:5]
	v_add_u32_e32 v6, 0x300, v0
	v_ashrrev_i32_e32 v4, 31, v6
	v_lshrrev_b32_e32 v4, 28, v4
	v_add_u32_e32 v4, v6, v4
	v_ashrrev_i32_e32 v7, 4, v4
	v_lshlrev_b32_e32 v5, 1, v7
	v_ashrrev_i32_e32 v4, 10, v4
	v_and_b32_e32 v5, 0x7e, v5
	v_add3_u32 v4, v4, s19, v5
	v_ashrrev_i32_e32 v5, 31, v4
	v_lshlrev_b64 v[4:5], 16, v[4:5]
	s_waitcnt lgkmcnt(0)
	v_lshl_add_u64 v[4:5], v[2:3], 0, v[4:5]
	v_lshl_add_u64 v[4:5], v[4:5], 0, s[94:95]
	v_cmp_ne_u64_e32 vcc, 0, v[4:5]
	s_and_saveexec_b64 s[4:5], vcc
	s_cbranch_execz .LBB0_616
	v_lshlrev_b32_e32 v2, 4, v7
	v_sub_u32_e32 v10, v6, v2
	v_mul_lo_u32 v2, v7, s23
	v_lshl_add_u32 v2, v10, 4, v2
	ds_read_b128 v[6:9], v2
	s_mov_b32 s1, s95
	v_lshl_add_u64 v[2:3], v[4:5], 0, s[0:1]
	v_lshlrev_b32_e32 v4, 3, v10
	v_ashrrev_i32_e32 v5, 31, v4
	v_lshl_add_u64 v[2:3], v[4:5], 1, v[2:3]
	s_waitcnt lgkmcnt(0)
	global_store_dwordx4 v[2:3], v[6:9], off sc1
	v_mov_b64_e32 v[2:3], s[40:41]
	s_load_dwordx2 s[100:101], s[40:41], 0x140
	s_waitcnt lgkmcnt(0)
	v_mov_b32_e32 v2, s100
	v_mov_b32_e32 v3, s101
; template <int NT, class VF, class RP>
; __device__ __forceinline__ void epi_staged_bf16(f32x4 (&acc)[4][NT], int r0, int c0, unsigned char* smem, VF vf, RP rowptr) {
;     ...
; #pragma unroll
;   for (int i = 0; i < CPR / 2; ++i) {
;     const int c = t + 256 * i, row = c / CPR, ch = c % CPR;
;     u16* d = rowptr(row);
;     if (d) *(u32x4*)(d + ch * 8) = *(const u32x4*)(Ts + row * PITCH + ch * 8);
;   }
.LBB0_616:
	s_or_b64 exec, exec, s[4:5]
	v_add_u32_e32 v6, 0x400, v0
	v_ashrrev_i32_e32 v4, 31, v6
	v_lshrrev_b32_e32 v4, 28, v4
	v_add_u32_e32 v4, v6, v4
	v_ashrrev_i32_e32 v7, 4, v4
	v_lshlrev_b32_e32 v5, 1, v7
	v_ashrrev_i32_e32 v4, 10, v4
	v_and_b32_e32 v5, 0x7e, v5
	v_add3_u32 v4, v4, s19, v5
	v_ashrrev_i32_e32 v5, 31, v4
	v_lshlrev_b64 v[4:5], 16, v[4:5]
	s_waitcnt lgkmcnt(0)
	v_lshl_add_u64 v[4:5], v[2:3], 0, v[4:5]
	v_lshl_add_u64 v[4:5], v[4:5], 0, s[94:95]
	v_cmp_ne_u64_e32 vcc, 0, v[4:5]
	s_and_saveexec_b64 s[4:5], vcc
	s_cbranch_execz .LBB0_618
	v_lshlrev_b32_e32 v2, 4, v7
	v_sub_u32_e32 v10, v6, v2
	v_mul_lo_u32 v2, v7, s23
	v_lshl_add_u32 v2, v10, 4, v2
	ds_read_b128 v[6:9], v2
	s_mov_b32 s1, s95
	v_lshl_add_u64 v[2:3], v[4:5], 0, s[0:1]
	v_lshlrev_b32_e32 v4, 3, v10
	v_ashrrev_i32_e32 v5, 31, v4
	v_lshl_add_u64 v[2:3], v[4:5], 1, v[2:3]
	s_waitcnt lgkmcnt(0)
	global_store_dwordx4 v[2:3], v[6:9], off sc1
	v_mov_b64_e32 v[2:3], s[40:41]
	s_load_dwordx2 s[100:101], s[40:41], 0x140
	s_waitcnt lgkmcnt(0)
	v_mov_b32_e32 v2, s100
	v_mov_b32_e32 v3, s101
.LBB0_618:
	s_or_b64 exec, exec, s[4:5]
	v_add_u32_e32 v6, 0x500, v0
	v_ashrrev_i32_e32 v4, 31, v6
	v_lshrrev_b32_e32 v4, 28, v4
	v_add_u32_e32 v4, v6, v4
	v_ashrrev_i32_e32 v7, 4, v4
	v_lshlrev_b32_e32 v5, 1, v7
	v_ashrrev_i32_e32 v4, 10, v4
	v_and_b32_e32 v5, 0x7e, v5
	v_add3_u32 v4, v4, s19, v5
	v_ashrrev_i32_e32 v5, 31, v4
	v_lshlrev_b64 v[4:5], 16, v[4:5]
	s_waitcnt lgkmcnt(0)
	v_lshl_add_u64 v[4:5], v[2:3], 0, v[4:5]
	v_lshl_add_u64 v[4:5], v[4:5], 0, s[94:95]
	v_cmp_ne_u64_e32 vcc, 0, v[4:5]
	s_and_saveexec_b64 s[4:5], vcc
	s_cbranch_execz .LBB0_620
	v_lshlrev_b32_e32 v2, 4, v7
	v_sub_u32_e32 v10, v6, v2
	v_mul_lo_u32 v2, v7, s23
	v_lshl_add_u32 v2, v10, 4, v2
	ds_read_b128 v[6:9], v2
	s_mov_b32 s1, s95
	v_lshl_add_u64 v[2:3], v[4:5], 0, s[0:1]
	v_lshlrev_b32_e32 v4, 3, v10
	v_ashrrev_i32_e32 v5, 31, v4
	v_lshl_add_u64 v[2:3], v[4:5], 1, v[2:3]
	s_waitcnt lgkmcnt(0)
	global_store_dwordx4 v[2:3], v[6:9], off sc1
	v_mov_b64_e32 v[2:3], s[40:41]
	s_load_dwordx2 s[100:101], s[40:41], 0x140
	s_waitcnt lgkmcnt(0)
	v_mov_b32_e32 v2, s100
	v_mov_b32_e32 v3, s101
.LBB0_620:
	s_or_b64 exec, exec, s[4:5]
	v_add_u32_e32 v6, 0x600, v0
	v_ashrrev_i32_e32 v4, 31, v6
	v_lshrrev_b32_e32 v4, 28, v4
	v_add_u32_e32 v4, v6, v4
	v_ashrrev_i32_e32 v7, 4, v4
	v_lshlrev_b32_e32 v5, 1, v7
	v_ashrrev_i32_e32 v4, 10, v4
	v_and_b32_e32 v5, 0x7e, v5
	v_add3_u32 v4, v4, s19, v5
	v_ashrrev_i32_e32 v5, 31, v4
	v_lshlrev_b64 v[4:5], 16, v[4:5]
	s_waitcnt lgkmcnt(0)
	v_lshl_add_u64 v[4:5], v[2:3], 0, v[4:5]
	v_lshl_add_u64 v[4:5], v[4:5], 0, s[94:95]
	v_cmp_ne_u64_e32 vcc, 0, v[4:5]
	s_and_saveexec_b64 s[4:5], vcc
	s_cbranch_execz .LBB0_622
	v_lshlrev_b32_e32 v2, 4, v7
	v_sub_u32_e32 v10, v6, v2
	v_mul_lo_u32 v2, v7, s23
	v_lshl_add_u32 v2, v10, 4, v2
	ds_read_b128 v[6:9], v2
	s_mov_b32 s1, s95
	v_lshl_add_u64 v[2:3], v[4:5], 0, s[0:1]
	v_lshlrev_b32_e32 v4, 3, v10
	v_ashrrev_i32_e32 v5, 31, v4
	v_lshl_add_u64 v[2:3], v[4:5], 1, v[2:3]
	s_waitcnt lgkmcnt(0)
	global_store_dwordx4 v[2:3], v[6:9], off sc1
	v_mov_b64_e32 v[2:3], s[40:41]
	s_load_dwordx2 s[100:101], s[40:41], 0x140
	s_waitcnt lgkmcnt(0)
	v_mov_b32_e32 v2, s100
	v_mov_b32_e32 v3, s101
.LBB0_622:
	s_or_b64 exec, exec, s[4:5]
	v_add_u32_e32 v0, 0x700, v0
	v_ashrrev_i32_e32 v4, 31, v0
	v_lshrrev_b32_e32 v4, 28, v4
	v_add_u32_e32 v5, v0, v4
	v_ashrrev_i32_e32 v4, 4, v5
	v_lshlrev_b32_e32 v6, 1, v4
	v_ashrrev_i32_e32 v5, 10, v5
	v_and_b32_e32 v6, 0x7e, v6
	v_add3_u32 v6, v5, s19, v6
	v_ashrrev_i32_e32 v7, 31, v6
	v_lshlrev_b64 v[6:7], 16, v[6:7]
	s_waitcnt lgkmcnt(0)
	v_lshl_add_u64 v[2:3], v[2:3], 0, v[6:7]
	v_lshl_add_u64 v[2:3], v[2:3], 0, s[94:95]
	v_cmp_ne_u64_e32 vcc, 0, v[2:3]
	s_and_saveexec_b64 s[4:5], vcc
	s_cbranch_execz .LBB0_607
	v_lshlrev_b32_e32 v5, 4, v4
	v_sub_u32_e32 v0, v0, v5
	v_mul_lo_u32 v4, v4, s23
	v_lshl_add_u32 v4, v0, 4, v4
	ds_read_b128 v[4:7], v4
	s_mov_b32 s1, s95
	v_lshlrev_b32_e32 v8, 3, v0
	v_lshl_add_u64 v[2:3], v[2:3], 0, s[0:1]
	v_ashrrev_i32_e32 v9, 31, v8
	v_lshl_add_u64 v[2:3], v[8:9], 1, v[2:3]
	s_waitcnt lgkmcnt(0)
	global_store_dwordx4 v[2:3], v[4:7], off sc1
	s_branch .LBB0_607

; __device__ __forceinline__ int tid_() { int t = threadIdx.x; asm volatile("" : "+v"(t)); return t; }
; template <int NT, bool BKN, bool MASK = false, bool ROWSS = false, class Epi> ...
;     ...
;   const int t = tid_(), lane = t & 63, wid = t >> 6, wr = wid >> 1, wc = wid & 1, l16 = lane & 15, quad = lane >> 4;
;   const u16* ap[4];
;   const u16* bp[NT];
;   unsigned amask = 0u;
; #pragma unroll
;   for (int i = 0; i < 4; ++i) {
;     const int row = (t >> 3) + 32 * i;
;     const bool v = MASK ? (row < mvalid) : true;
;     amask |= v ? (1u << i) : 0u;
;     int r = v ? row : 0;
;     if (arows) r = arows[r];
;     ap[i] = A + (size_t)r * lda + (t & 7) * 8;
;   }
; #pragma unroll
;   for (int i = 0; i < NT; ++i) {
;     if (!BKN) bp[i] = B + (size_t)((t >> 3) + 32 * i) * ldb + (t & 7) * 8;
;     else { const int c = t + 256 * i; bp[i] = B + (size_t)(c / CPR) * ldb + (c % CPR) * 8; }
;   }
;   const size_t bstep = BKN ? (size_t)64 * ldb : (size_t)64;
;   int nmi = 4;
;   if (MASK) { nmi = (mvalid - wr * 64 + 15) >> 4; nmi = nmi < 0 ? 0 : (nmi > 4 ? 4 : nmi); nmi = __builtin_amdgcn_readfirstlane(nmi); }
; __device__ __forceinline__ void phase_mix_b(const Params& p, int l, bool last, unsigned char* smem) {
;     ...
;     gemm_tile<2, true>(p.M2, 256, nullptr, 128, p.PF + (size_t)(b * 64 + k2) * 2 * 128 * 256 + nq * 64, 256, 256, smem, epi);
.LBB0_685:
	v_mov_b64_e32 v[18:19], s[4:5]
	s_load_dwordx2 s[100:101], s[4:5], 0x100
	s_waitcnt lgkmcnt(0)
	v_mov_b32_e32 v10, s100
	v_mov_b32_e32 v11, s101
	s_load_dwordx2 s[100:101], s[4:5], 0x140
	s_waitcnt lgkmcnt(0)
	v_mov_b32_e32 v12, s100
	v_mov_b32_e32 v13, s101
	v_mov_b32_e32 v4, v187
	s_ashr_i32 s38, s9, 8
	s_nop 0
	v_ashrrev_i32_e32 v2, 3, v4
	v_ashrrev_i32_e32 v7, 31, v4
	v_add_u32_e32 v8, 0x100, v4
	v_lshrrev_b32_e32 v5, 4, v4
	v_and_b32_e32 v29, 15, v4
	v_bfe_u32 v30, v4, 4, 2
	v_bfe_u32 v9, v4, 1, 3
	v_ashrrev_i32_e32 v3, 31, v2
	v_lshrrev_b32_e32 v7, 29, v7
	v_ashrrev_i32_e32 v16, 31, v8
	v_bfe_u32 v28, v4, 6, 1
	v_lshlrev_b32_e32 v6, 4, v4
	v_ashrrev_i32_e32 v31, 7, v4
	v_xor_b32_e32 v17, v5, v4
	v_bitop3_b32 v5, v5, v9, 3 bitop3:0x6c
	v_lshlrev_b32_e32 v20, 7, v29
	v_bitop3_b32 v9, v30, v9, 4 bitop3:0x36
	v_lshlrev_b64 v[14:15], 9, v[2:3]
	v_add_u32_e32 v3, v4, v7
	v_lshrrev_b32_e32 v7, 29, v16
	v_and_b32_e32 v0, 0x70, v6
	v_and_b32_e32 v6, 0xffffff80, v6
	v_lshlrev_b32_e32 v16, 4, v17
	v_lshl_or_b32 v17, v31, 13, v20
	v_lshl_or_b32 v20, v28, 12, v20
	v_lshlrev_b32_e32 v9, 4, v9
	v_ashrrev_i32_e32 v2, 3, v3
	v_and_b32_e32 v21, -8, v3
	v_add_u32_e32 v7, v8, v7
	v_lshlrev_b32_e32 v5, 4, v5
	v_and_or_b32 v36, v16, s14, v6
	v_or_b32_e32 v32, v9, v17
	v_or_b32_e32 v33, v9, v20
	v_ashrrev_i32_e32 v3, 31, v2
	v_sub_u32_e32 v9, v4, v21
	v_ashrrev_i32_e32 v4, 3, v7
	v_and_b32_e32 v16, -8, v7
	v_or_b32_e32 v34, v5, v17
	v_or_b32_e32 v35, v5, v20
	v_and_b32_e32 v17, -8, v2
	v_and_b32_e32 v20, 7, v2
	v_lshlrev_b64 v[6:7], 9, v[2:3]
	v_lshlrev_b32_e32 v2, 3, v9
	v_ashrrev_i32_e32 v5, 31, v4
	v_sub_u32_e32 v16, v8, v16
	v_lshlrev_b32_e32 v21, 9, v9
	v_lshlrev_b32_e32 v22, 5, v9
	v_and_b32_e32 v23, -8, v4
	v_and_b32_e32 v24, 7, v4
	v_lshlrev_b64 v[8:9], 9, v[4:5]
	v_lshlrev_b32_e32 v4, 3, v16
	v_bitop3_b32 v22, v22, v17, 32 bitop3:0x6c
	v_or_b32_e32 v25, v20, v21
	v_or_b32_e32 v26, 2, v2
	v_or_b32_e32 v27, 3, v2
	v_or_b32_e32 v38, 4, v2
	v_or_b32_e32 v39, 5, v2
	v_or_b32_e32 v40, 6, v2
	v_or_b32_e32 v41, 7, v2
	v_lshlrev_b32_e32 v42, 9, v16
	v_lshlrev_b32_e32 v16, 5, v16
	v_add_u32_e32 v21, v22, v21
	v_add_lshl_u32 v37, v25, v22, 1
	v_lshlrev_b32_e32 v22, 6, v26
	v_lshlrev_b32_e32 v25, 2, v26
	v_lshlrev_b32_e32 v26, 6, v27
	v_lshlrev_b32_e32 v27, 2, v27
	v_lshlrev_b32_e32 v43, 6, v38
	v_lshlrev_b32_e32 v38, 2, v38
	v_lshlrev_b32_e32 v44, 6, v39
	v_lshlrev_b32_e32 v39, 2, v39
	v_lshlrev_b32_e32 v45, 6, v40
	v_lshlrev_b32_e32 v40, 2, v40
	v_lshlrev_b32_e32 v46, 6, v41
	v_lshlrev_b32_e32 v41, 2, v41
	v_bitop3_b32 v16, v16, v23, 32 bitop3:0x6c
	v_or_b32_e32 v47, v24, v42
	v_or_b32_e32 v48, 2, v4
	v_or_b32_e32 v49, 3, v4
	s_bfe_u32 s19, s9, 0x60002
	s_and_b32 s0, s18, 0xc0
	s_lshl_b32 s1, s38, 6
	v_or_b32_e32 v50, 4, v4
	v_or_b32_e32 v51, 5, v4
	v_or_b32_e32 v52, 6, v4
	v_or_b32_e32 v53, 7, v4
	v_or_b32_e32 v21, v21, v20
	v_and_b32_e32 v25, 40, v25
	v_and_b32_e32 v27, 40, v27
	v_and_b32_e32 v54, 48, v38
	v_and_b32_e32 v55, 48, v39
	v_and_b32_e32 v40, 56, v40
	v_and_b32_e32 v41, 56, v41
	v_add_u32_e32 v42, v16, v42
	v_add_lshl_u32 v38, v47, v16, 1
	v_lshlrev_b32_e32 v16, 6, v48
	v_lshlrev_b32_e32 v47, 2, v48
	v_lshlrev_b32_e32 v48, 6, v49
	v_lshlrev_b32_e32 v49, 2, v49
	s_lshl_b32 s94, s0, 1
	s_or_b32 s0, s1, s19
	v_lshlrev_b32_e32 v56, 6, v50
	v_lshlrev_b32_e32 v50, 2, v50
	v_lshlrev_b32_e32 v57, 6, v51
	v_lshlrev_b32_e32 v51, 2, v51
	v_lshlrev_b32_e32 v58, 6, v52
	v_lshlrev_b32_e32 v52, 2, v52
	v_lshlrev_b32_e32 v59, 6, v53
	v_lshlrev_b32_e32 v53, 2, v53
	v_lshlrev_b32_e32 v39, 1, v21
	v_xad_u32 v21, v25, v17, v22
	v_xad_u32 v22, v27, v17, v26
	v_xad_u32 v25, v54, v17, v43
	v_xad_u32 v26, v55, v17, v44
	v_xad_u32 v27, v40, v17, v45
	v_xad_u32 v17, v41, v17, v46
	v_or_b32_e32 v40, v42, v24
	v_and_b32_e32 v41, 40, v47
	v_and_b32_e32 v42, 40, v49
	s_ashr_i32 s1, s0, 31
	v_and_b32_e32 v43, 48, v50
	v_and_b32_e32 v44, 48, v51
	v_and_b32_e32 v45, 56, v52
	v_and_b32_e32 v46, 56, v53
	v_or_b32_e32 v21, v21, v20
	v_or_b32_e32 v22, v22, v20
	v_or_b32_e32 v25, v25, v20
	v_or_b32_e32 v26, v26, v20
	v_or_b32_e32 v27, v27, v20
	v_or_b32_e32 v17, v17, v20
	v_xad_u32 v16, v41, v23, v16
	v_xad_u32 v20, v42, v23, v48
	s_lshl_b64 s[0:1], s[0:1], 17
	v_xad_u32 v47, v43, v23, v56
	v_xad_u32 v48, v44, v23, v57
	v_xad_u32 v49, v45, v23, v58
	v_xad_u32 v23, v46, v23, v59
	v_lshlrev_b32_e32 v46, 1, v17
	v_or_b32_e32 v16, v16, v24
	v_or_b32_e32 v17, v20, v24
	v_lshlrev_b32_e32 v41, 1, v21
	v_or_b32_e32 v20, v47, v24
	v_or_b32_e32 v21, v48, v24
	v_lshlrev_b32_e32 v47, 1, v16
	v_lshlrev_b32_e32 v48, 1, v17
	s_waitcnt lgkmcnt(0)
	v_lshl_add_u64 v[12:13], v[12:13], 0, s[0:1]
	v_lshl_add_u64 v[16:17], v[10:11], 0, v[0:1]
	v_lshlrev_b32_e32 v42, 1, v22
	v_lshlrev_b32_e32 v43, 1, v25
	v_or_b32_e32 v22, v49, v24
	v_or_b32_e32 v23, v23, v24
	v_lshl_add_u64 v[10:11], v[12:13], 0, s[94:95]
	v_lshl_add_u64 v[24:25], v[16:17], 0, v[14:15]
	v_lshl_add_u64 v[6:7], v[10:11], 0, v[6:7]
	v_lshl_add_u64 v[8:9], v[10:11], 0, v[8:9]
	v_add_co_u32_e32 v10, vcc, s69, v24
	s_mov_b64 s[0:1], 0xc000
	s_nop 0
	v_addc_co_u32_e32 v11, vcc, 0, v25, vcc
	v_add_co_u32_e32 v12, vcc, s34, v24
	v_lshlrev_b32_e32 v44, 1, v26
	v_lshlrev_b32_e32 v45, 1, v27
	v_lshl_add_u64 v[26:27], v[24:25], 0, s[0:1]
	v_addc_co_u32_e32 v13, vcc, 0, v25, vcc
	s_mov_b32 s0, 0xc000
	v_add_co_u32_e32 v14, vcc, s0, v24
	v_ashrrev_i32_e32 v3, 31, v2
	v_ashrrev_i32_e32 v5, 31, v4
	v_addc_co_u32_e32 v15, vcc, 0, v25, vcc
	s_barrier
; template <int NT, bool BKN, bool MASK = false, bool ROWSS = false, class Epi> ...
;     ...
;   GEMM_LOAD(ra0, rb0, 0);
;   GEMM_LOAD(ra1, rb1, 1);
;   GEMM_STORE(ra0, rb0, 0);
;   GEMM_LOAD(ra0, rb0, (2 < nkm1 ? 2 : nkm1));
;   __syncthreads();
;   for (int kt = 0; kt < nk - 2; kt += 2) {
;     GEMM_COMPUTE(0);
;     GEMM_STORE(ra1, rb1, 1);
;     GEMM_LOAD(ra1, rb1, kt + 3);
;     __syncthreads();
	v_lshlrev_b32_e32 v49, 1, v20
	v_lshlrev_b32_e32 v50, 1, v21
	v_lshlrev_b32_e32 v51, 1, v22
	v_lshlrev_b32_e32 v52, 1, v23
	v_lshl_add_u64 v[20:21], v[24:25], 0, s[62:63]
	v_lshl_add_u64 v[22:23], v[24:25], 0, s[10:11]
	global_load_dwordx4 v[54:57], v[24:25], off
	global_load_dwordx4 v[58:61], v[24:25], off offset:128
	v_lshl_add_u64 v[110:111], v[2:3], 1, v[6:7]
	v_lshl_add_u64 v[112:113], v[4:5], 1, v[8:9]
	global_load_dwordx4 v[62:65], v[10:11], off
	global_load_dwordx4 v[66:69], v[12:13], off
	global_load_dwordx4 v[70:73], v[14:15], off
	global_load_dwordx4 v[74:77], v[20:21], off offset:128
	global_load_dwordx4 v[2:5], v[24:25], off offset:256
	global_load_dwordx4 v[78:81], v[22:23], off offset:128
	global_load_dwordx4 v[6:9], v[20:21], off offset:256
	global_load_dwordx4 v[82:85], v[26:27], off offset:128
	global_load_dwordx4 v[10:13], v[22:23], off offset:256
	global_load_dwordx4 v[14:17], v[26:27], off offset:256
	global_load_dwordx4 v[86:89], v[110:111], off
	global_load_dwordx4 v[90:93], v[112:113], off
	v_add_co_u32_e32 v94, vcc, s34, v110
	v_lshlrev_b32_e32 v40, 1, v40
	s_nop 0
	v_addc_co_u32_e32 v95, vcc, 0, v111, vcc
	v_add_co_u32_e32 v98, vcc, s34, v112
	v_lshlrev_b32_e32 v0, 6, v31
	s_nop 0
	v_addc_co_u32_e32 v99, vcc, 0, v113, vcc
	v_add_co_u32_e32 v102, vcc, s15, v110
	v_lshlrev_b32_e32 v29, 1, v29
	s_nop 0
	v_addc_co_u32_e32 v103, vcc, 0, v111, vcc
	v_add_co_u32_e32 v106, vcc, s15, v112
	s_add_i32 s9, s9, s3
	s_nop 0
	v_addc_co_u32_e32 v107, vcc, 0, v113, vcc
	global_load_dwordx4 v[94:97], v[94:95], off
	s_nop 0
	global_load_dwordx4 v[98:101], v[98:99], off
	s_nop 0
	global_load_dwordx4 v[102:105], v[102:103], off
	s_nop 0
	global_load_dwordx4 v[106:109], v[106:107], off
	s_waitcnt vmcnt(0) lgkmcnt(0)
	ds_write_b128 v36, v[54:57]
	ds_write_b128 v36, v[62:65] offset:4096
	ds_write_b128 v36, v[66:69] offset:8192
	ds_write_b128 v36, v[70:73] offset:12288
	ds_write_b16 v39, v86 offset:16384
	ds_write_b16_d16_hi v37, v86 offset:16512
	ds_write_b16 v41, v87 offset:16384
	ds_write_b16_d16_hi v42, v87 offset:16384
	ds_write_b16 v43, v88 offset:16384
	ds_write_b16_d16_hi v44, v88 offset:16384
	ds_write_b16 v45, v89 offset:16384
	ds_write_b16_d16_hi v46, v89 offset:16384
	ds_write_b16 v40, v90 offset:16384
	ds_write_b16_d16_hi v38, v90 offset:16512
	ds_write_b16 v47, v91 offset:16384
	ds_write_b16_d16_hi v48, v91 offset:16384
	ds_write_b16 v49, v92 offset:16384
	ds_write_b16_d16_hi v50, v92 offset:16384
	ds_write_b16 v51, v93 offset:16384
	ds_write_b16_d16_hi v52, v93 offset:16384
	s_waitcnt lgkmcnt(0)
	s_barrier
	ds_read_b128 v[54:57], v34
	ds_read_b128 v[62:65], v35 offset:16384
	ds_read_b128 v[66:69], v34 offset:2048
	ds_read_b128 v[70:73], v35 offset:18432
	ds_read_b128 v[90:93], v34 offset:4096
	v_add_co_u32_e32 v146, vcc, s55, v110
	ds_read_b128 v[114:117], v34 offset:6144
	ds_read_b128 v[118:121], v32
	ds_read_b128 v[122:125], v32 offset:2048
	v_addc_co_u32_e32 v147, vcc, 0, v111, vcc
	v_add_co_u32_e32 v148, vcc, s55, v112
	ds_read_b128 v[126:129], v32 offset:4096
	ds_read_b128 v[130:133], v32 offset:6144
	ds_read_b128 v[134:137], v33 offset:16384
	ds_read_b128 v[142:145], v33 offset:18432
	ds_write_b128 v36, v[58:61] offset:32768
	ds_write_b128 v36, v[74:77] offset:36864
	ds_write_b128 v36, v[78:81] offset:40960
	ds_write_b128 v36, v[82:85] offset:45056
	v_addc_co_u32_e32 v149, vcc, 0, v113, vcc
	s_waitcnt lgkmcnt(11)
	v_mfma_f32_16x16x32_bf16 v[138:141], v[90:93], v[62:65], 0
	global_load_dwordx4 v[74:77], v[24:25], off offset:384
	global_load_dwordx4 v[78:81], v[20:21], off offset:384
	s_nop 0
	global_load_dwordx4 v[20:23], v[22:23], off offset:384
	s_nop 0
	global_load_dwordx4 v[24:27], v[26:27], off offset:384
	s_add_i32 s18, s18, s54
	v_mfma_f32_16x16x32_bf16 v[58:61], v[90:93], v[70:73], 0
	global_load_dwordx4 v[82:85], v[146:147], off
	global_load_dwordx4 v[90:93], v[148:149], off
	ds_write_b16 v39, v94 offset:49152
	ds_write_b16_d16_hi v37, v94 offset:49280
	ds_write_b16 v41, v95 offset:49152
	ds_write_b16_d16_hi v42, v95 offset:49152
	v_mfma_f32_16x16x32_bf16 v[86:89], v[54:57], v[62:65], 0
	ds_write_b16 v43, v96 offset:49152
	ds_write_b16_d16_hi v44, v96 offset:49152
	ds_write_b16 v45, v97 offset:49152
	ds_write_b16_d16_hi v46, v97 offset:49152
	ds_write_b16 v40, v98 offset:49152
	ds_write_b16_d16_hi v38, v98 offset:49280
	ds_write_b16 v47, v99 offset:49152
	ds_write_b16_d16_hi v48, v99 offset:49152
	ds_write_b16 v49, v100 offset:49152
	v_mfma_f32_16x16x32_bf16 v[54:57], v[54:57], v[70:73], 0
	ds_write_b16_d16_hi v50, v100 offset:49152
	ds_write_b16 v51, v101 offset:49152
	ds_write_b16_d16_hi v52, v101 offset:49152
	s_waitcnt lgkmcnt(0)
	s_barrier
; template <int NT, bool BKN, bool MASK = false, bool ROWSS = false, class Epi> ...
;     ...
;   for (int kt = 0; kt < nk - 2; kt += 2) {
;     GEMM_COMPUTE(0);
;     GEMM_STORE(ra1, rb1, 1);
;     GEMM_LOAD(ra1, rb1, kt + 3);
;     __syncthreads();
;     GEMM_COMPUTE(1);
;     GEMM_STORE(ra0, rb0, 0);
;     GEMM_LOAD(ra0, rb0, (kt + 4 < nkm1 ? kt + 4 : nkm1));
;     __syncthreads();
;   }
;   GEMM_COMPUTE(0);
;   GEMM_STORE(ra1, rb1, 1);
	v_mfma_f32_16x16x32_bf16 v[110:113], v[66:69], v[62:65], 0
	ds_read_b128 v[98:101], v34 offset:32768
	v_mfma_f32_16x16x32_bf16 v[66:69], v[66:69], v[70:73], 0
	v_mfma_f32_16x16x32_bf16 v[62:65], v[114:117], v[62:65], 0
	v_mfma_f32_16x16x32_bf16 v[70:73], v[114:117], v[70:73], 0
	v_mfma_f32_16x16x32_bf16 v[86:89], v[118:121], v[134:137], v[86:89]
	v_mfma_f32_16x16x32_bf16 v[54:57], v[118:121], v[142:145], v[54:57]
	v_mfma_f32_16x16x32_bf16 v[110:113], v[122:125], v[134:137], v[110:113]
	v_mfma_f32_16x16x32_bf16 v[66:69], v[122:125], v[142:145], v[66:69]
	ds_read_b128 v[114:117], v35 offset:49152
	ds_read_b128 v[118:121], v34 offset:34816
	ds_read_b128 v[122:125], v35 offset:51200
	s_waitcnt lgkmcnt(0)
	v_mfma_f32_16x16x32_bf16 v[86:89], v[98:101], v[114:117], v[86:89]
	v_mfma_f32_16x16x32_bf16 v[54:57], v[98:101], v[122:125], v[54:57]
	v_mfma_f32_16x16x32_bf16 v[98:101], v[118:121], v[114:117], v[110:113]
	v_mfma_f32_16x16x32_bf16 v[66:69], v[118:121], v[122:125], v[66:69]
	s_nop 1
	ds_read_b128 v[110:113], v34 offset:36864
	ds_read_b128 v[118:121], v34 offset:38912
	v_mfma_f32_16x16x32_bf16 v[94:97], v[126:129], v[134:137], v[138:141]
	v_mfma_f32_16x16x32_bf16 v[58:61], v[126:129], v[142:145], v[58:61]
	v_mfma_f32_16x16x32_bf16 v[62:65], v[130:133], v[134:137], v[62:65]
	v_mfma_f32_16x16x32_bf16 v[70:73], v[130:133], v[142:145], v[70:73]
	ds_read_b128 v[126:129], v32 offset:32768
	ds_read_b128 v[130:133], v32 offset:34816
	s_waitcnt lgkmcnt(0)
	v_mfma_f32_16x16x32_bf16 v[94:97], v[110:113], v[114:117], v[94:97]
	v_mfma_f32_16x16x32_bf16 v[58:61], v[110:113], v[122:125], v[58:61]
	ds_read_b128 v[110:113], v32 offset:36864
	ds_read_b128 v[134:137], v32 offset:38912
	ds_read_b128 v[138:141], v33 offset:49152
	v_mfma_f32_16x16x32_bf16 v[62:65], v[118:121], v[114:117], v[62:65]
	ds_read_b128 v[114:117], v33 offset:51200
	ds_write_b128 v36, v[2:5]
	ds_write_b128 v36, v[6:9] offset:4096
	ds_write_b128 v36, v[10:13] offset:8192
	ds_write_b128 v36, v[14:17] offset:12288
	ds_write_b16 v39, v102 offset:16384
	v_mfma_f32_16x16x32_bf16 v[2:5], v[118:121], v[122:125], v[70:73]
	ds_write_b16_d16_hi v37, v102 offset:16512
	ds_write_b16 v41, v103 offset:16384
	ds_write_b16_d16_hi v42, v103 offset:16384
	ds_write_b16 v43, v104 offset:16384
	ds_write_b16_d16_hi v44, v104 offset:16384
	ds_write_b16 v45, v105 offset:16384
	ds_write_b16_d16_hi v46, v105 offset:16384
	ds_write_b16 v40, v106 offset:16384
	ds_write_b16_d16_hi v38, v106 offset:16512
	ds_write_b16 v47, v107 offset:16384
	ds_write_b16_d16_hi v48, v107 offset:16384
	ds_write_b16 v49, v108 offset:16384
	ds_write_b16_d16_hi v50, v108 offset:16384
	ds_write_b16 v51, v109 offset:16384
	ds_write_b16_d16_hi v52, v109 offset:16384
	s_waitcnt lgkmcnt(0)
	s_barrier
	ds_read_b128 v[70:73], v34
	v_mfma_f32_16x16x32_bf16 v[6:9], v[126:129], v[138:141], v[86:89]
	v_mfma_f32_16x16x32_bf16 v[10:13], v[126:129], v[114:117], v[54:57]
	v_mfma_f32_16x16x32_bf16 v[14:17], v[130:133], v[138:141], v[98:101]
	v_mfma_f32_16x16x32_bf16 v[54:57], v[130:133], v[114:117], v[66:69]
	v_mfma_f32_16x16x32_bf16 v[66:69], v[110:113], v[138:141], v[94:97]
	ds_read_b128 v[86:89], v35 offset:16384
	s_nop 1
	ds_read_b128 v[94:97], v34 offset:2048
	ds_read_b128 v[98:101], v35 offset:18432
	v_mfma_f32_16x16x32_bf16 v[58:61], v[110:113], v[114:117], v[58:61]
	s_waitcnt lgkmcnt(0)
	v_mfma_f32_16x16x32_bf16 v[6:9], v[70:73], v[86:89], v[6:9]
	v_mfma_f32_16x16x32_bf16 v[10:13], v[70:73], v[98:101], v[10:13]
	v_mfma_f32_16x16x32_bf16 v[14:17], v[94:97], v[86:89], v[14:17]
	v_mfma_f32_16x16x32_bf16 v[54:57], v[94:97], v[98:101], v[54:57]
	ds_read_b128 v[70:73], v34 offset:4096
	ds_read_b128 v[94:97], v34 offset:6144
	v_mfma_f32_16x16x32_bf16 v[62:65], v[134:137], v[138:141], v[62:65]
	v_mfma_f32_16x16x32_bf16 v[2:5], v[134:137], v[114:117], v[2:5]
	s_waitcnt lgkmcnt(0)
	v_mfma_f32_16x16x32_bf16 v[66:69], v[70:73], v[86:89], v[66:69]
	v_mfma_f32_16x16x32_bf16 v[58:61], v[70:73], v[98:101], v[58:61]
	ds_read_b128 v[70:73], v32
	v_mfma_f32_16x16x32_bf16 v[62:65], v[94:97], v[86:89], v[62:65]
	v_mfma_f32_16x16x32_bf16 v[2:5], v[94:97], v[98:101], v[2:5]
	ds_read_b128 v[86:89], v33 offset:16384
	ds_read_b128 v[94:97], v32 offset:2048
	ds_read_b128 v[98:101], v33 offset:18432
	s_waitcnt lgkmcnt(0)
	v_mfma_f32_16x16x32_bf16 v[6:9], v[70:73], v[86:89], v[6:9]
	v_mfma_f32_16x16x32_bf16 v[10:13], v[70:73], v[98:101], v[10:13]
	v_mfma_f32_16x16x32_bf16 v[14:17], v[94:97], v[86:89], v[14:17]
	v_mfma_f32_16x16x32_bf16 v[54:57], v[94:97], v[98:101], v[54:57]
	ds_read_b128 v[70:73], v32 offset:4096
	ds_read_b128 v[94:97], v32 offset:6144
	s_waitcnt vmcnt(0)
	ds_write_b128 v36, v[74:77] offset:32768
	ds_write_b128 v36, v[78:81] offset:36864
	ds_write_b128 v36, v[20:23] offset:40960
	ds_write_b128 v36, v[24:27] offset:45056
	ds_write_b16 v39, v82 offset:49152
	ds_write_b16_d16_hi v37, v82 offset:49280
	ds_write_b16 v41, v83 offset:49152
	ds_write_b16_d16_hi v42, v83 offset:49152
	ds_write_b16 v43, v84 offset:49152
	ds_write_b16_d16_hi v44, v84 offset:49152
	ds_write_b16 v45, v85 offset:49152
	ds_write_b16_d16_hi v46, v85 offset:49152
	ds_write_b16 v40, v90 offset:49152
	ds_write_b16_d16_hi v38, v90 offset:49280
	ds_write_b16 v47, v91 offset:49152
	ds_write_b16_d16_hi v48, v91 offset:49152
	ds_write_b16 v49, v92 offset:49152
	ds_write_b16_d16_hi v50, v92 offset:49152
	ds_write_b16 v51, v93 offset:49152
	ds_write_b16_d16_hi v52, v93 offset:49152
	s_waitcnt lgkmcnt(0)
	s_barrier
; template <int NT, bool BKN, bool MASK = false, bool ROWSS = false, class Epi> ...
;     ...
;     GEMM_COMPUTE(1);
;     GEMM_STORE(ra0, rb0, 0);
;     GEMM_LOAD(ra0, rb0, (kt + 4 < nkm1 ? kt + 4 : nkm1));
;     __syncthreads();
;   }
;   GEMM_COMPUTE(0);
;   GEMM_STORE(ra1, rb1, 1);
;   __syncthreads();
;   GEMM_COMPUTE(1);
; __device__ __forceinline__ void phase_mix_b(const Params& p, int l, bool last, unsigned char* smem) {
;     ...
;       auto vf = [&](int, int, float v) { return v * 0.001381067932004976f; };
	ds_read_b128 v[20:23], v34 offset:32768
	ds_read_b128 v[24:27], v35 offset:49152
	ds_read_b128 v[36:39], v34 offset:34816
	ds_read_b128 v[40:43], v35 offset:51200
	s_waitcnt lgkmcnt(2)
	v_mfma_f32_16x16x32_bf16 v[6:9], v[20:23], v[24:27], v[6:9]
	s_waitcnt lgkmcnt(0)
	v_mfma_f32_16x16x32_bf16 v[10:13], v[20:23], v[40:43], v[10:13]
	v_mfma_f32_16x16x32_bf16 v[14:17], v[36:39], v[24:27], v[14:17]
	v_mfma_f32_16x16x32_bf16 v[20:23], v[36:39], v[40:43], v[54:57]
	ds_read_b128 v[36:39], v34 offset:36864
	ds_read_b128 v[44:47], v34 offset:38912
	s_nop 0
	ds_read_b128 v[52:55], v32 offset:32768
	v_mfma_f32_16x16x32_bf16 v[66:69], v[70:73], v[86:89], v[66:69]
	v_mfma_f32_16x16x32_bf16 v[58:61], v[70:73], v[98:101], v[58:61]
	v_mfma_f32_16x16x32_bf16 v[62:65], v[94:97], v[86:89], v[62:65]
	v_mfma_f32_16x16x32_bf16 v[2:5], v[94:97], v[98:101], v[2:5]
	s_waitcnt lgkmcnt(2)
	v_mfma_f32_16x16x32_bf16 v[48:51], v[36:39], v[24:27], v[66:69]
	v_mfma_f32_16x16x32_bf16 v[34:37], v[36:39], v[40:43], v[58:61]
	s_waitcnt lgkmcnt(1)
	v_mfma_f32_16x16x32_bf16 v[24:27], v[44:47], v[24:27], v[62:65]
	s_nop 0
	v_mov_b32_e32 v60, v187
	v_mfma_f32_16x16x32_bf16 v[2:5], v[44:47], v[40:43], v[2:5]
	ds_read_b128 v[38:41], v33 offset:49152
	ds_read_b128 v[42:45], v32 offset:34816
	ds_read_b128 v[56:59], v33 offset:51200
	s_waitcnt lgkmcnt(2)
	v_mfma_f32_16x16x32_bf16 v[6:9], v[52:55], v[38:41], v[6:9]
	s_waitcnt lgkmcnt(0)
	v_mfma_f32_16x16x32_bf16 v[10:13], v[52:55], v[56:59], v[10:13]
	v_mfma_f32_16x16x32_bf16 v[14:17], v[42:45], v[38:41], v[14:17]
	v_mfma_f32_16x16x32_bf16 v[20:23], v[42:45], v[56:59], v[20:23]
	ds_read_b128 v[42:45], v32 offset:36864
	ds_read_b128 v[52:55], v32 offset:38912
	v_lshl_or_b32 v32, v30, 2, v0
	v_lshl_or_b32 v0, v28, 6, v29
	s_waitcnt lgkmcnt(1)
	v_mfma_f32_16x16x32_bf16 v[46:49], v[42:45], v[38:41], v[48:51]
	v_mad_u64_u32 v[32:33], s[0:1], v32, s96, v[0:1]
	v_mul_f32_e32 v0, 0x3ab504f3, v6
	v_mfma_f32_16x16x32_bf16 v[28:31], v[42:45], v[56:59], v[34:37]
	v_mul_f32_e32 v6, 0x3ab504f3, v7
	v_mul_f32_e32 v7, 0x3ab504f3, v8
	v_mul_f32_e32 v8, 0x3ab504f3, v9
	s_waitcnt lgkmcnt(0)
	v_mfma_f32_16x16x32_bf16 v[24:27], v[52:55], v[38:41], v[24:27]
	v_mul_f32_e32 v9, 0x3ab504f3, v10
	v_mul_f32_e32 v10, 0x3ab504f3, v11
	v_mul_f32_e32 v11, 0x3ab504f3, v12
	v_mfma_f32_16x16x32_bf16 v[2:5], v[52:55], v[56:59], v[2:5]
	v_mul_f32_e32 v12, 0x3ab504f3, v13
	v_mul_f32_e32 v13, 0x3ab504f3, v14
	v_mul_f32_e32 v14, 0x3ab504f3, v15
	v_mul_f32_e32 v15, 0x3ab504f3, v16
	v_mul_f32_e32 v16, 0x3ab504f3, v17
	v_mul_f32_e32 v17, 0x3ab504f3, v20
	v_mul_f32_e32 v20, 0x3ab504f3, v21
	v_mul_f32_e32 v21, 0x3ab504f3, v22
	v_mul_f32_e32 v22, 0x3ab504f3, v23
	v_mul_f32_e32 v23, 0x3ab504f3, v46
	v_mul_f32_e32 v33, 0x3ab504f3, v47
	v_mul_f32_e32 v34, 0x3ab504f3, v48
	v_mul_f32_e32 v35, 0x3ab504f3, v49
	v_mul_f32_e32 v28, 0x3ab504f3, v28
	v_mul_f32_e32 v29, 0x3ab504f3, v29
	v_mul_f32_e32 v30, 0x3ab504f3, v30
	v_mul_f32_e32 v31, 0x3ab504f3, v31
	v_mul_f32_e32 v24, 0x3ab504f3, v24
	v_mul_f32_e32 v25, 0x3ab504f3, v25
	v_mul_f32_e32 v26, 0x3ab504f3, v26
	v_mul_f32_e32 v27, 0x3ab504f3, v27
	v_mul_f32_e32 v2, 0x3ab504f3, v2
	v_mul_f32_e32 v3, 0x3ab504f3, v3
	v_mul_f32_e32 v4, 0x3ab504f3, v4
	v_mul_f32_e32 v5, 0x3ab504f3, v5
	v_cvt_pk_bf16_f32 v0, v0, s0
	v_cvt_pk_bf16_f32 v6, v6, s0
	v_cvt_pk_bf16_f32 v7, v7, s0
	s_barrier
; __device__ __forceinline__ u16 f2bf(float f) { return (u16)(pack2(f, 0.f) & 0xffffu); }
; __device__ __forceinline__ int tid_() { int t = threadIdx.x; asm volatile("" : "+v"(t)); return t; }
; template <int NT, class VF, class RP>
; __device__ __forceinline__ void epi_staged_bf16(f32x4 (&acc)[4][NT], int r0, int c0, unsigned char* smem, VF vf, RP rowptr) {
;   constexpr int BN = NT * 32, PITCH = BN + 8, CPR = BN / 8;
;   u16* Ts = (u16*)smem;
;   const int t = tid_();
;   __syncthreads();
; #pragma unroll
;   for (int mi = 0; mi < 4; ++mi)
; #pragma unroll
;     for (int ni = 0; ni < NT; ++ni)
; #pragma unroll
;       for (int j = 0; j < 4; ++j) {
;         const int r = r0 + mi * 16 + j, c = c0 + ni * 16;
;         Ts[r * PITCH + c] = f2bf(vf(r, c, acc[mi][ni][j]));
;       }
;   __syncthreads();
; #pragma unroll
;   for (int i = 0; i < CPR / 2; ++i) {
;     const int c = t + 256 * i, row = c / CPR, ch = c % CPR;
;     u16* d = rowptr(row);
;     if (d) *(u32x4*)(d + ch * 8) = *(const u32x4*)(Ts + row * PITCH + ch * 8);
;   }
; __device__ __forceinline__ void phase_mix_b(const Params& p, int l, bool last, unsigned char* smem) {
;     ...
;       auto rp = [&](int k1) -> u16* { return p.YM + (size_t)(b * SEQ + 64 * k1 + k2) * 1024 + 256 + nq * 64; };
	v_cvt_pk_bf16_f32 v8, v8, s0
	v_cvt_pk_bf16_f32 v9, v9, s0
	v_cvt_pk_bf16_f32 v10, v10, s0
	v_cvt_pk_bf16_f32 v11, v11, s0
	v_cvt_pk_bf16_f32 v12, v12, s0
	v_cvt_pk_bf16_f32 v13, v13, s0
	v_cvt_pk_bf16_f32 v14, v14, s0
	v_cvt_pk_bf16_f32 v15, v15, s0
	v_cvt_pk_bf16_f32 v16, v16, s0
	v_cvt_pk_bf16_f32 v17, v17, s0
	v_cvt_pk_bf16_f32 v20, v20, s0
	v_cvt_pk_bf16_f32 v21, v21, s0
	v_cvt_pk_bf16_f32 v22, v22, s0
	v_cvt_pk_bf16_f32 v23, v23, s0
	v_cvt_pk_bf16_f32 v33, v33, s0
	v_cvt_pk_bf16_f32 v34, v34, s0
	v_cvt_pk_bf16_f32 v35, v35, s0
	v_cvt_pk_bf16_f32 v28, v28, s0
	v_cvt_pk_bf16_f32 v29, v29, s0
	v_cvt_pk_bf16_f32 v30, v30, s0
	v_cvt_pk_bf16_f32 v31, v31, s0
	v_cvt_pk_bf16_f32 v24, v24, s0
	v_cvt_pk_bf16_f32 v25, v25, s0
	v_cvt_pk_bf16_f32 v26, v26, s0
	v_cvt_pk_bf16_f32 v27, v27, s0
	v_cvt_pk_bf16_f32 v2, v2, s0
	v_cvt_pk_bf16_f32 v3, v3, s0
	v_cvt_pk_bf16_f32 v4, v4, s0
	v_cvt_pk_bf16_f32 v5, v5, s0
	ds_write_b16 v32, v0
	ds_write_b16 v32, v6 offset:144
	ds_write_b16 v32, v7 offset:288
	ds_write_b16 v32, v8 offset:432
	ds_write_b16 v32, v9 offset:32
	ds_write_b16 v32, v10 offset:176
	ds_write_b16 v32, v11 offset:320
	ds_write_b16 v32, v12 offset:464
	ds_write_b16 v32, v13 offset:2304
	ds_write_b16 v32, v14 offset:2448
	ds_write_b16 v32, v15 offset:2592
	ds_write_b16 v32, v16 offset:2736
	ds_write_b16 v32, v17 offset:2336
	ds_write_b16 v32, v20 offset:2480
	ds_write_b16 v32, v21 offset:2624
	ds_write_b16 v32, v22 offset:2768
	ds_write_b16 v32, v23 offset:4608
	ds_write_b16 v32, v33 offset:4752
	ds_write_b16 v32, v34 offset:4896
	ds_write_b16 v32, v35 offset:5040
	ds_write_b16 v32, v28 offset:4640
	ds_write_b16 v32, v29 offset:4784
	ds_write_b16 v32, v30 offset:4928
	ds_write_b16 v32, v31 offset:5072
	ds_write_b16 v32, v24 offset:6912
	ds_write_b16 v32, v25 offset:7056
	ds_write_b16 v32, v26 offset:7200
	ds_write_b16 v32, v27 offset:7344
	ds_write_b16 v32, v2 offset:6944
	ds_write_b16 v32, v3 offset:7088
	ds_write_b16 v32, v4 offset:7232
	ds_write_b16 v32, v5 offset:7376
	s_waitcnt lgkmcnt(0)
	s_barrier
	global_load_dwordx2 v[6:7], v[18:19], off offset:296
	v_ashrrev_i32_e32 v0, 31, v60
	v_lshrrev_b32_e32 v0, 29, v0
	v_add_u32_e32 v0, v60, v0
	s_lshl_b32 s0, s38, 13
	v_ashrrev_i32_e32 v2, 3, v0
	v_and_b32_e32 v0, -8, v0
	v_lshl_add_u32 v3, v2, 6, s0
	v_sub_u32_e32 v0, v60, v0
	v_mul_lo_u32 v2, v2, s96
	v_or_b32_e32 v8, s19, v3
	v_lshlrev_b32_e32 v10, 3, v0
	v_lshl_add_u32 v0, v0, 4, v2
	v_ashrrev_i32_e32 v9, 31, v8
	ds_read_b128 v[2:5], v0
	v_lshlrev_b64 v[8:9], 11, v[8:9]
	v_ashrrev_i32_e32 v11, 31, v10
	v_add_u32_e32 v0, 0x100, v60
	s_cmp_ge_i32 s9, s8
	s_waitcnt vmcnt(0) lgkmcnt(0)
	v_mov_b32_e32 v12, v6
	v_mov_b32_e32 v13, v7
	v_lshl_add_u64 v[6:7], v[6:7], 0, v[8:9]
	v_lshl_add_u64 v[6:7], v[6:7], 0, s[94:95]
	v_lshl_add_u64 v[6:7], v[10:11], 1, v[6:7]
	global_store_dwordx4 v[6:7], v[2:5], off offset:512 sc1
	v_mov_b32_e32 v6, v12
	v_mov_b32_e32 v7, v13
	s_nop 0
	v_ashrrev_i32_e32 v2, 31, v0
	v_lshrrev_b32_e32 v2, 29, v2
	v_add_u32_e32 v2, v0, v2
	v_ashrrev_i32_e32 v3, 3, v2
	v_and_b32_e32 v2, -8, v2
	v_lshl_add_u32 v4, v3, 6, s0
	v_sub_u32_e32 v0, v0, v2
	v_mul_lo_u32 v2, v3, s96
	v_or_b32_e32 v8, s19, v4
	v_lshlrev_b32_e32 v10, 3, v0
	v_lshl_add_u32 v0, v0, 4, v2
	v_ashrrev_i32_e32 v9, 31, v8
	ds_read_b128 v[2:5], v0
	v_lshlrev_b64 v[8:9], 11, v[8:9]
	v_ashrrev_i32_e32 v11, 31, v10
	v_add_u32_e32 v0, 0x200, v60
	s_waitcnt lgkmcnt(0)
	v_lshl_add_u64 v[6:7], v[6:7], 0, v[8:9]
	v_lshl_add_u64 v[6:7], v[6:7], 0, s[94:95]
	v_lshl_add_u64 v[6:7], v[10:11], 1, v[6:7]
	global_store_dwordx4 v[6:7], v[2:5], off offset:512 sc1
	v_mov_b32_e32 v6, v12
	v_mov_b32_e32 v7, v13
	s_nop 0
	v_ashrrev_i32_e32 v2, 31, v0
	v_lshrrev_b32_e32 v2, 29, v2
	v_add_u32_e32 v2, v0, v2
	v_ashrrev_i32_e32 v3, 3, v2
	v_and_b32_e32 v2, -8, v2
	v_lshl_add_u32 v4, v3, 6, s0
	v_sub_u32_e32 v0, v0, v2
	v_mul_lo_u32 v2, v3, s96
	v_or_b32_e32 v8, s19, v4
	v_lshlrev_b32_e32 v10, 3, v0
	v_lshl_add_u32 v0, v0, 4, v2
	v_ashrrev_i32_e32 v9, 31, v8
	ds_read_b128 v[2:5], v0
	v_lshlrev_b64 v[8:9], 11, v[8:9]
	v_ashrrev_i32_e32 v11, 31, v10
	v_add_u32_e32 v0, 0x300, v60
	s_waitcnt lgkmcnt(0)
	v_lshl_add_u64 v[6:7], v[6:7], 0, v[8:9]
	v_lshl_add_u64 v[6:7], v[6:7], 0, s[94:95]
	v_lshl_add_u64 v[6:7], v[10:11], 1, v[6:7]
	global_store_dwordx4 v[6:7], v[2:5], off offset:512 sc1
	v_mov_b32_e32 v6, v12
	v_mov_b32_e32 v7, v13
	s_nop 0
	v_ashrrev_i32_e32 v2, 31, v0
	v_lshrrev_b32_e32 v2, 29, v2
	v_add_u32_e32 v2, v0, v2
	v_ashrrev_i32_e32 v3, 3, v2
	v_and_b32_e32 v2, -8, v2
	v_lshl_add_u32 v4, v3, 6, s0
	v_sub_u32_e32 v0, v0, v2
	v_mul_lo_u32 v2, v3, s96
	v_or_b32_e32 v8, s19, v4
	v_lshlrev_b32_e32 v10, 3, v0
	v_lshl_add_u32 v0, v0, 4, v2
	v_ashrrev_i32_e32 v9, 31, v8
	ds_read_b128 v[2:5], v0
	v_lshlrev_b64 v[8:9], 11, v[8:9]
	v_ashrrev_i32_e32 v11, 31, v10
	s_waitcnt lgkmcnt(0)
	v_lshl_add_u64 v[6:7], v[6:7], 0, v[8:9]
	v_lshl_add_u64 v[6:7], v[6:7], 0, s[94:95]
	v_lshl_add_u64 v[6:7], v[10:11], 1, v[6:7]
	global_store_dwordx4 v[6:7], v[2:5], off offset:512 sc1
	s_cbranch_scc0 .LBB0_685

; __device__ __forceinline__ u16 f2bf(float f) { return (u16)(pack2(f, 0.f) & 0xffffu); }
; __device__ __forceinline__ void phase_mix_b(const Params& p, int l, bool last, unsigned char* smem) {
;     ...
;         const float rstd = rsqrtf(ss * (1.f / 192.f) + 1e-6f);
;         const float* qn = p.q_norm + l * 192;
;         v0 *= rstd * qn[lane]; v1 *= rstd * qn[lane + 64]; v2 *= rstd * qn[lane + 128];
;         if (lat) {
;           const float xp = __shfl_xor(v2, 16);
;           v2 = hi ? (xp * sn + v2 * cs) : (v2 * cs - xp * sn);
;     ...
;           const float xp = __shfl_xor(v2, 16);
;           v2 = hi ? (xp * sn + v2 * cs) : (v2 * cs - xp * sn);
;         }
;         u16* o = p.Kb + ((size_t)(b * 4 + h) * NPOS + pos) * 192;
;         o[lane] = f2bf(v0); o[lane + 64] = f2bf(v1); o[lane + 128] = f2bf(v2);
.Lmb_kpack:
	v_cvt_pk_bf16_f32 v230, v26, v27
	v_cvt_pk_bf16_f32 v231, v28, v29
	v_cvt_pk_bf16_f32 v232, v30, v31
	v_cvt_pk_bf16_f32 v233, v32, v33
	v_cvt_pk_bf16_f32 v234, v206, v207
	v_cvt_pk_bf16_f32 v235, v208, v209
	global_store_dwordx4 v154, v[230:233], s[18:19] sc1
	global_store_dwordx2 v155, v[234:235], s[18:19]
	s_cmp_eq_u32 s41, 0
	s_cbranch_scc1 .Lmb_next
	v_mul_f32_e32 v210, v156, v38
	v_mul_f32_e32 v14, v210, v14
	v_mul_f32_e32 v210, v157, v38
	v_mul_f32_e32 v15, v210, v15
	v_mul_f32_e32 v210, v158, v38
	v_mul_f32_e32 v16, v210, v16
	v_mul_f32_e32 v210, v159, v38
	v_mul_f32_e32 v17, v210, v17
	v_mul_f32_e32 v210, v160, v38
	v_mul_f32_e32 v18, v210, v18
	v_mul_f32_e32 v210, v161, v38
	v_mul_f32_e32 v19, v210, v19
	v_mul_f32_e32 v210, v162, v38
	v_mul_f32_e32 v20, v210, v20
	v_mul_f32_e32 v210, v163, v38
	v_mul_f32_e32 v21, v210, v21
	v_mul_f32_e32 v210, v164, v38
	v_mul_f32_e32 v22, v210, v22
	v_mul_f32_e32 v210, v165, v38
	v_mul_f32_e32 v23, v210, v23
	v_mul_f32_e32 v210, v166, v38
	v_mul_f32_e32 v24, v210, v24
	v_mul_f32_e32 v210, v167, v38
	v_mul_f32_e32 v25, v210, v25
	s_cmp_eq_u32 s40, 0
	s_cbranch_scc1 .Lmb_qplain
	v_mul_f32_e32 v202, v22, v191
	v_mul_f32_e32 v203, v23, v192
	v_mul_f32_e32 v204, v24, v193
	v_mul_f32_e32 v205, v25, v194
	v_fmac_f32_dpp v202, v22, v195 row_shl:4 row_mask:0xf bank_mask:0x5
	v_fmac_f32_dpp v202, v22, v195 row_shr:4 row_mask:0xf bank_mask:0xa
	v_fmac_f32_dpp v203, v23, v196 row_shl:4 row_mask:0xf bank_mask:0x5
	v_fmac_f32_dpp v203, v23, v196 row_shr:4 row_mask:0xf bank_mask:0xa
	v_fmac_f32_dpp v204, v24, v197 row_shl:4 row_mask:0xf bank_mask:0x5
	v_fmac_f32_dpp v204, v24, v197 row_shr:4 row_mask:0xf bank_mask:0xa
	v_fmac_f32_dpp v205, v25, v198 row_shl:4 row_mask:0xf bank_mask:0x5
	v_fmac_f32_dpp v205, v25, v198 row_shr:4 row_mask:0xf bank_mask:0xa
	s_branch .Lmb_qpack

; __device__ __forceinline__ u16 f2bf(float f) { return (u16)(pack2(f, 0.f) & 0xffffu); }
; __device__ __forceinline__ void phase_mix_b(const Params& p, int l, bool last, unsigned char* smem) {
;     ...
;         u16* o = p.Qall + ((size_t)(b * 4 + h) * NPOS + pos) * 192;
;         o[lane] = f2bf(v0 * QSCALE); o[lane + 64] = f2bf(v1 * QSCALE); o[lane + 128] = f2bf(v2 * QSCALE);
.Lmb_qpack:
	v_mul_f32_e32 v14, 0x3dd53b94, v14
	v_mul_f32_e32 v15, 0x3dd53b94, v15
	v_mul_f32_e32 v16, 0x3dd53b94, v16
	v_mul_f32_e32 v17, 0x3dd53b94, v17
	v_mul_f32_e32 v18, 0x3dd53b94, v18
	v_mul_f32_e32 v19, 0x3dd53b94, v19
	v_mul_f32_e32 v20, 0x3dd53b94, v20
	v_mul_f32_e32 v21, 0x3dd53b94, v21
	v_mul_f32_e32 v202, 0x3dd53b94, v202
	v_mul_f32_e32 v203, 0x3dd53b94, v203
	v_mul_f32_e32 v204, 0x3dd53b94, v204
	v_mul_f32_e32 v205, 0x3dd53b94, v205
	v_cvt_pk_bf16_f32 v216, v14, v15
	v_cvt_pk_bf16_f32 v217, v16, v17
	v_cvt_pk_bf16_f32 v218, v18, v19
	v_cvt_pk_bf16_f32 v219, v20, v21
	v_cvt_pk_bf16_f32 v220, v202, v203
	v_cvt_pk_bf16_f32 v221, v204, v205
	global_store_dwordx4 v154, v[216:219], s[98:99] sc1
	global_store_dwordx2 v155, v[220:221], s[98:99]

; __device__ __forceinline__ u16 f2bf(float f) { return (u16)(pack2(f, 0.f) & 0xffffu); }
; __device__ __forceinline__ void convT_tile(const float* __restrict__ src, int lds, int k0, int c0, u16* __restrict__ dst, int Kd,
;                                            int rbase, int mode, int which, unsigned char* smem, const float* __restrict__ kscale = nullptr) {
;     ...
;   for (int i = 0; i < 4; ++i) {
;     const int kk = i * 16 + (t >> 4), cc = (t & 15) * 4;
;     const float sc = kscale ? kscale[k0 + kk] : 1.f;
;     tile[kk * 65 + cc + 0] = v4[i].x * sc; tile[kk * 65 + cc + 1] = v4[i].y * sc;
;     tile[kk * 65 + cc + 2] = v4[i].z * sc; tile[kk * 65 + cc + 3] = v4[i].w * sc;
;   }
;   __syncthreads();
; #pragma unroll
;   for (int i = 0; i < 16; ++i) {
;     const int cc = i * 4 + (t >> 6), kk = t & 63;
;     int row;
;     if (mode == 0) row = rbase + cc;
;     else { const int f = c0 + cc; row = (((f >> 4) * 2 + which) << 4) + (f & 15); }
;     dst[(size_t)row * Kd + k0 + kk] = f2bf(tile[kk * 65 + cc]);
; __device__ __forceinline__ void conv_item(const Params& p, int it, unsigned char* smem) {
;     ...
;   if (r < 4096) {
;     const int which = r >> 11, r2 = r & 2047, e = r2 >> 7, r3 = r2 & 127, ct = r3 >> 4, kt = r3 & 15;
;     const float* src = (which ? p.w_up : p.w_gate) + (size_t)(l * 16 + e) * 1024 * 512;
;     convT_tile(src, 512, kt * 64, ct * 64, p.WguT + (size_t)(l * 16 + e) * 1024 * 1024, 1024, 0, 1, which, smem);
;     return;
.Lcv_de0:
	s_waitcnt vmcnt(4)
	ds_write2_b32 v107, v132, v133 offset1:1
	ds_write2_b32 v107, v134, v135 offset0:2 offset1:3
	ds_write2_b32 v108, v136, v137 offset1:1
	ds_write2_b32 v108, v138, v139 offset0:2 offset1:3
	ds_write2_b32 v109, v140, v141 offset1:1
	ds_write2_b32 v109, v142, v143 offset0:2 offset1:3
	ds_write2_b32 v110, v144, v145 offset1:1
	ds_write2_b32 v110, v146, v147 offset0:2 offset1:3
	s_waitcnt lgkmcnt(0)
	s_barrier
	ds_read_b32 v72, v115 offset:0
	ds_read_b32 v73, v115 offset:260
	ds_read_b32 v74, v115 offset:520
	ds_read_b32 v75, v115 offset:780
	ds_read_b32 v76, v115 offset:1040
	ds_read_b32 v77, v115 offset:1300
	ds_read_b32 v78, v115 offset:1560
	ds_read_b32 v79, v115 offset:1820
	ds_read_b32 v26, v115 offset:128
	ds_read_b32 v27, v115 offset:388
	ds_read_b32 v28, v115 offset:648
	ds_read_b32 v29, v115 offset:908
	ds_read_b32 v30, v115 offset:1168
	ds_read_b32 v31, v115 offset:1428
	ds_read_b32 v32, v115 offset:1688
	ds_read_b32 v33, v115 offset:1948
	s_waitcnt lgkmcnt(8)
	v_cvt_pk_bf16_f32 v124, v72, v73
	v_cvt_pk_bf16_f32 v125, v74, v75
	v_cvt_pk_bf16_f32 v126, v76, v77
	v_cvt_pk_bf16_f32 v127, v78, v79
	global_store_dwordx4 v120, v[124:127], s[0:1] sc1
	s_waitcnt lgkmcnt(0)
	v_cvt_pk_bf16_f32 v128, v26, v27
	v_cvt_pk_bf16_f32 v129, v28, v29
	v_cvt_pk_bf16_f32 v130, v30, v31
	v_cvt_pk_bf16_f32 v131, v32, v33
	global_store_dwordx4 v121, v[128:131], s[0:1] sc1
	s_add_i32 s59, s2, 0x400
	s_cmp_lt_u32 s59, 0x1000
	s_cbranch_scc0 .Lcv_sd2
	s_lshr_b32 s60, s59, 11
	s_bfe_u32 s71, s59, 0x40007
	s_bfe_u32 s35, s59, 0x30004
	s_and_b32 s51, s59, 15
	s_lshl_b32 s0, s36, 4
	s_add_i32 s71, s71, s0
	s_lshl_b32 s71, s71, 21
	s_lshl_b32 s0, s51, 17
	s_add_i32 s71, s71, s0
	s_lshl_b32 s0, s35, 8
	s_add_i32 s71, s71, s0
	s_cmp_eq_u32 s60, 0
	s_cselect_b32 s88, s52, s54
	s_cselect_b32 s89, s53, s55
	s_add_u32 s88, s88, s71
	s_addc_u32 s89, s89, 0
	s_mov_b32 s94, 11
	s_branch .Lcv_se2

; __device__ __forceinline__ u16 f2bf(float f) { return (u16)(pack2(f, 0.f) & 0xffffu); }
; __device__ __forceinline__ void convT_tile(const float* __restrict__ src, int lds, int k0, int c0, u16* __restrict__ dst, int Kd,
;                                            int rbase, int mode, int which, unsigned char* smem, const float* __restrict__ kscale = nullptr) {
;     ...
;   for (int i = 0; i < 4; ++i) {
;     const int kk = i * 16 + (t >> 4), cc = (t & 15) * 4;
;     const float sc = kscale ? kscale[k0 + kk] : 1.f;
;     tile[kk * 65 + cc + 0] = v4[i].x * sc; tile[kk * 65 + cc + 1] = v4[i].y * sc;
;     tile[kk * 65 + cc + 2] = v4[i].z * sc; tile[kk * 65 + cc + 3] = v4[i].w * sc;
;   }
;   __syncthreads();
; #pragma unroll
;   for (int i = 0; i < 16; ++i) {
;     const int cc = i * 4 + (t >> 6), kk = t & 63;
;     int row;
;     if (mode == 0) row = rbase + cc;
;     else { const int f = c0 + cc; row = (((f >> 4) * 2 + which) << 4) + (f & 15); }
;     dst[(size_t)row * Kd + k0 + kk] = f2bf(tile[kk * 65 + cc]);
; __device__ __forceinline__ void conv_item(const Params& p, int it, unsigned char* smem) {
;     ...
;   if (r < 4096) {
;     const int which = r >> 11, r2 = r & 2047, e = r2 >> 7, r3 = r2 & 127, ct = r3 >> 4, kt = r3 & 15;
;     const float* src = (which ? p.w_up : p.w_gate) + (size_t)(l * 16 + e) * 1024 * 512;
;     convT_tile(src, 512, kt * 64, ct * 64, p.WguT + (size_t)(l * 16 + e) * 1024 * 1024, 1024, 0, 1, which, smem);
;     return;
.Lcv_de1:
	s_waitcnt vmcnt(6)
	ds_write2_b32 v111, v148, v149 offset1:1
	ds_write2_b32 v111, v150, v151 offset0:2 offset1:3
	ds_write2_b32 v112, v152, v153 offset1:1
	ds_write2_b32 v112, v154, v155 offset0:2 offset1:3
	ds_write2_b32 v113, v156, v157 offset1:1
	ds_write2_b32 v113, v158, v159 offset0:2 offset1:3
	ds_write2_b32 v114, v160, v161 offset1:1
	ds_write2_b32 v114, v162, v163 offset0:2 offset1:3
	s_waitcnt lgkmcnt(0)
	s_barrier
	ds_read_b32 v72, v115 offset:16640
	ds_read_b32 v73, v115 offset:16900
	ds_read_b32 v74, v115 offset:17160
	ds_read_b32 v75, v115 offset:17420
	ds_read_b32 v76, v115 offset:17680
	ds_read_b32 v77, v115 offset:17940
	ds_read_b32 v78, v115 offset:18200
	ds_read_b32 v79, v115 offset:18460
	ds_read_b32 v26, v115 offset:16768
	ds_read_b32 v27, v115 offset:17028
	ds_read_b32 v28, v115 offset:17288
	ds_read_b32 v29, v115 offset:17548
	ds_read_b32 v30, v115 offset:17808
	ds_read_b32 v31, v115 offset:18068
	ds_read_b32 v32, v115 offset:18328
	ds_read_b32 v33, v115 offset:18588
	s_waitcnt lgkmcnt(8)
	v_cvt_pk_bf16_f32 v124, v72, v73
	v_cvt_pk_bf16_f32 v125, v74, v75
	v_cvt_pk_bf16_f32 v126, v76, v77
	v_cvt_pk_bf16_f32 v127, v78, v79
	global_store_dwordx4 v120, v[124:127], s[0:1] sc1
	s_waitcnt lgkmcnt(0)
	v_cvt_pk_bf16_f32 v128, v26, v27
	v_cvt_pk_bf16_f32 v129, v28, v29
	v_cvt_pk_bf16_f32 v130, v30, v31
	v_cvt_pk_bf16_f32 v131, v32, v33
	global_store_dwordx4 v121, v[128:131], s[0:1] sc1
	s_add_i32 s59, s2, 0x600
	s_cmp_lt_u32 s59, 0x1000
	s_cbranch_scc0 .Lcv_sd3
	s_lshr_b32 s60, s59, 11
	s_bfe_u32 s71, s59, 0x40007
	s_bfe_u32 s35, s59, 0x30004
	s_and_b32 s51, s59, 15
	s_lshl_b32 s0, s36, 4
	s_add_i32 s71, s71, s0
	s_lshl_b32 s71, s71, 21
	s_lshl_b32 s0, s51, 17
	s_add_i32 s71, s71, s0
	s_lshl_b32 s0, s35, 8
	s_add_i32 s71, s71, s0
	s_cmp_eq_u32 s60, 0
	s_cselect_b32 s88, s52, s54
	s_cselect_b32 s89, s53, s55
	s_add_u32 s88, s88, s71
	s_addc_u32 s89, s89, 0
	s_mov_b32 s94, 11
	s_branch .Lcv_se3

; __device__ __forceinline__ u16 f2bf(float f) { return (u16)(pack2(f, 0.f) & 0xffffu); }
; __device__ __forceinline__ void convT_tile(const float* __restrict__ src, int lds, int k0, int c0, u16* __restrict__ dst, int Kd,
;                                            int rbase, int mode, int which, unsigned char* smem, const float* __restrict__ kscale = nullptr) {
;     ...
;   for (int i = 0; i < 4; ++i) {
;     const int kk = i * 16 + (t >> 4), cc = (t & 15) * 4;
;     const float sc = kscale ? kscale[k0 + kk] : 1.f;
;     tile[kk * 65 + cc + 0] = v4[i].x * sc; tile[kk * 65 + cc + 1] = v4[i].y * sc;
;     tile[kk * 65 + cc + 2] = v4[i].z * sc; tile[kk * 65 + cc + 3] = v4[i].w * sc;
;   }
;   __syncthreads();
; #pragma unroll
;   for (int i = 0; i < 16; ++i) {
;     const int cc = i * 4 + (t >> 6), kk = t & 63;
;     int row;
;     if (mode == 0) row = rbase + cc;
;     else { const int f = c0 + cc; row = (((f >> 4) * 2 + which) << 4) + (f & 15); }
;     dst[(size_t)row * Kd + k0 + kk] = f2bf(tile[kk * 65 + cc]);
; __device__ __forceinline__ void conv_item(const Params& p, int it, unsigned char* smem) {
;     ...
;   if (r < 4096) {
;     const int which = r >> 11, r2 = r & 2047, e = r2 >> 7, r3 = r2 & 127, ct = r3 >> 4, kt = r3 & 15;
;     const float* src = (which ? p.w_up : p.w_gate) + (size_t)(l * 16 + e) * 1024 * 512;
;     convT_tile(src, 512, kt * 64, ct * 64, p.WguT + (size_t)(l * 16 + e) * 1024 * 1024, 1024, 0, 1, which, smem);
;     return;
.Lcv_de2:
	s_waitcnt vmcnt(6)
	ds_write2_b32 v107, v132, v133 offset1:1
	ds_write2_b32 v107, v134, v135 offset0:2 offset1:3
	ds_write2_b32 v108, v136, v137 offset1:1
	ds_write2_b32 v108, v138, v139 offset0:2 offset1:3
	ds_write2_b32 v109, v140, v141 offset1:1
	ds_write2_b32 v109, v142, v143 offset0:2 offset1:3
	ds_write2_b32 v110, v144, v145 offset1:1
	ds_write2_b32 v110, v146, v147 offset0:2 offset1:3
	s_waitcnt lgkmcnt(0)
	s_barrier
	ds_read_b32 v72, v115 offset:0
	ds_read_b32 v73, v115 offset:260
	ds_read_b32 v74, v115 offset:520
	ds_read_b32 v75, v115 offset:780
	ds_read_b32 v76, v115 offset:1040
	ds_read_b32 v77, v115 offset:1300
	ds_read_b32 v78, v115 offset:1560
	ds_read_b32 v79, v115 offset:1820
	ds_read_b32 v26, v115 offset:128
	ds_read_b32 v27, v115 offset:388
	ds_read_b32 v28, v115 offset:648
	ds_read_b32 v29, v115 offset:908
	ds_read_b32 v30, v115 offset:1168
	ds_read_b32 v31, v115 offset:1428
	ds_read_b32 v32, v115 offset:1688
	ds_read_b32 v33, v115 offset:1948
	s_waitcnt lgkmcnt(8)
	v_cvt_pk_bf16_f32 v124, v72, v73
	v_cvt_pk_bf16_f32 v125, v74, v75
	v_cvt_pk_bf16_f32 v126, v76, v77
	v_cvt_pk_bf16_f32 v127, v78, v79
	global_store_dwordx4 v120, v[124:127], s[0:1] sc1
	s_waitcnt lgkmcnt(0)
	v_cvt_pk_bf16_f32 v128, v26, v27
	v_cvt_pk_bf16_f32 v129, v28, v29
	v_cvt_pk_bf16_f32 v130, v30, v31
	v_cvt_pk_bf16_f32 v131, v32, v33
	global_store_dwordx4 v121, v[128:131], s[0:1] sc1
	s_add_i32 s59, s2, 0x800
	s_cmp_lt_u32 s59, 0x1000
	s_cbranch_scc0 .Lcv_sd4
	s_lshr_b32 s60, s59, 11
	s_bfe_u32 s71, s59, 0x40007
	s_bfe_u32 s35, s59, 0x30004
	s_and_b32 s51, s59, 15
	s_lshl_b32 s0, s36, 4
	s_add_i32 s71, s71, s0
	s_lshl_b32 s71, s71, 21
	s_lshl_b32 s0, s51, 17
	s_add_i32 s71, s71, s0
	s_lshl_b32 s0, s35, 8
	s_add_i32 s71, s71, s0
	s_cmp_eq_u32 s60, 0
	s_cselect_b32 s88, s52, s54
	s_cselect_b32 s89, s53, s55
	s_add_u32 s88, s88, s71
	s_addc_u32 s89, s89, 0
	s_mov_b32 s94, 11
	s_branch .Lcv_se4

; __device__ __forceinline__ u16 f2bf(float f) { return (u16)(pack2(f, 0.f) & 0xffffu); }
; __device__ __forceinline__ void convT_tile(const float* __restrict__ src, int lds, int k0, int c0, u16* __restrict__ dst, int Kd,
;                                            int rbase, int mode, int which, unsigned char* smem, const float* __restrict__ kscale = nullptr) {
;     ...
;   for (int i = 0; i < 4; ++i) {
;     const int kk = i * 16 + (t >> 4), cc = (t & 15) * 4;
;     const float sc = kscale ? kscale[k0 + kk] : 1.f;
;     tile[kk * 65 + cc + 0] = v4[i].x * sc; tile[kk * 65 + cc + 1] = v4[i].y * sc;
;     tile[kk * 65 + cc + 2] = v4[i].z * sc; tile[kk * 65 + cc + 3] = v4[i].w * sc;
;   }
;   __syncthreads();
; #pragma unroll
;   for (int i = 0; i < 16; ++i) {
;     const int cc = i * 4 + (t >> 6), kk = t & 63;
;     int row;
;     if (mode == 0) row = rbase + cc;
;     else { const int f = c0 + cc; row = (((f >> 4) * 2 + which) << 4) + (f & 15); }
;     dst[(size_t)row * Kd + k0 + kk] = f2bf(tile[kk * 65 + cc]);
; __device__ __forceinline__ void conv_item(const Params& p, int it, unsigned char* smem) {
;     ...
;   if (r < 4096) {
;     const int which = r >> 11, r2 = r & 2047, e = r2 >> 7, r3 = r2 & 127, ct = r3 >> 4, kt = r3 & 15;
;     const float* src = (which ? p.w_up : p.w_gate) + (size_t)(l * 16 + e) * 1024 * 512;
;     convT_tile(src, 512, kt * 64, ct * 64, p.WguT + (size_t)(l * 16 + e) * 1024 * 1024, 1024, 0, 1, which, smem);
;     return;
.Lcv_de3:
	s_waitcnt vmcnt(6)
	ds_write2_b32 v111, v148, v149 offset1:1
	ds_write2_b32 v111, v150, v151 offset0:2 offset1:3
	ds_write2_b32 v112, v152, v153 offset1:1
	ds_write2_b32 v112, v154, v155 offset0:2 offset1:3
	ds_write2_b32 v113, v156, v157 offset1:1
	ds_write2_b32 v113, v158, v159 offset0:2 offset1:3
	ds_write2_b32 v114, v160, v161 offset1:1
	ds_write2_b32 v114, v162, v163 offset0:2 offset1:3
	s_waitcnt lgkmcnt(0)
	s_barrier
	ds_read_b32 v72, v115 offset:16640
	ds_read_b32 v73, v115 offset:16900
	ds_read_b32 v74, v115 offset:17160
	ds_read_b32 v75, v115 offset:17420
	ds_read_b32 v76, v115 offset:17680
	ds_read_b32 v77, v115 offset:17940
	ds_read_b32 v78, v115 offset:18200
	ds_read_b32 v79, v115 offset:18460
	ds_read_b32 v26, v115 offset:16768
	ds_read_b32 v27, v115 offset:17028
	ds_read_b32 v28, v115 offset:17288
	ds_read_b32 v29, v115 offset:17548
	ds_read_b32 v30, v115 offset:17808
	ds_read_b32 v31, v115 offset:18068
	ds_read_b32 v32, v115 offset:18328
	ds_read_b32 v33, v115 offset:18588
	s_waitcnt lgkmcnt(8)
	v_cvt_pk_bf16_f32 v124, v72, v73
	v_cvt_pk_bf16_f32 v125, v74, v75
	v_cvt_pk_bf16_f32 v126, v76, v77
	v_cvt_pk_bf16_f32 v127, v78, v79
	global_store_dwordx4 v120, v[124:127], s[0:1] sc1
	s_waitcnt lgkmcnt(0)
	v_cvt_pk_bf16_f32 v128, v26, v27
	v_cvt_pk_bf16_f32 v129, v28, v29
	v_cvt_pk_bf16_f32 v130, v30, v31
	v_cvt_pk_bf16_f32 v131, v32, v33
	global_store_dwordx4 v121, v[128:131], s[0:1] sc1
	s_add_i32 s59, s2, 0xa00
	s_cmp_lt_u32 s59, 0x1000
	s_cbranch_scc0 .Lcv_sd5
	s_lshr_b32 s60, s59, 11
	s_bfe_u32 s71, s59, 0x40007
	s_bfe_u32 s35, s59, 0x30004
	s_and_b32 s51, s59, 15
	s_lshl_b32 s0, s36, 4
	s_add_i32 s71, s71, s0
	s_lshl_b32 s71, s71, 21
	s_lshl_b32 s0, s51, 17
	s_add_i32 s71, s71, s0
	s_lshl_b32 s0, s35, 8
	s_add_i32 s71, s71, s0
	s_cmp_eq_u32 s60, 0
	s_cselect_b32 s88, s52, s54
	s_cselect_b32 s89, s53, s55
	s_add_u32 s88, s88, s71
	s_addc_u32 s89, s89, 0
	s_mov_b32 s94, 11
	s_branch .Lcv_se5

; __device__ __forceinline__ u16 f2bf(float f) { return (u16)(pack2(f, 0.f) & 0xffffu); }
; __device__ __forceinline__ void convT_tile(const float* __restrict__ src, int lds, int k0, int c0, u16* __restrict__ dst, int Kd,
;                                            int rbase, int mode, int which, unsigned char* smem, const float* __restrict__ kscale = nullptr) {
;     ...
;   for (int i = 0; i < 4; ++i) {
;     const int kk = i * 16 + (t >> 4), cc = (t & 15) * 4;
;     const float sc = kscale ? kscale[k0 + kk] : 1.f;
;     tile[kk * 65 + cc + 0] = v4[i].x * sc; tile[kk * 65 + cc + 1] = v4[i].y * sc;
;     tile[kk * 65 + cc + 2] = v4[i].z * sc; tile[kk * 65 + cc + 3] = v4[i].w * sc;
;   }
;   __syncthreads();
; #pragma unroll
;   for (int i = 0; i < 16; ++i) {
;     const int cc = i * 4 + (t >> 6), kk = t & 63;
;     int row;
;     if (mode == 0) row = rbase + cc;
;     else { const int f = c0 + cc; row = (((f >> 4) * 2 + which) << 4) + (f & 15); }
;     dst[(size_t)row * Kd + k0 + kk] = f2bf(tile[kk * 65 + cc]);
; __device__ __forceinline__ void conv_item(const Params& p, int it, unsigned char* smem) {
;     ...
;   if (r < 4096) {
;     const int which = r >> 11, r2 = r & 2047, e = r2 >> 7, r3 = r2 & 127, ct = r3 >> 4, kt = r3 & 15;
;     const float* src = (which ? p.w_up : p.w_gate) + (size_t)(l * 16 + e) * 1024 * 512;
;     convT_tile(src, 512, kt * 64, ct * 64, p.WguT + (size_t)(l * 16 + e) * 1024 * 1024, 1024, 0, 1, which, smem);
;     return;
.Lcv_de4:
	s_waitcnt vmcnt(6)
	ds_write2_b32 v107, v132, v133 offset1:1
	ds_write2_b32 v107, v134, v135 offset0:2 offset1:3
	ds_write2_b32 v108, v136, v137 offset1:1
	ds_write2_b32 v108, v138, v139 offset0:2 offset1:3
	ds_write2_b32 v109, v140, v141 offset1:1
	ds_write2_b32 v109, v142, v143 offset0:2 offset1:3
	ds_write2_b32 v110, v144, v145 offset1:1
	ds_write2_b32 v110, v146, v147 offset0:2 offset1:3
	s_waitcnt lgkmcnt(0)
	s_barrier
	ds_read_b32 v72, v115 offset:0
	ds_read_b32 v73, v115 offset:260
	ds_read_b32 v74, v115 offset:520
	ds_read_b32 v75, v115 offset:780
	ds_read_b32 v76, v115 offset:1040
	ds_read_b32 v77, v115 offset:1300
	ds_read_b32 v78, v115 offset:1560
	ds_read_b32 v79, v115 offset:1820
	ds_read_b32 v26, v115 offset:128
	ds_read_b32 v27, v115 offset:388
	ds_read_b32 v28, v115 offset:648
	ds_read_b32 v29, v115 offset:908
	ds_read_b32 v30, v115 offset:1168
	ds_read_b32 v31, v115 offset:1428
	ds_read_b32 v32, v115 offset:1688
	ds_read_b32 v33, v115 offset:1948
	s_waitcnt lgkmcnt(8)
	v_cvt_pk_bf16_f32 v124, v72, v73
	v_cvt_pk_bf16_f32 v125, v74, v75
	v_cvt_pk_bf16_f32 v126, v76, v77
	v_cvt_pk_bf16_f32 v127, v78, v79
	global_store_dwordx4 v120, v[124:127], s[0:1] sc1
	s_waitcnt lgkmcnt(0)
	v_cvt_pk_bf16_f32 v128, v26, v27
	v_cvt_pk_bf16_f32 v129, v28, v29
	v_cvt_pk_bf16_f32 v130, v30, v31
	v_cvt_pk_bf16_f32 v131, v32, v33
	global_store_dwordx4 v121, v[128:131], s[0:1] sc1
	s_add_i32 s59, s2, 0xc00
	s_cmp_lt_u32 s59, 0x1000
	s_cbranch_scc0 .Lcv_sd6
	s_lshr_b32 s60, s59, 11
	s_bfe_u32 s71, s59, 0x40007
	s_bfe_u32 s35, s59, 0x30004
	s_and_b32 s51, s59, 15
	s_lshl_b32 s0, s36, 4
	s_add_i32 s71, s71, s0
	s_lshl_b32 s71, s71, 21
	s_lshl_b32 s0, s51, 17
	s_add_i32 s71, s71, s0
	s_lshl_b32 s0, s35, 8
	s_add_i32 s71, s71, s0
	s_cmp_eq_u32 s60, 0
	s_cselect_b32 s88, s52, s54
	s_cselect_b32 s89, s53, s55
	s_add_u32 s88, s88, s71
	s_addc_u32 s89, s89, 0
	s_mov_b32 s94, 11
	s_branch .Lcv_se6

; __device__ __forceinline__ u16 f2bf(float f) { return (u16)(pack2(f, 0.f) & 0xffffu); }
; __device__ __forceinline__ void convT_tile(const float* __restrict__ src, int lds, int k0, int c0, u16* __restrict__ dst, int Kd,
;                                            int rbase, int mode, int which, unsigned char* smem, const float* __restrict__ kscale = nullptr) {
;     ...
;   for (int i = 0; i < 4; ++i) {
;     const int kk = i * 16 + (t >> 4), cc = (t & 15) * 4;
;     const float sc = kscale ? kscale[k0 + kk] : 1.f;
;     tile[kk * 65 + cc + 0] = v4[i].x * sc; tile[kk * 65 + cc + 1] = v4[i].y * sc;
;     tile[kk * 65 + cc + 2] = v4[i].z * sc; tile[kk * 65 + cc + 3] = v4[i].w * sc;
;   }
;   __syncthreads();
; #pragma unroll
;   for (int i = 0; i < 16; ++i) {
;     const int cc = i * 4 + (t >> 6), kk = t & 63;
;     int row;
;     if (mode == 0) row = rbase + cc;
;     else { const int f = c0 + cc; row = (((f >> 4) * 2 + which) << 4) + (f & 15); }
;     dst[(size_t)row * Kd + k0 + kk] = f2bf(tile[kk * 65 + cc]);
; __device__ __forceinline__ void conv_item(const Params& p, int it, unsigned char* smem) {
;     ...
;   if (r < 4096) {
;     const int which = r >> 11, r2 = r & 2047, e = r2 >> 7, r3 = r2 & 127, ct = r3 >> 4, kt = r3 & 15;
;     const float* src = (which ? p.w_up : p.w_gate) + (size_t)(l * 16 + e) * 1024 * 512;
;     convT_tile(src, 512, kt * 64, ct * 64, p.WguT + (size_t)(l * 16 + e) * 1024 * 1024, 1024, 0, 1, which, smem);
;     return;
.Lcv_de5:
	s_waitcnt vmcnt(6)
	ds_write2_b32 v111, v148, v149 offset1:1
	ds_write2_b32 v111, v150, v151 offset0:2 offset1:3
	ds_write2_b32 v112, v152, v153 offset1:1
	ds_write2_b32 v112, v154, v155 offset0:2 offset1:3
	ds_write2_b32 v113, v156, v157 offset1:1
	ds_write2_b32 v113, v158, v159 offset0:2 offset1:3
	ds_write2_b32 v114, v160, v161 offset1:1
	ds_write2_b32 v114, v162, v163 offset0:2 offset1:3
	s_waitcnt lgkmcnt(0)
	s_barrier
	ds_read_b32 v72, v115 offset:16640
	ds_read_b32 v73, v115 offset:16900
	ds_read_b32 v74, v115 offset:17160
	ds_read_b32 v75, v115 offset:17420
	ds_read_b32 v76, v115 offset:17680
	ds_read_b32 v77, v115 offset:17940
	ds_read_b32 v78, v115 offset:18200
	ds_read_b32 v79, v115 offset:18460
	ds_read_b32 v26, v115 offset:16768
	ds_read_b32 v27, v115 offset:17028
	ds_read_b32 v28, v115 offset:17288
	ds_read_b32 v29, v115 offset:17548
	ds_read_b32 v30, v115 offset:17808
	ds_read_b32 v31, v115 offset:18068
	ds_read_b32 v32, v115 offset:18328
	ds_read_b32 v33, v115 offset:18588
	s_waitcnt lgkmcnt(8)
	v_cvt_pk_bf16_f32 v124, v72, v73
	v_cvt_pk_bf16_f32 v125, v74, v75
	v_cvt_pk_bf16_f32 v126, v76, v77
	v_cvt_pk_bf16_f32 v127, v78, v79
	global_store_dwordx4 v120, v[124:127], s[0:1] sc1
	s_waitcnt lgkmcnt(0)
	v_cvt_pk_bf16_f32 v128, v26, v27
	v_cvt_pk_bf16_f32 v129, v28, v29
	v_cvt_pk_bf16_f32 v130, v30, v31
	v_cvt_pk_bf16_f32 v131, v32, v33
	global_store_dwordx4 v121, v[128:131], s[0:1] sc1
	s_add_i32 s59, s2, 0xe00
	s_cmp_lt_u32 s59, 0x1000
	s_cbranch_scc0 .Lcv_sd7
	s_lshr_b32 s60, s59, 11
	s_bfe_u32 s71, s59, 0x40007
	s_bfe_u32 s35, s59, 0x30004
	s_and_b32 s51, s59, 15
	s_lshl_b32 s0, s36, 4
	s_add_i32 s71, s71, s0
	s_lshl_b32 s71, s71, 21
	s_lshl_b32 s0, s51, 17
	s_add_i32 s71, s71, s0
	s_lshl_b32 s0, s35, 8
	s_add_i32 s71, s71, s0
	s_cmp_eq_u32 s60, 0
	s_cselect_b32 s88, s52, s54
	s_cselect_b32 s89, s53, s55
	s_add_u32 s88, s88, s71
	s_addc_u32 s89, s89, 0
	s_mov_b32 s94, 11
	s_branch .Lcv_se7

; __device__ __forceinline__ u16 f2bf(float f) { return (u16)(pack2(f, 0.f) & 0xffffu); }
; __device__ __forceinline__ void convT_tile(const float* __restrict__ src, int lds, int k0, int c0, u16* __restrict__ dst, int Kd,
;                                            int rbase, int mode, int which, unsigned char* smem, const float* __restrict__ kscale = nullptr) {
;     ...
;   for (int i = 0; i < 4; ++i) {
;     const int kk = i * 16 + (t >> 4), cc = (t & 15) * 4;
;     const float sc = kscale ? kscale[k0 + kk] : 1.f;
;     tile[kk * 65 + cc + 0] = v4[i].x * sc; tile[kk * 65 + cc + 1] = v4[i].y * sc;
;     tile[kk * 65 + cc + 2] = v4[i].z * sc; tile[kk * 65 + cc + 3] = v4[i].w * sc;
;   }
;   __syncthreads();
; #pragma unroll
;   for (int i = 0; i < 16; ++i) {
;     const int cc = i * 4 + (t >> 6), kk = t & 63;
;     int row;
;     if (mode == 0) row = rbase + cc;
;     else { const int f = c0 + cc; row = (((f >> 4) * 2 + which) << 4) + (f & 15); }
;     dst[(size_t)row * Kd + k0 + kk] = f2bf(tile[kk * 65 + cc]);
; __device__ __forceinline__ void conv_item(const Params& p, int it, unsigned char* smem) {
;     ...
;   if (r < 4096) {
;     const int which = r >> 11, r2 = r & 2047, e = r2 >> 7, r3 = r2 & 127, ct = r3 >> 4, kt = r3 & 15;
;     const float* src = (which ? p.w_up : p.w_gate) + (size_t)(l * 16 + e) * 1024 * 512;
;     convT_tile(src, 512, kt * 64, ct * 64, p.WguT + (size_t)(l * 16 + e) * 1024 * 1024, 1024, 0, 1, which, smem);
;     return;
.Lcv_de6:
	s_waitcnt vmcnt(6)
	ds_write2_b32 v107, v132, v133 offset1:1
	ds_write2_b32 v107, v134, v135 offset0:2 offset1:3
	ds_write2_b32 v108, v136, v137 offset1:1
	ds_write2_b32 v108, v138, v139 offset0:2 offset1:3
	ds_write2_b32 v109, v140, v141 offset1:1
	ds_write2_b32 v109, v142, v143 offset0:2 offset1:3
	ds_write2_b32 v110, v144, v145 offset1:1
	ds_write2_b32 v110, v146, v147 offset0:2 offset1:3
	s_waitcnt lgkmcnt(0)
	s_barrier
	ds_read_b32 v72, v115 offset:0
	ds_read_b32 v73, v115 offset:260
	ds_read_b32 v74, v115 offset:520
	ds_read_b32 v75, v115 offset:780
	ds_read_b32 v76, v115 offset:1040
	ds_read_b32 v77, v115 offset:1300
	ds_read_b32 v78, v115 offset:1560
	ds_read_b32 v79, v115 offset:1820
	ds_read_b32 v26, v115 offset:128
	ds_read_b32 v27, v115 offset:388
	ds_read_b32 v28, v115 offset:648
	ds_read_b32 v29, v115 offset:908
	ds_read_b32 v30, v115 offset:1168
	ds_read_b32 v31, v115 offset:1428
	ds_read_b32 v32, v115 offset:1688
	ds_read_b32 v33, v115 offset:1948
	s_waitcnt lgkmcnt(8)
	v_cvt_pk_bf16_f32 v124, v72, v73
	v_cvt_pk_bf16_f32 v125, v74, v75
	v_cvt_pk_bf16_f32 v126, v76, v77
	v_cvt_pk_bf16_f32 v127, v78, v79
	global_store_dwordx4 v120, v[124:127], s[0:1] sc1
	s_waitcnt lgkmcnt(0)
	v_cvt_pk_bf16_f32 v128, v26, v27
	v_cvt_pk_bf16_f32 v129, v28, v29
	v_cvt_pk_bf16_f32 v130, v30, v31
	v_cvt_pk_bf16_f32 v131, v32, v33
	global_store_dwordx4 v121, v[128:131], s[0:1] sc1
	s_add_i32 s59, s2, 0x1000
	s_cmp_lt_u32 s59, 0x1000
	s_cbranch_scc0 .Lcv_sd8
	s_lshr_b32 s60, s59, 11
	s_bfe_u32 s71, s59, 0x40007
	s_bfe_u32 s35, s59, 0x30004
	s_and_b32 s51, s59, 15
	s_lshl_b32 s0, s36, 4
	s_add_i32 s71, s71, s0
	s_lshl_b32 s71, s71, 21
	s_lshl_b32 s0, s51, 17
	s_add_i32 s71, s71, s0
	s_lshl_b32 s0, s35, 8
	s_add_i32 s71, s71, s0
	s_cmp_eq_u32 s60, 0
	s_cselect_b32 s88, s52, s54
	s_cselect_b32 s89, s53, s55
	s_add_u32 s88, s88, s71
	s_addc_u32 s89, s89, 0
	s_mov_b32 s94, 11
	s_branch .Lcv_se8

; __device__ __forceinline__ u16 f2bf(float f) { return (u16)(pack2(f, 0.f) & 0xffffu); }
; __device__ __forceinline__ void convT_tile(const float* __restrict__ src, int lds, int k0, int c0, u16* __restrict__ dst, int Kd,
;                                            int rbase, int mode, int which, unsigned char* smem, const float* __restrict__ kscale = nullptr) {
;     ...
;   for (int i = 0; i < 4; ++i) {
;     const int kk = i * 16 + (t >> 4), cc = (t & 15) * 4;
;     const float sc = kscale ? kscale[k0 + kk] : 1.f;
;     tile[kk * 65 + cc + 0] = v4[i].x * sc; tile[kk * 65 + cc + 1] = v4[i].y * sc;
;     tile[kk * 65 + cc + 2] = v4[i].z * sc; tile[kk * 65 + cc + 3] = v4[i].w * sc;
;   }
;   __syncthreads();
; #pragma unroll
;   for (int i = 0; i < 16; ++i) {
;     const int cc = i * 4 + (t >> 6), kk = t & 63;
;     int row;
;     if (mode == 0) row = rbase + cc;
;     else { const int f = c0 + cc; row = (((f >> 4) * 2 + which) << 4) + (f & 15); }
;     dst[(size_t)row * Kd + k0 + kk] = f2bf(tile[kk * 65 + cc]);
; __device__ __forceinline__ void conv_item(const Params& p, int it, unsigned char* smem) {
;     ...
;   if (r < 4096) {
;     const int which = r >> 11, r2 = r & 2047, e = r2 >> 7, r3 = r2 & 127, ct = r3 >> 4, kt = r3 & 15;
;     const float* src = (which ? p.w_up : p.w_gate) + (size_t)(l * 16 + e) * 1024 * 512;
;     convT_tile(src, 512, kt * 64, ct * 64, p.WguT + (size_t)(l * 16 + e) * 1024 * 1024, 1024, 0, 1, which, smem);
;     return;
.Lcv_de7:
	s_waitcnt vmcnt(6)
	ds_write2_b32 v111, v148, v149 offset1:1
	ds_write2_b32 v111, v150, v151 offset0:2 offset1:3
	ds_write2_b32 v112, v152, v153 offset1:1
	ds_write2_b32 v112, v154, v155 offset0:2 offset1:3
	ds_write2_b32 v113, v156, v157 offset1:1
	ds_write2_b32 v113, v158, v159 offset0:2 offset1:3
	ds_write2_b32 v114, v160, v161 offset1:1
	ds_write2_b32 v114, v162, v163 offset0:2 offset1:3
	s_waitcnt lgkmcnt(0)
	s_barrier
	ds_read_b32 v72, v115 offset:16640
	ds_read_b32 v73, v115 offset:16900
	ds_read_b32 v74, v115 offset:17160
	ds_read_b32 v75, v115 offset:17420
	ds_read_b32 v76, v115 offset:17680
	ds_read_b32 v77, v115 offset:17940
	ds_read_b32 v78, v115 offset:18200
	ds_read_b32 v79, v115 offset:18460
	ds_read_b32 v26, v115 offset:16768
	ds_read_b32 v27, v115 offset:17028
	ds_read_b32 v28, v115 offset:17288
	ds_read_b32 v29, v115 offset:17548
	ds_read_b32 v30, v115 offset:17808
	ds_read_b32 v31, v115 offset:18068
	ds_read_b32 v32, v115 offset:18328
	ds_read_b32 v33, v115 offset:18588
	s_waitcnt lgkmcnt(8)
	v_cvt_pk_bf16_f32 v124, v72, v73
	v_cvt_pk_bf16_f32 v125, v74, v75
	v_cvt_pk_bf16_f32 v126, v76, v77
	v_cvt_pk_bf16_f32 v127, v78, v79
	global_store_dwordx4 v120, v[124:127], s[0:1] sc1
	s_waitcnt lgkmcnt(0)
	v_cvt_pk_bf16_f32 v128, v26, v27
	v_cvt_pk_bf16_f32 v129, v28, v29
	v_cvt_pk_bf16_f32 v130, v30, v31
	v_cvt_pk_bf16_f32 v131, v32, v33
	global_store_dwordx4 v121, v[128:131], s[0:1] sc1
	s_add_i32 s59, s2, 0x1200
	s_cmp_lt_u32 s59, 0x1000
	s_cbranch_scc0 .Lcv_sd9
	s_lshr_b32 s60, s59, 11
	s_bfe_u32 s71, s59, 0x40007
	s_bfe_u32 s35, s59, 0x30004
	s_and_b32 s51, s59, 15
	s_lshl_b32 s0, s36, 4
	s_add_i32 s71, s71, s0
	s_lshl_b32 s71, s71, 21
	s_lshl_b32 s0, s51, 17
	s_add_i32 s71, s71, s0
	s_lshl_b32 s0, s35, 8
	s_add_i32 s71, s71, s0
	s_cmp_eq_u32 s60, 0
	s_cselect_b32 s88, s52, s54
	s_cselect_b32 s89, s53, s55
	s_add_u32 s88, s88, s71
	s_addc_u32 s89, s89, 0
	s_mov_b32 s94, 11
	s_branch .Lcv_se9

; __device__ __forceinline__ u16 f2bf(float f) { return (u16)(pack2(f, 0.f) & 0xffffu); }
; __device__ __forceinline__ void convT_tile(const float* __restrict__ src, int lds, int k0, int c0, u16* __restrict__ dst, int Kd,
;                                            int rbase, int mode, int which, unsigned char* smem, const float* __restrict__ kscale = nullptr) {
;     ...
;   for (int i = 0; i < 4; ++i) {
;     const int kk = i * 16 + (t >> 4), cc = (t & 15) * 4;
;     const float sc = kscale ? kscale[k0 + kk] : 1.f;
;     tile[kk * 65 + cc + 0] = v4[i].x * sc; tile[kk * 65 + cc + 1] = v4[i].y * sc;
;     tile[kk * 65 + cc + 2] = v4[i].z * sc; tile[kk * 65 + cc + 3] = v4[i].w * sc;
;   }
;   __syncthreads();
; #pragma unroll
;   for (int i = 0; i < 16; ++i) {
;     const int cc = i * 4 + (t >> 6), kk = t & 63;
;     int row;
;     if (mode == 0) row = rbase + cc;
;     else { const int f = c0 + cc; row = (((f >> 4) * 2 + which) << 4) + (f & 15); }
;     dst[(size_t)row * Kd + k0 + kk] = f2bf(tile[kk * 65 + cc]);
; __device__ __forceinline__ void conv_item(const Params& p, int it, unsigned char* smem) {
;     ...
;   if (r < 4096) {
;     const int which = r >> 11, r2 = r & 2047, e = r2 >> 7, r3 = r2 & 127, ct = r3 >> 4, kt = r3 & 15;
;     const float* src = (which ? p.w_up : p.w_gate) + (size_t)(l * 16 + e) * 1024 * 512;
;     convT_tile(src, 512, kt * 64, ct * 64, p.WguT + (size_t)(l * 16 + e) * 1024 * 1024, 1024, 0, 1, which, smem);
;     return;
.Lcv_de8:
	s_waitcnt vmcnt(6)
	ds_write2_b32 v107, v132, v133 offset1:1
	ds_write2_b32 v107, v134, v135 offset0:2 offset1:3
	ds_write2_b32 v108, v136, v137 offset1:1
	ds_write2_b32 v108, v138, v139 offset0:2 offset1:3
	ds_write2_b32 v109, v140, v141 offset1:1
	ds_write2_b32 v109, v142, v143 offset0:2 offset1:3
	ds_write2_b32 v110, v144, v145 offset1:1
	ds_write2_b32 v110, v146, v147 offset0:2 offset1:3
	s_waitcnt lgkmcnt(0)
	s_barrier
	ds_read_b32 v72, v115 offset:0
	ds_read_b32 v73, v115 offset:260
	ds_read_b32 v74, v115 offset:520
	ds_read_b32 v75, v115 offset:780
	ds_read_b32 v76, v115 offset:1040
	ds_read_b32 v77, v115 offset:1300
	ds_read_b32 v78, v115 offset:1560
	ds_read_b32 v79, v115 offset:1820
	ds_read_b32 v26, v115 offset:128
	ds_read_b32 v27, v115 offset:388
	ds_read_b32 v28, v115 offset:648
	ds_read_b32 v29, v115 offset:908
	ds_read_b32 v30, v115 offset:1168
	ds_read_b32 v31, v115 offset:1428
	ds_read_b32 v32, v115 offset:1688
	ds_read_b32 v33, v115 offset:1948
	s_waitcnt lgkmcnt(8)
	v_cvt_pk_bf16_f32 v124, v72, v73
	v_cvt_pk_bf16_f32 v125, v74, v75
	v_cvt_pk_bf16_f32 v126, v76, v77
	v_cvt_pk_bf16_f32 v127, v78, v79
	global_store_dwordx4 v120, v[124:127], s[0:1] sc1
	s_waitcnt lgkmcnt(0)
	v_cvt_pk_bf16_f32 v128, v26, v27
	v_cvt_pk_bf16_f32 v129, v28, v29
	v_cvt_pk_bf16_f32 v130, v30, v31
	v_cvt_pk_bf16_f32 v131, v32, v33
	global_store_dwordx4 v121, v[128:131], s[0:1] sc1
	s_add_i32 s59, s2, 0x1400
	s_cmp_lt_u32 s59, 0x1000
	s_cbranch_scc0 .Lcv_sd10
	s_lshr_b32 s60, s59, 11
	s_bfe_u32 s71, s59, 0x40007
	s_bfe_u32 s35, s59, 0x30004
	s_and_b32 s51, s59, 15
	s_lshl_b32 s0, s36, 4
	s_add_i32 s71, s71, s0
	s_lshl_b32 s71, s71, 21
	s_lshl_b32 s0, s51, 17
	s_add_i32 s71, s71, s0
	s_lshl_b32 s0, s35, 8
	s_add_i32 s71, s71, s0
	s_cmp_eq_u32 s60, 0
	s_cselect_b32 s88, s52, s54
	s_cselect_b32 s89, s53, s55
	s_add_u32 s88, s88, s71
	s_addc_u32 s89, s89, 0
	s_mov_b32 s94, 11
	s_branch .Lcv_se10

; __device__ __forceinline__ u16 f2bf(float f) { return (u16)(pack2(f, 0.f) & 0xffffu); }
; __device__ __forceinline__ void convT_tile(const float* __restrict__ src, int lds, int k0, int c0, u16* __restrict__ dst, int Kd,
;                                            int rbase, int mode, int which, unsigned char* smem, const float* __restrict__ kscale = nullptr) {
;     ...
;   for (int i = 0; i < 4; ++i) {
;     const int kk = i * 16 + (t >> 4), cc = (t & 15) * 4;
;     const float sc = kscale ? kscale[k0 + kk] : 1.f;
;     tile[kk * 65 + cc + 0] = v4[i].x * sc; tile[kk * 65 + cc + 1] = v4[i].y * sc;
;     tile[kk * 65 + cc + 2] = v4[i].z * sc; tile[kk * 65 + cc + 3] = v4[i].w * sc;
;   }
;   __syncthreads();
; #pragma unroll
;   for (int i = 0; i < 16; ++i) {
;     const int cc = i * 4 + (t >> 6), kk = t & 63;
;     int row;
;     if (mode == 0) row = rbase + cc;
;     else { const int f = c0 + cc; row = (((f >> 4) * 2 + which) << 4) + (f & 15); }
;     dst[(size_t)row * Kd + k0 + kk] = f2bf(tile[kk * 65 + cc]);
; __device__ __forceinline__ void conv_item(const Params& p, int it, unsigned char* smem) {
;     ...
;   if (r < 4096) {
;     const int which = r >> 11, r2 = r & 2047, e = r2 >> 7, r3 = r2 & 127, ct = r3 >> 4, kt = r3 & 15;
;     const float* src = (which ? p.w_up : p.w_gate) + (size_t)(l * 16 + e) * 1024 * 512;
;     convT_tile(src, 512, kt * 64, ct * 64, p.WguT + (size_t)(l * 16 + e) * 1024 * 1024, 1024, 0, 1, which, smem);
;     return;
.Lcv_de9:
	s_waitcnt vmcnt(6)
	ds_write2_b32 v111, v148, v149 offset1:1
	ds_write2_b32 v111, v150, v151 offset0:2 offset1:3
	ds_write2_b32 v112, v152, v153 offset1:1
	ds_write2_b32 v112, v154, v155 offset0:2 offset1:3
	ds_write2_b32 v113, v156, v157 offset1:1
	ds_write2_b32 v113, v158, v159 offset0:2 offset1:3
	ds_write2_b32 v114, v160, v161 offset1:1
	ds_write2_b32 v114, v162, v163 offset0:2 offset1:3
	s_waitcnt lgkmcnt(0)
	s_barrier
	ds_read_b32 v72, v115 offset:16640
	ds_read_b32 v73, v115 offset:16900
	ds_read_b32 v74, v115 offset:17160
	ds_read_b32 v75, v115 offset:17420
	ds_read_b32 v76, v115 offset:17680
	ds_read_b32 v77, v115 offset:17940
	ds_read_b32 v78, v115 offset:18200
	ds_read_b32 v79, v115 offset:18460
	ds_read_b32 v26, v115 offset:16768
	ds_read_b32 v27, v115 offset:17028
	ds_read_b32 v28, v115 offset:17288
	ds_read_b32 v29, v115 offset:17548
	ds_read_b32 v30, v115 offset:17808
	ds_read_b32 v31, v115 offset:18068
	ds_read_b32 v32, v115 offset:18328
	ds_read_b32 v33, v115 offset:18588
	s_waitcnt lgkmcnt(8)
	v_cvt_pk_bf16_f32 v124, v72, v73
	v_cvt_pk_bf16_f32 v125, v74, v75
	v_cvt_pk_bf16_f32 v126, v76, v77
	v_cvt_pk_bf16_f32 v127, v78, v79
	global_store_dwordx4 v120, v[124:127], s[0:1] sc1
	s_waitcnt lgkmcnt(0)
	v_cvt_pk_bf16_f32 v128, v26, v27
	v_cvt_pk_bf16_f32 v129, v28, v29
	v_cvt_pk_bf16_f32 v130, v30, v31
	v_cvt_pk_bf16_f32 v131, v32, v33
	global_store_dwordx4 v121, v[128:131], s[0:1] sc1
	s_add_i32 s59, s2, 0x1600
	s_cmp_lt_u32 s59, 0x1000
	s_cbranch_scc0 .Lcv_sd11
	s_lshr_b32 s60, s59, 11
	s_bfe_u32 s71, s59, 0x40007
	s_bfe_u32 s35, s59, 0x30004
	s_and_b32 s51, s59, 15
	s_lshl_b32 s0, s36, 4
	s_add_i32 s71, s71, s0
	s_lshl_b32 s71, s71, 21
	s_lshl_b32 s0, s51, 17
	s_add_i32 s71, s71, s0
	s_lshl_b32 s0, s35, 8
	s_add_i32 s71, s71, s0
	s_cmp_eq_u32 s60, 0
	s_cselect_b32 s88, s52, s54
	s_cselect_b32 s89, s53, s55
	s_add_u32 s88, s88, s71
	s_addc_u32 s89, s89, 0
	s_mov_b32 s94, 11
	s_branch .Lcv_se11

; __device__ __forceinline__ u16 f2bf(float f) { return (u16)(pack2(f, 0.f) & 0xffffu); }
; __device__ __forceinline__ void convT_tile(const float* __restrict__ src, int lds, int k0, int c0, u16* __restrict__ dst, int Kd,
;                                            int rbase, int mode, int which, unsigned char* smem, const float* __restrict__ kscale = nullptr) {
;     ...
;   for (int i = 0; i < 4; ++i) {
;     const int kk = i * 16 + (t >> 4), cc = (t & 15) * 4;
;     const float sc = kscale ? kscale[k0 + kk] : 1.f;
;     tile[kk * 65 + cc + 0] = v4[i].x * sc; tile[kk * 65 + cc + 1] = v4[i].y * sc;
;     tile[kk * 65 + cc + 2] = v4[i].z * sc; tile[kk * 65 + cc + 3] = v4[i].w * sc;
;   }
;   __syncthreads();
; #pragma unroll
;   for (int i = 0; i < 16; ++i) {
;     const int cc = i * 4 + (t >> 6), kk = t & 63;
;     int row;
;     if (mode == 0) row = rbase + cc;
;     else { const int f = c0 + cc; row = (((f >> 4) * 2 + which) << 4) + (f & 15); }
;     dst[(size_t)row * Kd + k0 + kk] = f2bf(tile[kk * 65 + cc]);
; __device__ __forceinline__ void conv_item(const Params& p, int it, unsigned char* smem) {
;     ...
;   if (r < 4096) {
;     const int which = r >> 11, r2 = r & 2047, e = r2 >> 7, r3 = r2 & 127, ct = r3 >> 4, kt = r3 & 15;
;     const float* src = (which ? p.w_up : p.w_gate) + (size_t)(l * 16 + e) * 1024 * 512;
;     convT_tile(src, 512, kt * 64, ct * 64, p.WguT + (size_t)(l * 16 + e) * 1024 * 1024, 1024, 0, 1, which, smem);
;     return;
.Lcv_de10:
	s_waitcnt vmcnt(6)
	ds_write2_b32 v107, v132, v133 offset1:1
	ds_write2_b32 v107, v134, v135 offset0:2 offset1:3
	ds_write2_b32 v108, v136, v137 offset1:1
	ds_write2_b32 v108, v138, v139 offset0:2 offset1:3
	ds_write2_b32 v109, v140, v141 offset1:1
	ds_write2_b32 v109, v142, v143 offset0:2 offset1:3
	ds_write2_b32 v110, v144, v145 offset1:1
	ds_write2_b32 v110, v146, v147 offset0:2 offset1:3
	s_waitcnt lgkmcnt(0)
	s_barrier
	ds_read_b32 v72, v115 offset:0
	ds_read_b32 v73, v115 offset:260
	ds_read_b32 v74, v115 offset:520
	ds_read_b32 v75, v115 offset:780
	ds_read_b32 v76, v115 offset:1040
	ds_read_b32 v77, v115 offset:1300
	ds_read_b32 v78, v115 offset:1560
	ds_read_b32 v79, v115 offset:1820
	ds_read_b32 v26, v115 offset:128
	ds_read_b32 v27, v115 offset:388
	ds_read_b32 v28, v115 offset:648
	ds_read_b32 v29, v115 offset:908
	ds_read_b32 v30, v115 offset:1168
	ds_read_b32 v31, v115 offset:1428
	ds_read_b32 v32, v115 offset:1688
	ds_read_b32 v33, v115 offset:1948
	s_waitcnt lgkmcnt(8)
	v_cvt_pk_bf16_f32 v124, v72, v73
	v_cvt_pk_bf16_f32 v125, v74, v75
	v_cvt_pk_bf16_f32 v126, v76, v77
	v_cvt_pk_bf16_f32 v127, v78, v79
	global_store_dwordx4 v120, v[124:127], s[0:1] sc1
	s_waitcnt lgkmcnt(0)
	v_cvt_pk_bf16_f32 v128, v26, v27
	v_cvt_pk_bf16_f32 v129, v28, v29
	v_cvt_pk_bf16_f32 v130, v30, v31
	v_cvt_pk_bf16_f32 v131, v32, v33
	global_store_dwordx4 v121, v[128:131], s[0:1] sc1
	s_cmp_lt_i32 s34, 0
	s_cbranch_scc1 .Lcv_nol12
	s_mov_b32 s59, s34
	s_cmp_lt_u32 s59, 0x1000
	s_cbranch_scc0 .Lcv_sd12
	s_lshr_b32 s60, s59, 11
	s_bfe_u32 s71, s59, 0x40007
	s_bfe_u32 s35, s59, 0x30004
	s_and_b32 s51, s59, 15
	s_lshl_b32 s0, s36, 4
	s_add_i32 s71, s71, s0
	s_lshl_b32 s71, s71, 21
	s_lshl_b32 s0, s51, 17
	s_add_i32 s71, s71, s0
	s_lshl_b32 s0, s35, 8
	s_add_i32 s71, s71, s0
	s_cmp_eq_u32 s60, 0
	s_cselect_b32 s88, s52, s54
	s_cselect_b32 s89, s53, s55
	s_add_u32 s88, s88, s71
	s_addc_u32 s89, s89, 0
	s_mov_b32 s94, 11
	s_branch .Lcv_se12

; __device__ __forceinline__ u16 f2bf(float f) { return (u16)(pack2(f, 0.f) & 0xffffu); }
; __device__ __forceinline__ void convT_tile(const float* __restrict__ src, int lds, int k0, int c0, u16* __restrict__ dst, int Kd,
;                                            int rbase, int mode, int which, unsigned char* smem, const float* __restrict__ kscale = nullptr) {
;     ...
;     if (mode == 0) row = rbase + cc;
;     else { const int f = c0 + cc; row = (((f >> 4) * 2 + which) << 4) + (f & 15); }
;     dst[(size_t)row * Kd + k0 + kk] = f2bf(tile[kk * 65 + cc]);
; __device__ __forceinline__ void conv_item(const Params& p, int it, unsigned char* smem) {
;     ...
;   if (r < 4096) {
;     const int which = r >> 11, r2 = r & 2047, e = r2 >> 7, r3 = r2 & 127, ct = r3 >> 4, kt = r3 & 15;
;     const float* src = (which ? p.w_up : p.w_gate) + (size_t)(l * 16 + e) * 1024 * 512;
;     convT_tile(src, 512, kt * 64, ct * 64, p.WguT + (size_t)(l * 16 + e) * 1024 * 1024, 1024, 0, 1, which, smem);
.Lcv_w11b:
	ds_write2_b32 v111, v148, v149 offset1:1
	ds_write2_b32 v111, v150, v151 offset0:2 offset1:3
	ds_write2_b32 v112, v152, v153 offset1:1
	ds_write2_b32 v112, v154, v155 offset0:2 offset1:3
	ds_write2_b32 v113, v156, v157 offset1:1
	ds_write2_b32 v113, v158, v159 offset0:2 offset1:3
	ds_write2_b32 v114, v160, v161 offset1:1
	ds_write2_b32 v114, v162, v163 offset0:2 offset1:3
	s_waitcnt lgkmcnt(0)
	s_barrier
	ds_read_b32 v72, v115 offset:16640
	ds_read_b32 v73, v115 offset:16900
	ds_read_b32 v74, v115 offset:17160
	ds_read_b32 v75, v115 offset:17420
	ds_read_b32 v76, v115 offset:17680
	ds_read_b32 v77, v115 offset:17940
	ds_read_b32 v78, v115 offset:18200
	ds_read_b32 v79, v115 offset:18460
	ds_read_b32 v26, v115 offset:16768
	ds_read_b32 v27, v115 offset:17028
	ds_read_b32 v28, v115 offset:17288
	ds_read_b32 v29, v115 offset:17548
	ds_read_b32 v30, v115 offset:17808
	ds_read_b32 v31, v115 offset:18068
	ds_read_b32 v32, v115 offset:18328
	ds_read_b32 v33, v115 offset:18588
	s_waitcnt lgkmcnt(8)
	v_cvt_pk_bf16_f32 v124, v72, v73
	v_cvt_pk_bf16_f32 v125, v74, v75
	v_cvt_pk_bf16_f32 v126, v76, v77
	v_cvt_pk_bf16_f32 v127, v78, v79
	global_store_dwordx4 v120, v[124:127], s[0:1] sc1
	s_waitcnt lgkmcnt(0)
	v_cvt_pk_bf16_f32 v128, v26, v27
	v_cvt_pk_bf16_f32 v129, v28, v29
	v_cvt_pk_bf16_f32 v130, v30, v31
	v_cvt_pk_bf16_f32 v131, v32, v33
	global_store_dwordx4 v121, v[128:131], s[0:1] sc1
	s_cmp_lt_i32 s34, 0
	s_cbranch_scc1 .Lcv_exit
	s_mov_b32 s59, s34
	s_cmp_lt_u32 s59, 0x1000
	s_cbranch_scc0 .Lcv_dd12
	s_lshr_b32 s60, s59, 11
	s_bfe_u32 s71, s59, 0x40007
	s_bfe_u32 s35, s59, 0x30004
	s_and_b32 s51, s59, 15
	s_lshl_b32 s0, s36, 4
	s_add_i32 s71, s71, s0
	s_lshl_b32 s71, s71, 21
	s_lshl_b32 s35, s35, 7
	s_lshl_b32 s60, s60, 4
	s_add_i32 s35, s35, s60
	s_lshl_b32 s35, s35, 11
	s_add_i32 s71, s71, s35
	s_lshl_b32 s51, s51, 7
	s_add_i32 s71, s71, s51
	s_add_u32 s0, s98, s71
	s_addc_u32 s1, s99, 0
	v_mov_b32_e32 v120, v103
	v_mov_b32_e32 v121, v104
	s_branch .Lcv_de12

; __device__ __forceinline__ u16 f2bf(float f) { return (u16)(pack2(f, 0.f) & 0xffffu); }
; __device__ __forceinline__ void convT_tile(const float* __restrict__ src, int lds, int k0, int c0, u16* __restrict__ dst, int Kd,
;                                            int rbase, int mode, int which, unsigned char* smem, const float* __restrict__ kscale = nullptr) {
;     ...
;   for (int i = 0; i < 4; ++i) {
;     const int kk = i * 16 + (t >> 4), cc = (t & 15) * 4;
;     const float sc = kscale ? kscale[k0 + kk] : 1.f;
;     tile[kk * 65 + cc + 0] = v4[i].x * sc; tile[kk * 65 + cc + 1] = v4[i].y * sc;
;     tile[kk * 65 + cc + 2] = v4[i].z * sc; tile[kk * 65 + cc + 3] = v4[i].w * sc;
;   }
;   __syncthreads();
; #pragma unroll
;   for (int i = 0; i < 16; ++i) {
;     const int cc = i * 4 + (t >> 6), kk = t & 63;
;     int row;
;     if (mode == 0) row = rbase + cc;
;     else { const int f = c0 + cc; row = (((f >> 4) * 2 + which) << 4) + (f & 15); }
;     dst[(size_t)row * Kd + k0 + kk] = f2bf(tile[kk * 65 + cc]);
.Lcv_de12:
	s_waitcnt vmcnt(2)
	ds_write2_b32 v107, v132, v133 offset1:1
	ds_write2_b32 v107, v134, v135 offset0:2 offset1:3
	ds_write2_b32 v108, v136, v137 offset1:1
	ds_write2_b32 v108, v138, v139 offset0:2 offset1:3
	ds_write2_b32 v109, v140, v141 offset1:1
	ds_write2_b32 v109, v142, v143 offset0:2 offset1:3
	ds_write2_b32 v110, v144, v145 offset1:1
	ds_write2_b32 v110, v146, v147 offset0:2 offset1:3
	s_waitcnt lgkmcnt(0)
	s_barrier
	ds_read_b32 v72, v115 offset:0
	ds_read_b32 v73, v115 offset:260
	ds_read_b32 v74, v115 offset:520
	ds_read_b32 v75, v115 offset:780
	ds_read_b32 v76, v115 offset:1040
	ds_read_b32 v77, v115 offset:1300
	ds_read_b32 v78, v115 offset:1560
	ds_read_b32 v79, v115 offset:1820
	ds_read_b32 v26, v115 offset:128
	ds_read_b32 v27, v115 offset:388
	ds_read_b32 v28, v115 offset:648
	ds_read_b32 v29, v115 offset:908
	ds_read_b32 v30, v115 offset:1168
	ds_read_b32 v31, v115 offset:1428
	ds_read_b32 v32, v115 offset:1688
	ds_read_b32 v33, v115 offset:1948
	s_waitcnt lgkmcnt(8)
	v_cvt_pk_bf16_f32 v124, v72, v73
	v_cvt_pk_bf16_f32 v125, v74, v75
	v_cvt_pk_bf16_f32 v126, v76, v77
	v_cvt_pk_bf16_f32 v127, v78, v79
	global_store_dwordx4 v120, v[124:127], s[0:1] sc1
	s_waitcnt lgkmcnt(0)
	v_cvt_pk_bf16_f32 v128, v26, v27
	v_cvt_pk_bf16_f32 v129, v28, v29
	v_cvt_pk_bf16_f32 v130, v30, v31
	v_cvt_pk_bf16_f32 v131, v32, v33
	global_store_dwordx4 v121, v[128:131], s[0:1] sc1

; __device__ __forceinline__ void epi_staged_residual(f32x4 (&acc)[4][4], int r0, int c0, unsigned char* smem, const float* __restrict__ g,
;                                                     const float* __restrict__ xs, float* __restrict__ xd) {
;     ...
; #pragma unroll
;     for (int i = 0; i < 8; ++i) {
;       const int c = t + 256 * i, row = c >> 5, ch = c & 31;
;       const float4 a = *(const float4*)(Ts + row * PITCH + ch * 4);
;       const float4 gg = *(const float4*)(g + ch * 4);
;       const size_t o = (size_t)(pass * 64 + row) * DM + ch * 4;
;       float4 x = *(const float4*)(xs + o);
;       x.x += gg.x * a.x; x.y += gg.y * a.y; x.z += gg.z * a.z; x.w += gg.w * a.w;
;       *(float4*)(xd + o) = x;
;     }
.LBB0_844:
	s_or_b64 exec, exec, s[8:9]
	s_add_u32 s98, s0, s28
	s_addc_u32 s99, s1, s29
	s_add_u32 s100, s46, s28
	s_addc_u32 s101, s47, s29
	s_waitcnt lgkmcnt(0)
	s_barrier
	global_load_dwordx4 v[72:75], v89, s[98:99]
	global_load_dwordx4 v[76:79], v90, s[98:99]
	global_load_dwordx4 v[80:83], v91, s[98:99]
	global_load_dwordx4 v[96:99], v92, s[98:99]
	global_load_dwordx4 v[100:103], v93, s[98:99]
	global_load_dwordx4 v[236:239], v94, s[98:99]
	global_load_dwordx4 v[240:243], v95, s[98:99]
	global_load_dwordx4 v[244:247], v104, s[98:99]
	ds_read_b128 v[206:209], v88 offset:0
	ds_read_b128 v[210:213], v88 offset:4224
	ds_read_b128 v[216:219], v88 offset:8448
	ds_read_b128 v[220:223], v88 offset:12672
	s_waitcnt vmcnt(4) lgkmcnt(0)
	v_pk_fma_f32 v[206:207], v[2:3], v[206:207], v[72:73]
	v_pk_fma_f32 v[208:209], v[4:5], v[208:209], v[74:75]
	v_pk_fma_f32 v[210:211], v[2:3], v[210:211], v[76:77]
	v_pk_fma_f32 v[212:213], v[4:5], v[212:213], v[78:79]
	v_pk_fma_f32 v[216:217], v[2:3], v[216:217], v[80:81]
	v_pk_fma_f32 v[218:219], v[4:5], v[218:219], v[82:83]
	v_pk_fma_f32 v[220:221], v[2:3], v[220:221], v[96:97]
	v_pk_fma_f32 v[222:223], v[4:5], v[222:223], v[98:99]
	global_store_dwordx4 v89, v[206:209], s[100:101] sc1
	global_store_dwordx4 v90, v[210:213], s[100:101] sc1
	global_store_dwordx4 v91, v[216:219], s[100:101] sc1
	global_store_dwordx4 v92, v[220:223], s[100:101] sc1
	ds_read_b128 v[206:209], v88 offset:16896
	ds_read_b128 v[210:213], v88 offset:21120
	ds_read_b128 v[216:219], v88 offset:25344
	ds_read_b128 v[220:223], v88 offset:29568
	s_waitcnt vmcnt(4) lgkmcnt(0)
	v_pk_fma_f32 v[206:207], v[2:3], v[206:207], v[100:101]
	v_pk_fma_f32 v[208:209], v[4:5], v[208:209], v[102:103]
	v_pk_fma_f32 v[210:211], v[2:3], v[210:211], v[236:237]
	v_pk_fma_f32 v[212:213], v[4:5], v[212:213], v[238:239]
	v_pk_fma_f32 v[216:217], v[2:3], v[216:217], v[240:241]
	v_pk_fma_f32 v[218:219], v[4:5], v[218:219], v[242:243]
	v_pk_fma_f32 v[220:221], v[2:3], v[220:221], v[244:245]
	v_pk_fma_f32 v[222:223], v[4:5], v[222:223], v[246:247]
	global_store_dwordx4 v93, v[206:209], s[100:101] sc1
	global_store_dwordx4 v94, v[210:213], s[100:101] sc1
	global_store_dwordx4 v95, v[216:219], s[100:101] sc1
	global_store_dwordx4 v104, v[220:223], s[100:101] sc1
	s_add_i32 s19, s19, s3
	s_add_i32 s50, s50, s3
	s_add_i32 s51, s51, s21
	s_cmp_ge_i32 s19, s18
	s_cbranch_scc1 .LBB0_851

; __device__ __forceinline__ void epi_staged_residual(f32x4 (&acc)[4][4], int r0, int c0, unsigned char* smem, const float* __restrict__ g,
;                                                     const float* __restrict__ xs, float* __restrict__ xd) {
;     ...
; #pragma unroll
;   for (int pass = 0; pass < 2; ++pass) {
;     __syncthreads();
;     if (wr == pass) {
; #pragma unroll
;       for (int mi = 0; mi < 4; ++mi)
; #pragma unroll
;         for (int ni = 0; ni < 4; ++ni)
; #pragma unroll
;           for (int j = 0; j < 4; ++j) Ts[((r0 & 63) + mi * 16 + j) * PITCH + c0 + ni * 16] = acc[mi][ni][j];
;     }
;     __syncthreads();
; #pragma unroll
;     for (int i = 0; i < 8; ++i) {
;       const int c = t + 256 * i, row = c >> 5, ch = c & 31;
;       const float4 a = *(const float4*)(Ts + row * PITCH + ch * 4);
;       const float4 gg = *(const float4*)(g + ch * 4);
;       const size_t o = (size_t)(pass * 64 + row) * DM + ch * 4;
;       float4 x = *(const float4*)(xs + o);
;       x.x += gg.x * a.x; x.y += gg.y * a.y; x.z += gg.z * a.z; x.w += gg.w * a.w;
;       *(float4*)(xd + o) = x;
;     }
.LBB0_849:
	s_or_b64 exec, exec, s[8:9]
	s_lshl_b32 s8, s52, 7
	s_lshl_b64 s[0:1], s[0:1], 2
	s_add_u32 s9, s42, s0
	s_addc_u32 s34, s43, s1
	v_ashrrev_i32_e32 v70, 5, v84
	s_add_u32 s35, s4, s0
	v_mul_lo_u32 v71, v70, s97
	s_addc_u32 s47, s5, s1
	s_lshl_b32 s8, s8, 2
	v_add_u32_e32 v88, v0, v71
	v_ashrrev_i32_e32 v71, 31, v70
	s_add_u32 s0, s9, s8
	v_lshlrev_b64 v[70:71], 12, v[70:71]
	s_addc_u32 s1, s34, 0
	v_or_b32_e32 v70, v70, v0
	v_lshl_add_u64 v[76:77], s[0:1], 0, v[70:71]
	s_waitcnt lgkmcnt(0)
	s_barrier
	s_add_u32 s46, s35, s8
	s_addc_u32 s47, s47, 0
	v_cmp_eq_u32_e32 vcc, 1, v158
	v_mov_b32_e32 v89, v70
	v_add_u32_e32 v90, 0x8000, v70
	v_add_u32_e32 v91, 0x10000, v70
	v_add_u32_e32 v92, 0x18000, v70
	v_add_u32_e32 v93, 0x20000, v70
	v_add_u32_e32 v94, 0x28000, v70
	v_add_u32_e32 v95, 0x30000, v70
	v_add_u32_e32 v104, 0x38000, v70
	global_load_dwordx4 v[72:75], v89, s[0:1]
	global_load_dwordx4 v[76:79], v90, s[0:1]
	global_load_dwordx4 v[80:83], v91, s[0:1]
	global_load_dwordx4 v[96:99], v92, s[0:1]
	global_load_dwordx4 v[100:103], v93, s[0:1]
	global_load_dwordx4 v[236:239], v94, s[0:1]
	global_load_dwordx4 v[240:243], v95, s[0:1]
	global_load_dwordx4 v[244:247], v104, s[0:1]
	ds_read_b128 v[206:209], v88 offset:0
	ds_read_b128 v[210:213], v88 offset:4224
	ds_read_b128 v[216:219], v88 offset:8448
	ds_read_b128 v[220:223], v88 offset:12672
	s_waitcnt vmcnt(4) lgkmcnt(0)
	v_pk_fma_f32 v[206:207], v[2:3], v[206:207], v[72:73]
	v_pk_fma_f32 v[208:209], v[4:5], v[208:209], v[74:75]
	v_pk_fma_f32 v[210:211], v[2:3], v[210:211], v[76:77]
	v_pk_fma_f32 v[212:213], v[4:5], v[212:213], v[78:79]
	v_pk_fma_f32 v[216:217], v[2:3], v[216:217], v[80:81]
	v_pk_fma_f32 v[218:219], v[4:5], v[218:219], v[82:83]
	v_pk_fma_f32 v[220:221], v[2:3], v[220:221], v[96:97]
	v_pk_fma_f32 v[222:223], v[4:5], v[222:223], v[98:99]
	global_store_dwordx4 v89, v[206:209], s[46:47] sc1
	global_store_dwordx4 v90, v[210:213], s[46:47] sc1
	global_store_dwordx4 v91, v[216:219], s[46:47] sc1
	global_store_dwordx4 v92, v[220:223], s[46:47] sc1
	ds_read_b128 v[206:209], v88 offset:16896
	ds_read_b128 v[210:213], v88 offset:21120
	ds_read_b128 v[216:219], v88 offset:25344
	ds_read_b128 v[220:223], v88 offset:29568
	s_waitcnt vmcnt(4) lgkmcnt(0)
	v_pk_fma_f32 v[206:207], v[2:3], v[206:207], v[100:101]
	v_pk_fma_f32 v[208:209], v[4:5], v[208:209], v[102:103]
	v_pk_fma_f32 v[210:211], v[2:3], v[210:211], v[236:237]
	v_pk_fma_f32 v[212:213], v[4:5], v[212:213], v[238:239]
	v_pk_fma_f32 v[216:217], v[2:3], v[216:217], v[240:241]
	v_pk_fma_f32 v[218:219], v[4:5], v[218:219], v[242:243]
	v_pk_fma_f32 v[220:221], v[2:3], v[220:221], v[244:245]
	v_pk_fma_f32 v[222:223], v[4:5], v[222:223], v[246:247]
	global_store_dwordx4 v93, v[206:209], s[46:47] sc1
	global_store_dwordx4 v94, v[210:213], s[46:47] sc1
	global_store_dwordx4 v95, v[216:219], s[46:47] sc1
	global_store_dwordx4 v104, v[220:223], s[46:47] sc1
	s_barrier
	s_and_saveexec_b64 s[8:9], vcc
	s_cbranch_execz .LBB0_844
	v_lshl_add_u32 v0, v86, 2, v87
	ds_write2_b32 v0, v6, v14 offset1:16
	ds_write2_b32 v0, v7, v15 offset0:132 offset1:148
	v_add_u32_e32 v6, 0x400, v0
	ds_write2_b32 v6, v8, v16 offset0:8 offset1:24
	ds_write2_b32 v6, v9, v17 offset0:140 offset1:156
	ds_write2_b32 v0, v10, v18 offset0:32 offset1:48
	ds_write2_b32 v0, v11, v19 offset0:164 offset1:180
	ds_write2_b32 v6, v12, v20 offset0:40 offset1:56
	ds_write2_b32 v6, v13, v21 offset0:172 offset1:188
	v_add_u32_e32 v6, 0x2000, v0
	v_add_u32_e32 v7, 0x2400, v0
	ds_write2_b32 v6, v26, v38 offset0:64 offset1:80
	ds_write2_b32 v6, v27, v39 offset0:196 offset1:212
	ds_write2_b32 v7, v28, v40 offset0:72 offset1:88
	ds_write2_b32 v7, v29, v41 offset0:204 offset1:220
	ds_write2_b32 v6, v22, v30 offset0:96 offset1:112
	ds_write2_b32 v6, v23, v31 offset0:228 offset1:244
	ds_write2_b32 v7, v24, v32 offset0:104 offset1:120
	ds_write2_b32 v7, v25, v33 offset0:236 offset1:252
	v_add_u32_e32 v6, 0x4000, v0
	v_add_u32_e32 v7, 0x4400, v0
	v_add_u32_e32 v8, 0x4800, v0
	ds_write2_b32 v6, v34, v42 offset0:128 offset1:144
	ds_write2_b32 v7, v35, v43 offset0:4 offset1:20
	ds_write2_b32 v7, v36, v44 offset0:136 offset1:152
	ds_write2_b32 v8, v37, v45 offset0:12 offset1:28
	ds_write2_b32 v6, v46, v50 offset0:160 offset1:176
	ds_write2_b32 v7, v47, v51 offset0:36 offset1:52
	ds_write2_b32 v7, v48, v52 offset0:168 offset1:184
	ds_write2_b32 v8, v49, v53 offset0:44 offset1:60
	v_add_u32_e32 v6, 0x6000, v0
	v_add_u32_e32 v7, 0x6400, v0
	v_add_u32_e32 v0, 0x6800, v0
	ds_write2_b32 v6, v54, v58 offset0:192 offset1:208
	ds_write2_b32 v7, v55, v59 offset0:68 offset1:84
	ds_write2_b32 v7, v56, v60 offset0:200 offset1:216
	ds_write2_b32 v0, v57, v61 offset0:76 offset1:92
	ds_write2_b32 v6, v62, v66 offset0:224 offset1:240
	ds_write2_b32 v7, v63, v67 offset0:100 offset1:116
	ds_write2_b32 v7, v64, v68 offset0:232 offset1:248
	ds_write2_b32 v0, v65, v69 offset0:108 offset1:124
	s_branch .LBB0_844

; template <int NT, bool BKN, bool MASK = false, bool ROWSS = false, class Epi> ...
;     ...
;   for (int kt = 0; kt < nk - 2; kt += 2) {
;     GEMM_COMPUTE(0);
;     GEMM_STORE(ra1, rb1, 1);
;     GEMM_LOAD(ra1, rb1, kt + 3);
;     __syncthreads();
;     GEMM_COMPUTE(1);
;     GEMM_STORE(ra0, rb0, 0);
;     GEMM_LOAD(ra0, rb0, (kt + 4 < nkm1 ? kt + 4 : nkm1));
;     __syncthreads();
;   }
.LBB0_1162:
	s_add_i32 s0, s0, 2
	s_min_u32 s1, s0, 11
	s_lshl_b32 s94, s1, 7
	s_cmp_lt_u32 s0, 12
	s_waitcnt lgkmcnt(3)
	v_mfma_f32_16x16x32_bf16 v[78:81], v[158:161], v[188:191], v[78:81]
	v_mfma_f32_16x16x32_bf16 v[74:77], v[158:161], v[192:195], v[74:77]
	v_mfma_f32_16x16x32_bf16 v[66:69], v[158:161], v[196:199], v[66:69]
	v_mfma_f32_16x16x32_bf16 v[70:73], v[158:161], v[200:203], v[70:73]
	ds_read_b128 v[230:233], v167
	ds_read_b128 v[204:207], v166 offset:16384
	ds_read_b128 v[208:211], v166 offset:18432
	ds_read_b128 v[216:219], v166 offset:20480
	ds_read_b128 v[220:223], v166 offset:22528
	s_waitcnt lgkmcnt(7)
	v_mfma_f32_16x16x32_bf16 v[90:93], v[172:175], v[188:191], v[90:93]
	v_mfma_f32_16x16x32_bf16 v[86:89], v[172:175], v[192:195], v[86:89]
	v_mfma_f32_16x16x32_bf16 v[82:85], v[172:175], v[196:199], v[82:85]
	v_mfma_f32_16x16x32_bf16 v[114:117], v[172:175], v[200:203], v[114:117]
	s_waitcnt lgkmcnt(6)
	v_mfma_f32_16x16x32_bf16 v[102:105], v[176:179], v[188:191], v[102:105]
	v_mfma_f32_16x16x32_bf16 v[110:113], v[176:179], v[192:195], v[110:113]
	v_mfma_f32_16x16x32_bf16 v[106:109], v[176:179], v[196:199], v[106:109]
	v_mfma_f32_16x16x32_bf16 v[98:101], v[176:179], v[200:203], v[98:101]
	ds_read_b128 v[242:245], v167 offset:2048
	ds_read_b128 v[234:237], v167 offset:4096
	ds_read_b128 v[238:241], v167 offset:6144
	s_waitcnt lgkmcnt(8)
	v_mfma_f32_16x16x32_bf16 v[94:97], v[180:183], v[188:191], v[94:97]
	v_mfma_f32_16x16x32_bf16 v[126:129], v[180:183], v[192:195], v[126:129]
	v_mfma_f32_16x16x32_bf16 v[122:125], v[180:183], v[196:199], v[122:125]
	v_mfma_f32_16x16x32_bf16 v[118:121], v[180:183], v[200:203], v[118:121]
	s_waitcnt lgkmcnt(3)
	v_mfma_f32_16x16x32_bf16 v[78:81], v[230:233], v[204:207], v[78:81]
	s_waitcnt vmcnt(8)
	ds_write_b128 v170, v[14:17] offset:32768
	ds_write_b128 v170, v[10:13] offset:36864
	ds_write_b128 v170, v[6:9] offset:40960
	ds_write_b128 v170, v[18:21] offset:45056
	v_mfma_f32_16x16x32_bf16 v[74:77], v[230:233], v[208:211], v[74:77]
	ds_write_b128 v170, v[2:5] offset:49152
	ds_write_b128 v170, v[30:33] offset:53248
	ds_write_b128 v170, v[22:25] offset:57344
	ds_write_b128 v170, v[26:29] offset:61440
	v_mfma_f32_16x16x32_bf16 v[66:69], v[230:233], v[216:219], v[66:69]
	v_lshl_add_u64 v[2:3], v[156:157], 0, v[0:1]
	v_lshl_add_u64 v[4:5], v[154:155], 0, v[0:1]
	v_lshl_add_u64 v[6:7], v[152:153], 0, v[0:1]
	v_lshl_add_u64 v[18:19], v[150:151], 0, v[0:1]
	v_mfma_f32_16x16x32_bf16 v[70:73], v[230:233], v[220:223], v[70:73]
	v_lshl_add_u64 v[22:23], v[148:149], 0, v[0:1]
	v_lshl_add_u64 v[24:25], v[146:147], 0, v[0:1]
	global_load_dwordx4 v[14:17], v[2:3], off
	global_load_dwordx4 v[10:13], v[4:5], off
	s_waitcnt lgkmcnt(10)
	v_mfma_f32_16x16x32_bf16 v[90:93], v[242:245], v[204:207], v[90:93]
	s_nop 0
	global_load_dwordx4 v[6:9], v[6:7], off
	s_nop 0
	global_load_dwordx4 v[18:21], v[18:19], off
	s_nop 0
	global_load_dwordx4 v[2:5], v[22:23], off
	v_add_co_u32_e32 v22, vcc, s15, v24
	v_mfma_f32_16x16x32_bf16 v[86:89], v[242:245], v[208:211], v[86:89]
	v_addc_co_u32_e32 v23, vcc, 0, v25, vcc
	v_add_co_u32_e32 v26, vcc, s16, v24
	v_addc_co_u32_e32 v27, vcc, 0, v25, vcc
	v_add_co_u32_e32 v28, vcc, s17, v24
	v_mfma_f32_16x16x32_bf16 v[82:85], v[242:245], v[216:219], v[82:85]
	v_addc_co_u32_e32 v29, vcc, 0, v25, vcc
	global_load_dwordx4 v[30:33], v[22:23], off offset:384
	s_nop 0
	global_load_dwordx4 v[22:25], v[26:27], off offset:384
	s_nop 0
	global_load_dwordx4 v[26:29], v[28:29], off offset:384
	v_mfma_f32_16x16x32_bf16 v[114:117], v[242:245], v[220:223], v[114:117]
	s_waitcnt lgkmcnt(0)
	s_barrier
	ds_read_b128 v[158:161], v169 offset:32768
	ds_read_b128 v[188:191], v168 offset:49152
	ds_read_b128 v[192:195], v168 offset:51200
	ds_read_b128 v[196:199], v168 offset:53248
	ds_read_b128 v[200:203], v168 offset:55296
	ds_read_b128 v[172:175], v169 offset:34816
	ds_read_b128 v[176:179], v169 offset:36864
	ds_read_b128 v[180:183], v169 offset:38912
	v_mfma_f32_16x16x32_bf16 v[102:105], v[234:237], v[204:207], v[102:105]
	v_mfma_f32_16x16x32_bf16 v[110:113], v[234:237], v[208:211], v[110:113]
	v_mfma_f32_16x16x32_bf16 v[106:109], v[234:237], v[216:219], v[106:109]
	v_mfma_f32_16x16x32_bf16 v[98:101], v[234:237], v[220:223], v[98:101]
	v_mfma_f32_16x16x32_bf16 v[94:97], v[238:241], v[204:207], v[94:97]
	v_mfma_f32_16x16x32_bf16 v[126:129], v[238:241], v[208:211], v[126:129]
	v_mfma_f32_16x16x32_bf16 v[122:125], v[238:241], v[216:219], v[122:125]
	v_mfma_f32_16x16x32_bf16 v[118:121], v[238:241], v[220:223], v[118:121]
	s_waitcnt lgkmcnt(3)
	v_mfma_f32_16x16x32_bf16 v[78:81], v[158:161], v[188:191], v[78:81]
	v_mfma_f32_16x16x32_bf16 v[74:77], v[158:161], v[192:195], v[74:77]
	v_mfma_f32_16x16x32_bf16 v[66:69], v[158:161], v[196:199], v[66:69]
	v_mfma_f32_16x16x32_bf16 v[70:73], v[158:161], v[200:203], v[70:73]
	ds_read_b128 v[230:233], v167 offset:32768
	ds_read_b128 v[204:207], v166 offset:49152
	ds_read_b128 v[208:211], v166 offset:51200
	ds_read_b128 v[216:219], v166 offset:53248
	ds_read_b128 v[220:223], v166 offset:55296
	s_waitcnt lgkmcnt(7)
	v_mfma_f32_16x16x32_bf16 v[90:93], v[172:175], v[188:191], v[90:93]
	v_mfma_f32_16x16x32_bf16 v[86:89], v[172:175], v[192:195], v[86:89]
	v_mfma_f32_16x16x32_bf16 v[82:85], v[172:175], v[196:199], v[82:85]
	v_mfma_f32_16x16x32_bf16 v[114:117], v[172:175], v[200:203], v[114:117]
	s_waitcnt lgkmcnt(6)
	v_mfma_f32_16x16x32_bf16 v[102:105], v[176:179], v[188:191], v[102:105]
	v_mfma_f32_16x16x32_bf16 v[110:113], v[176:179], v[192:195], v[110:113]
	v_mfma_f32_16x16x32_bf16 v[106:109], v[176:179], v[196:199], v[106:109]
	v_mfma_f32_16x16x32_bf16 v[98:101], v[176:179], v[200:203], v[98:101]
	ds_read_b128 v[242:245], v167 offset:34816
	ds_read_b128 v[234:237], v167 offset:36864
	ds_read_b128 v[238:241], v167 offset:38912
	s_waitcnt lgkmcnt(8)
; template <int NT, bool BKN, bool MASK = false, bool ROWSS = false, class Epi> ...
;     ...
;   for (int kt = 0; kt < nk - 2; kt += 2) {
;     GEMM_COMPUTE(0);
;     GEMM_STORE(ra1, rb1, 1);
;     GEMM_LOAD(ra1, rb1, kt + 3);
;     __syncthreads();
;     GEMM_COMPUTE(1);
;     GEMM_STORE(ra0, rb0, 0);
;     GEMM_LOAD(ra0, rb0, (kt + 4 < nkm1 ? kt + 4 : nkm1));
;     __syncthreads();
;   }
;   GEMM_COMPUTE(0);
;   GEMM_STORE(ra1, rb1, 1);
;   __syncthreads();
;   GEMM_COMPUTE(1);
	v_mfma_f32_16x16x32_bf16 v[94:97], v[180:183], v[188:191], v[94:97]
	v_mfma_f32_16x16x32_bf16 v[126:129], v[180:183], v[192:195], v[126:129]
	v_mfma_f32_16x16x32_bf16 v[122:125], v[180:183], v[196:199], v[122:125]
	v_mfma_f32_16x16x32_bf16 v[118:121], v[180:183], v[200:203], v[118:121]
	s_waitcnt lgkmcnt(3)
	v_mfma_f32_16x16x32_bf16 v[78:81], v[230:233], v[204:207], v[78:81]
	v_lshl_add_u64 v[146:147], v[146:147], 0, s[6:7]
	v_lshl_add_u64 v[148:149], v[148:149], 0, s[6:7]
	v_lshl_add_u64 v[150:151], v[150:151], 0, s[6:7]
	v_lshl_add_u64 v[152:153], v[152:153], 0, s[6:7]
	v_mfma_f32_16x16x32_bf16 v[74:77], v[230:233], v[208:211], v[74:77]
	v_lshl_add_u64 v[154:155], v[154:155], 0, s[6:7]
	v_lshl_add_u64 v[156:157], v[156:157], 0, s[6:7]
	s_waitcnt vmcnt(8)
	ds_write_b128 v170, v[34:37]
	ds_write_b128 v170, v[38:41] offset:4096
	v_mfma_f32_16x16x32_bf16 v[66:69], v[230:233], v[216:219], v[66:69]
	ds_write_b128 v170, v[42:45] offset:8192
	ds_write_b128 v170, v[46:49] offset:12288
	ds_write_b128 v170, v[50:53] offset:16384
	ds_write_b128 v170, v[58:61] offset:20480
	v_mfma_f32_16x16x32_bf16 v[70:73], v[230:233], v[220:223], v[70:73]
	ds_write_b128 v170, v[54:57] offset:24576
	ds_write_b128 v170, v[62:65] offset:28672
	v_lshl_add_u64 v[34:35], v[134:135], 0, s[94:95]
	v_lshl_add_u64 v[38:39], v[132:133], 0, s[94:95]
	s_waitcnt lgkmcnt(10)
	v_mfma_f32_16x16x32_bf16 v[90:93], v[242:245], v[204:207], v[90:93]
	v_lshl_add_u64 v[42:43], v[130:131], 0, s[94:95]
	v_lshl_add_u64 v[46:47], v[136:137], 0, s[94:95]
	v_lshl_add_u64 v[50:51], v[138:139], 0, s[94:95]
	v_lshl_add_u64 v[54:55], v[140:141], 0, s[94:95]
	v_mfma_f32_16x16x32_bf16 v[86:89], v[242:245], v[208:211], v[86:89]
	v_lshl_add_u64 v[56:57], v[142:143], 0, s[94:95]
	v_lshl_add_u64 v[62:63], v[144:145], 0, s[94:95]
	global_load_dwordx4 v[34:37], v[34:35], off offset:512
	s_nop 0
	global_load_dwordx4 v[38:41], v[38:39], off offset:512
	v_mfma_f32_16x16x32_bf16 v[82:85], v[242:245], v[216:219], v[82:85]
	s_nop 0
	global_load_dwordx4 v[42:45], v[42:43], off offset:512
	s_nop 0
	global_load_dwordx4 v[46:49], v[46:47], off offset:512
	s_nop 0
	global_load_dwordx4 v[50:53], v[50:51], off offset:512
	s_nop 0
	global_load_dwordx4 v[58:61], v[54:55], off offset:512
	v_mfma_f32_16x16x32_bf16 v[114:117], v[242:245], v[220:223], v[114:117]
	s_nop 0
	global_load_dwordx4 v[54:57], v[56:57], off offset:512
	global_load_dwordx4 v[62:65], v[62:63], off offset:512
	s_waitcnt lgkmcnt(0)
	s_barrier
	ds_read_b128 v[158:161], v169
	ds_read_b128 v[188:191], v168 offset:16384
	ds_read_b128 v[192:195], v168 offset:18432
	ds_read_b128 v[196:199], v168 offset:20480
	ds_read_b128 v[200:203], v168 offset:22528
	ds_read_b128 v[172:175], v169 offset:2048
	ds_read_b128 v[176:179], v169 offset:4096
	ds_read_b128 v[180:183], v169 offset:6144
	v_mfma_f32_16x16x32_bf16 v[102:105], v[234:237], v[204:207], v[102:105]
	v_mfma_f32_16x16x32_bf16 v[110:113], v[234:237], v[208:211], v[110:113]
	v_mfma_f32_16x16x32_bf16 v[106:109], v[234:237], v[216:219], v[106:109]
	v_mfma_f32_16x16x32_bf16 v[98:101], v[234:237], v[220:223], v[98:101]
	v_mfma_f32_16x16x32_bf16 v[94:97], v[238:241], v[204:207], v[94:97]
	v_mfma_f32_16x16x32_bf16 v[126:129], v[238:241], v[208:211], v[126:129]
	v_mfma_f32_16x16x32_bf16 v[122:125], v[238:241], v[216:219], v[122:125]
	v_mfma_f32_16x16x32_bf16 v[118:121], v[238:241], v[220:223], v[118:121]
	s_cbranch_scc1 .LBB0_1162
	s_waitcnt vmcnt(0)
	ds_read_b128 v[34:37], v169
	ds_read_b128 v[38:41], v169 offset:2048
	ds_read_b128 v[42:45], v169 offset:4096
	ds_read_b128 v[46:49], v169 offset:6144
	ds_read_b128 v[50:53], v168 offset:16384
	ds_read_b128 v[54:57], v168 offset:18432
	ds_read_b128 v[58:61], v168 offset:20480
	ds_read_b128 v[62:65], v168 offset:22528
	v_lshlrev_b32_e32 v0, 6, v164
	s_waitcnt lgkmcnt(3)
	v_mfma_f32_16x16x32_bf16 v[78:81], v[34:37], v[50:53], v[78:81]
	v_lshl_or_b32 v0, v165, 2, v0
	v_mul_lo_u32 v0, v0, s96
	s_waitcnt lgkmcnt(2)
	v_mfma_f32_16x16x32_bf16 v[74:77], v[34:37], v[54:57], v[74:77]
	s_waitcnt lgkmcnt(1)
	v_mfma_f32_16x16x32_bf16 v[66:69], v[34:37], v[58:61], v[66:69]
	s_waitcnt lgkmcnt(0)
	v_mfma_f32_16x16x32_bf16 v[34:37], v[34:37], v[62:65], v[70:73]
	v_mfma_f32_16x16x32_bf16 v[70:73], v[38:41], v[50:53], v[90:93]
	v_mfma_f32_16x16x32_bf16 v[86:89], v[38:41], v[54:57], v[86:89]
	v_mfma_f32_16x16x32_bf16 v[82:85], v[38:41], v[58:61], v[82:85]
	v_mfma_f32_16x16x32_bf16 v[38:41], v[38:41], v[62:65], v[114:117]
	v_mfma_f32_16x16x32_bf16 v[90:93], v[42:45], v[50:53], v[102:105]
	v_mfma_f32_16x16x32_bf16 v[102:105], v[42:45], v[54:57], v[110:113]
	v_mfma_f32_16x16x32_bf16 v[106:109], v[42:45], v[58:61], v[106:109]
	v_mfma_f32_16x16x32_bf16 v[42:45], v[42:45], v[62:65], v[98:101]
	v_mfma_f32_16x16x32_bf16 v[50:53], v[46:49], v[50:53], v[94:97]
	v_mfma_f32_16x16x32_bf16 v[54:57], v[46:49], v[54:57], v[126:129]
	v_mfma_f32_16x16x32_bf16 v[58:61], v[46:49], v[58:61], v[122:125]
	v_mfma_f32_16x16x32_bf16 v[46:49], v[46:49], v[62:65], v[118:121]
	ds_read_b128 v[62:65], v167
	ds_read_b128 v[94:97], v167 offset:2048
	ds_read_b128 v[98:101], v167 offset:4096
	ds_read_b128 v[110:113], v167 offset:6144
	ds_read_b128 v[114:117], v166 offset:16384
	ds_read_b128 v[118:121], v166 offset:18432
	ds_read_b128 v[122:125], v166 offset:20480
	ds_read_b128 v[126:129], v166 offset:22528
	ds_write_b128 v170, v[14:17] offset:32768
	ds_write_b128 v170, v[10:13] offset:36864
	ds_write_b128 v170, v[6:9] offset:40960
	ds_write_b128 v170, v[18:21] offset:45056
	ds_write_b128 v170, v[2:5] offset:49152
	ds_write_b128 v170, v[30:33] offset:53248
	ds_write_b128 v170, v[22:25] offset:57344
	ds_write_b128 v170, v[26:29] offset:61440
	s_waitcnt lgkmcnt(0)
	v_mfma_f32_16x16x32_bf16 v[78:81], v[62:65], v[114:117], v[78:81]
	s_barrier
; __device__ __forceinline__ u16 f2bf(float f) { return (u16)(pack2(f, 0.f) & 0xffffu); }
; __device__ __forceinline__ float silu_f(float x) { return x / (1.f + __expf(-x)); }
; template <int NT, bool BKN, bool MASK = false, bool ROWSS = false, class Epi> ...
;     ...
;   GEMM_COMPUTE(1);
; __device__ __forceinline__ void phase_moe_up(const Params& p, int l, bool last, unsigned char* smem) {
;     ...
; #pragma unroll
;       for (int mi = 0; mi < 4; ++mi)
; #pragma unroll
;         for (int n2 = 0; n2 < 2; ++n2)
; #pragma unroll
;           for (int j = 0; j < 4; ++j) {
;             const int m = r0 + mi * 16 + j;
;             const int fl = (c0 >> 6) * 32 + n2 * 16 + (c0 & 15);
;             Ts[m * 72 + fl] = f2bf(silu_f(acc[mi][2 * n2][j]) * acc[mi][2 * n2 + 1][j]);
;           }
	ds_read_b128 v[2:5], v169 offset:32768
	ds_read_b128 v[6:9], v169 offset:34816
	ds_read_b128 v[10:13], v169 offset:36864
	ds_read_b128 v[14:17], v169 offset:38912
	ds_read_b128 v[18:21], v168 offset:49152
	ds_read_b128 v[22:25], v168 offset:51200
	ds_read_b128 v[26:29], v168 offset:53248
	ds_read_b128 v[30:33], v168 offset:55296
	v_mfma_f32_16x16x32_bf16 v[74:77], v[62:65], v[118:121], v[74:77]
	v_mfma_f32_16x16x32_bf16 v[66:69], v[62:65], v[122:125], v[66:69]
	v_mfma_f32_16x16x32_bf16 v[34:37], v[62:65], v[126:129], v[34:37]
	v_mfma_f32_16x16x32_bf16 v[62:65], v[94:97], v[114:117], v[70:73]
	v_mfma_f32_16x16x32_bf16 v[70:73], v[94:97], v[118:121], v[86:89]
	v_mfma_f32_16x16x32_bf16 v[86:89], v[98:101], v[114:117], v[90:93]
	v_mfma_f32_16x16x32_bf16 v[90:93], v[98:101], v[118:121], v[102:105]
	v_mfma_f32_16x16x32_bf16 v[50:53], v[110:113], v[114:117], v[50:53]
	v_mfma_f32_16x16x32_bf16 v[54:57], v[110:113], v[118:121], v[54:57]
	v_mfma_f32_16x16x32_bf16 v[58:61], v[110:113], v[122:125], v[58:61]
	v_mfma_f32_16x16x32_bf16 v[46:49], v[110:113], v[126:129], v[46:49]
	s_waitcnt lgkmcnt(3)
	v_mfma_f32_16x16x32_bf16 v[78:81], v[2:5], v[18:21], v[78:81]
	v_mfma_f32_16x16x32_bf16 v[82:85], v[94:97], v[122:125], v[82:85]
	v_mfma_f32_16x16x32_bf16 v[38:41], v[94:97], v[126:129], v[38:41]
	v_mfma_f32_16x16x32_bf16 v[94:97], v[98:101], v[122:125], v[106:109]
	v_mfma_f32_16x16x32_bf16 v[42:45], v[98:101], v[126:129], v[42:45]
	s_waitcnt lgkmcnt(2)
	v_mfma_f32_16x16x32_bf16 v[74:77], v[2:5], v[22:25], v[74:77]
	s_waitcnt lgkmcnt(1)
	v_mfma_f32_16x16x32_bf16 v[66:69], v[2:5], v[26:29], v[66:69]
	s_waitcnt lgkmcnt(0)
	v_mfma_f32_16x16x32_bf16 v[2:5], v[2:5], v[30:33], v[34:37]
	v_mfma_f32_16x16x32_bf16 v[34:37], v[6:9], v[18:21], v[62:65]
	v_mfma_f32_16x16x32_bf16 v[70:73], v[6:9], v[22:25], v[70:73]
	v_mfma_f32_16x16x32_bf16 v[86:89], v[10:13], v[18:21], v[86:89]
	v_mfma_f32_16x16x32_bf16 v[90:93], v[10:13], v[22:25], v[90:93]
	v_mfma_f32_16x16x32_bf16 v[98:101], v[14:17], v[18:21], v[50:53]
	v_mfma_f32_16x16x32_bf16 v[102:105], v[14:17], v[22:25], v[54:57]
	v_mfma_f32_16x16x32_bf16 v[106:109], v[14:17], v[26:29], v[58:61]
	v_mfma_f32_16x16x32_bf16 v[110:113], v[14:17], v[30:33], v[46:49]
	ds_read_b128 v[14:17], v167 offset:32768
	ds_read_b128 v[18:21], v167 offset:34816
	ds_read_b128 v[22:25], v167 offset:36864
	ds_read_b128 v[114:117], v167 offset:38912
	ds_read_b128 v[118:121], v166 offset:49152
	ds_read_b128 v[122:125], v166 offset:51200
	ds_read_b128 v[126:129], v166 offset:53248
	ds_read_b128 v[130:133], v166 offset:55296
	s_waitcnt lgkmcnt(3)
	v_mfma_f32_16x16x32_bf16 v[58:61], v[14:17], v[118:121], v[78:81]
	s_waitcnt lgkmcnt(1)
	v_mfma_f32_16x16x32_bf16 v[50:53], v[14:17], v[126:129], v[66:69]
	v_mfma_f32_16x16x32_bf16 v[46:49], v[18:21], v[122:125], v[70:73]
	s_nop 4
	v_mul_f32_e32 v68, 0xbfb8aa3b, v58
	v_exp_f32_e32 v68, v68
	v_lshlrev_b32_e32 v67, 5, v163
	v_mfma_f32_16x16x32_bf16 v[62:65], v[14:17], v[122:125], v[74:77]
	v_and_or_b32 v67, v67, 32, v162
	v_add_f32_e32 v68, 1.0, v68
	v_div_scale_f32 v69, s[0:1], v68, v68, v58
	v_rcp_f32_e32 v70, v69
	v_mov_b32_e32 v66, v187
	v_lshl_add_u32 v0, v67, 1, v0
	v_fma_f32 v71, -v69, v70, 1.0
	v_fmac_f32_e32 v70, v71, v70
	v_div_scale_f32 v71, vcc, v58, v68, v58
	v_mul_f32_e32 v72, v71, v70
	v_fma_f32 v73, -v69, v72, v71
	v_fmac_f32_e32 v72, v73, v70
	v_fma_f32 v69, -v69, v72, v71
	v_div_fmas_f32 v69, v69, v70, v72
	v_div_fixup_f32 v58, v69, v68, v58
	v_mul_f32_e32 v58, v62, v58
	v_cvt_pk_bf16_f32 v58, v58, s0
	s_waitcnt lgkmcnt(0)
	s_barrier
	ds_write_b16 v0, v58
	v_mul_f32_e32 v58, 0xbfb8aa3b, v59
	v_exp_f32_e32 v58, v58
	v_mfma_f32_16x16x32_bf16 v[54:57], v[14:17], v[130:133], v[2:5]
	v_add_f32_e32 v58, 1.0, v58
	v_div_scale_f32 v62, s[0:1], v58, v58, v59
	v_rcp_f32_e32 v67, v62
	v_mfma_f32_16x16x32_bf16 v[94:97], v[10:13], v[26:29], v[94:97]
	v_fma_f32 v68, -v62, v67, 1.0
	v_fmac_f32_e32 v67, v68, v67
	v_div_scale_f32 v68, vcc, v59, v58, v59
	v_mul_f32_e32 v69, v68, v67
	v_fma_f32 v70, -v62, v69, v68
	v_fmac_f32_e32 v69, v70, v67
	v_fma_f32 v62, -v62, v69, v68
	v_div_fmas_f32 v62, v62, v67, v69
	v_div_fixup_f32 v58, v62, v58, v59
	v_mul_f32_e32 v58, v63, v58
	v_cvt_pk_bf16_f32 v58, v58, s0
	ds_write_b16 v0, v58 offset:144
	v_mul_f32_e32 v58, 0xbfb8aa3b, v60
	v_exp_f32_e32 v58, v58
	v_mfma_f32_16x16x32_bf16 v[10:13], v[10:13], v[30:33], v[42:45]
	v_add_f32_e32 v58, 1.0, v58
	v_div_scale_f32 v59, s[0:1], v58, v58, v60
	v_rcp_f32_e32 v62, v59
	v_mfma_f32_16x16x32_bf16 v[42:45], v[18:21], v[118:121], v[34:37]
	v_fma_f32 v63, -v59, v62, 1.0
	v_fmac_f32_e32 v62, v63, v62
	v_div_scale_f32 v63, vcc, v60, v58, v60
	v_mul_f32_e32 v67, v63, v62
	v_fma_f32 v68, -v59, v67, v63
	v_fmac_f32_e32 v67, v68, v62
	v_fma_f32 v59, -v59, v67, v63
	v_div_fmas_f32 v59, v59, v62, v67
	v_div_fixup_f32 v58, v59, v58, v60
	v_mul_f32_e32 v58, v64, v58
	v_cvt_pk_bf16_f32 v58, v58, s0
	ds_write_b16 v0, v58 offset:288
	v_mul_f32_e32 v58, 0xbfb8aa3b, v61
	v_exp_f32_e32 v58, v58
	v_mfma_f32_16x16x32_bf16 v[82:85], v[6:9], v[26:29], v[82:85]
	v_add_f32_e32 v58, 1.0, v58
	v_div_scale_f32 v59, s[0:1], v58, v58, v61
	v_rcp_f32_e32 v60, v59
	v_mfma_f32_16x16x32_bf16 v[34:37], v[18:21], v[126:129], v[82:85]
	v_fma_f32 v62, -v59, v60, 1.0
	v_fmac_f32_e32 v60, v62, v60
	v_div_scale_f32 v62, vcc, v61, v58, v61
	v_mul_f32_e32 v63, v62, v60
	v_fma_f32 v64, -v59, v63, v62
	v_fmac_f32_e32 v63, v64, v60
	v_fma_f32 v59, -v59, v63, v62
	v_div_fmas_f32 v59, v59, v60, v63
	v_div_fixup_f32 v58, v59, v58, v61
	v_mul_f32_e32 v58, v65, v58
	v_cvt_pk_bf16_f32 v58, v58, s0
	ds_write_b16 v0, v58 offset:432
	v_mul_f32_e32 v58, 0xbfb8aa3b, v50
; __device__ __forceinline__ u16 f2bf(float f) { return (u16)(pack2(f, 0.f) & 0xffffu); }
; __device__ __forceinline__ float silu_f(float x) { return x / (1.f + __expf(-x)); }
; __device__ __forceinline__ void phase_moe_up(const Params& p, int l, bool last, unsigned char* smem) {
;     ...
;       for (int mi = 0; mi < 4; ++mi)
; #pragma unroll
;         for (int n2 = 0; n2 < 2; ++n2)
; #pragma unroll
;           for (int j = 0; j < 4; ++j) {
;             const int m = r0 + mi * 16 + j;
;             const int fl = (c0 >> 6) * 32 + n2 * 16 + (c0 & 15);
;             Ts[m * 72 + fl] = f2bf(silu_f(acc[mi][2 * n2][j]) * acc[mi][2 * n2 + 1][j]);
;           }
	v_exp_f32_e32 v58, v58
	v_mfma_f32_16x16x32_bf16 v[6:9], v[6:9], v[30:33], v[38:41]
	v_add_f32_e32 v58, 1.0, v58
	v_div_scale_f32 v59, s[0:1], v58, v58, v50
	v_rcp_f32_e32 v60, v59
	v_mfma_f32_16x16x32_bf16 v[38:41], v[18:21], v[130:133], v[6:9]
	v_fma_f32 v61, -v59, v60, 1.0
	v_fmac_f32_e32 v60, v61, v60
	v_div_scale_f32 v61, vcc, v50, v58, v50
	v_mul_f32_e32 v62, v61, v60
	v_fma_f32 v63, -v59, v62, v61
	v_fmac_f32_e32 v62, v63, v60
	v_fma_f32 v59, -v59, v62, v61
	v_div_fmas_f32 v59, v59, v60, v62
	v_div_fixup_f32 v50, v59, v58, v50
	v_mul_f32_e32 v50, v54, v50
	v_cvt_pk_bf16_f32 v50, v50, s0
	ds_write_b16 v0, v50 offset:32
	v_mul_f32_e32 v50, 0xbfb8aa3b, v51
	v_exp_f32_e32 v50, v50
	v_mfma_f32_16x16x32_bf16 v[26:29], v[22:25], v[118:121], v[86:89]
	v_add_f32_e32 v50, 1.0, v50
	v_div_scale_f32 v54, s[0:1], v50, v50, v51
	v_rcp_f32_e32 v58, v54
	v_mfma_f32_16x16x32_bf16 v[30:33], v[22:25], v[122:125], v[90:93]
	v_fma_f32 v59, -v54, v58, 1.0
	v_fmac_f32_e32 v58, v59, v58
	v_div_scale_f32 v59, vcc, v51, v50, v51
	v_mul_f32_e32 v60, v59, v58
	v_fma_f32 v61, -v54, v60, v59
	v_fmac_f32_e32 v60, v61, v58
	v_fma_f32 v54, -v54, v60, v59
	v_div_fmas_f32 v54, v54, v58, v60
	v_div_fixup_f32 v50, v54, v50, v51
	v_mul_f32_e32 v50, v55, v50
	v_cvt_pk_bf16_f32 v50, v50, s0
	ds_write_b16 v0, v50 offset:176
	v_mul_f32_e32 v50, 0xbfb8aa3b, v52
	v_exp_f32_e32 v50, v50
	v_mfma_f32_16x16x32_bf16 v[18:21], v[22:25], v[126:129], v[94:97]
	v_add_f32_e32 v50, 1.0, v50
	v_div_scale_f32 v51, s[0:1], v50, v50, v52
	v_rcp_f32_e32 v54, v51
	v_mfma_f32_16x16x32_bf16 v[22:25], v[22:25], v[130:133], v[10:13]
	v_fma_f32 v55, -v51, v54, 1.0
	v_fmac_f32_e32 v54, v55, v54
	v_div_scale_f32 v55, vcc, v52, v50, v52
	v_mul_f32_e32 v58, v55, v54
	v_fma_f32 v59, -v51, v58, v55
	v_fmac_f32_e32 v58, v59, v54
	v_fma_f32 v51, -v51, v58, v55
	v_div_fmas_f32 v51, v51, v54, v58
	v_div_fixup_f32 v50, v51, v50, v52
	v_mul_f32_e32 v50, v56, v50
	v_cvt_pk_bf16_f32 v50, v50, s0
	ds_write_b16 v0, v50 offset:320
	v_mul_f32_e32 v50, 0xbfb8aa3b, v53
	v_exp_f32_e32 v50, v50
	v_mfma_f32_16x16x32_bf16 v[10:13], v[114:117], v[118:121], v[98:101]
	v_add_f32_e32 v50, 1.0, v50
	v_div_scale_f32 v51, s[0:1], v50, v50, v53
	v_rcp_f32_e32 v52, v51
	v_mfma_f32_16x16x32_bf16 v[14:17], v[114:117], v[122:125], v[102:105]
	v_fma_f32 v54, -v51, v52, 1.0
	v_fmac_f32_e32 v52, v54, v52
	v_div_scale_f32 v54, vcc, v53, v50, v53
	v_mul_f32_e32 v55, v54, v52
	v_fma_f32 v56, -v51, v55, v54
	v_fmac_f32_e32 v55, v56, v52
	v_fma_f32 v51, -v51, v55, v54
	v_div_fmas_f32 v51, v51, v52, v55
	v_div_fixup_f32 v50, v51, v50, v53
	v_mul_f32_e32 v50, v57, v50
	v_cvt_pk_bf16_f32 v50, v50, s0
	ds_write_b16 v0, v50 offset:464
	v_mul_f32_e32 v50, 0xbfb8aa3b, v42
	v_exp_f32_e32 v50, v50
	v_mfma_f32_16x16x32_bf16 v[2:5], v[114:117], v[126:129], v[106:109]
	v_add_f32_e32 v50, 1.0, v50
	v_div_scale_f32 v51, s[0:1], v50, v50, v42
	v_rcp_f32_e32 v52, v51
	v_mfma_f32_16x16x32_bf16 v[6:9], v[114:117], v[130:133], v[110:113]
	v_fma_f32 v53, -v51, v52, 1.0
	v_fmac_f32_e32 v52, v53, v52
	v_div_scale_f32 v53, vcc, v42, v50, v42
	v_mul_f32_e32 v54, v53, v52
	v_fma_f32 v55, -v51, v54, v53
	v_fmac_f32_e32 v54, v55, v52
	v_fma_f32 v51, -v51, v54, v53
	v_div_fmas_f32 v51, v51, v52, v54
	v_div_fixup_f32 v42, v51, v50, v42
	v_mul_f32_e32 v42, v46, v42
	v_cvt_pk_bf16_f32 v42, v42, s0
	ds_write_b16 v0, v42 offset:2304
	v_mul_f32_e32 v42, 0xbfb8aa3b, v43
	v_exp_f32_e32 v42, v42
	s_nop 0
	v_add_f32_e32 v42, 1.0, v42
	v_div_scale_f32 v46, s[0:1], v42, v42, v43
	v_rcp_f32_e32 v50, v46
	s_nop 0
	v_fma_f32 v51, -v46, v50, 1.0
	v_fmac_f32_e32 v50, v51, v50
	v_div_scale_f32 v51, vcc, v43, v42, v43
	v_mul_f32_e32 v52, v51, v50
	v_fma_f32 v53, -v46, v52, v51
	v_fmac_f32_e32 v52, v53, v50
	v_fma_f32 v46, -v46, v52, v51
	v_div_fmas_f32 v46, v46, v50, v52
	v_div_fixup_f32 v42, v46, v42, v43
	v_mul_f32_e32 v42, v47, v42
	v_cvt_pk_bf16_f32 v42, v42, s0
	ds_write_b16 v0, v42 offset:2448
	v_mul_f32_e32 v42, 0xbfb8aa3b, v44
	v_exp_f32_e32 v42, v42
	s_nop 0
	v_add_f32_e32 v42, 1.0, v42
	v_div_scale_f32 v43, s[0:1], v42, v42, v44
	v_rcp_f32_e32 v46, v43
	s_nop 0
	v_fma_f32 v47, -v43, v46, 1.0
	v_fmac_f32_e32 v46, v47, v46
	v_div_scale_f32 v47, vcc, v44, v42, v44
	v_mul_f32_e32 v50, v47, v46
	v_fma_f32 v51, -v43, v50, v47
	v_fmac_f32_e32 v50, v51, v46
	v_fma_f32 v43, -v43, v50, v47
	v_div_fmas_f32 v43, v43, v46, v50
	v_div_fixup_f32 v42, v43, v42, v44
	v_mul_f32_e32 v42, v48, v42
	v_cvt_pk_bf16_f32 v42, v42, s0
	ds_write_b16 v0, v42 offset:2592
	v_mul_f32_e32 v42, 0xbfb8aa3b, v45
	v_exp_f32_e32 v42, v42
	s_nop 0
	v_add_f32_e32 v42, 1.0, v42
	v_div_scale_f32 v43, s[0:1], v42, v42, v45
	v_rcp_f32_e32 v44, v43
	s_nop 0
	v_fma_f32 v46, -v43, v44, 1.0
	v_fmac_f32_e32 v44, v46, v44
	v_div_scale_f32 v46, vcc, v45, v42, v45
	v_mul_f32_e32 v47, v46, v44
	v_fma_f32 v48, -v43, v47, v46
	v_fmac_f32_e32 v47, v48, v44
	v_fma_f32 v43, -v43, v47, v46
	v_div_fmas_f32 v43, v43, v44, v47
	v_div_fixup_f32 v42, v43, v42, v45
	v_mul_f32_e32 v42, v49, v42
	v_cvt_pk_bf16_f32 v42, v42, s0
	ds_write_b16 v0, v42 offset:2736
	v_mul_f32_e32 v42, 0xbfb8aa3b, v34
	v_exp_f32_e32 v42, v42
	s_nop 0
	v_add_f32_e32 v42, 1.0, v42
	v_div_scale_f32 v43, s[0:1], v42, v42, v34
	v_rcp_f32_e32 v44, v43
	s_nop 0
	v_fma_f32 v45, -v43, v44, 1.0
	v_fmac_f32_e32 v44, v45, v44
	v_div_scale_f32 v45, vcc, v34, v42, v34
	v_mul_f32_e32 v46, v45, v44
	v_fma_f32 v47, -v43, v46, v45
	v_fmac_f32_e32 v46, v47, v44
	v_fma_f32 v43, -v43, v46, v45
	v_div_fmas_f32 v43, v43, v44, v46
	v_div_fixup_f32 v34, v43, v42, v34
	v_mul_f32_e32 v34, v38, v34
	v_cvt_pk_bf16_f32 v34, v34, s0
	ds_write_b16 v0, v34 offset:2336
	v_mul_f32_e32 v34, 0xbfb8aa3b, v35
; __device__ __forceinline__ u16 f2bf(float f) { return (u16)(pack2(f, 0.f) & 0xffffu); }
; __device__ __forceinline__ float silu_f(float x) { return x / (1.f + __expf(-x)); }
; __device__ __forceinline__ void phase_moe_up(const Params& p, int l, bool last, unsigned char* smem) {
;     ...
;       for (int mi = 0; mi < 4; ++mi)
; #pragma unroll
;         for (int n2 = 0; n2 < 2; ++n2)
; #pragma unroll
;           for (int j = 0; j < 4; ++j) {
;             const int m = r0 + mi * 16 + j;
;             const int fl = (c0 >> 6) * 32 + n2 * 16 + (c0 & 15);
;             Ts[m * 72 + fl] = f2bf(silu_f(acc[mi][2 * n2][j]) * acc[mi][2 * n2 + 1][j]);
;           }
	v_exp_f32_e32 v34, v34
	s_nop 0
	v_add_f32_e32 v34, 1.0, v34
	v_div_scale_f32 v38, s[0:1], v34, v34, v35
	v_rcp_f32_e32 v42, v38
	s_nop 0
	v_fma_f32 v43, -v38, v42, 1.0
	v_fmac_f32_e32 v42, v43, v42
	v_div_scale_f32 v43, vcc, v35, v34, v35
	v_mul_f32_e32 v44, v43, v42
	v_fma_f32 v45, -v38, v44, v43
	v_fmac_f32_e32 v44, v45, v42
	v_fma_f32 v38, -v38, v44, v43
	v_div_fmas_f32 v38, v38, v42, v44
	v_div_fixup_f32 v34, v38, v34, v35
	v_mul_f32_e32 v34, v39, v34
	v_cvt_pk_bf16_f32 v34, v34, s0
	ds_write_b16 v0, v34 offset:2480
	v_mul_f32_e32 v34, 0xbfb8aa3b, v36
	v_exp_f32_e32 v34, v34
	s_nop 0
	v_add_f32_e32 v34, 1.0, v34
	v_div_scale_f32 v35, s[0:1], v34, v34, v36
	v_rcp_f32_e32 v38, v35
	s_nop 0
	v_fma_f32 v39, -v35, v38, 1.0
	v_fmac_f32_e32 v38, v39, v38
	v_div_scale_f32 v39, vcc, v36, v34, v36
	v_mul_f32_e32 v42, v39, v38
	v_fma_f32 v43, -v35, v42, v39
	v_fmac_f32_e32 v42, v43, v38
	v_fma_f32 v35, -v35, v42, v39
	v_div_fmas_f32 v35, v35, v38, v42
	v_div_fixup_f32 v34, v35, v34, v36
	v_mul_f32_e32 v34, v40, v34
	v_cvt_pk_bf16_f32 v34, v34, s0
	ds_write_b16 v0, v34 offset:2624
	v_mul_f32_e32 v34, 0xbfb8aa3b, v37
	v_exp_f32_e32 v34, v34
	s_nop 0
	v_add_f32_e32 v34, 1.0, v34
	v_div_scale_f32 v35, s[0:1], v34, v34, v37
	v_rcp_f32_e32 v36, v35
	s_nop 0
	v_fma_f32 v38, -v35, v36, 1.0
	v_fmac_f32_e32 v36, v38, v36
	v_div_scale_f32 v38, vcc, v37, v34, v37
	v_mul_f32_e32 v39, v38, v36
	v_fma_f32 v40, -v35, v39, v38
	v_fmac_f32_e32 v39, v40, v36
	v_fma_f32 v35, -v35, v39, v38
	v_div_fmas_f32 v35, v35, v36, v39
	v_div_fixup_f32 v34, v35, v34, v37
	v_mul_f32_e32 v34, v41, v34
	v_cvt_pk_bf16_f32 v34, v34, s0
	ds_write_b16 v0, v34 offset:2768
	v_mul_f32_e32 v34, 0xbfb8aa3b, v26
	v_exp_f32_e32 v34, v34
	s_nop 0
	v_add_f32_e32 v34, 1.0, v34
	v_div_scale_f32 v35, s[0:1], v34, v34, v26
	v_rcp_f32_e32 v36, v35
	s_nop 0
	v_fma_f32 v37, -v35, v36, 1.0
	v_fmac_f32_e32 v36, v37, v36
	v_div_scale_f32 v37, vcc, v26, v34, v26
	v_mul_f32_e32 v38, v37, v36
	v_fma_f32 v39, -v35, v38, v37
	v_fmac_f32_e32 v38, v39, v36
	v_fma_f32 v35, -v35, v38, v37
	v_div_fmas_f32 v35, v35, v36, v38
	v_div_fixup_f32 v26, v35, v34, v26
	v_mul_f32_e32 v26, v30, v26
	v_cvt_pk_bf16_f32 v26, v26, s0
	ds_write_b16 v0, v26 offset:4608
	v_mul_f32_e32 v26, 0xbfb8aa3b, v27
	v_exp_f32_e32 v26, v26
	s_nop 0
	v_add_f32_e32 v26, 1.0, v26
	v_div_scale_f32 v30, s[0:1], v26, v26, v27
	v_rcp_f32_e32 v34, v30
	s_nop 0
	v_fma_f32 v35, -v30, v34, 1.0
	v_fmac_f32_e32 v34, v35, v34
	v_div_scale_f32 v35, vcc, v27, v26, v27
	v_mul_f32_e32 v36, v35, v34
	v_fma_f32 v37, -v30, v36, v35
	v_fmac_f32_e32 v36, v37, v34
	v_fma_f32 v30, -v30, v36, v35
	v_div_fmas_f32 v30, v30, v34, v36
	v_div_fixup_f32 v26, v30, v26, v27
	v_mul_f32_e32 v26, v31, v26
	v_cvt_pk_bf16_f32 v26, v26, s0
	ds_write_b16 v0, v26 offset:4752
	v_mul_f32_e32 v26, 0xbfb8aa3b, v28
	v_exp_f32_e32 v26, v26
	s_nop 0
	v_add_f32_e32 v26, 1.0, v26
	v_div_scale_f32 v27, s[0:1], v26, v26, v28
	v_rcp_f32_e32 v30, v27
	s_nop 0
	v_fma_f32 v31, -v27, v30, 1.0
	v_fmac_f32_e32 v30, v31, v30
	v_div_scale_f32 v31, vcc, v28, v26, v28
	v_mul_f32_e32 v34, v31, v30
	v_fma_f32 v35, -v27, v34, v31
	v_fmac_f32_e32 v34, v35, v30
	v_fma_f32 v27, -v27, v34, v31
	v_div_fmas_f32 v27, v27, v30, v34
	v_div_fixup_f32 v26, v27, v26, v28
	v_mul_f32_e32 v26, v32, v26
	v_cvt_pk_bf16_f32 v26, v26, s0
	ds_write_b16 v0, v26 offset:4896
	v_mul_f32_e32 v26, 0xbfb8aa3b, v29
	v_exp_f32_e32 v26, v26
	s_nop 0
	v_add_f32_e32 v26, 1.0, v26
	v_div_scale_f32 v27, s[0:1], v26, v26, v29
	v_rcp_f32_e32 v28, v27
	s_nop 0
	v_fma_f32 v30, -v27, v28, 1.0
	v_fmac_f32_e32 v28, v30, v28
	v_div_scale_f32 v30, vcc, v29, v26, v29
	v_mul_f32_e32 v31, v30, v28
	v_fma_f32 v32, -v27, v31, v30
	v_fmac_f32_e32 v31, v32, v28
	v_fma_f32 v27, -v27, v31, v30
	v_div_fmas_f32 v27, v27, v28, v31
	v_div_fixup_f32 v26, v27, v26, v29
	v_mul_f32_e32 v26, v33, v26
	v_cvt_pk_bf16_f32 v26, v26, s0
	ds_write_b16 v0, v26 offset:5040
	v_mul_f32_e32 v26, 0xbfb8aa3b, v18
	v_exp_f32_e32 v26, v26
	s_nop 0
	v_add_f32_e32 v26, 1.0, v26
	v_div_scale_f32 v27, s[0:1], v26, v26, v18
	v_rcp_f32_e32 v28, v27
	s_nop 0
	v_fma_f32 v29, -v27, v28, 1.0
	v_fmac_f32_e32 v28, v29, v28
	v_div_scale_f32 v29, vcc, v18, v26, v18
	v_mul_f32_e32 v30, v29, v28
	v_fma_f32 v31, -v27, v30, v29
	v_fmac_f32_e32 v30, v31, v28
	v_fma_f32 v27, -v27, v30, v29
	v_div_fmas_f32 v27, v27, v28, v30
	v_div_fixup_f32 v18, v27, v26, v18
	v_mul_f32_e32 v18, v22, v18
	v_cvt_pk_bf16_f32 v18, v18, s0
	ds_write_b16 v0, v18 offset:4640
	v_mul_f32_e32 v18, 0xbfb8aa3b, v19
	v_exp_f32_e32 v18, v18
	s_nop 0
	v_add_f32_e32 v18, 1.0, v18
	v_div_scale_f32 v22, s[0:1], v18, v18, v19
	v_rcp_f32_e32 v26, v22
	s_nop 0
	v_fma_f32 v27, -v22, v26, 1.0
	v_fmac_f32_e32 v26, v27, v26
	v_div_scale_f32 v27, vcc, v19, v18, v19
	v_mul_f32_e32 v28, v27, v26
	v_fma_f32 v29, -v22, v28, v27
	v_fmac_f32_e32 v28, v29, v26
	v_fma_f32 v22, -v22, v28, v27
	v_div_fmas_f32 v22, v22, v26, v28
	v_div_fixup_f32 v18, v22, v18, v19
	v_mul_f32_e32 v18, v23, v18
	v_cvt_pk_bf16_f32 v18, v18, s0
	ds_write_b16 v0, v18 offset:4784
	v_mul_f32_e32 v18, 0xbfb8aa3b, v20
	v_exp_f32_e32 v18, v18
	s_nop 0
	v_add_f32_e32 v18, 1.0, v18
	v_div_scale_f32 v19, s[0:1], v18, v18, v20
	v_rcp_f32_e32 v22, v19
	s_nop 0
	v_fma_f32 v23, -v19, v22, 1.0
	v_fmac_f32_e32 v22, v23, v22
	v_div_scale_f32 v23, vcc, v20, v18, v20
	v_mul_f32_e32 v26, v23, v22
	v_fma_f32 v27, -v19, v26, v23
	v_fmac_f32_e32 v26, v27, v22
	v_fma_f32 v19, -v19, v26, v23
	v_div_fmas_f32 v19, v19, v22, v26
	v_div_fixup_f32 v18, v19, v18, v20
	v_mul_f32_e32 v18, v24, v18
	v_cvt_pk_bf16_f32 v18, v18, s0
	ds_write_b16 v0, v18 offset:4928
	v_mul_f32_e32 v18, 0xbfb8aa3b, v21
; __device__ __forceinline__ u16 f2bf(float f) { return (u16)(pack2(f, 0.f) & 0xffffu); }
; __device__ __forceinline__ float silu_f(float x) { return x / (1.f + __expf(-x)); }
; __device__ __forceinline__ void phase_moe_up(const Params& p, int l, bool last, unsigned char* smem) {
;     ...
; #pragma unroll
;       for (int mi = 0; mi < 4; ++mi)
; #pragma unroll
;         for (int n2 = 0; n2 < 2; ++n2)
; #pragma unroll
;           for (int j = 0; j < 4; ++j) {
;             const int m = r0 + mi * 16 + j;
;             const int fl = (c0 >> 6) * 32 + n2 * 16 + (c0 & 15);
;             Ts[m * 72 + fl] = f2bf(silu_f(acc[mi][2 * n2][j]) * acc[mi][2 * n2 + 1][j]);
;           }
;       __syncthreads();
; #pragma unroll
;       for (int i = 0; i < 4; ++i) {
;         const int c = t2 + 256 * i, row = c >> 3, ch = c & 7;
;         if (row < mvalid) *(u32x4*)(p.HID + (size_t)(hid_row + row) * 512 + nt * 64 + ch * 8) = *(const u32x4*)(Ts + row * 72 + ch * 8);
	v_exp_f32_e32 v18, v18
	s_nop 0
	v_add_f32_e32 v18, 1.0, v18
	v_div_scale_f32 v19, s[0:1], v18, v18, v21
	v_rcp_f32_e32 v20, v19
	s_nop 0
	v_fma_f32 v22, -v19, v20, 1.0
	v_fmac_f32_e32 v20, v22, v20
	v_div_scale_f32 v22, vcc, v21, v18, v21
	v_mul_f32_e32 v23, v22, v20
	v_fma_f32 v24, -v19, v23, v22
	v_fmac_f32_e32 v23, v24, v20
	v_fma_f32 v19, -v19, v23, v22
	v_div_fmas_f32 v19, v19, v20, v23
	v_div_fixup_f32 v18, v19, v18, v21
	v_mul_f32_e32 v18, v25, v18
	v_cvt_pk_bf16_f32 v18, v18, s0
	ds_write_b16 v0, v18 offset:5072
	v_mul_f32_e32 v18, 0xbfb8aa3b, v10
	v_exp_f32_e32 v18, v18
	s_nop 0
	v_add_f32_e32 v18, 1.0, v18
	v_div_scale_f32 v19, s[0:1], v18, v18, v10
	v_rcp_f32_e32 v20, v19
	s_nop 0
	v_fma_f32 v21, -v19, v20, 1.0
	v_fmac_f32_e32 v20, v21, v20
	v_div_scale_f32 v21, vcc, v10, v18, v10
	v_mul_f32_e32 v22, v21, v20
	v_fma_f32 v23, -v19, v22, v21
	v_fmac_f32_e32 v22, v23, v20
	v_fma_f32 v19, -v19, v22, v21
	v_div_fmas_f32 v19, v19, v20, v22
	v_div_fixup_f32 v10, v19, v18, v10
	v_mul_f32_e32 v10, v14, v10
	v_cvt_pk_bf16_f32 v10, v10, s0
	ds_write_b16 v0, v10 offset:6912
	v_mul_f32_e32 v10, 0xbfb8aa3b, v11
	v_exp_f32_e32 v10, v10
	s_nop 0
	v_add_f32_e32 v10, 1.0, v10
	v_div_scale_f32 v14, s[0:1], v10, v10, v11
	v_rcp_f32_e32 v18, v14
	s_nop 0
	v_fma_f32 v19, -v14, v18, 1.0
	v_fmac_f32_e32 v18, v19, v18
	v_div_scale_f32 v19, vcc, v11, v10, v11
	v_mul_f32_e32 v20, v19, v18
	v_fma_f32 v21, -v14, v20, v19
	v_fmac_f32_e32 v20, v21, v18
	v_fma_f32 v14, -v14, v20, v19
	v_div_fmas_f32 v14, v14, v18, v20
	v_div_fixup_f32 v10, v14, v10, v11
	v_mul_f32_e32 v10, v15, v10
	v_cvt_pk_bf16_f32 v10, v10, s0
	ds_write_b16 v0, v10 offset:7056
	v_mul_f32_e32 v10, 0xbfb8aa3b, v12
	v_exp_f32_e32 v10, v10
	s_nop 0
	v_add_f32_e32 v10, 1.0, v10
	v_div_scale_f32 v11, s[0:1], v10, v10, v12
	v_rcp_f32_e32 v14, v11
	s_nop 0
	v_fma_f32 v15, -v11, v14, 1.0
	v_fmac_f32_e32 v14, v15, v14
	v_div_scale_f32 v15, vcc, v12, v10, v12
	v_mul_f32_e32 v18, v15, v14
	v_fma_f32 v19, -v11, v18, v15
	v_fmac_f32_e32 v18, v19, v14
	v_fma_f32 v11, -v11, v18, v15
	v_div_fmas_f32 v11, v11, v14, v18
	v_div_fixup_f32 v10, v11, v10, v12
	v_mul_f32_e32 v10, v16, v10
	v_cvt_pk_bf16_f32 v10, v10, s0
	ds_write_b16 v0, v10 offset:7200
	v_mul_f32_e32 v10, 0xbfb8aa3b, v13
	v_exp_f32_e32 v10, v10
	s_nop 0
	v_add_f32_e32 v10, 1.0, v10
	v_div_scale_f32 v11, s[0:1], v10, v10, v13
	v_rcp_f32_e32 v12, v11
	s_nop 0
	v_fma_f32 v14, -v11, v12, 1.0
	v_fmac_f32_e32 v12, v14, v12
	v_div_scale_f32 v14, vcc, v13, v10, v13
	v_mul_f32_e32 v15, v14, v12
	v_fma_f32 v16, -v11, v15, v14
	v_fmac_f32_e32 v15, v16, v12
	v_fma_f32 v11, -v11, v15, v14
	v_div_fmas_f32 v11, v11, v12, v15
	v_div_fixup_f32 v10, v11, v10, v13
	v_mul_f32_e32 v10, v17, v10
	v_cvt_pk_bf16_f32 v10, v10, s0
	ds_write_b16 v0, v10 offset:7344
	v_mul_f32_e32 v10, 0xbfb8aa3b, v2
	v_exp_f32_e32 v10, v10
	s_nop 0
	v_add_f32_e32 v10, 1.0, v10
	v_div_scale_f32 v11, s[0:1], v10, v10, v2
	v_rcp_f32_e32 v12, v11
	s_nop 0
	v_fma_f32 v13, -v11, v12, 1.0
	v_fmac_f32_e32 v12, v13, v12
	v_div_scale_f32 v13, vcc, v2, v10, v2
	v_mul_f32_e32 v14, v13, v12
	v_fma_f32 v15, -v11, v14, v13
	v_fmac_f32_e32 v14, v15, v12
	v_fma_f32 v11, -v11, v14, v13
	v_div_fmas_f32 v11, v11, v12, v14
	v_div_fixup_f32 v2, v11, v10, v2
	v_mul_f32_e32 v2, v6, v2
	v_cvt_pk_bf16_f32 v2, v2, s0
	ds_write_b16 v0, v2 offset:6944
	v_mul_f32_e32 v2, 0xbfb8aa3b, v3
	v_exp_f32_e32 v2, v2
	s_nop 0
	v_add_f32_e32 v2, 1.0, v2
	v_div_scale_f32 v6, s[0:1], v2, v2, v3
	v_rcp_f32_e32 v10, v6
	s_nop 0
	v_fma_f32 v11, -v6, v10, 1.0
	v_fmac_f32_e32 v10, v11, v10
	v_div_scale_f32 v11, vcc, v3, v2, v3
	v_mul_f32_e32 v12, v11, v10
	v_fma_f32 v13, -v6, v12, v11
	v_fmac_f32_e32 v12, v13, v10
	v_fma_f32 v6, -v6, v12, v11
	v_div_fmas_f32 v6, v6, v10, v12
	v_div_fixup_f32 v2, v6, v2, v3
	v_mul_f32_e32 v2, v7, v2
	v_cvt_pk_bf16_f32 v2, v2, s0
	ds_write_b16 v0, v2 offset:7088
	v_mul_f32_e32 v2, 0xbfb8aa3b, v4
	v_exp_f32_e32 v2, v2
	s_nop 0
	v_add_f32_e32 v2, 1.0, v2
	v_div_scale_f32 v3, s[0:1], v2, v2, v4
	v_rcp_f32_e32 v6, v3
	s_nop 0
	v_fma_f32 v7, -v3, v6, 1.0
	v_fmac_f32_e32 v6, v7, v6
	v_div_scale_f32 v7, vcc, v4, v2, v4
	v_mul_f32_e32 v10, v7, v6
	v_fma_f32 v11, -v3, v10, v7
	v_fmac_f32_e32 v10, v11, v6
	v_fma_f32 v3, -v3, v10, v7
	v_div_fmas_f32 v3, v3, v6, v10
	v_div_fixup_f32 v2, v3, v2, v4
	v_mul_f32_e32 v2, v8, v2
	v_cvt_pk_bf16_f32 v2, v2, s0
	ds_write_b16 v0, v2 offset:7232
	v_mul_f32_e32 v2, 0xbfb8aa3b, v5
	v_exp_f32_e32 v2, v2
	s_nop 0
	v_add_f32_e32 v2, 1.0, v2
	v_div_scale_f32 v3, s[0:1], v2, v2, v5
	v_rcp_f32_e32 v4, v3
	s_nop 0
	v_fma_f32 v6, -v3, v4, 1.0
	v_fmac_f32_e32 v4, v6, v4
	v_div_scale_f32 v6, vcc, v5, v2, v5
	v_mul_f32_e32 v7, v6, v4
	v_fma_f32 v8, -v3, v7, v6
	v_fmac_f32_e32 v7, v8, v4
	v_fma_f32 v3, -v3, v7, v6
	v_div_fmas_f32 v3, v3, v4, v7
	v_div_fixup_f32 v2, v3, v2, v5
	v_mul_f32_e32 v2, v9, v2
	v_cvt_pk_bf16_f32 v2, v2, s0
	ds_write_b16 v0, v2 offset:7376
	v_lshlrev_b32_e32 v0, 3, v66
	v_and_b32_e32 v0, 56, v0
	v_ashrrev_i32_e32 v3, 3, v66
	v_lshlrev_b32_e32 v2, 1, v0
	v_cmp_gt_i32_e32 vcc, s86, v3
	s_waitcnt lgkmcnt(0)
	s_barrier
	s_and_saveexec_b64 s[0:1], vcc
	s_cbranch_execz .LBB0_1165
	v_mov_b64_e32 v[4:5], s[4:5]
	s_load_dwordx2 s[100:101], s[4:5], 0x170
	s_waitcnt lgkmcnt(0)
	v_mov_b32_e32 v8, s100
	v_mov_b32_e32 v9, s101
	v_mad_u64_u32 v[4:5], s[8:9], v3, s96, v[2:3]
	v_add_u32_e32 v10, s82, v3
	ds_read_b128 v[4:7], v4
	v_ashrrev_i32_e32 v11, 31, v10
	v_lshlrev_b64 v[10:11], 10, v[10:11]
	s_lshl_b32 s94, s83, 7
	v_mov_b32_e32 v3, v1
	s_waitcnt lgkmcnt(0)
	v_lshl_add_u64 v[8:9], v[8:9], 0, v[10:11]
	v_lshl_add_u64 v[8:9], v[8:9], 0, s[94:95]
	v_lshl_add_u64 v[8:9], v[8:9], 0, v[2:3]
	global_store_dwordx4 v[8:9], v[4:7], off sc1
; __device__ __forceinline__ void phase_moe_up(const Params& p, int l, bool last, unsigned char* smem) {
;     ...
; #pragma unroll
;       for (int i = 0; i < 4; ++i) {
;         const int c = t2 + 256 * i, row = c >> 3, ch = c & 7;
;         if (row < mvalid) *(u32x4*)(p.HID + (size_t)(hid_row + row) * 512 + nt * 64 + ch * 8) = *(const u32x4*)(Ts + row * 72 + ch * 8);
.LBB0_1165:
	s_or_b64 exec, exec, s[0:1]
	v_add_u32_e32 v3, 0x100, v66
	v_ashrrev_i32_e32 v3, 3, v3
	v_cmp_gt_i32_e32 vcc, s86, v3
	s_and_saveexec_b64 s[0:1], vcc
	s_cbranch_execz .LBB0_1167
	v_mov_b64_e32 v[4:5], s[4:5]
	s_load_dwordx2 s[100:101], s[4:5], 0x170
	s_waitcnt lgkmcnt(0)
	v_mov_b32_e32 v8, s100
	v_mov_b32_e32 v9, s101
	v_mad_u64_u32 v[4:5], s[8:9], v3, s96, v[2:3]
	v_add_u32_e32 v10, s82, v3
	ds_read_b128 v[4:7], v4
	v_ashrrev_i32_e32 v11, 31, v10
	v_lshlrev_b64 v[10:11], 10, v[10:11]
	s_lshl_b32 s94, s83, 7
	v_mov_b32_e32 v3, v1
	s_waitcnt lgkmcnt(0)
	v_lshl_add_u64 v[8:9], v[8:9], 0, v[10:11]
	v_lshl_add_u64 v[8:9], v[8:9], 0, s[94:95]
	v_lshl_add_u64 v[8:9], v[8:9], 0, v[2:3]
	global_store_dwordx4 v[8:9], v[4:7], off sc1
.LBB0_1167:
	s_or_b64 exec, exec, s[0:1]
	v_add_u32_e32 v3, 0x200, v66
	v_ashrrev_i32_e32 v3, 3, v3
	v_cmp_gt_i32_e32 vcc, s86, v3
	s_and_saveexec_b64 s[0:1], vcc
	s_cbranch_execz .LBB0_1169
	v_mov_b64_e32 v[4:5], s[4:5]
	s_load_dwordx2 s[100:101], s[4:5], 0x170
	s_waitcnt lgkmcnt(0)
	v_mov_b32_e32 v8, s100
	v_mov_b32_e32 v9, s101
	v_mad_u64_u32 v[4:5], s[8:9], v3, s96, v[2:3]
	v_add_u32_e32 v10, s82, v3
	ds_read_b128 v[4:7], v4
	v_ashrrev_i32_e32 v11, 31, v10
	v_lshlrev_b64 v[10:11], 10, v[10:11]
	s_lshl_b32 s94, s83, 7
	v_mov_b32_e32 v3, v1
	s_waitcnt lgkmcnt(0)
	v_lshl_add_u64 v[8:9], v[8:9], 0, v[10:11]
	v_lshl_add_u64 v[8:9], v[8:9], 0, s[94:95]
	v_lshl_add_u64 v[2:3], v[8:9], 0, v[2:3]
	global_store_dwordx4 v[2:3], v[4:7], off sc1

; __device__ __forceinline__ u16 f2bf(float f) { return (u16)(pack2(f, 0.f) & 0xffffu); }
; __device__ __forceinline__ float silu_f(float x) { return x / (1.f + __expf(-x)); }
; __device__ __forceinline__ void phase_moe_up(const Params& p, int l, bool last, unsigned char* smem) {
;     ...
; #pragma unroll
;       for (int mi = 0; mi < 4; ++mi)
; #pragma unroll
;         for (int n2 = 0; n2 < 2; ++n2)
; #pragma unroll
;           for (int j = 0; j < 4; ++j) {
;             const int m = r0 + mi * 16 + j;
;             const int fl = (c0 >> 6) * 32 + n2 * 16 + (c0 & 15);
;             Ts[m * 72 + fl] = f2bf(silu_f(acc[mi][2 * n2][j]) * acc[mi][2 * n2 + 1][j]);
;           }
.LBB0_1194:
	s_waitcnt lgkmcnt(4)
	v_mul_f32_e32 v66, 0xbfb8aa3b, v62
	v_exp_f32_e32 v68, v66
	v_lshl_or_b32 v0, v196, 2, v197
	v_lshlrev_b32_e32 v67, 5, v195
	v_and_or_b32 v67, v67, 32, v194
	v_add_f32_e32 v68, 1.0, v68
	v_div_scale_f32 v69, s[0:1], v68, v68, v62
	s_waitcnt lgkmcnt(3)
	v_rcp_f32_e32 v70, v69
	v_mul_lo_u32 v0, v0, s96
	v_mov_b32_e32 v66, v187
	v_lshl_add_u32 v0, v67, 1, v0
	v_fma_f32 v71, -v69, v70, 1.0
	v_fmac_f32_e32 v70, v71, v70
	v_div_scale_f32 v71, vcc, v62, v68, v62
	v_mul_f32_e32 v72, v71, v70
	v_fma_f32 v73, -v69, v72, v71
	v_fmac_f32_e32 v72, v73, v70
	v_fma_f32 v69, -v69, v72, v71
	v_div_fmas_f32 v69, v69, v70, v72
	v_mul_f32_e32 v70, 0xbfb8aa3b, v63
	v_exp_f32_e32 v70, v70
	v_div_fixup_f32 v62, v69, v68, v62
	v_mul_f32_e32 v58, v58, v62
	v_cvt_pk_bf16_f32 v58, v58, s0
	v_add_f32_e32 v62, 1.0, v70
	v_div_scale_f32 v68, s[0:1], v62, v62, v63
	v_rcp_f32_e32 v69, v68
	s_waitcnt lgkmcnt(0)
	s_barrier
	ds_write_b16 v0, v58
	v_fma_f32 v58, -v68, v69, 1.0
	v_fmac_f32_e32 v69, v58, v69
	v_div_scale_f32 v58, vcc, v63, v62, v63
	v_mul_f32_e32 v67, v58, v69
	v_fma_f32 v70, -v68, v67, v58
	v_fmac_f32_e32 v67, v70, v69
	v_fma_f32 v58, -v68, v67, v58
	v_mul_f32_e32 v68, 0xbfb8aa3b, v64
	v_exp_f32_e32 v68, v68
	v_div_fmas_f32 v58, v58, v69, v67
	v_div_fixup_f32 v58, v58, v62, v63
	v_mul_f32_e32 v58, v59, v58
	v_add_f32_e32 v62, 1.0, v68
	v_div_scale_f32 v63, s[0:1], v62, v62, v64
	v_rcp_f32_e32 v67, v63
	s_nop 0
	v_cvt_pk_bf16_f32 v58, v58, s0
	ds_write_b16 v0, v58 offset:144
	v_fma_f32 v58, -v63, v67, 1.0
	v_fmac_f32_e32 v67, v58, v67
	v_div_scale_f32 v58, vcc, v64, v62, v64
	v_mul_f32_e32 v59, v58, v67
	v_fma_f32 v68, -v63, v59, v58
	v_fmac_f32_e32 v59, v68, v67
	v_fma_f32 v58, -v63, v59, v58
	v_mul_f32_e32 v63, 0xbfb8aa3b, v65
	v_exp_f32_e32 v63, v63
	v_div_fmas_f32 v58, v58, v67, v59
	v_div_fixup_f32 v58, v58, v62, v64
	v_mul_f32_e32 v58, v60, v58
	v_add_f32_e32 v59, 1.0, v63
	v_div_scale_f32 v62, s[0:1], v59, v59, v65
	v_rcp_f32_e32 v63, v62
	s_nop 0
	v_cvt_pk_bf16_f32 v58, v58, s0
	ds_write_b16 v0, v58 offset:288
	v_fma_f32 v58, -v62, v63, 1.0
	v_fmac_f32_e32 v63, v58, v63
	v_div_scale_f32 v58, vcc, v65, v59, v65
	v_mul_f32_e32 v60, v58, v63
	v_fma_f32 v64, -v62, v60, v58
	v_fmac_f32_e32 v60, v64, v63
	v_fma_f32 v58, -v62, v60, v58
	v_mul_f32_e32 v62, 0xbfb8aa3b, v54
	v_exp_f32_e32 v62, v62
	v_div_fmas_f32 v58, v58, v63, v60
	v_div_fixup_f32 v58, v58, v59, v65
	v_mul_f32_e32 v58, v61, v58
	v_add_f32_e32 v59, 1.0, v62
	v_div_scale_f32 v60, s[0:1], v59, v59, v54
	v_rcp_f32_e32 v62, v60
	s_nop 0
	v_cvt_pk_bf16_f32 v58, v58, s0
	ds_write_b16 v0, v58 offset:432
	v_fma_f32 v58, -v60, v62, 1.0
	v_fmac_f32_e32 v62, v58, v62
	v_div_scale_f32 v58, vcc, v54, v59, v54
	v_mul_f32_e32 v61, v58, v62
	v_fma_f32 v63, -v60, v61, v58
	v_fmac_f32_e32 v61, v63, v62
	v_fma_f32 v58, -v60, v61, v58
	v_mul_f32_e32 v60, 0xbfb8aa3b, v55
	v_exp_f32_e32 v60, v60
	v_div_fmas_f32 v58, v58, v62, v61
	v_div_fixup_f32 v54, v58, v59, v54
	v_mul_f32_e32 v50, v50, v54
	v_add_f32_e32 v58, 1.0, v60
	v_div_scale_f32 v59, s[0:1], v58, v58, v55
	v_rcp_f32_e32 v60, v59
	s_nop 0
	v_cvt_pk_bf16_f32 v50, v50, s0
	ds_write_b16 v0, v50 offset:32
	v_fma_f32 v50, -v59, v60, 1.0
	v_fmac_f32_e32 v60, v50, v60
	v_div_scale_f32 v50, vcc, v55, v58, v55
	v_mul_f32_e32 v54, v50, v60
	v_fma_f32 v61, -v59, v54, v50
	v_fmac_f32_e32 v54, v61, v60
	v_fma_f32 v50, -v59, v54, v50
	v_mul_f32_e32 v59, 0xbfb8aa3b, v56
	v_exp_f32_e32 v59, v59
	v_div_fmas_f32 v50, v50, v60, v54
	v_div_fixup_f32 v50, v50, v58, v55
	v_mul_f32_e32 v50, v51, v50
	v_add_f32_e32 v54, 1.0, v59
	v_div_scale_f32 v55, s[0:1], v54, v54, v56
	v_rcp_f32_e32 v58, v55
	s_nop 0
	v_cvt_pk_bf16_f32 v50, v50, s0
	ds_write_b16 v0, v50 offset:176
	v_fma_f32 v50, -v55, v58, 1.0
	v_fmac_f32_e32 v58, v50, v58
	v_div_scale_f32 v50, vcc, v56, v54, v56
	v_mul_f32_e32 v51, v50, v58
	v_fma_f32 v59, -v55, v51, v50
	v_fmac_f32_e32 v51, v59, v58
	v_fma_f32 v50, -v55, v51, v50
	v_mul_f32_e32 v55, 0xbfb8aa3b, v57
	v_exp_f32_e32 v55, v55
	v_div_fmas_f32 v50, v50, v58, v51
	v_div_fixup_f32 v50, v50, v54, v56
	v_mul_f32_e32 v50, v52, v50
	v_add_f32_e32 v51, 1.0, v55
	v_div_scale_f32 v54, s[0:1], v51, v51, v57
	v_rcp_f32_e32 v55, v54
	s_nop 0
	v_cvt_pk_bf16_f32 v50, v50, s0
	ds_write_b16 v0, v50 offset:320
	v_fma_f32 v50, -v54, v55, 1.0
	v_fmac_f32_e32 v55, v50, v55
	v_div_scale_f32 v50, vcc, v57, v51, v57
	v_mul_f32_e32 v52, v50, v55
	v_fma_f32 v56, -v54, v52, v50
	v_fmac_f32_e32 v52, v56, v55
	v_fma_f32 v50, -v54, v52, v50
	v_mul_f32_e32 v54, 0xbfb8aa3b, v46
	v_exp_f32_e32 v54, v54
	v_div_fmas_f32 v50, v50, v55, v52
	v_div_fixup_f32 v50, v50, v51, v57
	v_mul_f32_e32 v50, v53, v50
	v_add_f32_e32 v51, 1.0, v54
	v_div_scale_f32 v52, s[0:1], v51, v51, v46
	v_rcp_f32_e32 v54, v52
	s_nop 0
	v_cvt_pk_bf16_f32 v50, v50, s0
	ds_write_b16 v0, v50 offset:464
	v_fma_f32 v50, -v52, v54, 1.0
	v_fmac_f32_e32 v54, v50, v54
	v_div_scale_f32 v50, vcc, v46, v51, v46
	v_mul_f32_e32 v53, v50, v54
	v_fma_f32 v55, -v52, v53, v50
	v_fmac_f32_e32 v53, v55, v54
	v_fma_f32 v50, -v52, v53, v50
	v_mul_f32_e32 v52, 0xbfb8aa3b, v47
	v_exp_f32_e32 v52, v52
	v_div_fmas_f32 v50, v50, v54, v53
	v_div_fixup_f32 v46, v50, v51, v46
	v_mul_f32_e32 v42, v42, v46
	v_add_f32_e32 v50, 1.0, v52
	v_div_scale_f32 v51, s[0:1], v50, v50, v47
	v_rcp_f32_e32 v52, v51
	s_nop 0
	v_cvt_pk_bf16_f32 v42, v42, s0
	ds_write_b16 v0, v42 offset:2304
	v_fma_f32 v42, -v51, v52, 1.0
	v_fmac_f32_e32 v52, v42, v52
	v_div_scale_f32 v42, vcc, v47, v50, v47
	v_mul_f32_e32 v46, v42, v52
	v_fma_f32 v53, -v51, v46, v42
	v_fmac_f32_e32 v46, v53, v52
	v_fma_f32 v42, -v51, v46, v42
	v_mul_f32_e32 v51, 0xbfb8aa3b, v48
; __device__ __forceinline__ u16 f2bf(float f) { return (u16)(pack2(f, 0.f) & 0xffffu); }
; __device__ __forceinline__ float silu_f(float x) { return x / (1.f + __expf(-x)); }
; __device__ __forceinline__ void phase_moe_up(const Params& p, int l, bool last, unsigned char* smem) {
;     ...
; #pragma unroll
;       for (int mi = 0; mi < 4; ++mi)
; #pragma unroll
;         for (int n2 = 0; n2 < 2; ++n2)
; #pragma unroll
;           for (int j = 0; j < 4; ++j) {
;             const int m = r0 + mi * 16 + j;
;             const int fl = (c0 >> 6) * 32 + n2 * 16 + (c0 & 15);
;             Ts[m * 72 + fl] = f2bf(silu_f(acc[mi][2 * n2][j]) * acc[mi][2 * n2 + 1][j]);
;           }
	v_exp_f32_e32 v51, v51
	v_div_fmas_f32 v42, v42, v52, v46
	v_div_fixup_f32 v42, v42, v50, v47
	v_mul_f32_e32 v42, v43, v42
	v_add_f32_e32 v46, 1.0, v51
	v_div_scale_f32 v47, s[0:1], v46, v46, v48
	v_rcp_f32_e32 v50, v47
	s_nop 0
	v_cvt_pk_bf16_f32 v42, v42, s0
	ds_write_b16 v0, v42 offset:2448
	v_fma_f32 v42, -v47, v50, 1.0
	v_fmac_f32_e32 v50, v42, v50
	v_div_scale_f32 v42, vcc, v48, v46, v48
	v_mul_f32_e32 v43, v42, v50
	v_fma_f32 v51, -v47, v43, v42
	v_fmac_f32_e32 v43, v51, v50
	v_fma_f32 v42, -v47, v43, v42
	v_mul_f32_e32 v47, 0xbfb8aa3b, v49
	v_exp_f32_e32 v47, v47
	v_div_fmas_f32 v42, v42, v50, v43
	v_div_fixup_f32 v42, v42, v46, v48
	v_mul_f32_e32 v42, v44, v42
	v_add_f32_e32 v43, 1.0, v47
	v_div_scale_f32 v46, s[0:1], v43, v43, v49
	v_rcp_f32_e32 v47, v46
	s_nop 0
	v_cvt_pk_bf16_f32 v42, v42, s0
	ds_write_b16 v0, v42 offset:2592
	v_fma_f32 v42, -v46, v47, 1.0
	v_fmac_f32_e32 v47, v42, v47
	v_div_scale_f32 v42, vcc, v49, v43, v49
	v_mul_f32_e32 v44, v42, v47
	v_fma_f32 v48, -v46, v44, v42
	v_fmac_f32_e32 v44, v48, v47
	v_fma_f32 v42, -v46, v44, v42
	v_mul_f32_e32 v46, 0xbfb8aa3b, v38
	v_exp_f32_e32 v46, v46
	v_div_fmas_f32 v42, v42, v47, v44
	v_div_fixup_f32 v42, v42, v43, v49
	v_mul_f32_e32 v42, v45, v42
	v_add_f32_e32 v43, 1.0, v46
	v_div_scale_f32 v44, s[0:1], v43, v43, v38
	v_rcp_f32_e32 v46, v44
	s_nop 0
	v_cvt_pk_bf16_f32 v42, v42, s0
	ds_write_b16 v0, v42 offset:2736
	v_fma_f32 v42, -v44, v46, 1.0
	v_fmac_f32_e32 v46, v42, v46
	v_div_scale_f32 v42, vcc, v38, v43, v38
	v_mul_f32_e32 v45, v42, v46
	v_fma_f32 v47, -v44, v45, v42
	v_fmac_f32_e32 v45, v47, v46
	v_fma_f32 v42, -v44, v45, v42
	v_mul_f32_e32 v44, 0xbfb8aa3b, v39
	v_exp_f32_e32 v44, v44
	v_div_fmas_f32 v42, v42, v46, v45
	v_div_fixup_f32 v38, v42, v43, v38
	v_mul_f32_e32 v34, v34, v38
	v_add_f32_e32 v42, 1.0, v44
	v_div_scale_f32 v43, s[0:1], v42, v42, v39
	v_rcp_f32_e32 v44, v43
	s_nop 0
	v_cvt_pk_bf16_f32 v34, v34, s0
	ds_write_b16 v0, v34 offset:2336
	v_fma_f32 v34, -v43, v44, 1.0
	v_fmac_f32_e32 v44, v34, v44
	v_div_scale_f32 v34, vcc, v39, v42, v39
	v_mul_f32_e32 v38, v34, v44
	v_fma_f32 v45, -v43, v38, v34
	v_fmac_f32_e32 v38, v45, v44
	v_fma_f32 v34, -v43, v38, v34
	v_mul_f32_e32 v43, 0xbfb8aa3b, v40
	v_exp_f32_e32 v43, v43
	v_div_fmas_f32 v34, v34, v44, v38
	v_div_fixup_f32 v34, v34, v42, v39
	v_mul_f32_e32 v34, v35, v34
	v_add_f32_e32 v38, 1.0, v43
	v_div_scale_f32 v39, s[0:1], v38, v38, v40
	v_rcp_f32_e32 v42, v39
	s_nop 0
	v_cvt_pk_bf16_f32 v34, v34, s0
	ds_write_b16 v0, v34 offset:2480
	v_fma_f32 v34, -v39, v42, 1.0
	v_fmac_f32_e32 v42, v34, v42
	v_div_scale_f32 v34, vcc, v40, v38, v40
	v_mul_f32_e32 v35, v34, v42
	v_fma_f32 v43, -v39, v35, v34
	v_fmac_f32_e32 v35, v43, v42
	v_fma_f32 v34, -v39, v35, v34
	v_mul_f32_e32 v39, 0xbfb8aa3b, v41
	v_exp_f32_e32 v39, v39
	v_div_fmas_f32 v34, v34, v42, v35
	v_div_fixup_f32 v34, v34, v38, v40
	v_mul_f32_e32 v34, v36, v34
	v_add_f32_e32 v35, 1.0, v39
	v_div_scale_f32 v38, s[0:1], v35, v35, v41
	v_rcp_f32_e32 v39, v38
	s_nop 0
	v_cvt_pk_bf16_f32 v34, v34, s0
	ds_write_b16 v0, v34 offset:2624
	v_fma_f32 v34, -v38, v39, 1.0
	v_fmac_f32_e32 v39, v34, v39
	v_div_scale_f32 v34, vcc, v41, v35, v41
	v_mul_f32_e32 v36, v34, v39
	v_fma_f32 v40, -v38, v36, v34
	v_fmac_f32_e32 v36, v40, v39
	v_fma_f32 v34, -v38, v36, v34
	v_mul_f32_e32 v38, 0xbfb8aa3b, v30
	v_exp_f32_e32 v38, v38
	v_div_fmas_f32 v34, v34, v39, v36
	v_div_fixup_f32 v34, v34, v35, v41
	v_mul_f32_e32 v34, v37, v34
	v_add_f32_e32 v35, 1.0, v38
	v_div_scale_f32 v36, s[0:1], v35, v35, v30
	v_rcp_f32_e32 v38, v36
	s_nop 0
	v_cvt_pk_bf16_f32 v34, v34, s0
	ds_write_b16 v0, v34 offset:2768
	v_fma_f32 v34, -v36, v38, 1.0
	v_fmac_f32_e32 v38, v34, v38
	v_div_scale_f32 v34, vcc, v30, v35, v30
	v_mul_f32_e32 v37, v34, v38
	v_fma_f32 v39, -v36, v37, v34
	v_fmac_f32_e32 v37, v39, v38
	v_fma_f32 v34, -v36, v37, v34
	v_mul_f32_e32 v36, 0xbfb8aa3b, v31
	v_exp_f32_e32 v36, v36
	v_div_fmas_f32 v34, v34, v38, v37
	v_div_fixup_f32 v30, v34, v35, v30
	v_mul_f32_e32 v26, v26, v30
	v_add_f32_e32 v34, 1.0, v36
	v_div_scale_f32 v35, s[0:1], v34, v34, v31
	v_rcp_f32_e32 v36, v35
	s_nop 0
	v_cvt_pk_bf16_f32 v26, v26, s0
	ds_write_b16 v0, v26 offset:4608
	v_fma_f32 v26, -v35, v36, 1.0
	v_fmac_f32_e32 v36, v26, v36
	v_div_scale_f32 v26, vcc, v31, v34, v31
	v_mul_f32_e32 v30, v26, v36
	v_fma_f32 v37, -v35, v30, v26
	v_fmac_f32_e32 v30, v37, v36
	v_fma_f32 v26, -v35, v30, v26
	v_mul_f32_e32 v35, 0xbfb8aa3b, v32
	v_exp_f32_e32 v35, v35
	v_div_fmas_f32 v26, v26, v36, v30
	v_div_fixup_f32 v26, v26, v34, v31
	v_mul_f32_e32 v26, v27, v26
	v_add_f32_e32 v30, 1.0, v35
	v_div_scale_f32 v31, s[0:1], v30, v30, v32
	v_rcp_f32_e32 v34, v31
	s_nop 0
	v_cvt_pk_bf16_f32 v26, v26, s0
	ds_write_b16 v0, v26 offset:4752
	v_fma_f32 v26, -v31, v34, 1.0
	v_fmac_f32_e32 v34, v26, v34
	v_div_scale_f32 v26, vcc, v32, v30, v32
	v_mul_f32_e32 v27, v26, v34
	v_fma_f32 v35, -v31, v27, v26
	v_fmac_f32_e32 v27, v35, v34
	v_fma_f32 v26, -v31, v27, v26
	v_mul_f32_e32 v31, 0xbfb8aa3b, v33
	v_exp_f32_e32 v31, v31
	v_div_fmas_f32 v26, v26, v34, v27
	v_div_fixup_f32 v26, v26, v30, v32
	v_mul_f32_e32 v26, v28, v26
	v_add_f32_e32 v27, 1.0, v31
	v_div_scale_f32 v30, s[0:1], v27, v27, v33
	v_rcp_f32_e32 v31, v30
	s_nop 0
	v_cvt_pk_bf16_f32 v26, v26, s0
	ds_write_b16 v0, v26 offset:4896
	v_fma_f32 v26, -v30, v31, 1.0
	v_fmac_f32_e32 v31, v26, v31
	v_div_scale_f32 v26, vcc, v33, v27, v33
	v_mul_f32_e32 v28, v26, v31
	v_fma_f32 v32, -v30, v28, v26
	v_fmac_f32_e32 v28, v32, v31
	v_fma_f32 v26, -v30, v28, v26
	v_mul_f32_e32 v30, 0xbfb8aa3b, v22
	v_exp_f32_e32 v30, v30
	v_div_fmas_f32 v26, v26, v31, v28
	v_div_fixup_f32 v26, v26, v27, v33
; __device__ __forceinline__ u16 f2bf(float f) { return (u16)(pack2(f, 0.f) & 0xffffu); }
; __device__ __forceinline__ float silu_f(float x) { return x / (1.f + __expf(-x)); }
; __device__ __forceinline__ void phase_moe_up(const Params& p, int l, bool last, unsigned char* smem) {
;     ...
; #pragma unroll
;       for (int mi = 0; mi < 4; ++mi)
; #pragma unroll
;         for (int n2 = 0; n2 < 2; ++n2)
; #pragma unroll
;           for (int j = 0; j < 4; ++j) {
;             const int m = r0 + mi * 16 + j;
;             const int fl = (c0 >> 6) * 32 + n2 * 16 + (c0 & 15);
;             Ts[m * 72 + fl] = f2bf(silu_f(acc[mi][2 * n2][j]) * acc[mi][2 * n2 + 1][j]);
;           }
;       __syncthreads();
; #pragma unroll
;       for (int i = 0; i < 4; ++i) {
;         const int c = t2 + 256 * i, row = c >> 3, ch = c & 7;
;         if (row < mvalid) *(u32x4*)(p.HID + (size_t)(hid_row + row) * 512 + nt * 64 + ch * 8) = *(const u32x4*)(Ts + row * 72 + ch * 8);
	v_mul_f32_e32 v26, v29, v26
	v_add_f32_e32 v27, 1.0, v30
	v_div_scale_f32 v28, s[0:1], v27, v27, v22
	v_rcp_f32_e32 v30, v28
	s_nop 0
	v_cvt_pk_bf16_f32 v26, v26, s0
	ds_write_b16 v0, v26 offset:5040
	v_fma_f32 v26, -v28, v30, 1.0
	v_fmac_f32_e32 v30, v26, v30
	v_div_scale_f32 v26, vcc, v22, v27, v22
	v_mul_f32_e32 v29, v26, v30
	v_fma_f32 v31, -v28, v29, v26
	v_fmac_f32_e32 v29, v31, v30
	v_fma_f32 v26, -v28, v29, v26
	v_mul_f32_e32 v28, 0xbfb8aa3b, v23
	v_exp_f32_e32 v28, v28
	v_div_fmas_f32 v26, v26, v30, v29
	v_div_fixup_f32 v22, v26, v27, v22
	v_mul_f32_e32 v18, v18, v22
	v_add_f32_e32 v26, 1.0, v28
	v_div_scale_f32 v27, s[0:1], v26, v26, v23
	v_rcp_f32_e32 v28, v27
	s_nop 0
	v_cvt_pk_bf16_f32 v18, v18, s0
	ds_write_b16 v0, v18 offset:4640
	v_fma_f32 v18, -v27, v28, 1.0
	v_fmac_f32_e32 v28, v18, v28
	v_div_scale_f32 v18, vcc, v23, v26, v23
	v_mul_f32_e32 v22, v18, v28
	v_fma_f32 v29, -v27, v22, v18
	v_fmac_f32_e32 v22, v29, v28
	v_fma_f32 v18, -v27, v22, v18
	v_mul_f32_e32 v27, 0xbfb8aa3b, v24
	v_exp_f32_e32 v27, v27
	v_div_fmas_f32 v18, v18, v28, v22
	v_div_fixup_f32 v18, v18, v26, v23
	v_mul_f32_e32 v18, v19, v18
	v_add_f32_e32 v22, 1.0, v27
	v_div_scale_f32 v23, s[0:1], v22, v22, v24
	v_rcp_f32_e32 v26, v23
	s_nop 0
	v_cvt_pk_bf16_f32 v18, v18, s0
	ds_write_b16 v0, v18 offset:4784
	v_fma_f32 v18, -v23, v26, 1.0
	v_fmac_f32_e32 v26, v18, v26
	v_div_scale_f32 v18, vcc, v24, v22, v24
	v_mul_f32_e32 v19, v18, v26
	v_fma_f32 v27, -v23, v19, v18
	v_fmac_f32_e32 v19, v27, v26
	v_fma_f32 v18, -v23, v19, v18
	v_mul_f32_e32 v23, 0xbfb8aa3b, v25
	v_exp_f32_e32 v23, v23
	v_div_fmas_f32 v18, v18, v26, v19
	v_div_fixup_f32 v18, v18, v22, v24
	v_mul_f32_e32 v18, v20, v18
	v_add_f32_e32 v19, 1.0, v23
	v_div_scale_f32 v22, s[0:1], v19, v19, v25
	v_rcp_f32_e32 v23, v22
	s_nop 0
	v_cvt_pk_bf16_f32 v18, v18, s0
	ds_write_b16 v0, v18 offset:4928
	v_fma_f32 v18, -v22, v23, 1.0
	v_fmac_f32_e32 v23, v18, v23
	v_div_scale_f32 v18, vcc, v25, v19, v25
	v_mul_f32_e32 v20, v18, v23
	v_fma_f32 v24, -v22, v20, v18
	v_fmac_f32_e32 v20, v24, v23
	v_fma_f32 v18, -v22, v20, v18
	v_mul_f32_e32 v22, 0xbfb8aa3b, v14
	v_exp_f32_e32 v22, v22
	v_div_fmas_f32 v18, v18, v23, v20
	v_div_fixup_f32 v18, v18, v19, v25
	v_mul_f32_e32 v18, v21, v18
	v_add_f32_e32 v19, 1.0, v22
	v_div_scale_f32 v20, s[0:1], v19, v19, v14
	v_rcp_f32_e32 v22, v20
	s_nop 0
	v_cvt_pk_bf16_f32 v18, v18, s0
	ds_write_b16 v0, v18 offset:5072
	v_fma_f32 v18, -v20, v22, 1.0
	v_fmac_f32_e32 v22, v18, v22
	v_div_scale_f32 v18, vcc, v14, v19, v14
	v_mul_f32_e32 v21, v18, v22
	v_fma_f32 v23, -v20, v21, v18
	v_fmac_f32_e32 v21, v23, v22
	v_fma_f32 v18, -v20, v21, v18
	v_mul_f32_e32 v20, 0xbfb8aa3b, v15
	v_exp_f32_e32 v20, v20
	v_div_fmas_f32 v18, v18, v22, v21
	v_div_fixup_f32 v14, v18, v19, v14
	v_mul_f32_e32 v10, v10, v14
	v_add_f32_e32 v18, 1.0, v20
	v_div_scale_f32 v19, s[0:1], v18, v18, v15
	v_rcp_f32_e32 v20, v19
	s_nop 0
	v_cvt_pk_bf16_f32 v10, v10, s0
	ds_write_b16 v0, v10 offset:6912
	v_fma_f32 v10, -v19, v20, 1.0
	v_fmac_f32_e32 v20, v10, v20
	v_div_scale_f32 v10, vcc, v15, v18, v15
	v_mul_f32_e32 v14, v10, v20
	v_fma_f32 v21, -v19, v14, v10
	v_fmac_f32_e32 v14, v21, v20
	v_fma_f32 v10, -v19, v14, v10
	v_mul_f32_e32 v19, 0xbfb8aa3b, v16
	v_exp_f32_e32 v19, v19
	v_div_fmas_f32 v10, v10, v20, v14
	v_div_fixup_f32 v10, v10, v18, v15
	v_mul_f32_e32 v10, v11, v10
	v_add_f32_e32 v14, 1.0, v19
	v_div_scale_f32 v15, s[0:1], v14, v14, v16
	v_rcp_f32_e32 v18, v15
	s_nop 0
	v_cvt_pk_bf16_f32 v10, v10, s0
	ds_write_b16 v0, v10 offset:7056
	v_fma_f32 v10, -v15, v18, 1.0
	v_fmac_f32_e32 v18, v10, v18
	v_div_scale_f32 v10, vcc, v16, v14, v16
	v_mul_f32_e32 v11, v10, v18
	v_fma_f32 v19, -v15, v11, v10
	v_fmac_f32_e32 v11, v19, v18
	v_fma_f32 v10, -v15, v11, v10
	v_mul_f32_e32 v15, 0xbfb8aa3b, v17
	v_exp_f32_e32 v15, v15
	v_div_fmas_f32 v10, v10, v18, v11
	v_div_fixup_f32 v10, v10, v14, v16
	v_mul_f32_e32 v10, v12, v10
	v_add_f32_e32 v11, 1.0, v15
	v_div_scale_f32 v14, s[0:1], v11, v11, v17
	v_rcp_f32_e32 v15, v14
	s_nop 0
	v_cvt_pk_bf16_f32 v10, v10, s0
	ds_write_b16 v0, v10 offset:7200
	v_fma_f32 v10, -v14, v15, 1.0
	v_fmac_f32_e32 v15, v10, v15
	v_div_scale_f32 v10, vcc, v17, v11, v17
	v_mul_f32_e32 v12, v10, v15
	v_fma_f32 v16, -v14, v12, v10
	v_fmac_f32_e32 v12, v16, v15
	v_fma_f32 v10, -v14, v12, v10
	v_mul_f32_e32 v14, 0xbfb8aa3b, v6
	v_exp_f32_e32 v14, v14
	v_div_fmas_f32 v10, v10, v15, v12
	v_div_fixup_f32 v10, v10, v11, v17
	v_mul_f32_e32 v10, v13, v10
	v_add_f32_e32 v11, 1.0, v14
	v_div_scale_f32 v12, s[0:1], v11, v11, v6
	v_rcp_f32_e32 v14, v12
	s_nop 0
	v_cvt_pk_bf16_f32 v10, v10, s0
	ds_write_b16 v0, v10 offset:7344
	v_fma_f32 v10, -v12, v14, 1.0
	v_fmac_f32_e32 v14, v10, v14
	v_div_scale_f32 v10, vcc, v6, v11, v6
	v_mul_f32_e32 v13, v10, v14
	v_fma_f32 v15, -v12, v13, v10
	v_fmac_f32_e32 v13, v15, v14
	v_fma_f32 v10, -v12, v13, v10
	v_mul_f32_e32 v12, 0xbfb8aa3b, v7
	v_exp_f32_e32 v12, v12
	v_div_fmas_f32 v10, v10, v14, v13
	v_div_fixup_f32 v6, v10, v11, v6
	v_mul_f32_e32 v2, v2, v6
	v_add_f32_e32 v10, 1.0, v12
	v_div_scale_f32 v11, s[0:1], v10, v10, v7
	v_rcp_f32_e32 v12, v11
	s_nop 0
	v_cvt_pk_bf16_f32 v2, v2, s0
	ds_write_b16 v0, v2 offset:6944
	v_fma_f32 v2, -v11, v12, 1.0
	v_fmac_f32_e32 v12, v2, v12
	v_div_scale_f32 v2, vcc, v7, v10, v7
	v_mul_f32_e32 v6, v2, v12
	v_fma_f32 v13, -v11, v6, v2
	v_fmac_f32_e32 v6, v13, v12
	v_fma_f32 v2, -v11, v6, v2
	v_mul_f32_e32 v11, 0xbfb8aa3b, v8
	v_exp_f32_e32 v11, v11
	v_div_fmas_f32 v2, v2, v12, v6
	v_div_fixup_f32 v2, v2, v10, v7
	v_mul_f32_e32 v2, v3, v2
	v_add_f32_e32 v6, 1.0, v11
	v_div_scale_f32 v7, s[0:1], v6, v6, v8
	v_rcp_f32_e32 v10, v7
	s_nop 0
	v_cvt_pk_bf16_f32 v2, v2, s0
	ds_write_b16 v0, v2 offset:7088
	v_fma_f32 v2, -v7, v10, 1.0
	v_fmac_f32_e32 v10, v2, v10
	v_div_scale_f32 v2, vcc, v8, v6, v8
	v_mul_f32_e32 v3, v2, v10
	v_fma_f32 v11, -v7, v3, v2
	v_fmac_f32_e32 v3, v11, v10
	v_fma_f32 v2, -v7, v3, v2
	v_mul_f32_e32 v7, 0xbfb8aa3b, v9
	v_exp_f32_e32 v7, v7
	v_div_fmas_f32 v2, v2, v10, v3
	v_div_fixup_f32 v2, v2, v6, v8
	v_mul_f32_e32 v2, v4, v2
	v_add_f32_e32 v3, 1.0, v7
	v_div_scale_f32 v6, s[0:1], v3, v3, v9
	v_rcp_f32_e32 v7, v6
	s_nop 0
	v_cvt_pk_bf16_f32 v2, v2, s0
	ds_write_b16 v0, v2 offset:7232
	v_fma_f32 v2, -v6, v7, 1.0
	v_fmac_f32_e32 v7, v2, v7
	v_div_scale_f32 v2, vcc, v9, v3, v9
	v_mul_f32_e32 v4, v2, v7
	v_fma_f32 v8, -v6, v4, v2
	v_fmac_f32_e32 v4, v8, v7
	v_fma_f32 v2, -v6, v4, v2
	v_div_fmas_f32 v2, v2, v7, v4
	v_div_fixup_f32 v2, v2, v3, v9
	v_mul_f32_e32 v2, v5, v2
	v_cvt_pk_bf16_f32 v2, v2, s0
	ds_write_b16 v0, v2 offset:7376
	v_lshlrev_b32_e32 v0, 3, v66
	v_and_b32_e32 v0, 56, v0
	v_ashrrev_i32_e32 v3, 3, v66
	v_lshlrev_b32_e32 v2, 1, v0
	v_cmp_gt_i32_e32 vcc, s86, v3
	s_waitcnt lgkmcnt(0)
	s_barrier
; __device__ __forceinline__ void phase_moe_up(const Params& p, int l, bool last, unsigned char* smem) {
;     ...
; #pragma unroll
;       for (int i = 0; i < 4; ++i) {
;         const int c = t2 + 256 * i, row = c >> 3, ch = c & 7;
;         if (row < mvalid) *(u32x4*)(p.HID + (size_t)(hid_row + row) * 512 + nt * 64 + ch * 8) = *(const u32x4*)(Ts + row * 72 + ch * 8);
	s_and_saveexec_b64 s[0:1], vcc
	s_xor_b64 s[0:1], exec, s[0:1]
	s_cbranch_execz .LBB0_1196
	v_mov_b64_e32 v[4:5], s[4:5]
	s_load_dwordx2 s[100:101], s[4:5], 0x170
	s_waitcnt lgkmcnt(0)
	v_mov_b32_e32 v8, s100
	v_mov_b32_e32 v9, s101
	v_mad_u64_u32 v[4:5], s[40:41], v3, s96, v[2:3]
	v_add_u32_e32 v10, s82, v3
	ds_read_b128 v[4:7], v4
	v_ashrrev_i32_e32 v11, 31, v10
	v_lshlrev_b64 v[10:11], 10, v[10:11]
	s_lshl_b32 s94, s83, 7
	v_mov_b32_e32 v3, v1
	s_waitcnt lgkmcnt(0)
	v_lshl_add_u64 v[8:9], v[8:9], 0, v[10:11]
	v_lshl_add_u64 v[8:9], v[8:9], 0, s[94:95]
	v_lshl_add_u64 v[8:9], v[8:9], 0, v[2:3]
	global_store_dwordx4 v[8:9], v[4:7], off sc1
.LBB0_1196:
	s_or_b64 exec, exec, s[0:1]
	v_add_u32_e32 v3, 0x100, v66
	v_ashrrev_i32_e32 v3, 3, v3
	v_cmp_gt_i32_e32 vcc, s86, v3
	s_and_saveexec_b64 s[0:1], vcc
	s_cbranch_execz .LBB0_1198
	v_mov_b64_e32 v[4:5], s[4:5]
	s_load_dwordx2 s[100:101], s[4:5], 0x170
	s_waitcnt lgkmcnt(0)
	v_mov_b32_e32 v8, s100
	v_mov_b32_e32 v9, s101
	v_mad_u64_u32 v[4:5], s[40:41], v3, s96, v[2:3]
	v_add_u32_e32 v10, s82, v3
	ds_read_b128 v[4:7], v4
	v_ashrrev_i32_e32 v11, 31, v10
	v_lshlrev_b64 v[10:11], 10, v[10:11]
	s_lshl_b32 s94, s83, 7
	v_mov_b32_e32 v3, v1
	s_waitcnt lgkmcnt(0)
	v_lshl_add_u64 v[8:9], v[8:9], 0, v[10:11]
	v_lshl_add_u64 v[8:9], v[8:9], 0, s[94:95]
	v_lshl_add_u64 v[8:9], v[8:9], 0, v[2:3]
	global_store_dwordx4 v[8:9], v[4:7], off sc1
.LBB0_1198:
	s_or_b64 exec, exec, s[0:1]
	v_add_u32_e32 v3, 0x200, v66
	v_ashrrev_i32_e32 v3, 3, v3
	v_cmp_gt_i32_e32 vcc, s86, v3
	s_and_saveexec_b64 s[0:1], vcc
	s_cbranch_execz .LBB0_1200
	v_mov_b64_e32 v[4:5], s[4:5]
	s_load_dwordx2 s[100:101], s[4:5], 0x170
	s_waitcnt lgkmcnt(0)
	v_mov_b32_e32 v8, s100
	v_mov_b32_e32 v9, s101
	v_mad_u64_u32 v[4:5], s[40:41], v3, s96, v[2:3]
	v_add_u32_e32 v10, s82, v3
	ds_read_b128 v[4:7], v4
	v_ashrrev_i32_e32 v11, 31, v10
	v_lshlrev_b64 v[10:11], 10, v[10:11]
	s_lshl_b32 s94, s83, 7
	v_mov_b32_e32 v3, v1
	s_waitcnt lgkmcnt(0)
	v_lshl_add_u64 v[8:9], v[8:9], 0, v[10:11]
	v_lshl_add_u64 v[8:9], v[8:9], 0, s[94:95]
	v_lshl_add_u64 v[2:3], v[8:9], 0, v[2:3]
	global_store_dwordx4 v[2:3], v[4:7], off sc1

; __device__ __forceinline__ void phase_moe_up(const Params& p, int l, bool last, unsigned char* smem) {
;     ...
; #pragma unroll
;       for (int i = 0; i < 4; ++i) {
;         const int c = t2 + 256 * i, row = c >> 3, ch = c & 7;
;         if (row < mvalid) *(u32x4*)(p.HID + (size_t)(hid_row + row) * 512 + nt * 64 + ch * 8) = *(const u32x4*)(Ts + row * 72 + ch * 8);
.LBB0_1202:
	v_mov_b64_e32 v[4:5], s[4:5]
	s_load_dwordx2 s[100:101], s[4:5], 0x170
	s_waitcnt lgkmcnt(0)
	v_mov_b32_e32 v6, s100
	v_mov_b32_e32 v7, s101
	v_mul_lo_u32 v3, v2, s96
	v_add_u32_e32 v8, s82, v2
	v_lshl_add_u32 v2, v0, 1, v3
	v_ashrrev_i32_e32 v9, 31, v8
	ds_read_b128 v[2:5], v2
	v_lshlrev_b64 v[8:9], 10, v[8:9]
	s_lshl_b32 s94, s83, 7
	s_waitcnt lgkmcnt(0)
	v_lshl_add_u64 v[6:7], v[6:7], 0, v[8:9]
	v_lshl_add_u64 v[6:7], v[6:7], 0, s[94:95]
	v_lshl_add_u64 v[6:7], v[0:1], 1, v[6:7]
	global_store_dwordx4 v[6:7], v[2:5], off sc1
	s_branch .LBB0_1102

; __device__ __forceinline__ u16 f2bf(float f) { return (u16)(pack2(f, 0.f) & 0xffffu); }
; template <int NT, class VF, class RP>
; __device__ __forceinline__ void epi_staged_bf16(f32x4 (&acc)[4][NT], int r0, int c0, unsigned char* smem, VF vf, RP rowptr) {
;     ...
;         Ts[r * PITCH + c] = f2bf(vf(r, c, acc[mi][ni][j]));
;       }
;   __syncthreads();
; #pragma unroll
;   for (int i = 0; i < CPR / 2; ++i) {
;     const int c = t + 256 * i, row = c / CPR, ch = c % CPR;
;     u16* d = rowptr(row);
;     if (d) *(u32x4*)(d + ch * 8) = *(const u32x4*)(Ts + row * PITCH + ch * 8);
;   }
; __device__ __forceinline__ void phase_moe_down(const Params& p, int l, bool last, unsigned char* smem) {
;     ...
;       auto vf = [&](int r, int, float v) { return (r < mvalid ? gate[r] : 0.f) * v; };
;       auto rp = [&](int r) -> u16* { return r < mvalid ? yb + (size_t)r * 1024 : nullptr; };
.LBB0_1407:
	s_or_b64 exec, exec, s[0:1]
	s_waitcnt lgkmcnt(0)
	v_mul_f32_e32 v2, v5, v2
	v_cvt_pk_bf16_f32 v2, v2, s0
	ds_write_b16 v10, v2 offset:96
	v_ashrrev_i32_e32 v2, 31, v0
	v_lshrrev_b32_e32 v2, 28, v2
	v_add_u32_e32 v2, v0, v2
	v_ashrrev_i32_e32 v2, 4, v2
	v_cmp_gt_i32_e64 s[38:39], s60, v2
	v_cmp_ne_u64_e64 s[40:41], 0, v[164:165]
	v_cmp_eq_u64_e32 vcc, 0, v[164:165]
	s_and_b64 s[8:9], s[38:39], s[40:41]
	s_waitcnt lgkmcnt(0)
	s_barrier
	s_and_saveexec_b64 s[0:1], s[8:9]
	s_cbranch_execz .LBB0_1409
	v_ashrrev_i32_e32 v3, 31, v2
	v_lshlrev_b64 v[6:7], 11, v[2:3]
	v_lshlrev_b32_e32 v3, 4, v2
	v_sub_u32_e32 v8, v0, v3
	v_mul_lo_u32 v2, v2, s23
	v_lshl_add_u32 v2, v8, 4, v2
	ds_read_b128 v[2:5], v2
	v_lshlrev_b32_e32 v8, 3, v8
	v_lshl_add_u64 v[6:7], v[160:161], 0, v[6:7]
	v_ashrrev_i32_e32 v9, 31, v8
	v_lshl_add_u64 v[6:7], v[8:9], 1, v[6:7]
	s_waitcnt lgkmcnt(0)
	global_store_dwordx4 v[6:7], v[2:5], off sc1
.LBB0_1409:
	s_or_b64 exec, exec, s[0:1]
	s_nop 0
	v_add_u32_e32 v4, 0x100, v0
	v_ashrrev_i32_e32 v2, 31, v4
	v_lshrrev_b32_e32 v2, 28, v2
	v_add_u32_e32 v2, v4, v2
	v_ashrrev_i32_e32 v2, 4, v2
	v_cmp_gt_i32_e64 s[38:39], s60, v2
	s_xor_b64 s[0:1], vcc, -1
	s_and_b64 s[36:37], s[38:39], s[0:1]
	s_and_saveexec_b64 s[8:9], s[36:37]
	s_cbranch_execz .LBB0_1411
	v_ashrrev_i32_e32 v3, 31, v2
	v_lshlrev_b64 v[6:7], 11, v[2:3]
	v_lshlrev_b32_e32 v3, 4, v2
	v_sub_u32_e32 v8, v4, v3
	v_mul_lo_u32 v2, v2, s23
	v_lshl_add_u32 v2, v8, 4, v2
	ds_read_b128 v[2:5], v2
	v_lshlrev_b32_e32 v8, 3, v8
	v_lshl_add_u64 v[6:7], v[160:161], 0, v[6:7]
	v_ashrrev_i32_e32 v9, 31, v8
	v_lshl_add_u64 v[6:7], v[8:9], 1, v[6:7]
	s_waitcnt lgkmcnt(0)
	global_store_dwordx4 v[6:7], v[2:5], off sc1
.LBB0_1411:
	s_or_b64 exec, exec, s[8:9]
	s_nop 0
	v_add_u32_e32 v4, 0x200, v0
	v_ashrrev_i32_e32 v2, 31, v4
	v_lshrrev_b32_e32 v2, 28, v2
	v_add_u32_e32 v2, v4, v2
	v_ashrrev_i32_e32 v2, 4, v2
	v_cmp_gt_i32_e32 vcc, s60, v2
	s_and_b64 s[36:37], vcc, s[0:1]
	s_and_saveexec_b64 s[8:9], s[36:37]
	s_cbranch_execz .LBB0_1413
	v_ashrrev_i32_e32 v3, 31, v2
	v_lshlrev_b64 v[6:7], 11, v[2:3]
	v_lshlrev_b32_e32 v3, 4, v2
	v_sub_u32_e32 v8, v4, v3
	v_mul_lo_u32 v2, v2, s23
	v_lshl_add_u32 v2, v8, 4, v2
	ds_read_b128 v[2:5], v2
	v_lshlrev_b32_e32 v8, 3, v8
	v_lshl_add_u64 v[6:7], v[160:161], 0, v[6:7]
	v_ashrrev_i32_e32 v9, 31, v8
	v_lshl_add_u64 v[6:7], v[8:9], 1, v[6:7]
	s_waitcnt lgkmcnt(0)
	global_store_dwordx4 v[6:7], v[2:5], off sc1
.LBB0_1413:
	s_or_b64 exec, exec, s[8:9]
	s_nop 0
	v_add_u32_e32 v4, 0x300, v0
	v_ashrrev_i32_e32 v2, 31, v4
	v_lshrrev_b32_e32 v2, 28, v2
	v_add_u32_e32 v2, v4, v2
	v_ashrrev_i32_e32 v2, 4, v2
	v_cmp_gt_i32_e32 vcc, s60, v2
	s_and_b64 s[36:37], vcc, s[0:1]
	s_and_saveexec_b64 s[8:9], s[36:37]
	s_cbranch_execz .LBB0_1415
	v_ashrrev_i32_e32 v3, 31, v2
	v_lshlrev_b64 v[6:7], 11, v[2:3]
	v_lshlrev_b32_e32 v3, 4, v2
	v_sub_u32_e32 v8, v4, v3
	v_mul_lo_u32 v2, v2, s23
	v_lshl_add_u32 v2, v8, 4, v2
	ds_read_b128 v[2:5], v2
	v_lshlrev_b32_e32 v8, 3, v8
	v_lshl_add_u64 v[6:7], v[160:161], 0, v[6:7]
	v_ashrrev_i32_e32 v9, 31, v8
	v_lshl_add_u64 v[6:7], v[8:9], 1, v[6:7]
	s_waitcnt lgkmcnt(0)
	global_store_dwordx4 v[6:7], v[2:5], off sc1
.LBB0_1415:
	s_or_b64 exec, exec, s[8:9]
	s_nop 0
	v_add_u32_e32 v4, 0x400, v0
	v_ashrrev_i32_e32 v2, 31, v4
	v_lshrrev_b32_e32 v2, 28, v2
	v_add_u32_e32 v2, v4, v2
	v_ashrrev_i32_e32 v2, 4, v2
	v_cmp_gt_i32_e32 vcc, s60, v2
	s_and_b64 s[36:37], vcc, s[0:1]
	s_and_saveexec_b64 s[8:9], s[36:37]
	s_cbranch_execz .LBB0_1417
	v_ashrrev_i32_e32 v3, 31, v2
	v_lshlrev_b64 v[6:7], 11, v[2:3]
	v_lshlrev_b32_e32 v3, 4, v2
	v_sub_u32_e32 v8, v4, v3
	v_mul_lo_u32 v2, v2, s23
	v_lshl_add_u32 v2, v8, 4, v2
	ds_read_b128 v[2:5], v2
	v_lshlrev_b32_e32 v8, 3, v8
	v_lshl_add_u64 v[6:7], v[160:161], 0, v[6:7]
	v_ashrrev_i32_e32 v9, 31, v8
	v_lshl_add_u64 v[6:7], v[8:9], 1, v[6:7]
	s_waitcnt lgkmcnt(0)
	global_store_dwordx4 v[6:7], v[2:5], off sc1
.LBB0_1417:
	s_or_b64 exec, exec, s[8:9]
	s_nop 0
	v_add_u32_e32 v4, 0x500, v0
	v_ashrrev_i32_e32 v2, 31, v4
	v_lshrrev_b32_e32 v2, 28, v2
	v_add_u32_e32 v2, v4, v2
	v_ashrrev_i32_e32 v2, 4, v2
	v_cmp_gt_i32_e32 vcc, s60, v2
	s_and_b64 s[36:37], vcc, s[0:1]
	s_and_saveexec_b64 s[8:9], s[36:37]
	s_cbranch_execz .LBB0_1419
	v_ashrrev_i32_e32 v3, 31, v2
	v_lshlrev_b64 v[6:7], 11, v[2:3]
	v_lshlrev_b32_e32 v3, 4, v2
	v_sub_u32_e32 v8, v4, v3
	v_mul_lo_u32 v2, v2, s23
	v_lshl_add_u32 v2, v8, 4, v2
	ds_read_b128 v[2:5], v2
	v_lshlrev_b32_e32 v8, 3, v8
	v_lshl_add_u64 v[6:7], v[160:161], 0, v[6:7]
	v_ashrrev_i32_e32 v9, 31, v8
	v_lshl_add_u64 v[6:7], v[8:9], 1, v[6:7]
	s_waitcnt lgkmcnt(0)
	global_store_dwordx4 v[6:7], v[2:5], off sc1
.LBB0_1419:
	s_or_b64 exec, exec, s[8:9]
	s_nop 0
	v_add_u32_e32 v4, 0x600, v0
	v_ashrrev_i32_e32 v2, 31, v4
	v_lshrrev_b32_e32 v2, 28, v2
	v_add_u32_e32 v2, v4, v2
	v_ashrrev_i32_e32 v2, 4, v2
	v_cmp_gt_i32_e32 vcc, s60, v2
	s_and_b64 s[36:37], vcc, s[0:1]
	s_and_saveexec_b64 s[8:9], s[36:37]
	s_cbranch_execz .LBB0_1421
	v_ashrrev_i32_e32 v3, 31, v2
	v_lshlrev_b64 v[6:7], 11, v[2:3]
	v_lshlrev_b32_e32 v3, 4, v2
	v_sub_u32_e32 v8, v4, v3
	v_mul_lo_u32 v2, v2, s23
	v_lshl_add_u32 v2, v8, 4, v2
	ds_read_b128 v[2:5], v2
	v_lshlrev_b32_e32 v8, 3, v8
	v_lshl_add_u64 v[6:7], v[160:161], 0, v[6:7]
	v_ashrrev_i32_e32 v9, 31, v8
	v_lshl_add_u64 v[6:7], v[8:9], 1, v[6:7]
	s_waitcnt lgkmcnt(0)
	global_store_dwordx4 v[6:7], v[2:5], off sc1

; __device__ __forceinline__ u16 f2bf(float f) { return (u16)(pack2(f, 0.f) & 0xffffu); }
; template <int NT, class VF, class RP>
; __device__ __forceinline__ void epi_staged_bf16(f32x4 (&acc)[4][NT], int r0, int c0, unsigned char* smem, VF vf, RP rowptr) {
;     ...
;         Ts[r * PITCH + c] = f2bf(vf(r, c, acc[mi][ni][j]));
;       }
;   __syncthreads();
; #pragma unroll
;   for (int i = 0; i < CPR / 2; ++i) {
;     const int c = t + 256 * i, row = c / CPR, ch = c % CPR;
;     u16* d = rowptr(row);
;     if (d) *(u32x4*)(d + ch * 8) = *(const u32x4*)(Ts + row * PITCH + ch * 8);
.LBB0_1644:
	s_or_b64 exec, exec, s[0:1]
	s_waitcnt lgkmcnt(0)
	v_mul_f32_e32 v2, v7, v4
	v_cvt_pk_bf16_f32 v2, v2, s0
	ds_write_b16 v12, v2 offset:96
	v_ashrrev_i32_e32 v2, 31, v0
	v_lshrrev_b32_e32 v2, 28, v2
	v_add_u32_e32 v2, v0, v2
	v_ashrrev_i32_e32 v2, 4, v2
	v_cmp_gt_i32_e64 s[38:39], s60, v2
	v_cmp_ne_u64_e64 s[40:41], 0, v[164:165]
	v_cmp_eq_u64_e32 vcc, 0, v[164:165]
	s_and_b64 s[8:9], s[38:39], s[40:41]
	s_waitcnt lgkmcnt(0)
	s_barrier
	s_and_saveexec_b64 s[0:1], s[8:9]
	s_cbranch_execz .LBB0_1646
	v_ashrrev_i32_e32 v3, 31, v2
	v_lshlrev_b64 v[6:7], 11, v[2:3]
	v_lshlrev_b32_e32 v3, 4, v2
	v_sub_u32_e32 v8, v0, v3
	v_mul_lo_u32 v2, v2, s23
	v_lshl_add_u32 v2, v8, 4, v2
	ds_read_b128 v[2:5], v2
	v_lshlrev_b32_e32 v8, 3, v8
	v_lshl_add_u64 v[6:7], v[160:161], 0, v[6:7]
	v_ashrrev_i32_e32 v9, 31, v8
	v_lshl_add_u64 v[6:7], v[8:9], 1, v[6:7]
	s_waitcnt lgkmcnt(0)
	global_store_dwordx4 v[6:7], v[2:5], off sc1

; template <int NT, class VF, class RP>
; __device__ __forceinline__ void epi_staged_bf16(f32x4 (&acc)[4][NT], int r0, int c0, unsigned char* smem, VF vf, RP rowptr) {
;     ...
; #pragma unroll
;   for (int i = 0; i < CPR / 2; ++i) {
;     const int c = t + 256 * i, row = c / CPR, ch = c % CPR;
;     u16* d = rowptr(row);
;     if (d) *(u32x4*)(d + ch * 8) = *(const u32x4*)(Ts + row * PITCH + ch * 8);
;   }
.LBB0_1660:
	v_ashrrev_i32_e32 v3, 31, v2
	v_lshlrev_b64 v[4:5], 11, v[2:3]
	v_ashrrev_i32_e32 v3, 31, v0
	v_lshrrev_b32_e32 v3, 28, v3
	v_add_u32_e32 v3, v0, v3
	v_and_b32_e32 v3, -16, v3
	v_sub_u32_e32 v0, v0, v3
	v_mul_lo_u32 v2, v2, s23
	v_lshlrev_b32_e32 v8, 3, v0
	v_lshl_add_u32 v0, v0, 4, v2
	v_lshl_add_u64 v[6:7], v[160:161], 0, v[4:5]
	ds_read_b128 v[2:5], v0
	v_ashrrev_i32_e32 v9, 31, v8
	v_lshl_add_u64 v[6:7], v[8:9], 1, v[6:7]
	s_waitcnt lgkmcnt(0)
	global_store_dwordx4 v[6:7], v[2:5], off sc1
	s_branch .LBB0_1267

; template <bool COMBINE, bool MOD>
; __device__ __forceinline__ void phase_combine_modulate(const Params& p, int lprev, int lnext, const float* xlat, const float* xctx,
;                                                        float* olat, float* octx, int nrows) {
;     ...
; #pragma unroll
;         for (int i = 0; i < 4; ++i) {
;           const int col = i * 256 + lane * 4;
;           const float4 g4 = *(const float4*)(g2 + col);
;           v[r][i].x += g4.x * s[i].x; v[r][i].y += g4.y * s[i].y; v[r][i].z += g4.z * s[i].z; v[r][i].w += g4.w * s[i].w;
;           *(float4*)(orow + (size_t)r * DM + col) = v[r][i];
;         }
.Lcb2_acc1:
	v_pk_fma_f32 v[100:101], v[34:35], v[2:3], v[100:101]
	v_pk_fma_f32 v[102:103], v[36:37], v[4:5], v[102:103]
	global_store_dwordx4 v188, v[100:103], s[98:99] sc1
	v_pk_fma_f32 v[104:105], v[38:39], v[6:7], v[104:105]
	v_pk_fma_f32 v[106:107], v[40:41], v[8:9], v[106:107]
	global_store_dwordx4 v188, v[104:107], s[98:99] offset:1024 sc1
	v_pk_fma_f32 v[108:109], v[42:43], v[10:11], v[108:109]
	v_pk_fma_f32 v[110:111], v[44:45], v[12:13], v[110:111]
	global_store_dwordx4 v188, v[108:111], s[98:99] offset:2048 sc1
	v_pk_fma_f32 v[112:113], v[46:47], v[14:15], v[112:113]
	v_pk_fma_f32 v[114:115], v[48:49], v[16:17], v[114:115]
	global_store_dwordx4 v188, v[112:115], s[98:99] offset:3072 sc1
	v_pk_fma_f32 v[116:117], v[34:35], v[18:19], v[116:117]
	v_pk_fma_f32 v[118:119], v[36:37], v[20:21], v[118:119]
	global_store_dwordx4 v189, v[116:119], s[98:99] sc1
	v_pk_fma_f32 v[120:121], v[38:39], v[22:23], v[120:121]
	v_pk_fma_f32 v[122:123], v[40:41], v[24:25], v[122:123]
	global_store_dwordx4 v189, v[120:123], s[98:99] offset:1024 sc1
	v_pk_fma_f32 v[124:125], v[42:43], v[26:27], v[124:125]
	v_pk_fma_f32 v[126:127], v[44:45], v[28:29], v[126:127]
	global_store_dwordx4 v189, v[124:127], s[98:99] offset:2048 sc1
	v_pk_fma_f32 v[128:129], v[46:47], v[30:31], v[128:129]
	v_pk_fma_f32 v[130:131], v[48:49], v[32:33], v[130:131]
	global_store_dwordx4 v189, v[128:131], s[98:99] offset:3072 sc1
	v_mov_b32_e32 v100, v132
	v_mov_b32_e32 v101, v133
	v_mov_b32_e32 v102, v134
	v_mov_b32_e32 v103, v135
	v_mov_b32_e32 v104, v136
	v_mov_b32_e32 v105, v137
	v_mov_b32_e32 v106, v138
	v_mov_b32_e32 v107, v139
	v_mov_b32_e32 v108, v140
	v_mov_b32_e32 v109, v141
	v_mov_b32_e32 v110, v142
	v_mov_b32_e32 v111, v143
	v_mov_b32_e32 v112, v144
	v_mov_b32_e32 v113, v145
	v_mov_b32_e32 v114, v146
	v_mov_b32_e32 v115, v147
	v_mov_b32_e32 v116, v148
	v_mov_b32_e32 v117, v149
	v_mov_b32_e32 v118, v150
	v_mov_b32_e32 v119, v151
	v_mov_b32_e32 v120, v152
	v_mov_b32_e32 v121, v153
	v_mov_b32_e32 v122, v154
	v_mov_b32_e32 v123, v155
	v_mov_b32_e32 v124, v156
	v_mov_b32_e32 v125, v157
	v_mov_b32_e32 v126, v158
	v_mov_b32_e32 v127, v159
	v_mov_b32_e32 v128, v160
	v_mov_b32_e32 v129, v161
	v_mov_b32_e32 v130, v162
	v_mov_b32_e32 v131, v163
	v_mov_b32_e32 v199, v211
	s_mov_b64 s[98:99], s[100:101]
	s_mov_b32 s52, s94
	s_cmp_lt_i32 s52, 0x4000
	s_cbranch_scc1 .Lcb2_loop
	s_waitcnt vmcnt(0)
